# non-temporal cache hint on single-use streams: f32 weight and x-row reads of the conversion code and the final output stores (operands of the GEMMs and the residual stream stay cached)
# speedup vs baseline: 1.0016x; 1.0016x over previous
; #define LAS __attribute__((address_space(3)))
; template <bool PERMUTE, bool BLOCKED = false>
; __device__ __forceinline__ void cvt_tile64(const float* W, int K, int N, bf16* WT, int ldo, const float* gk, LAS float* scr, int tile, int lane) {
;     const int nblk = N >> 6, kb = tile / nblk, nb = tile - kb * nblk, k0 = 64 * kb, n0 = 64 * nb;
;     const int lk = lane >> 4, ln = (lane & 15) * 4;
;     ...
;     {
;         f32x4 v[16];
; #pragma unroll
;         for (int i = 0; i < 16; ++i) v[i] = *(const f32x4*)(W + (size_t)(k0 + 4 * i + lk) * N + n0 + ln);
; #pragma unroll
;         for (int i = 0; i < 16; ++i) { const int kk = 4 * i + lk; const float g = gk ? gk[k0 + kk] : 1.0f; LAS float* d = scr + kk * 65 + ln;
;             d[0] = v[i][0] * g; d[1] = v[i][1] * g; d[2] = v[i][2] * g; d[3] = v[i][3] * g; }
;     }
;     ...
; #pragma unroll
;     for (int hh = 0; hh < 2; ++hh) {
;         f32x4 v[8];
; #pragma unroll
;         for (int i = 0; i < 8; ++i) v[i] = *(const f32x4*)(W + (size_t)(k0 + 32 * hh + 4 * i + lk) * N + n0 + ln);
; #pragma unroll
;         for (int i = 0; i < 8; ++i) { const int kk = 32 * hh + 4 * i + lk; const float g = gk ? gk[k0 + kk] : 1.0f; LAS float* d = scr + kk * 65 + ln;
;             d[0] = v[i][0] * g; d[1] = v[i][1] * g; d[2] = v[i][2] * g; d[3] = v[i][3] * g; }
.LBB0_12:
	s_mul_hi_i32 s0, s15, 0x38e38e39
	s_lshr_b32 s1, s0, 31
	s_ashr_i32 s17, s0, 5
	s_add_i32 s17, s17, s1
	s_mul_i32 s0, s17, 0xffffdc00
	s_add_i32 s12, s3, s0
	s_lshl_b32 s10, s17, 6
	s_ashr_i32 s13, s12, 31
	v_or_b32_e32 v50, s10, v44
	v_lshl_add_u64 v[52:53], s[12:13], 2, v[46:47]
	v_mad_i64_i32 v[0:1], s[0:1], v50, s14, v[52:53]
	v_or_b32_e32 v2, 4, v50
	v_mad_i64_i32 v[2:3], s[0:1], v2, s14, v[52:53]
	global_load_dwordx4 v[28:31], v[0:1], off nt
	global_load_dwordx4 v[24:27], v[2:3], off nt
	v_or_b32_e32 v0, 8, v50
	v_mad_i64_i32 v[0:1], s[0:1], v0, s14, v[52:53]
	v_or_b32_e32 v2, 12, v50
	v_mad_i64_i32 v[2:3], s[0:1], v2, s14, v[52:53]
	global_load_dwordx4 v[20:23], v[0:1], off nt
	global_load_dwordx4 v[16:19], v[2:3], off nt
	v_or_b32_e32 v0, 16, v50
	v_mad_i64_i32 v[0:1], s[0:1], v0, s14, v[52:53]
	v_or_b32_e32 v2, 20, v50
	v_mad_i64_i32 v[2:3], s[0:1], v2, s14, v[52:53]
	global_load_dwordx4 v[12:15], v[0:1], off nt
	global_load_dwordx4 v[8:11], v[2:3], off nt
	v_or_b32_e32 v0, 24, v50
	v_mad_i64_i32 v[32:33], s[0:1], v0, s14, v[52:53]
	v_or_b32_e32 v0, 28, v50
	v_mad_i64_i32 v[34:35], s[0:1], v0, s14, v[52:53]
	global_load_dwordx4 v[4:7], v[32:33], off nt
	global_load_dwordx4 v[0:3], v[34:35], off nt
	v_ashrrev_i32_e32 v51, 31, v50
	v_mov_b32_e32 v32, 1.0
	s_and_b64 vcc, exec, s[4:5]
	v_mov_b32_e32 v34, 1.0
	s_cbranch_vccnz .LBB0_14
	v_readlane_b32 s48, v253, 11
	v_readlane_b32 s50, v253, 13
	v_readlane_b32 s51, v253, 14
	s_ashr_i32 s11, s10, 31
	v_readlane_b32 s49, v253, 12
	v_lshl_add_u64 v[34:35], v[50:51], 2, s[50:51]
	global_load_dword v110, v[34:35], off offset:16
	global_load_dword v124, v[34:35], off offset:32
	global_load_dword v125, v[34:35], off offset:48
	global_load_dword v126, v[34:35], off offset:64
	global_load_dword v127, v[34:35], off offset:80
	global_load_dword v178, v[34:35], off offset:96
	global_load_dword v179, v[34:35], off offset:112
	global_load_dword v180, v[34:35], off offset:128
	global_load_dword v181, v[34:35], off offset:144
	global_load_dword v182, v[34:35], off offset:160
	global_load_dword v183, v[34:35], off offset:176
	global_load_dword v184, v[34:35], off offset:192
	global_load_dword v185, v[34:35], off offset:208
	global_load_dword v186, v[34:35], off offset:224
	global_load_dword v187, v[34:35], off offset:240
	global_load_dword v36, v[34:35], off
	s_waitcnt vmcnt(0)
	v_lshl_add_u64 v[34:35], s[10:11], 0, v[44:45]
	v_lshl_add_u64 v[34:35], v[34:35], 2, s[50:51]
	v_mov_b32_e32 v34, v110
	v_readlane_b32 s52, v253, 15
	v_readlane_b32 s53, v253, 16
	v_readlane_b32 s54, v253, 17
	v_readlane_b32 s55, v253, 18
	v_readlane_b32 s56, v253, 19
	v_readlane_b32 s57, v253, 20
	v_readlane_b32 s58, v253, 21
	v_readlane_b32 s59, v253, 22
	v_readlane_b32 s60, v253, 23
	v_readlane_b32 s61, v253, 24
	v_readlane_b32 s62, v253, 25
	v_readlane_b32 s63, v253, 26
	s_waitcnt vmcnt(1)
	v_pk_mul_f32 v[28:29], v[28:29], v[36:37] op_sel_hi:[1,0]
	v_pk_mul_f32 v[30:31], v[30:31], v[36:37] op_sel_hi:[1,0]

; #define LAS __attribute__((address_space(3)))
; template <bool PERMUTE, bool BLOCKED = false>
; __device__ __forceinline__ void cvt_tile64(const float* W, int K, int N, bf16* WT, int ldo, const float* gk, LAS float* scr, int tile, int lane) {
;     ...
;     for (int hh = 0; hh < 2; ++hh) {
;         f32x4 v[8];
; #pragma unroll
;         for (int i = 0; i < 8; ++i) v[i] = *(const f32x4*)(W + (size_t)(k0 + 32 * hh + 4 * i + lk) * N + n0 + ln);
; #pragma unroll
;         for (int i = 0; i < 8; ++i) { const int kk = 32 * hh + 4 * i + lk; const float g = gk ? gk[k0 + kk] : 1.0f; LAS float* d = scr + kk * 65 + ln;
;             d[0] = v[i][0] * g; d[1] = v[i][1] * g; d[2] = v[i][2] * g; d[3] = v[i][3] * g; }
.LBB0_20:
	v_or_b32_e32 v8, 32, v50
	v_mad_i64_i32 v[8:9], s[0:1], v8, s14, v[52:53]
	v_or_b32_e32 v10, 36, v50
	v_mad_i64_i32 v[10:11], s[0:1], v10, s14, v[52:53]
	global_load_dwordx4 v[36:39], v[8:9], off nt
	global_load_dwordx4 v[32:35], v[10:11], off nt
	v_or_b32_e32 v8, 40, v50
	v_mad_i64_i32 v[8:9], s[0:1], v8, s14, v[52:53]
	v_or_b32_e32 v10, 44, v50
	v_mad_i64_i32 v[10:11], s[0:1], v10, s14, v[52:53]
	global_load_dwordx4 v[28:31], v[8:9], off nt
	global_load_dwordx4 v[24:27], v[10:11], off nt
	v_or_b32_e32 v8, 48, v50
	v_mad_i64_i32 v[8:9], s[0:1], v8, s14, v[52:53]
	v_or_b32_e32 v10, 52, v50
	v_mad_i64_i32 v[10:11], s[0:1], v10, s14, v[52:53]
	global_load_dwordx4 v[20:23], v[8:9], off nt
	global_load_dwordx4 v[16:19], v[10:11], off nt
	v_or_b32_e32 v8, 56, v50
	v_mad_i64_i32 v[64:65], s[0:1], v8, s14, v[52:53]
	v_or_b32_e32 v8, 60, v50
	v_mad_i64_i32 v[50:51], s[0:1], v8, s14, v[52:53]
	global_load_dwordx4 v[12:15], v[64:65], off nt
	global_load_dwordx4 v[8:11], v[50:51], off nt
	v_add_u32_e32 v50, 0x1860, v63
	ds_write2_b32 v50, v4, v5 offset1:1
	v_add_u32_e32 v4, 0x1868, v63
	ds_write2_b32 v4, v6, v7 offset1:1
	s_waitcnt vmcnt(8)
	v_pk_mul_f32 v[0:1], v[0:1], v[54:55] op_sel_hi:[1,0]
	v_add_u32_e32 v4, 0x1c70, v63
	ds_write2_b32 v4, v0, v1 offset1:1
	v_pk_mul_f32 v[0:1], v[2:3], v[54:55] op_sel_hi:[1,0]
	v_add_u32_e32 v2, 0x1c78, v63
	ds_write2_b32 v2, v0, v1 offset1:1
	v_mov_b32_e32 v0, 1.0
	s_and_b64 vcc, exec, s[4:5]
	v_mov_b32_e32 v2, 1.0
	s_cbranch_vccnz .LBB0_22
	s_ashr_i32 s11, s10, 31
	v_readlane_b32 s48, v253, 11
	v_lshl_add_u64 v[2:3], s[10:11], 0, v[44:45]
	v_readlane_b32 s50, v253, 13
	v_readlane_b32 s51, v253, 14
	v_readlane_b32 s49, v253, 12
	v_readlane_b32 s52, v253, 15
	v_lshl_add_u64 v[4:5], v[2:3], 2, s[50:51]
	v_mov_b32_e32 v6, v180
	v_mov_b32_e32 v2, v181
	v_readlane_b32 s53, v253, 16
	v_readlane_b32 s54, v253, 17
	v_readlane_b32 s55, v253, 18
	v_readlane_b32 s56, v253, 19
	v_readlane_b32 s57, v253, 20
	v_readlane_b32 s58, v253, 21
	v_readlane_b32 s59, v253, 22
	v_readlane_b32 s60, v253, 23
	v_readlane_b32 s61, v253, 24
	v_readlane_b32 s62, v253, 25
	v_readlane_b32 s63, v253, 26
	s_waitcnt vmcnt(1)
	v_pk_mul_f32 v[36:37], v[36:37], v[6:7] op_sel_hi:[1,0]
	v_pk_mul_f32 v[38:39], v[38:39], v[6:7] op_sel_hi:[1,0]

; __device__ __forceinline__ unsigned cvt_pk_bf16(float lo, float hi) { const f32x2c_t v = {lo, hi}; return __builtin_bit_cast(unsigned, __builtin_convertvector(v, bf16x2c_t)); }
; __device__ __forceinline__ void cvt_rows_bf16(const float* x, bf16* out, float* part, int gw, int ngw, int lane) {
;     for (int m = gw; m < M; m += ngw) {
;         const f32x4* xr = (const f32x4*)(x + (size_t)m * DM) + lane;
;         v2u* o = (v2u*)(out + (size_t)m * DM) + lane;
;         float ss = 0.f;
; #pragma unroll
;         for (int j = 0; j < 16; ++j) { const f32x4 v = xr[64 * j]; ss += (v[0] * v[0] + v[1] * v[1]) + (v[2] * v[2] + v[3] * v[3]);
;             v2u ov; ov[0] = cvt_pk_bf16(v[0], v[1]); ov[1] = cvt_pk_bf16(v[2], v[3]); o[64 * j] = ov; }
;         ss = wave_sum(ss);
;         part[(size_t)m * 64 + lane] = (lane == 0) ? ss : 0.f;
;     }
.LBB0_35:
	v_add_co_u32_e32 v10, vcc, s1, v18
	s_nop 1
	v_addc_co_u32_e32 v11, vcc, 0, v19, vcc
	v_add_co_u32_e32 v12, vcc, s2, v18
	s_nop 1
	v_addc_co_u32_e32 v13, vcc, 0, v19, vcc
	v_add_co_u32_e32 v194, vcc, s9, v18
	s_nop 1
	v_addc_co_u32_e32 v195, vcc, 0, v19, vcc
	global_load_dwordx4 v[32:35], v[18:19], off nt
	global_load_dwordx4 v[36:39], v[18:19], off offset:1024 nt
	global_load_dwordx4 v[40:43], v[18:19], off offset:2048 nt
	global_load_dwordx4 v[44:47], v[18:19], off offset:3072 nt
	global_load_dwordx4 v[48:51], v[10:11], off nt
	global_load_dwordx4 v[52:55], v[10:11], off offset:1024 nt
	global_load_dwordx4 v[56:59], v[10:11], off offset:2048 nt
	global_load_dwordx4 v[60:63], v[10:11], off offset:3072 nt
	global_load_dwordx4 v[64:67], v[12:13], off nt
	global_load_dwordx4 v[68:71], v[12:13], off offset:1024 nt
	global_load_dwordx4 v[72:75], v[12:13], off offset:2048 nt
	global_load_dwordx4 v[76:79], v[12:13], off offset:3072 nt
	global_load_dwordx4 v[178:181], v[194:195], off nt
	global_load_dwordx4 v[182:185], v[194:195], off offset:1024 nt
	global_load_dwordx4 v[186:189], v[194:195], off offset:2048 nt
	global_load_dwordx4 v[190:193], v[194:195], off offset:3072 nt
	v_lshl_add_u64 v[8:9], s[46:47], 0, v[20:21]
	v_add_co_u32_e32 v14, vcc, s0, v8
	s_nop 1
	v_addc_co_u32_e32 v15, vcc, 0, v9, vcc
	v_add_co_u32_e32 v22, vcc, s3, v8
	s_nop 1
	v_addc_co_u32_e32 v23, vcc, 0, v9, vcc
	v_lshl_add_u64 v[196:197], s[46:47], 0, v[16:17]
	v_lshl_add_u64 v[18:19], v[18:19], 0, s[12:13]
	v_lshl_add_u64 v[20:21], v[20:21], 0, s[14:15]
	v_lshl_add_u64 v[16:17], v[16:17], 0, s[10:11]
	s_waitcnt vmcnt(15)
	v_cvt_pk_bf16_f32 v6, v32, v33
	v_cvt_pk_bf16_f32 v7, v34, v35
	global_store_dwordx2 v[14:15], v[6:7], off
	v_pk_mul_f32 v[2:3], v[32:33], v[32:33]
	v_pk_mul_f32 v[4:5], v[34:35], v[34:35]
	v_add_f32_e32 v2, v2, v3
	v_add_f32_e32 v4, v4, v5
	v_add_f32_e32 v0, v2, v4
	s_waitcnt vmcnt(15)
	v_cvt_pk_bf16_f32 v198, v36, v37
	v_cvt_pk_bf16_f32 v199, v38, v39
	global_store_dwordx2 v[14:15], v[198:199], off offset:512
	v_pk_mul_f32 v[2:3], v[36:37], v[36:37]
	v_pk_mul_f32 v[4:5], v[38:39], v[38:39]
	v_add_f32_e32 v2, v2, v3
	v_add_f32_e32 v4, v4, v5
	v_add_f32_e32 v2, v2, v4
	v_add_f32_e32 v0, v0, v2
	s_waitcnt vmcnt(15)
	v_cvt_pk_bf16_f32 v6, v40, v41
	v_cvt_pk_bf16_f32 v7, v42, v43
	global_store_dwordx2 v[14:15], v[6:7], off offset:1024
	v_pk_mul_f32 v[2:3], v[40:41], v[40:41]
	v_pk_mul_f32 v[4:5], v[42:43], v[42:43]
	v_add_f32_e32 v2, v2, v3
	v_add_f32_e32 v4, v4, v5
	v_add_f32_e32 v2, v2, v4
	v_add_f32_e32 v0, v0, v2
	s_waitcnt vmcnt(15)
	v_cvt_pk_bf16_f32 v198, v44, v45
	v_cvt_pk_bf16_f32 v199, v46, v47
	global_store_dwordx2 v[14:15], v[198:199], off offset:1536
	v_pk_mul_f32 v[2:3], v[44:45], v[44:45]
	v_pk_mul_f32 v[4:5], v[46:47], v[46:47]
	v_add_f32_e32 v2, v2, v3
	v_add_f32_e32 v4, v4, v5
	v_add_f32_e32 v2, v2, v4
	v_add_f32_e32 v0, v0, v2
	s_waitcnt vmcnt(15)
	v_cvt_pk_bf16_f32 v6, v48, v49
	v_cvt_pk_bf16_f32 v7, v50, v51
	global_store_dwordx2 v[14:15], v[6:7], off offset:2048
	v_pk_mul_f32 v[2:3], v[48:49], v[48:49]
	v_pk_mul_f32 v[4:5], v[50:51], v[50:51]
	v_add_f32_e32 v2, v2, v3
	v_add_f32_e32 v4, v4, v5
	v_add_f32_e32 v2, v2, v4
	v_add_f32_e32 v0, v0, v2
	s_waitcnt vmcnt(15)
	v_cvt_pk_bf16_f32 v198, v52, v53
	v_cvt_pk_bf16_f32 v199, v54, v55
	global_store_dwordx2 v[14:15], v[198:199], off offset:2560
	v_pk_mul_f32 v[2:3], v[52:53], v[52:53]
	v_pk_mul_f32 v[4:5], v[54:55], v[54:55]
	v_add_f32_e32 v2, v2, v3
	v_add_f32_e32 v4, v4, v5
	v_add_f32_e32 v2, v2, v4
	v_add_f32_e32 v0, v0, v2
	s_waitcnt vmcnt(15)
	v_cvt_pk_bf16_f32 v6, v56, v57
	v_cvt_pk_bf16_f32 v7, v58, v59
	global_store_dwordx2 v[14:15], v[6:7], off offset:3072
	v_pk_mul_f32 v[2:3], v[56:57], v[56:57]
	v_pk_mul_f32 v[4:5], v[58:59], v[58:59]
	v_add_f32_e32 v2, v2, v3
	v_add_f32_e32 v4, v4, v5
	v_add_f32_e32 v2, v2, v4
	v_add_f32_e32 v0, v0, v2
	s_waitcnt vmcnt(15)
; __device__ __forceinline__ unsigned cvt_pk_bf16(float lo, float hi) { const f32x2c_t v = {lo, hi}; return __builtin_bit_cast(unsigned, __builtin_convertvector(v, bf16x2c_t)); }
; __device__ __forceinline__ float wave_sum(float v) {
; #pragma unroll
;     for (int o = 1; o < 64; o <<= 1) v += __shfl_xor(v, o);
;     return v;
; }
; __device__ __forceinline__ void cvt_rows_bf16(const float* x, bf16* out, float* part, int gw, int ngw, int lane) {
;     for (int m = gw; m < M; m += ngw) {
;         const f32x4* xr = (const f32x4*)(x + (size_t)m * DM) + lane;
;         v2u* o = (v2u*)(out + (size_t)m * DM) + lane;
;         float ss = 0.f;
; #pragma unroll
;         for (int j = 0; j < 16; ++j) { const f32x4 v = xr[64 * j]; ss += (v[0] * v[0] + v[1] * v[1]) + (v[2] * v[2] + v[3] * v[3]);
;             v2u ov; ov[0] = cvt_pk_bf16(v[0], v[1]); ov[1] = cvt_pk_bf16(v[2], v[3]); o[64 * j] = ov; }
;         ss = wave_sum(ss);
;         part[(size_t)m * 64 + lane] = (lane == 0) ? ss : 0.f;
;     }
	v_cvt_pk_bf16_f32 v198, v60, v61
	v_cvt_pk_bf16_f32 v199, v62, v63
	global_store_dwordx2 v[14:15], v[198:199], off offset:3584
	v_pk_mul_f32 v[2:3], v[60:61], v[60:61]
	v_pk_mul_f32 v[4:5], v[62:63], v[62:63]
	v_add_f32_e32 v2, v2, v3
	v_add_f32_e32 v4, v4, v5
	v_add_f32_e32 v2, v2, v4
	v_add_f32_e32 v0, v0, v2
	s_waitcnt vmcnt(15)
	v_cvt_pk_bf16_f32 v6, v64, v65
	v_cvt_pk_bf16_f32 v7, v66, v67
	global_store_dwordx2 v[22:23], v[6:7], off
	v_pk_mul_f32 v[2:3], v[64:65], v[64:65]
	v_pk_mul_f32 v[4:5], v[66:67], v[66:67]
	v_add_f32_e32 v2, v2, v3
	v_add_f32_e32 v4, v4, v5
	v_add_f32_e32 v2, v2, v4
	v_add_f32_e32 v0, v0, v2
	s_waitcnt vmcnt(15)
	v_cvt_pk_bf16_f32 v198, v68, v69
	v_cvt_pk_bf16_f32 v199, v70, v71
	global_store_dwordx2 v[22:23], v[198:199], off offset:512
	v_pk_mul_f32 v[2:3], v[68:69], v[68:69]
	v_pk_mul_f32 v[4:5], v[70:71], v[70:71]
	v_add_f32_e32 v2, v2, v3
	v_add_f32_e32 v4, v4, v5
	v_add_f32_e32 v2, v2, v4
	v_add_f32_e32 v0, v0, v2
	s_waitcnt vmcnt(15)
	v_cvt_pk_bf16_f32 v6, v72, v73
	v_cvt_pk_bf16_f32 v7, v74, v75
	global_store_dwordx2 v[22:23], v[6:7], off offset:1024
	v_pk_mul_f32 v[2:3], v[72:73], v[72:73]
	v_pk_mul_f32 v[4:5], v[74:75], v[74:75]
	v_add_f32_e32 v2, v2, v3
	v_add_f32_e32 v4, v4, v5
	v_add_f32_e32 v2, v2, v4
	v_add_f32_e32 v0, v0, v2
	s_waitcnt vmcnt(15)
	v_cvt_pk_bf16_f32 v198, v76, v77
	v_cvt_pk_bf16_f32 v199, v78, v79
	global_store_dwordx2 v[22:23], v[198:199], off offset:1536
	v_pk_mul_f32 v[2:3], v[76:77], v[76:77]
	v_pk_mul_f32 v[4:5], v[78:79], v[78:79]
	v_add_f32_e32 v2, v2, v3
	v_add_f32_e32 v4, v4, v5
	v_add_f32_e32 v2, v2, v4
	v_add_f32_e32 v0, v0, v2
	s_waitcnt vmcnt(15)
	v_cvt_pk_bf16_f32 v6, v178, v179
	v_cvt_pk_bf16_f32 v7, v180, v181
	global_store_dwordx2 v[22:23], v[6:7], off offset:2048
	v_pk_mul_f32 v[2:3], v[178:179], v[178:179]
	v_pk_mul_f32 v[4:5], v[180:181], v[180:181]
	v_add_f32_e32 v2, v2, v3
	v_add_f32_e32 v4, v4, v5
	v_add_f32_e32 v2, v2, v4
	v_add_f32_e32 v0, v0, v2
	s_waitcnt vmcnt(15)
	v_cvt_pk_bf16_f32 v198, v182, v183
	v_cvt_pk_bf16_f32 v199, v184, v185
	global_store_dwordx2 v[22:23], v[198:199], off offset:2560
	v_pk_mul_f32 v[2:3], v[182:183], v[182:183]
	v_pk_mul_f32 v[4:5], v[184:185], v[184:185]
	v_add_f32_e32 v2, v2, v3
	v_add_f32_e32 v4, v4, v5
	v_add_f32_e32 v2, v2, v4
	v_add_f32_e32 v0, v0, v2
	s_waitcnt vmcnt(15)
	v_cvt_pk_bf16_f32 v6, v186, v187
	v_cvt_pk_bf16_f32 v7, v188, v189
	global_store_dwordx2 v[22:23], v[6:7], off offset:3072
	v_pk_mul_f32 v[2:3], v[186:187], v[186:187]
	v_pk_mul_f32 v[4:5], v[188:189], v[188:189]
	v_add_f32_e32 v2, v2, v3
	v_add_f32_e32 v4, v4, v5
	v_add_f32_e32 v2, v2, v4
	v_add_f32_e32 v0, v0, v2
	s_waitcnt vmcnt(15)
	v_cvt_pk_bf16_f32 v198, v190, v191
	v_cvt_pk_bf16_f32 v199, v192, v193
	global_store_dwordx2 v[22:23], v[198:199], off offset:3584
	v_pk_mul_f32 v[2:3], v[190:191], v[190:191]
	v_pk_mul_f32 v[4:5], v[192:193], v[192:193]
	v_add_f32_e32 v2, v2, v3
	v_add_f32_e32 v4, v4, v5
	v_add_f32_e32 v2, v2, v4
	v_add_f32_e32 v0, v0, v2
	ds_bpermute_b32 v1, v25, v0
	s_waitcnt lgkmcnt(0)
	v_add_f32_e32 v0, v0, v1
	ds_bpermute_b32 v1, v26, v0
	s_waitcnt lgkmcnt(0)
	v_add_f32_e32 v0, v0, v1
	ds_bpermute_b32 v1, v27, v0
	s_waitcnt lgkmcnt(0)
	v_add_f32_e32 v0, v0, v1
	ds_bpermute_b32 v1, v28, v0
	s_waitcnt lgkmcnt(0)
	v_add_f32_e32 v0, v0, v1
	ds_bpermute_b32 v1, v29, v0
	s_waitcnt lgkmcnt(0)
	v_add_f32_e32 v0, v0, v1
	ds_bpermute_b32 v1, v30, v0
	s_waitcnt lgkmcnt(0)
	v_add_f32_e32 v0, v0, v1
	v_cndmask_b32_e64 v0, 0, v0, s[4:5]
	global_store_dword v[196:197], v0, off
	s_add_i32 s8, s8, s68
	s_cmpk_lt_i32 s8, 0x4000
	s_cbranch_scc1 .LBB0_35

; #define LAS __attribute__((address_space(3)))
; template <bool PERMUTE, bool BLOCKED = false>
; __device__ __forceinline__ void cvt_tile64(const float* W, int K, int N, bf16* WT, int ldo, const float* gk, LAS float* scr, int tile, int lane) {
;     const int nblk = N >> 6, kb = tile / nblk, nb = tile - kb * nblk, k0 = 64 * kb, n0 = 64 * nb;
;     const int lk = lane >> 4, ln = (lane & 15) * 4;
;     ...
;     {
;         f32x4 v[16];
; #pragma unroll
;         for (int i = 0; i < 16; ++i) v[i] = *(const f32x4*)(W + (size_t)(k0 + 4 * i + lk) * N + n0 + ln);
; #pragma unroll
;         for (int i = 0; i < 16; ++i) { const int kk = 4 * i + lk; const float g = gk ? gk[k0 + kk] : 1.0f; LAS float* d = scr + kk * 65 + ln;
;             d[0] = v[i][0] * g; d[1] = v[i][1] * g; d[2] = v[i][2] * g; d[3] = v[i][3] * g; }
;     }
;     ...
; #pragma unroll
;     for (int hh = 0; hh < 2; ++hh) {
;         f32x4 v[8];
; #pragma unroll
;         for (int i = 0; i < 8; ++i) v[i] = *(const f32x4*)(W + (size_t)(k0 + 32 * hh + 4 * i + lk) * N + n0 + ln);
; #pragma unroll
;         for (int i = 0; i < 8; ++i) { const int kk = 32 * hh + 4 * i + lk; const float g = gk ? gk[k0 + kk] : 1.0f; LAS float* d = scr + kk * 65 + ln;
;             d[0] = v[i][0] * g; d[1] = v[i][1] * g; d[2] = v[i][2] * g; d[3] = v[i][3] * g; }
.LBB0_94:
	s_cmpk_gt_i32 s14, 0x1ff
	s_mov_b64 s[0:1], -1
	s_cbranch_scc0 .LBB0_114
	s_add_i32 s0, s5, 0xfffff000
	s_ashr_i32 s1, s0, 31
	s_lshr_b32 s1, s1, 24
	s_add_i32 s0, s0, s1
	s_ashr_i32 s0, s0, 8
	s_lshl_b32 s12, s0, 6
	s_lshl_b32 s15, s0, 14
	s_sub_i32 s0, s4, s15
	v_or_b32_e32 v52, s12, v16
	s_add_i32 s0, s0, 0xfffc0000
	v_or_b32_e32 v2, 4, v52
	s_ashr_i32 s1, s0, 31
	v_ashrrev_i32_e32 v53, 31, v52
	v_ashrrev_i32_e32 v3, 31, v2
	v_lshl_add_u64 v[50:51], s[0:1], 2, v[42:43]
	v_lshlrev_b64 v[0:1], 16, v[52:53]
	v_lshlrev_b64 v[2:3], 16, v[2:3]
	v_lshl_add_u64 v[0:1], v[50:51], 0, v[0:1]
	v_lshl_add_u64 v[2:3], v[50:51], 0, v[2:3]
	global_load_dwordx4 v[30:33], v[0:1], off nt
	global_load_dwordx4 v[26:29], v[2:3], off nt
	v_or_b32_e32 v0, 8, v52
	v_or_b32_e32 v2, 12, v52
	v_ashrrev_i32_e32 v1, 31, v0
	v_ashrrev_i32_e32 v3, 31, v2
	v_lshlrev_b64 v[0:1], 16, v[0:1]
	v_lshlrev_b64 v[2:3], 16, v[2:3]
	v_lshl_add_u64 v[0:1], v[50:51], 0, v[0:1]
	v_lshl_add_u64 v[2:3], v[50:51], 0, v[2:3]
	global_load_dwordx4 v[22:25], v[0:1], off nt
	global_load_dwordx4 v[18:21], v[2:3], off nt
	v_or_b32_e32 v0, 16, v52
	v_or_b32_e32 v2, 20, v52
	v_ashrrev_i32_e32 v1, 31, v0
	v_ashrrev_i32_e32 v3, 31, v2
	v_lshlrev_b64 v[0:1], 16, v[0:1]
	v_lshlrev_b64 v[2:3], 16, v[2:3]
	v_lshl_add_u64 v[0:1], v[50:51], 0, v[0:1]
	v_lshl_add_u64 v[2:3], v[50:51], 0, v[2:3]
	global_load_dwordx4 v[12:15], v[0:1], off nt
	global_load_dwordx4 v[8:11], v[2:3], off nt
	v_or_b32_e32 v0, 24, v52
	v_or_b32_e32 v2, 28, v52
	v_ashrrev_i32_e32 v1, 31, v0
	v_ashrrev_i32_e32 v3, 31, v2
	v_lshlrev_b64 v[0:1], 16, v[0:1]
	v_lshlrev_b64 v[2:3], 16, v[2:3]
	v_lshl_add_u64 v[0:1], v[50:51], 0, v[0:1]
	v_lshl_add_u64 v[2:3], v[50:51], 0, v[2:3]
	global_load_dwordx4 v[4:7], v[0:1], off nt
	s_nop 0
	global_load_dwordx4 v[0:3], v[2:3], off nt
	v_cmp_ne_u32_e64 s[6:7], 1, v59
	s_andn2_b64 vcc, exec, s[10:11]
	v_mov_b32_e32 v34, 1.0
	v_mov_b32_e32 v36, 1.0
	s_cbranch_vccnz .LBB0_97
	v_lshl_add_u64 v[36:37], v[52:53], 2, s[8:9]
	s_ashr_i32 s13, s12, 31
	global_load_dword v110, v[36:37], off offset:16
	global_load_dword v124, v[36:37], off offset:32
	global_load_dword v125, v[36:37], off offset:48
	global_load_dword v126, v[36:37], off offset:64
	global_load_dword v127, v[36:37], off offset:80
	global_load_dword v178, v[36:37], off offset:96
	global_load_dword v179, v[36:37], off offset:112
	global_load_dword v180, v[36:37], off offset:128
	global_load_dword v181, v[36:37], off offset:144
	global_load_dword v182, v[36:37], off offset:160
	global_load_dword v183, v[36:37], off offset:176
	global_load_dword v184, v[36:37], off offset:192
	global_load_dword v185, v[36:37], off offset:208
	global_load_dword v186, v[36:37], off offset:224
	global_load_dword v187, v[36:37], off offset:240
	global_load_dword v38, v[36:37], off
	s_waitcnt vmcnt(0)
	v_lshl_add_u64 v[36:37], s[12:13], 0, v[16:17]
	v_lshl_add_u64 v[36:37], v[36:37], 2, s[8:9]
	v_mov_b32_e32 v36, v110
	s_waitcnt vmcnt(1)
	v_pk_mul_f32 v[30:31], v[30:31], v[38:39] op_sel_hi:[1,0]
	v_pk_mul_f32 v[32:33], v[32:33], v[38:39] op_sel_hi:[1,0]

; #define LAS __attribute__((address_space(3)))
; template <bool PERMUTE, bool BLOCKED = false>
; __device__ __forceinline__ void cvt_tile64(const float* W, int K, int N, bf16* WT, int ldo, const float* gk, LAS float* scr, int tile, int lane) {
;     ...
;     for (int hh = 0; hh < 2; ++hh) {
;         f32x4 v[8];
; #pragma unroll
;         for (int i = 0; i < 8; ++i) v[i] = *(const f32x4*)(W + (size_t)(k0 + 32 * hh + 4 * i + lk) * N + n0 + ln);
; #pragma unroll
;         for (int i = 0; i < 8; ++i) { const int kk = 32 * hh + 4 * i + lk; const float g = gk ? gk[k0 + kk] : 1.0f; LAS float* d = scr + kk * 65 + ln;
;             d[0] = v[i][0] * g; d[1] = v[i][1] * g; d[2] = v[i][2] * g; d[3] = v[i][3] * g; }
.LBB0_103:
	v_or_b32_e32 v8, 32, v52
	v_or_b32_e32 v10, 36, v52
	v_ashrrev_i32_e32 v9, 31, v8
	v_ashrrev_i32_e32 v11, 31, v10
	v_lshlrev_b64 v[8:9], 16, v[8:9]
	v_lshlrev_b64 v[10:11], 16, v[10:11]
	v_lshl_add_u64 v[8:9], v[50:51], 0, v[8:9]
	v_lshl_add_u64 v[10:11], v[50:51], 0, v[10:11]
	global_load_dwordx4 v[38:41], v[8:9], off nt
	global_load_dwordx4 v[34:37], v[10:11], off nt
	v_or_b32_e32 v8, 40, v52
	v_or_b32_e32 v10, 44, v52
	v_ashrrev_i32_e32 v9, 31, v8
	v_ashrrev_i32_e32 v11, 31, v10
	v_lshlrev_b64 v[8:9], 16, v[8:9]
	v_lshlrev_b64 v[10:11], 16, v[10:11]
	v_lshl_add_u64 v[8:9], v[50:51], 0, v[8:9]
	v_lshl_add_u64 v[10:11], v[50:51], 0, v[10:11]
	global_load_dwordx4 v[30:33], v[8:9], off nt
	global_load_dwordx4 v[26:29], v[10:11], off nt
	v_or_b32_e32 v8, 48, v52
	v_or_b32_e32 v10, 52, v52
	v_ashrrev_i32_e32 v9, 31, v8
	v_ashrrev_i32_e32 v11, 31, v10
	v_lshlrev_b64 v[8:9], 16, v[8:9]
	v_lshlrev_b64 v[10:11], 16, v[10:11]
	v_lshl_add_u64 v[8:9], v[50:51], 0, v[8:9]
	v_lshl_add_u64 v[10:11], v[50:51], 0, v[10:11]
	global_load_dwordx4 v[22:25], v[8:9], off nt
	global_load_dwordx4 v[18:21], v[10:11], off nt
	v_or_b32_e32 v8, 56, v52
	v_or_b32_e32 v10, 60, v52
	v_ashrrev_i32_e32 v9, 31, v8
	v_ashrrev_i32_e32 v11, 31, v10
	v_lshlrev_b64 v[8:9], 16, v[8:9]
	v_lshlrev_b64 v[10:11], 16, v[10:11]
	v_lshl_add_u64 v[8:9], v[50:51], 0, v[8:9]
	v_lshl_add_u64 v[10:11], v[50:51], 0, v[10:11]
	global_load_dwordx4 v[12:15], v[8:9], off nt
	s_nop 0
	global_load_dwordx4 v[8:11], v[10:11], off nt
	v_add_u32_e32 v50, 0x1860, v53
	ds_write2_b32 v50, v4, v5 offset1:1
	v_add_u32_e32 v4, 0x1868, v53
	ds_write2_b32 v4, v6, v7 offset1:1
	s_waitcnt vmcnt(8)
	v_pk_mul_f32 v[0:1], v[0:1], v[54:55] op_sel_hi:[1,0]
	v_add_u32_e32 v4, 0x1c70, v53
	ds_write2_b32 v4, v0, v1 offset1:1
	v_pk_mul_f32 v[0:1], v[2:3], v[54:55] op_sel_hi:[1,0]
	v_add_u32_e32 v2, 0x1c78, v53
	ds_write2_b32 v2, v0, v1 offset1:1
	v_mov_b32_e32 v0, 1.0
	s_and_b64 vcc, exec, s[6:7]
	v_mov_b32_e32 v2, 1.0
	s_cbranch_vccnz .LBB0_105
	s_ashr_i32 s13, s12, 31
	v_lshl_add_u64 v[2:3], s[12:13], 0, v[16:17]
	v_lshl_add_u64 v[2:3], v[2:3], 2, s[8:9]
	v_mov_b32_e32 v4, v180
	s_nop 0
	v_mov_b32_e32 v2, v181
	s_waitcnt vmcnt(1)
	v_pk_mul_f32 v[38:39], v[38:39], v[4:5] op_sel_hi:[1,0]
	v_pk_mul_f32 v[40:41], v[40:41], v[4:5] op_sel_hi:[1,0]

; #define LAS __attribute__((address_space(3)))
; #define LDS_WAIT() asm volatile("s_waitcnt lgkmcnt(0)" ::: "memory")
; template <bool PERMUTE, bool BLOCKED = false>
; __device__ __forceinline__ void cvt_tile64(const float* W, int K, int N, bf16* WT, int ldo, const float* gk, LAS float* scr, int tile, int lane) {
;     const int nblk = N >> 6, kb = tile / nblk, nb = tile - kb * nblk, k0 = 64 * kb, n0 = 64 * nb;
;     const int lk = lane >> 4, ln = (lane & 15) * 4;
;     ...
;     {
;         f32x4 v[16];
; #pragma unroll
;         for (int i = 0; i < 16; ++i) v[i] = *(const f32x4*)(W + (size_t)(k0 + 4 * i + lk) * N + n0 + ln);
; #pragma unroll
;         for (int i = 0; i < 16; ++i) { const int kk = 4 * i + lk; const float g = gk ? gk[k0 + kk] : 1.0f; LAS float* d = scr + kk * 65 + ln;
;             d[0] = v[i][0] * g; d[1] = v[i][1] * g; d[2] = v[i][2] * g; d[3] = v[i][3] * g; }
;     }
;     ...
; #pragma unroll
;     for (int hh = 0; hh < 2; ++hh) {
;         f32x4 v[8];
; #pragma unroll
;         for (int i = 0; i < 8; ++i) v[i] = *(const f32x4*)(W + (size_t)(k0 + 32 * hh + 4 * i + lk) * N + n0 + ln);
; #pragma unroll
;         for (int i = 0; i < 8; ++i) { const int kk = 32 * hh + 4 * i + lk; const float g = gk ? gk[k0 + kk] : 1.0f; LAS float* d = scr + kk * 65 + ln;
;             d[0] = v[i][0] * g; d[1] = v[i][1] * g; d[2] = v[i][2] * g; d[3] = v[i][3] * g; }
;     }
;     ...
;     LDS_WAIT(); asm volatile("" ::: "memory");
.LBB0_114:
	s_and_b64 vcc, exec, s[0:1]
	s_cbranch_vccz .LBB0_93
	s_ashr_i32 s0, s5, 31
	s_lshr_b32 s0, s0, 26
	s_add_i32 s0, s5, s0
	s_and_b32 s12, s0, 0xffffffc0
	s_lshl_b32 s0, s0, 6
	s_and_b32 s0, s0, 0xfffff000
	v_or_b32_e32 v0, s12, v16
	s_sub_i32 s6, s4, s0
	v_or_b32_e32 v4, 4, v0
	s_ashr_i32 s7, s6, 31
	v_ashrrev_i32_e32 v5, 31, v4
	v_or_b32_e32 v8, 8, v0
	v_lshl_add_u64 v[2:3], s[6:7], 2, v[46:47]
	v_lshlrev_b64 v[4:5], 14, v[4:5]
	v_ashrrev_i32_e32 v9, 31, v8
	v_lshl_add_u64 v[4:5], v[2:3], 0, v[4:5]
	v_lshlrev_b64 v[8:9], 14, v[8:9]
	global_load_dwordx4 v[4:7], v[4:5], off nt
	v_lshl_add_u64 v[8:9], v[2:3], 0, v[8:9]
	global_load_dwordx4 v[8:11], v[8:9], off nt
	v_or_b32_e32 v12, 12, v0
	v_ashrrev_i32_e32 v13, 31, v12
	v_or_b32_e32 v18, 16, v0
	v_lshlrev_b64 v[12:13], 14, v[12:13]
	v_ashrrev_i32_e32 v19, 31, v18
	v_lshl_add_u64 v[12:13], v[2:3], 0, v[12:13]
	v_lshlrev_b64 v[18:19], 14, v[18:19]
	global_load_dwordx4 v[12:15], v[12:13], off nt
	v_lshl_add_u64 v[18:19], v[2:3], 0, v[18:19]
	global_load_dwordx4 v[18:21], v[18:19], off nt
	v_or_b32_e32 v22, 20, v0
	v_ashrrev_i32_e32 v23, 31, v22
	v_lshlrev_b64 v[22:23], 14, v[22:23]
	v_lshl_add_u64 v[22:23], v[2:3], 0, v[22:23]
	global_load_dwordx4 v[22:25], v[22:23], off nt
	v_add_u32_e32 v30, v55, v56
	v_add_u32_e32 v26, 0x410, v30
	v_ashrrev_i32_e32 v1, 31, v0
	v_add_u32_e32 v27, 0x418, v30
	v_add_u32_e32 v28, 0xc30, v30
	s_ashr_i32 s13, s12, 31
	s_waitcnt vmcnt(4)
	ds_write2_b32 v26, v4, v5 offset1:1
	v_lshlrev_b64 v[4:5], 14, v[0:1]
	v_add_u32_e32 v1, 0x820, v30
	v_add_u32_e32 v26, 0x828, v30
	s_waitcnt vmcnt(3)
	ds_write2_b32 v1, v8, v9 offset1:1
	v_or_b32_e32 v8, 24, v0
	ds_write2_b32 v26, v10, v11 offset1:1
	v_or_b32_e32 v10, 28, v0
	v_ashrrev_i32_e32 v9, 31, v8
	v_lshl_add_u64 v[4:5], v[2:3], 0, v[4:5]
	v_ashrrev_i32_e32 v11, 31, v10
	v_lshlrev_b64 v[8:9], 14, v[8:9]
	ds_write2_b32 v27, v6, v7 offset1:1
	global_load_dwordx4 v[4:7], v[4:5], off nt
	v_add_u32_e32 v1, 0xc38, v30
	v_lshlrev_b64 v[10:11], 14, v[10:11]
	v_lshl_add_u64 v[8:9], v[2:3], 0, v[8:9]
	v_lshl_add_u64 v[26:27], v[2:3], 0, v[10:11]
	global_load_dwordx4 v[8:11], v[8:9], off nt
	s_waitcnt vmcnt(4)
	ds_write2_b32 v1, v14, v15 offset1:1
	v_add_u32_e32 v1, 0x1040, v30
	s_waitcnt vmcnt(3)
	ds_write2_b32 v1, v18, v19 offset1:1
	v_or_b32_e32 v18, 32, v0
	ds_write2_b32 v28, v12, v13 offset1:1
	global_load_dwordx4 v[12:15], v[26:27], off nt
	v_ashrrev_i32_e32 v19, 31, v18
	v_lshlrev_b64 v[18:19], 14, v[18:19]
	v_add_u32_e32 v26, 0x1048, v30
	v_lshl_add_u64 v[18:19], v[2:3], 0, v[18:19]
	ds_write2_b32 v26, v20, v21 offset1:1
	global_load_dwordx4 v[18:21], v[18:19], off nt
	v_add_u32_e32 v1, 0x1450, v30
	s_waitcnt vmcnt(4)
	ds_write2_b32 v1, v22, v23 offset1:1
	v_or_b32_e32 v22, 36, v0
	v_ashrrev_i32_e32 v23, 31, v22
	v_lshlrev_b64 v[22:23], 14, v[22:23]
	v_add_u32_e32 v26, 0x1458, v30
	v_lshl_add_u64 v[22:23], v[2:3], 0, v[22:23]
	ds_write2_b32 v26, v24, v25 offset1:1
	global_load_dwordx4 v[22:25], v[22:23], off nt
	v_add_u32_e32 v1, 0x1860, v30
	v_add_u32_e32 v26, 0x1868, v30
	v_add_u32_e32 v27, 0x1c70, v30
	s_waitcnt vmcnt(4)
	ds_write2_b32 v30, v4, v5 offset1:1
	ds_write2_b32 v30, v6, v7 offset0:2 offset1:3
	v_add_u32_e32 v4, 0x1c78, v30
	s_waitcnt vmcnt(3)
	ds_write2_b32 v1, v8, v9 offset1:1
	ds_write2_b32 v26, v10, v11 offset1:1
	s_waitcnt vmcnt(2)
	ds_write2_b32 v27, v12, v13 offset1:1
	ds_write2_b32 v4, v14, v15 offset1:1
	v_or_b32_e32 v4, 40, v0
	v_or_b32_e32 v6, 44, v0
	v_ashrrev_i32_e32 v5, 31, v4
	v_ashrrev_i32_e32 v7, 31, v6
	v_lshlrev_b64 v[4:5], 14, v[4:5]
	v_lshlrev_b64 v[6:7], 14, v[6:7]
	v_lshl_add_u64 v[4:5], v[2:3], 0, v[4:5]
	v_lshl_add_u64 v[8:9], v[2:3], 0, v[6:7]
	v_or_b32_e32 v12, 48, v0
	v_or_b32_e32 v14, 52, v0
	global_load_dwordx4 v[4:7], v[4:5], off nt
	s_nop 0
	global_load_dwordx4 v[8:11], v[8:9], off nt
	v_ashrrev_i32_e32 v13, 31, v12
	v_ashrrev_i32_e32 v15, 31, v14
	v_add_u32_e32 v1, 0x2080, v30
	v_lshlrev_b64 v[12:13], 14, v[12:13]
	v_lshlrev_b64 v[14:15], 14, v[14:15]
	s_waitcnt vmcnt(3)
	ds_write2_b32 v1, v18, v19 offset1:1
	v_add_u32_e32 v1, 0x2088, v30
	v_lshl_add_u64 v[12:13], v[2:3], 0, v[12:13]
	v_lshl_add_u64 v[26:27], v[2:3], 0, v[14:15]
	ds_write2_b32 v1, v20, v21 offset1:1
	global_load_dwordx4 v[12:15], v[12:13], off nt
	s_nop 0
	global_load_dwordx4 v[18:21], v[26:27], off nt
	v_or_b32_e32 v26, 56, v0
	v_ashrrev_i32_e32 v27, 31, v26
	v_or_b32_e32 v0, 60, v0
	v_lshlrev_b64 v[26:27], 14, v[26:27]
	v_ashrrev_i32_e32 v1, 31, v0
	v_lshl_add_u64 v[26:27], v[2:3], 0, v[26:27]
	v_lshlrev_b64 v[0:1], 14, v[0:1]
	v_lshl_add_u64 v[28:29], v[2:3], 0, v[0:1]
	global_load_dwordx4 v[0:3], v[26:27], off nt
	v_add_u32_e32 v26, 0x2490, v30
	s_waitcnt vmcnt(5)
	ds_write2_b32 v26, v22, v23 offset1:1
	v_add_u32_e32 v22, 0x2498, v30
	ds_write2_b32 v22, v24, v25 offset1:1
	global_load_dwordx4 v[22:25], v[28:29], off nt
	v_add_u32_e32 v26, 0x28a0, v30
	v_add_u32_e32 v28, 0x400, v58
	s_waitcnt vmcnt(5)
	ds_write2_b32 v26, v4, v5 offset1:1
	v_add_u32_e32 v4, 0x28a8, v30
	ds_write2_b32 v4, v6, v7 offset1:1
	v_add_u32_e32 v4, 0x2cb0, v30
	s_waitcnt vmcnt(4)
	ds_write2_b32 v4, v8, v9 offset1:1
	v_add_u32_e32 v4, 0x2cb8, v30
	ds_write2_b32 v4, v10, v11 offset1:1
	v_add_u32_e32 v4, 0x30c0, v30
	s_waitcnt vmcnt(3)
	ds_write2_b32 v4, v12, v13 offset1:1
	v_add_u32_e32 v4, 0x30c8, v30
	ds_write2_b32 v4, v14, v15 offset1:1
	v_add_u32_e32 v4, 0x34d0, v30
	s_waitcnt vmcnt(2)
	ds_write2_b32 v4, v18, v19 offset1:1
	v_add_u32_e32 v4, 0x34d8, v30
	ds_write2_b32 v4, v20, v21 offset1:1
	v_add_u32_e32 v4, 0x38e0, v30
	s_waitcnt vmcnt(1)
	ds_write2_b32 v4, v0, v1 offset1:1
	v_add_u32_e32 v0, 0x38e8, v30
	ds_write2_b32 v0, v2, v3 offset1:1
	v_add_u32_e32 v0, 0x3cf0, v30
	s_waitcnt vmcnt(0)
; __host__ __device__ __forceinline__ size_t blocked_off(int row, int col, int K) { return (((size_t)(row >> 8) * (K >> 6) + (col >> 6)) * 256 + (row & 255)) * 64 + (col & 63); }
; __device__ __forceinline__ unsigned cvt_pk_bf16(float lo, float hi) { const f32x2c_t v = {lo, hi}; return __builtin_bit_cast(unsigned, __builtin_convertvector(v, bf16x2c_t)); }
; #define LAS __attribute__((address_space(3)))
; #define LDS_WAIT() asm volatile("s_waitcnt lgkmcnt(0)" ::: "memory")
; __host__ __device__ __forceinline__ int win_phys_col(int n) { if (!win_rope_tile(n >> 8)) return n; const int cl = n & 255; return (n & ~255) | (cl & 63) | ((cl & 64) << 1) | ((cl & 128) >> 1); }
; __device__ __forceinline__ float wrnd(float x) {
;     ...
;     unsigned u = __float_as_uint(x); u = (u + (1u << (22 - W_MANT))) & ~((1u << (23 - W_MANT)) - 1u); return __uint_as_float(u);
;     ...
;     return x;
;     ...
; }
; template <bool PERMUTE, bool BLOCKED = false>
; __device__ __forceinline__ void cvt_tile64(const float* W, int K, int N, bf16* WT, int ldo, const float* gk, LAS float* scr, int tile, int lane) {
;     ...
;     const int kc = lane & 7, nrow0 = PERMUTE ? win_phys_col(n0) : n0;
; #pragma unroll
;     for (int j = 0; j < 8; ++j) { const int n = (lane >> 3) + 8 * j; const LAS float* s = scr + (8 * kc) * 65 + n;
;         v4u o; o[0] = cvt_pk_bf16(wrnd(s[0 * 65]), wrnd(s[1 * 65])); o[1] = cvt_pk_bf16(wrnd(s[2 * 65]), wrnd(s[3 * 65])); o[2] = cvt_pk_bf16(wrnd(s[4 * 65]), wrnd(s[5 * 65])); o[3] = cvt_pk_bf16(wrnd(s[6 * 65]), wrnd(s[7 * 65]));
;         *(v4u*)(WT + (BLOCKED ? pg8::blocked_off(nrow0 + n, k0 + 8 * kc, K) : (size_t)(nrow0 + n) * ldo + k0 + 8 * kc)) = o; }
;     LDS_WAIT(); asm volatile("" ::: "memory");
	ds_write2_b32 v0, v22, v23 offset1:1
	v_add_u32_e32 v0, 0x3cf8, v30
	ds_write2_b32 v0, v24, v25 offset1:1
	s_waitcnt lgkmcnt(0)
	ds_read2_b32 v[8:9], v58 offset1:8
	ds_read2_b32 v[10:11], v58 offset0:65 offset1:73
	ds_read2_b32 v[12:13], v58 offset0:130 offset1:138
	ds_read2_b32 v[14:15], v58 offset0:195 offset1:203
	ds_read2_b32 v[18:19], v28 offset0:4 offset1:12
	ds_read2_b32 v[20:21], v28 offset0:69 offset1:77
	s_waitcnt lgkmcnt(5)
	v_add_u32_e32 v2, 0x20000, v8
	s_waitcnt lgkmcnt(4)
	v_add_u32_e32 v3, 0x20000, v10
	v_and_b32_e32 v2, 0xfffc0000, v2
	v_and_b32_e32 v3, 0xfffc0000, v3
	ds_read2_b32 v[22:23], v28 offset0:134 offset1:142
	ds_read2_b32 v[24:25], v28 offset0:199 offset1:207
	v_cvt_pk_bf16_f32 v4, v2, v3
	s_waitcnt lgkmcnt(5)
	v_add_u32_e32 v2, 0x20000, v12
	s_waitcnt lgkmcnt(4)
	v_add_u32_e32 v3, 0x20000, v14
	v_and_b32_e32 v2, 0xfffc0000, v2
	v_and_b32_e32 v3, 0xfffc0000, v3
	v_cvt_pk_bf16_f32 v5, v2, v3
	s_waitcnt lgkmcnt(3)
	v_add_u32_e32 v2, 0x20000, v18
	s_waitcnt lgkmcnt(2)
	v_add_u32_e32 v3, 0x20000, v20
	v_and_b32_e32 v2, 0xfffc0000, v2
	v_and_b32_e32 v3, 0xfffc0000, v3
	v_cvt_pk_bf16_f32 v6, v2, v3
	s_waitcnt lgkmcnt(1)
	v_add_u32_e32 v2, 0x20000, v22
	s_waitcnt lgkmcnt(0)
	v_add_u32_e32 v3, 0x20000, v24
	v_and_b32_e32 v2, 0xfffc0000, v2
	v_and_b32_e32 v3, 0xfffc0000, v3
	v_cvt_pk_bf16_f32 v7, v2, v3
	v_add_u32_e32 v2, s6, v57
	v_ashrrev_i32_e32 v3, 31, v2
	v_lshl_add_u64 v[0:1], s[12:13], 1, v[48:49]
	v_lshlrev_b64 v[26:27], 13, v[2:3]
	v_lshl_add_u64 v[26:27], v[0:1], 0, v[26:27]
	global_store_dwordx4 v[26:27], v[4:7], off
	v_add_u32_e32 v3, 0x20000, v9
	v_and_b32_e32 v3, 0xfffc0000, v3
	v_add_u32_e32 v4, 0x20000, v11
	v_and_b32_e32 v4, 0xfffc0000, v4
	v_cvt_pk_bf16_f32 v4, v3, v4
	v_add_u32_e32 v3, 0x20000, v13
	v_add_u32_e32 v5, 0x20000, v15
	v_and_b32_e32 v3, 0xfffc0000, v3
	v_and_b32_e32 v5, 0xfffc0000, v5
	v_cvt_pk_bf16_f32 v5, v3, v5
	v_add_u32_e32 v3, 0x20000, v19
	v_add_u32_e32 v6, 0x20000, v21
	v_and_b32_e32 v3, 0xfffc0000, v3
	v_and_b32_e32 v6, 0xfffc0000, v6
	v_add_u32_e32 v8, 8, v2
	v_cvt_pk_bf16_f32 v6, v3, v6
	v_add_u32_e32 v3, 0x20000, v23
	v_add_u32_e32 v7, 0x20000, v25
	v_ashrrev_i32_e32 v9, 31, v8
	v_and_b32_e32 v3, 0xfffc0000, v3
	v_and_b32_e32 v7, 0xfffc0000, v7
	ds_read2_b32 v[10:11], v58 offset0:16 offset1:24
	v_lshlrev_b64 v[8:9], 13, v[8:9]
	ds_read2_b32 v[12:13], v58 offset0:81 offset1:89
	v_cvt_pk_bf16_f32 v7, v3, v7
	v_lshl_add_u64 v[8:9], v[0:1], 0, v[8:9]
	global_store_dwordx4 v[8:9], v[4:7], off
	ds_read2_b32 v[8:9], v58 offset0:146 offset1:154
	ds_read2_b32 v[14:15], v58 offset0:211 offset1:219
	ds_read2_b32 v[18:19], v28 offset0:20 offset1:28
	ds_read2_b32 v[20:21], v28 offset0:85 offset1:93
	s_waitcnt lgkmcnt(5)
	v_add_u32_e32 v3, 0x20000, v10
	s_waitcnt lgkmcnt(4)
	v_add_u32_e32 v4, 0x20000, v12
	v_and_b32_e32 v3, 0xfffc0000, v3
	v_and_b32_e32 v4, 0xfffc0000, v4
	ds_read2_b32 v[22:23], v28 offset0:150 offset1:158
	ds_read2_b32 v[24:25], v28 offset0:215 offset1:223
	v_cvt_pk_bf16_f32 v4, v3, v4
	s_waitcnt lgkmcnt(5)
	v_add_u32_e32 v3, 0x20000, v8
	s_waitcnt lgkmcnt(4)
	v_add_u32_e32 v5, 0x20000, v14
	v_and_b32_e32 v3, 0xfffc0000, v3
	v_and_b32_e32 v5, 0xfffc0000, v5
	v_cvt_pk_bf16_f32 v5, v3, v5
	s_waitcnt lgkmcnt(3)
	v_add_u32_e32 v3, 0x20000, v18
	s_waitcnt lgkmcnt(2)
	v_add_u32_e32 v6, 0x20000, v20
	v_and_b32_e32 v3, 0xfffc0000, v3
	v_and_b32_e32 v6, 0xfffc0000, v6
	v_add_u32_e32 v26, 16, v2
	v_cvt_pk_bf16_f32 v6, v3, v6
	s_waitcnt lgkmcnt(1)
	v_add_u32_e32 v3, 0x20000, v22
	s_waitcnt lgkmcnt(0)
	v_add_u32_e32 v7, 0x20000, v24
	v_ashrrev_i32_e32 v27, 31, v26
	v_and_b32_e32 v3, 0xfffc0000, v3
	v_and_b32_e32 v7, 0xfffc0000, v7
	v_lshlrev_b64 v[26:27], 13, v[26:27]
	v_cvt_pk_bf16_f32 v7, v3, v7
	v_lshl_add_u64 v[26:27], v[0:1], 0, v[26:27]
	global_store_dwordx4 v[26:27], v[4:7], off
	v_add_u32_e32 v3, 0x20000, v11
	v_and_b32_e32 v3, 0xfffc0000, v3
	v_add_u32_e32 v4, 0x20000, v13
	v_and_b32_e32 v4, 0xfffc0000, v4
	v_cvt_pk_bf16_f32 v4, v3, v4
	v_add_u32_e32 v3, 0x20000, v9
	v_add_u32_e32 v5, 0x20000, v15
	v_and_b32_e32 v3, 0xfffc0000, v3
	v_and_b32_e32 v5, 0xfffc0000, v5
	v_cvt_pk_bf16_f32 v5, v3, v5
	v_add_u32_e32 v3, 0x20000, v19
	v_add_u32_e32 v6, 0x20000, v21
	v_and_b32_e32 v3, 0xfffc0000, v3
	v_and_b32_e32 v6, 0xfffc0000, v6
	v_add_u32_e32 v8, 24, v2
	v_cvt_pk_bf16_f32 v6, v3, v6
	v_add_u32_e32 v3, 0x20000, v23
	v_add_u32_e32 v7, 0x20000, v25
	v_ashrrev_i32_e32 v9, 31, v8
	v_and_b32_e32 v3, 0xfffc0000, v3
	v_and_b32_e32 v7, 0xfffc0000, v7
	ds_read2_b32 v[10:11], v58 offset0:32 offset1:40
	v_lshlrev_b64 v[8:9], 13, v[8:9]
	ds_read2_b32 v[12:13], v58 offset0:97 offset1:105
	v_cvt_pk_bf16_f32 v7, v3, v7
	v_lshl_add_u64 v[8:9], v[0:1], 0, v[8:9]
	global_store_dwordx4 v[8:9], v[4:7], off
	ds_read2_b32 v[8:9], v58 offset0:162 offset1:170
	ds_read2_b32 v[14:15], v58 offset0:227 offset1:235
	ds_read2_b32 v[18:19], v28 offset0:36 offset1:44
	ds_read2_b32 v[20:21], v28 offset0:101 offset1:109
	s_waitcnt lgkmcnt(5)
; __host__ __device__ __forceinline__ size_t blocked_off(int row, int col, int K) { return (((size_t)(row >> 8) * (K >> 6) + (col >> 6)) * 256 + (row & 255)) * 64 + (col & 63); }
; __device__ __forceinline__ unsigned cvt_pk_bf16(float lo, float hi) { const f32x2c_t v = {lo, hi}; return __builtin_bit_cast(unsigned, __builtin_convertvector(v, bf16x2c_t)); }
; #define LAS __attribute__((address_space(3)))
; #define LDS_WAIT() asm volatile("s_waitcnt lgkmcnt(0)" ::: "memory")
; __host__ __device__ __forceinline__ int win_phys_col(int n) { if (!win_rope_tile(n >> 8)) return n; const int cl = n & 255; return (n & ~255) | (cl & 63) | ((cl & 64) << 1) | ((cl & 128) >> 1); }
; template <bool PERMUTE, bool BLOCKED = false>
; __device__ __forceinline__ void cvt_tile64(const float* W, int K, int N, bf16* WT, int ldo, const float* gk, LAS float* scr, int tile, int lane) {
;     ...
;     const int kc = lane & 7, nrow0 = PERMUTE ? win_phys_col(n0) : n0;
; #pragma unroll
;     for (int j = 0; j < 8; ++j) { const int n = (lane >> 3) + 8 * j; const LAS float* s = scr + (8 * kc) * 65 + n;
;         v4u o; o[0] = cvt_pk_bf16(wrnd(s[0 * 65]), wrnd(s[1 * 65])); o[1] = cvt_pk_bf16(wrnd(s[2 * 65]), wrnd(s[3 * 65])); o[2] = cvt_pk_bf16(wrnd(s[4 * 65]), wrnd(s[5 * 65])); o[3] = cvt_pk_bf16(wrnd(s[6 * 65]), wrnd(s[7 * 65]));
;         *(v4u*)(WT + (BLOCKED ? pg8::blocked_off(nrow0 + n, k0 + 8 * kc, K) : (size_t)(nrow0 + n) * ldo + k0 + 8 * kc)) = o; }
;     LDS_WAIT(); asm volatile("" ::: "memory");
	v_add_u32_e32 v3, 0x20000, v10
	s_waitcnt lgkmcnt(4)
	v_add_u32_e32 v4, 0x20000, v12
	v_and_b32_e32 v3, 0xfffc0000, v3
	v_and_b32_e32 v4, 0xfffc0000, v4
	ds_read2_b32 v[22:23], v28 offset0:166 offset1:174
	ds_read2_b32 v[24:25], v28 offset0:231 offset1:239
	v_cvt_pk_bf16_f32 v4, v3, v4
	s_waitcnt lgkmcnt(5)
	v_add_u32_e32 v3, 0x20000, v8
	s_waitcnt lgkmcnt(4)
	v_add_u32_e32 v5, 0x20000, v14
	v_and_b32_e32 v3, 0xfffc0000, v3
	v_and_b32_e32 v5, 0xfffc0000, v5
	v_cvt_pk_bf16_f32 v5, v3, v5
	s_waitcnt lgkmcnt(3)
	v_add_u32_e32 v3, 0x20000, v18
	s_waitcnt lgkmcnt(2)
	v_add_u32_e32 v6, 0x20000, v20
	v_and_b32_e32 v3, 0xfffc0000, v3
	v_and_b32_e32 v6, 0xfffc0000, v6
	v_add_u32_e32 v26, 32, v2
	v_cvt_pk_bf16_f32 v6, v3, v6
	s_waitcnt lgkmcnt(1)
	v_add_u32_e32 v3, 0x20000, v22
	s_waitcnt lgkmcnt(0)
	v_add_u32_e32 v7, 0x20000, v24
	v_ashrrev_i32_e32 v27, 31, v26
	v_and_b32_e32 v3, 0xfffc0000, v3
	v_and_b32_e32 v7, 0xfffc0000, v7
	v_lshlrev_b64 v[26:27], 13, v[26:27]
	v_cvt_pk_bf16_f32 v7, v3, v7
	v_lshl_add_u64 v[26:27], v[0:1], 0, v[26:27]
	global_store_dwordx4 v[26:27], v[4:7], off
	v_add_u32_e32 v3, 0x20000, v11
	v_and_b32_e32 v3, 0xfffc0000, v3
	v_add_u32_e32 v4, 0x20000, v13
	v_and_b32_e32 v4, 0xfffc0000, v4
	v_cvt_pk_bf16_f32 v4, v3, v4
	v_add_u32_e32 v3, 0x20000, v9
	v_add_u32_e32 v5, 0x20000, v15
	v_and_b32_e32 v3, 0xfffc0000, v3
	v_and_b32_e32 v5, 0xfffc0000, v5
	v_cvt_pk_bf16_f32 v5, v3, v5
	v_add_u32_e32 v3, 0x20000, v19
	v_add_u32_e32 v6, 0x20000, v21
	v_and_b32_e32 v3, 0xfffc0000, v3
	v_and_b32_e32 v6, 0xfffc0000, v6
	v_add_u32_e32 v8, 40, v2
	v_cvt_pk_bf16_f32 v6, v3, v6
	v_add_u32_e32 v3, 0x20000, v23
	v_add_u32_e32 v7, 0x20000, v25
	v_ashrrev_i32_e32 v9, 31, v8
	v_and_b32_e32 v3, 0xfffc0000, v3
	v_and_b32_e32 v7, 0xfffc0000, v7
	ds_read2_b32 v[10:11], v58 offset0:48 offset1:56
	v_lshlrev_b64 v[8:9], 13, v[8:9]
	ds_read2_b32 v[12:13], v58 offset0:113 offset1:121
	v_cvt_pk_bf16_f32 v7, v3, v7
	v_lshl_add_u64 v[8:9], v[0:1], 0, v[8:9]
	global_store_dwordx4 v[8:9], v[4:7], off
	ds_read2_b32 v[8:9], v58 offset0:178 offset1:186
	ds_read2_b32 v[14:15], v58 offset0:243 offset1:251
	ds_read2_b32 v[18:19], v28 offset0:52 offset1:60
	ds_read2_b32 v[20:21], v28 offset0:117 offset1:125
	s_waitcnt lgkmcnt(5)
	v_add_u32_e32 v3, 0x20000, v10
	s_waitcnt lgkmcnt(4)
	v_add_u32_e32 v4, 0x20000, v12
	v_and_b32_e32 v3, 0xfffc0000, v3
	v_and_b32_e32 v4, 0xfffc0000, v4
	ds_read2_b32 v[22:23], v28 offset0:182 offset1:190
	ds_read2_b32 v[24:25], v28 offset0:247 offset1:255
	v_cvt_pk_bf16_f32 v4, v3, v4
	s_waitcnt lgkmcnt(5)
	v_add_u32_e32 v3, 0x20000, v8
	s_waitcnt lgkmcnt(4)
	v_add_u32_e32 v5, 0x20000, v14
	v_and_b32_e32 v3, 0xfffc0000, v3
	v_and_b32_e32 v5, 0xfffc0000, v5
	v_cvt_pk_bf16_f32 v5, v3, v5
	s_waitcnt lgkmcnt(3)
	v_add_u32_e32 v3, 0x20000, v18
	s_waitcnt lgkmcnt(2)
	v_add_u32_e32 v6, 0x20000, v20
	v_and_b32_e32 v3, 0xfffc0000, v3
	v_and_b32_e32 v6, 0xfffc0000, v6
	v_add_u32_e32 v26, 48, v2
	v_cvt_pk_bf16_f32 v6, v3, v6
	s_waitcnt lgkmcnt(1)
	v_add_u32_e32 v3, 0x20000, v22
	s_waitcnt lgkmcnt(0)
	v_add_u32_e32 v7, 0x20000, v24
	v_ashrrev_i32_e32 v27, 31, v26
	v_and_b32_e32 v3, 0xfffc0000, v3
	v_and_b32_e32 v7, 0xfffc0000, v7
	v_lshlrev_b64 v[26:27], 13, v[26:27]
	v_cvt_pk_bf16_f32 v7, v3, v7
	v_lshl_add_u64 v[26:27], v[0:1], 0, v[26:27]
	global_store_dwordx4 v[26:27], v[4:7], off
	v_add_u32_e32 v3, 0x20000, v11
	v_and_b32_e32 v3, 0xfffc0000, v3
	v_add_u32_e32 v4, 0x20000, v13
	v_and_b32_e32 v4, 0xfffc0000, v4
	v_cvt_pk_bf16_f32 v4, v3, v4
	v_add_u32_e32 v3, 0x20000, v9
	v_add_u32_e32 v5, 0x20000, v15
	v_and_b32_e32 v3, 0xfffc0000, v3
	v_and_b32_e32 v5, 0xfffc0000, v5
	v_cvt_pk_bf16_f32 v5, v3, v5
	v_add_u32_e32 v3, 0x20000, v19
	v_add_u32_e32 v6, 0x20000, v21
	v_and_b32_e32 v3, 0xfffc0000, v3
	v_and_b32_e32 v6, 0xfffc0000, v6
	v_cvt_pk_bf16_f32 v6, v3, v6
	v_add_u32_e32 v3, 0x20000, v23
	v_add_u32_e32 v7, 0x20000, v25
	v_and_b32_e32 v3, 0xfffc0000, v3
	v_and_b32_e32 v7, 0xfffc0000, v7
	v_add_u32_e32 v2, 56, v2
	v_cvt_pk_bf16_f32 v7, v3, v7
	v_ashrrev_i32_e32 v3, 31, v2
	v_lshlrev_b64 v[2:3], 13, v[2:3]
	v_lshl_add_u64 v[0:1], v[0:1], 0, v[2:3]
	global_store_dwordx4 v[0:1], v[4:7], off
	s_waitcnt lgkmcnt(0)
	s_branch .LBB0_93

; #define LAS __attribute__((address_space(3)))
; __device__ __forceinline__ void build_rstd(LAS float* tab, const float* part, int pm, int tid) {
;     const f32x4* p = (const f32x4*)(part + ((size_t)pm * 256 + (tid >> 1)) * 64 + (tid & 1) * 32); float s = 0.f;
; #pragma unroll
;     for (int k = 0; k < 8; ++k) { const f32x4 v = p[k]; s += (v[0] + v[1]) + (v[2] + v[3]); }
;     s += __shfl_xor(s, 1);
;     if ((tid & 1) == 0) tab[tid >> 1] = 1.0f / sqrtf(s * (1.f / DM) + NORM_EPS);
;     __syncthreads();
.LBB0_118:
	v_readlane_b32 s0, v253, 42
	v_readlane_b32 s1, v253, 43
	s_andn2_b64 vcc, exec, s[0:1]
	s_nop 0
	v_cndmask_b32_e64 v0, 0, 1, s[0:1]
	s_getreg_b32 s0, hwreg(HW_REG_HW_ID, 0, 6)
	s_lshl_b32 s0, s0, 2
	s_and_b32 s0, s0, 0xfc
	s_add_i32 s0, s0, 0
	s_add_i32 s0, s0, 0x22240
	v_cmp_ne_u32_e64 s[6:7], 1, v0
	v_mov_b32_e32 v0, s0
	ds_read_b32 v0, v0
	v_readlane_b32 s0, v254, 37
	v_readlane_b32 s1, v254, 38
	s_mov_b32 s4, s0
	s_ashr_i32 s5, s0, 31
	v_writelane_b32 v254, s0, 37
	v_mbcnt_lo_u32_b32 v1, -1, 0
	v_mbcnt_hi_u32_b32 v1, -1, v1
	s_nop 1
	v_writelane_b32 v254, s1, 38
	s_lshl_b64 s[0:1], s[4:5], 16
	s_waitcnt lgkmcnt(0)
	v_readfirstlane_b32 s4, v0
	s_add_u32 s0, s76, s0
	s_addc_u32 s1, s77, s1
	v_lshl_add_u32 v4, s4, 6, v1
	s_nop 0
	v_ashrrev_i32_e32 v0, 1, v4
	v_ashrrev_i32_e32 v1, 31, v0
	v_lshlrev_b64 v[2:3], 8, v[0:1]
	v_and_b32_e32 v38, 1, v4
	v_lshl_add_u64 v[2:3], s[0:1], 0, v[2:3]
	v_lshlrev_b32_e32 v16, 7, v38
	v_lshl_add_u64 v[14:15], v[2:3], 0, v[16:17]
	global_load_dwordx4 v[2:5], v[14:15], off nt
	global_load_dwordx4 v[6:9], v[14:15], off offset:16 nt
	global_load_dwordx4 v[10:13], v[14:15], off offset:32 nt
	global_load_dwordx4 v[18:21], v[14:15], off offset:48 nt
	global_load_dwordx4 v[22:25], v[14:15], off offset:64 nt
	global_load_dwordx4 v[26:29], v[14:15], off offset:80 nt
	global_load_dwordx4 v[30:33], v[14:15], off offset:96 nt
	global_load_dwordx4 v[34:37], v[14:15], off offset:112 nt
	v_and_b32_e32 v14, 64, v233
	v_xor_b32_e32 v1, 1, v233
	v_add_u32_e32 v235, 64, v14
	v_cmp_lt_i32_e32 vcc, v1, v235
	s_waitcnt vmcnt(1)
	v_add_f32_e32 v15, v32, v33
	v_cndmask_b32_e32 v14, v233, v1, vcc
	v_add_f32_e32 v1, v2, v3
	v_add_f32_e32 v2, v4, v5
	v_add_f32_e32 v3, v6, v7
	v_add_f32_e32 v4, v8, v9
	v_add_f32_e32 v1, v1, v2
	v_add_f32_e32 v5, v10, v11
	v_add_f32_e32 v6, v12, v13
	v_add_f32_e32 v2, v3, v4
	v_add_f32_e32 v1, 0, v1
	v_add_f32_e32 v7, v18, v19
	v_add_f32_e32 v8, v20, v21
	v_add_f32_e32 v3, v5, v6
	v_add_f32_e32 v1, v1, v2
	v_add_f32_e32 v9, v22, v23
	v_add_f32_e32 v10, v24, v25
	v_add_f32_e32 v4, v7, v8
	v_add_f32_e32 v1, v1, v3
	v_add_f32_e32 v11, v26, v27
	v_add_f32_e32 v12, v28, v29
	v_add_f32_e32 v5, v9, v10
	v_add_f32_e32 v1, v1, v4
	v_add_f32_e32 v13, v30, v31
	v_add_f32_e32 v6, v11, v12
	v_add_f32_e32 v1, v1, v5
	s_waitcnt vmcnt(0)
	v_add_f32_e32 v16, v34, v35
	v_add_f32_e32 v18, v36, v37
	v_add_f32_e32 v7, v13, v15
	v_add_f32_e32 v1, v1, v6
	v_add_f32_e32 v8, v16, v18
	v_add_f32_e32 v1, v1, v7
	v_add_f32_e32 v1, v1, v8
	v_lshlrev_b32_e32 v244, 2, v14
	ds_bpermute_b32 v2, v244, v1
	v_cmp_eq_u32_e32 vcc, 0, v38
	s_and_saveexec_b64 s[0:1], vcc
	s_cbranch_execz .LBB0_120
	s_waitcnt lgkmcnt(0)
	v_add_f32_e32 v1, v1, v2
	v_fmamk_f32 v1, v1, 0x39800000, v234
	v_mul_f32_e32 v2, 0x4f800000, v1
	v_cmp_gt_f32_e32 vcc, s78, v1
	v_readlane_b32 s4, v254, 37
	v_readlane_b32 s5, v254, 38
	v_cndmask_b32_e32 v1, v1, v2, vcc
	v_sqrt_f32_e32 v2, v1
	s_lshl_b32 s10, s4, 6
	v_add_u32_e32 v3, -1, v2
	v_fma_f32 v4, -v3, v2, v1
	v_cmp_ge_f32_e64 s[8:9], 0, v4
	v_add_u32_e32 v4, 1, v2
	s_nop 0
	v_cndmask_b32_e64 v3, v2, v3, s[8:9]
	v_fma_f32 v2, -v4, v2, v1
	v_cmp_lt_f32_e64 s[8:9], 0, v2
	s_nop 1
	v_cndmask_b32_e64 v2, v3, v4, s[8:9]
	v_mul_f32_e32 v3, 0x37800000, v2
	v_cndmask_b32_e32 v2, v2, v3, vcc
	v_cmp_class_f32_e32 vcc, v1, v229
	s_nop 1
	v_cndmask_b32_e32 v1, v2, v1, vcc
	v_div_scale_f32 v2, s[4:5], v1, v1, 1.0
	v_rcp_f32_e32 v3, v2
	s_and_b32 s4, s10, 0xfffffc00
	s_add_i32 s4, s4, 0
	v_lshl_add_u32 v0, v0, 2, s4
	v_fma_f32 v4, -v2, v3, 1.0
	v_fmac_f32_e32 v3, v4, v3
	v_div_scale_f32 v4, vcc, 1.0, v1, 1.0
	v_mul_f32_e32 v5, v4, v3
	v_fma_f32 v6, -v2, v5, v4
	v_fmac_f32_e32 v5, v6, v3
	v_fma_f32 v2, -v2, v5, v4
	v_div_fmas_f32 v2, v2, v3, v5
	v_div_fixup_f32 v1, v2, v1, 1.0
	v_add_u32_e32 v0, 0x20000, v0
	ds_write_b32 v0, v1

; #define LAS __attribute__((address_space(3)))
; template <bool PERMUTE, bool BLOCKED = false>
; __device__ __forceinline__ void cvt_tile64(const float* W, int K, int N, bf16* WT, int ldo, const float* gk, LAS float* scr, int tile, int lane) {
;     const int nblk = N >> 6, kb = tile / nblk, nb = tile - kb * nblk, k0 = 64 * kb, n0 = 64 * nb;
;     const int lk = lane >> 4, ln = (lane & 15) * 4;
;     ...
;     {
;         f32x4 v[16];
; #pragma unroll
;         for (int i = 0; i < 16; ++i) v[i] = *(const f32x4*)(W + (size_t)(k0 + 4 * i + lk) * N + n0 + ln);
; #pragma unroll
;         for (int i = 0; i < 16; ++i) { const int kk = 4 * i + lk; const float g = gk ? gk[k0 + kk] : 1.0f; LAS float* d = scr + kk * 65 + ln;
;             d[0] = v[i][0] * g; d[1] = v[i][1] * g; d[2] = v[i][2] * g; d[3] = v[i][3] * g; }
;     }
;     ...
; #pragma unroll
;     for (int hh = 0; hh < 2; ++hh) {
;         f32x4 v[8];
; #pragma unroll
;         for (int i = 0; i < 8; ++i) v[i] = *(const f32x4*)(W + (size_t)(k0 + 32 * hh + 4 * i + lk) * N + n0 + ln);
; #pragma unroll
;         for (int i = 0; i < 8; ++i) { const int kk = 32 * hh + 4 * i + lk; const float g = gk ? gk[k0 + kk] : 1.0f; LAS float* d = scr + kk * 65 + ln;
;             d[0] = v[i][0] * g; d[1] = v[i][1] * g; d[2] = v[i][2] * g; d[3] = v[i][3] * g; }
.LBB0_216:
	s_cmpk_gt_i32 s12, 0x1ff
	s_mov_b64 s[0:1], -1
	s_cbranch_scc0 .LBB0_236
	s_add_i32 s0, s5, 0xfffff000
	s_ashr_i32 s1, s0, 31
	s_lshr_b32 s1, s1, 24
	s_add_i32 s0, s0, s1
	s_ashr_i32 s0, s0, 8
	s_lshl_b32 s14, s0, 6
	s_lshl_b32 s13, s0, 14
	s_sub_i32 s0, s4, s13
	v_or_b32_e32 v44, s14, v16
	s_add_i32 s0, s0, 0xfffc0000
	v_or_b32_e32 v2, 4, v44
	s_ashr_i32 s1, s0, 31
	v_ashrrev_i32_e32 v45, 31, v44
	v_ashrrev_i32_e32 v3, 31, v2
	v_lshl_add_u64 v[42:43], s[0:1], 2, v[34:35]
	v_lshlrev_b64 v[0:1], 16, v[44:45]
	v_lshlrev_b64 v[2:3], 16, v[2:3]
	v_lshl_add_u64 v[0:1], v[42:43], 0, v[0:1]
	v_lshl_add_u64 v[2:3], v[42:43], 0, v[2:3]
	global_load_dwordx4 v[30:33], v[0:1], off nt
	global_load_dwordx4 v[26:29], v[2:3], off nt
	v_or_b32_e32 v0, 8, v44
	v_or_b32_e32 v2, 12, v44
	v_ashrrev_i32_e32 v1, 31, v0
	v_ashrrev_i32_e32 v3, 31, v2
	v_lshlrev_b64 v[0:1], 16, v[0:1]
	v_lshlrev_b64 v[2:3], 16, v[2:3]
	v_lshl_add_u64 v[0:1], v[42:43], 0, v[0:1]
	v_lshl_add_u64 v[2:3], v[42:43], 0, v[2:3]
	global_load_dwordx4 v[22:25], v[0:1], off nt
	global_load_dwordx4 v[18:21], v[2:3], off nt
	v_or_b32_e32 v0, 16, v44
	v_or_b32_e32 v2, 20, v44
	v_ashrrev_i32_e32 v1, 31, v0
	v_ashrrev_i32_e32 v3, 31, v2
	v_lshlrev_b64 v[0:1], 16, v[0:1]
	v_lshlrev_b64 v[2:3], 16, v[2:3]
	v_lshl_add_u64 v[0:1], v[42:43], 0, v[0:1]
	v_lshl_add_u64 v[2:3], v[42:43], 0, v[2:3]
	global_load_dwordx4 v[12:15], v[0:1], off nt
	global_load_dwordx4 v[8:11], v[2:3], off nt
	v_or_b32_e32 v0, 24, v44
	v_or_b32_e32 v2, 28, v44
	v_ashrrev_i32_e32 v1, 31, v0
	v_ashrrev_i32_e32 v3, 31, v2
	v_lshlrev_b64 v[0:1], 16, v[0:1]
	v_lshlrev_b64 v[2:3], 16, v[2:3]
	v_lshl_add_u64 v[0:1], v[42:43], 0, v[0:1]
	v_lshl_add_u64 v[2:3], v[42:43], 0, v[2:3]
	global_load_dwordx4 v[4:7], v[0:1], off nt
	s_nop 0
	global_load_dwordx4 v[0:3], v[2:3], off nt
	v_cndmask_b32_e64 v48, 0, 1, s[10:11]
	v_mov_b32_e32 v46, 1.0
	v_cmp_ne_u32_e64 s[6:7], 1, v48
	s_andn2_b64 vcc, exec, s[10:11]
	v_mov_b32_e32 v48, 1.0
	s_cbranch_vccnz .LBB0_219
	v_lshl_add_u64 v[52:53], v[44:45], 2, s[8:9]
	global_load_dword v110, v[52:53], off offset:16
	global_load_dword v124, v[52:53], off offset:32
	global_load_dword v125, v[52:53], off offset:48
	global_load_dword v126, v[52:53], off offset:64
	global_load_dword v127, v[52:53], off offset:80
	global_load_dword v178, v[52:53], off offset:96
	global_load_dword v179, v[52:53], off offset:112
	global_load_dword v180, v[52:53], off offset:128
	global_load_dword v181, v[52:53], off offset:144
	global_load_dword v182, v[52:53], off offset:160
	global_load_dword v183, v[52:53], off offset:176
	global_load_dword v184, v[52:53], off offset:192
	global_load_dword v185, v[52:53], off offset:208
	global_load_dword v186, v[52:53], off offset:224
	global_load_dword v187, v[52:53], off offset:240
	global_load_dword v48, v[52:53], off
	s_waitcnt vmcnt(0)
	s_ashr_i32 s15, s14, 31
	v_lshl_add_u64 v[52:53], s[14:15], 0, v[16:17]
	v_lshl_add_u64 v[52:53], v[52:53], 2, s[8:9]
	s_waitcnt vmcnt(0)
	v_pk_mul_f32 v[30:31], v[30:31], v[48:49] op_sel_hi:[1,0]
	v_pk_mul_f32 v[32:33], v[32:33], v[48:49] op_sel_hi:[1,0]
	v_mov_b32_e32 v48, v110

; #define LAS __attribute__((address_space(3)))
; template <bool PERMUTE, bool BLOCKED = false>
; __device__ __forceinline__ void cvt_tile64(const float* W, int K, int N, bf16* WT, int ldo, const float* gk, LAS float* scr, int tile, int lane) {
;     ...
;     for (int hh = 0; hh < 2; ++hh) {
;         f32x4 v[8];
; #pragma unroll
;         for (int i = 0; i < 8; ++i) v[i] = *(const f32x4*)(W + (size_t)(k0 + 32 * hh + 4 * i + lk) * N + n0 + ln);
; #pragma unroll
;         for (int i = 0; i < 8; ++i) { const int kk = 32 * hh + 4 * i + lk; const float g = gk ? gk[k0 + kk] : 1.0f; LAS float* d = scr + kk * 65 + ln;
;             d[0] = v[i][0] * g; d[1] = v[i][1] * g; d[2] = v[i][2] * g; d[3] = v[i][3] * g; }
.LBB0_225:
	v_add_u32_e32 v8, 0x1860, v45
	ds_write2_b32 v8, v4, v5 offset1:1
	v_add_u32_e32 v4, 0x1868, v45
	ds_write2_b32 v4, v6, v7 offset1:1
	s_waitcnt vmcnt(0)
	v_pk_mul_f32 v[0:1], v[0:1], v[18:19] op_sel_hi:[1,0]
	v_add_u32_e32 v4, 0x1c70, v45
	ds_write2_b32 v4, v0, v1 offset1:1
	v_pk_mul_f32 v[0:1], v[2:3], v[18:19] op_sel_hi:[1,0]
	v_add_u32_e32 v2, 0x1c78, v45
	ds_write2_b32 v2, v0, v1 offset1:1
	v_or_b32_e32 v0, 32, v44
	v_or_b32_e32 v4, 60, v44
	v_ashrrev_i32_e32 v1, 31, v0
	v_ashrrev_i32_e32 v5, 31, v4
	v_lshlrev_b64 v[0:1], 16, v[0:1]
	v_lshlrev_b64 v[4:5], 16, v[4:5]
	v_lshl_add_u64 v[0:1], v[42:43], 0, v[0:1]
	v_lshl_add_u64 v[4:5], v[42:43], 0, v[4:5]
	global_load_dwordx4 v[26:29], v[0:1], off nt
	s_and_b64 vcc, exec, s[6:7]
	global_load_dwordx4 v[4:7], v[4:5], off nt
	v_or_b32_e32 v0, 36, v44
	v_ashrrev_i32_e32 v1, 31, v0
	v_lshlrev_b64 v[0:1], 16, v[0:1]
	v_lshl_add_u64 v[0:1], v[42:43], 0, v[0:1]
	global_load_dwordx4 v[30:33], v[0:1], off nt
	v_or_b32_e32 v0, 40, v44
	v_ashrrev_i32_e32 v1, 31, v0
	v_lshlrev_b64 v[0:1], 16, v[0:1]
	v_lshl_add_u64 v[0:1], v[42:43], 0, v[0:1]
	global_load_dwordx4 v[18:21], v[0:1], off nt
	v_or_b32_e32 v0, 44, v44
	v_ashrrev_i32_e32 v1, 31, v0
	v_lshlrev_b64 v[0:1], 16, v[0:1]
	v_lshl_add_u64 v[0:1], v[42:43], 0, v[0:1]
	global_load_dwordx4 v[22:25], v[0:1], off nt
	v_or_b32_e32 v0, 48, v44
	v_ashrrev_i32_e32 v1, 31, v0
	v_lshlrev_b64 v[0:1], 16, v[0:1]
	v_lshl_add_u64 v[0:1], v[42:43], 0, v[0:1]
	global_load_dwordx4 v[8:11], v[0:1], off nt
	v_or_b32_e32 v0, 52, v44
	v_ashrrev_i32_e32 v1, 31, v0
	v_lshlrev_b64 v[0:1], 16, v[0:1]
	v_lshl_add_u64 v[0:1], v[42:43], 0, v[0:1]
	global_load_dwordx4 v[12:15], v[0:1], off nt
	v_or_b32_e32 v0, 56, v44
	v_ashrrev_i32_e32 v1, 31, v0
	v_lshlrev_b64 v[0:1], 16, v[0:1]
	v_lshl_add_u64 v[0:1], v[42:43], 0, v[0:1]
	global_load_dwordx4 v[0:3], v[0:1], off nt
	v_mov_b32_e32 v42, 1.0
	v_mov_b32_e32 v44, 1.0
	s_cbranch_vccnz .LBB0_227
	s_ashr_i32 s15, s14, 31
	v_lshl_add_u64 v[52:53], s[14:15], 0, v[16:17]
	v_lshl_add_u64 v[52:53], v[52:53], 2, s[8:9]
	v_mov_b32_e32 v44, v180
	s_waitcnt vmcnt(0)
	v_pk_mul_f32 v[26:27], v[26:27], v[44:45] op_sel_hi:[1,0]
	v_pk_mul_f32 v[28:29], v[28:29], v[44:45] op_sel_hi:[1,0]
	v_mov_b32_e32 v44, v181

; #define LAS __attribute__((address_space(3)))
; #define LDS_WAIT() asm volatile("s_waitcnt lgkmcnt(0)" ::: "memory")
; template <bool PERMUTE, bool BLOCKED = false>
; __device__ __forceinline__ void cvt_tile64(const float* W, int K, int N, bf16* WT, int ldo, const float* gk, LAS float* scr, int tile, int lane) {
;     const int nblk = N >> 6, kb = tile / nblk, nb = tile - kb * nblk, k0 = 64 * kb, n0 = 64 * nb;
;     const int lk = lane >> 4, ln = (lane & 15) * 4;
;     ...
;     {
;         f32x4 v[16];
; #pragma unroll
;         for (int i = 0; i < 16; ++i) v[i] = *(const f32x4*)(W + (size_t)(k0 + 4 * i + lk) * N + n0 + ln);
; #pragma unroll
;         for (int i = 0; i < 16; ++i) { const int kk = 4 * i + lk; const float g = gk ? gk[k0 + kk] : 1.0f; LAS float* d = scr + kk * 65 + ln;
;             d[0] = v[i][0] * g; d[1] = v[i][1] * g; d[2] = v[i][2] * g; d[3] = v[i][3] * g; }
;     }
;     ...
; #pragma unroll
;     for (int hh = 0; hh < 2; ++hh) {
;         f32x4 v[8];
; #pragma unroll
;         for (int i = 0; i < 8; ++i) v[i] = *(const f32x4*)(W + (size_t)(k0 + 32 * hh + 4 * i + lk) * N + n0 + ln);
; #pragma unroll
;         for (int i = 0; i < 8; ++i) { const int kk = 32 * hh + 4 * i + lk; const float g = gk ? gk[k0 + kk] : 1.0f; LAS float* d = scr + kk * 65 + ln;
;             d[0] = v[i][0] * g; d[1] = v[i][1] * g; d[2] = v[i][2] * g; d[3] = v[i][3] * g; }
;     }
;     ...
;     LDS_WAIT(); asm volatile("" ::: "memory");
.LBB0_236:
	s_and_b64 vcc, exec, s[0:1]
	s_cbranch_vccz .LBB0_215
	s_ashr_i32 s0, s5, 31
	s_lshr_b32 s0, s0, 26
	s_add_i32 s0, s5, s0
	s_and_b32 s14, s0, 0xffffffc0
	s_lshl_b32 s0, s0, 6
	s_and_b32 s0, s0, 0xfffff000
	s_sub_i32 s6, s4, s0
	v_or_b32_e32 v2, s14, v16
	s_ashr_i32 s7, s6, 31
	v_ashrrev_i32_e32 v3, 31, v2
	v_lshl_add_u64 v[0:1], s[6:7], 2, v[38:39]
	v_lshlrev_b64 v[4:5], 14, v[2:3]
	v_or_b32_e32 v8, 4, v2
	v_lshl_add_u64 v[4:5], v[0:1], 0, v[4:5]
	v_ashrrev_i32_e32 v9, 31, v8
	global_load_dwordx4 v[4:7], v[4:5], off nt
	v_lshlrev_b64 v[8:9], 14, v[8:9]
	v_or_b32_e32 v12, 8, v2
	v_lshl_add_u64 v[8:9], v[0:1], 0, v[8:9]
	v_ashrrev_i32_e32 v13, 31, v12
	global_load_dwordx4 v[8:11], v[8:9], off nt
	v_lshlrev_b64 v[12:13], 14, v[12:13]
	v_or_b32_e32 v18, 12, v2
	v_lshl_add_u64 v[12:13], v[0:1], 0, v[12:13]
	v_ashrrev_i32_e32 v19, 31, v18
	global_load_dwordx4 v[12:15], v[12:13], off nt
	v_lshlrev_b64 v[18:19], 14, v[18:19]
	v_or_b32_e32 v22, 16, v2
	v_lshl_add_u64 v[18:19], v[0:1], 0, v[18:19]
	v_ashrrev_i32_e32 v23, 31, v22
	global_load_dwordx4 v[18:21], v[18:19], off nt
	v_lshlrev_b64 v[22:23], 14, v[22:23]
	v_or_b32_e32 v26, 20, v2
	v_lshl_add_u64 v[22:23], v[0:1], 0, v[22:23]
	v_ashrrev_i32_e32 v27, 31, v26
	global_load_dwordx4 v[22:25], v[22:23], off nt
	v_lshlrev_b64 v[26:27], 14, v[26:27]
	v_or_b32_e32 v30, 24, v2
	v_lshl_add_u64 v[26:27], v[0:1], 0, v[26:27]
	v_ashrrev_i32_e32 v31, 31, v30
	global_load_dwordx4 v[26:29], v[26:27], off nt
	v_lshlrev_b64 v[30:31], 14, v[30:31]
	v_or_b32_e32 v42, 28, v2
	v_lshl_add_u64 v[30:31], v[0:1], 0, v[30:31]
	v_ashrrev_i32_e32 v43, 31, v42
	global_load_dwordx4 v[30:33], v[30:31], off nt
	v_lshlrev_b64 v[42:43], 14, v[42:43]
	v_lshl_add_u64 v[42:43], v[0:1], 0, v[42:43]
	global_load_dwordx4 v[42:45], v[42:43], off nt
	v_add_u32_e32 v46, v47, v49
	v_add_u32_e32 v3, 0x410, v46
	s_ashr_i32 s15, s14, 31
	s_waitcnt vmcnt(7)
	ds_write2_b32 v46, v4, v5 offset1:1
	ds_write2_b32 v46, v6, v7 offset0:2 offset1:3
	v_or_b32_e32 v4, 32, v2
	v_ashrrev_i32_e32 v5, 31, v4
	v_lshlrev_b64 v[4:5], 14, v[4:5]
	v_lshl_add_u64 v[4:5], v[0:1], 0, v[4:5]
	s_waitcnt vmcnt(6)
	ds_write2_b32 v3, v8, v9 offset1:1
	v_add_u32_e32 v3, 0x418, v46
	v_or_b32_e32 v8, 36, v2
	ds_write2_b32 v3, v10, v11 offset1:1
	v_add_u32_e32 v3, 0x820, v46
	v_ashrrev_i32_e32 v9, 31, v8
	s_waitcnt vmcnt(5)
	ds_write2_b32 v3, v12, v13 offset1:1
	v_add_u32_e32 v3, 0x828, v46
	global_load_dwordx4 v[4:7], v[4:5], off nt
	v_lshlrev_b64 v[8:9], 14, v[8:9]
	v_or_b32_e32 v12, 40, v2
	ds_write2_b32 v3, v14, v15 offset1:1
	v_add_u32_e32 v3, 0xc30, v46
	v_lshl_add_u64 v[8:9], v[0:1], 0, v[8:9]
	v_ashrrev_i32_e32 v13, 31, v12
	s_waitcnt vmcnt(5)
	ds_write2_b32 v3, v18, v19 offset1:1
	v_add_u32_e32 v3, 0xc38, v46
	global_load_dwordx4 v[8:11], v[8:9], off nt
	v_lshlrev_b64 v[12:13], 14, v[12:13]
	v_or_b32_e32 v18, 44, v2
	ds_write2_b32 v3, v20, v21 offset1:1
	v_add_u32_e32 v3, 0x1040, v46
	v_lshl_add_u64 v[12:13], v[0:1], 0, v[12:13]
	v_ashrrev_i32_e32 v19, 31, v18
	s_waitcnt vmcnt(5)
	ds_write2_b32 v3, v22, v23 offset1:1
	v_add_u32_e32 v3, 0x1048, v46
	global_load_dwordx4 v[12:15], v[12:13], off nt
	v_lshlrev_b64 v[18:19], 14, v[18:19]
	v_or_b32_e32 v22, 48, v2
	ds_write2_b32 v3, v24, v25 offset1:1
	v_add_u32_e32 v3, 0x1450, v46
	v_lshl_add_u64 v[18:19], v[0:1], 0, v[18:19]
	v_ashrrev_i32_e32 v23, 31, v22
	s_waitcnt vmcnt(5)
	ds_write2_b32 v3, v26, v27 offset1:1
	v_add_u32_e32 v3, 0x1458, v46
	global_load_dwordx4 v[18:21], v[18:19], off nt
	v_lshlrev_b64 v[22:23], 14, v[22:23]
	v_or_b32_e32 v26, 52, v2
	ds_write2_b32 v3, v28, v29 offset1:1
	v_add_u32_e32 v3, 0x1860, v46
	v_lshl_add_u64 v[22:23], v[0:1], 0, v[22:23]
	v_ashrrev_i32_e32 v27, 31, v26
	s_waitcnt vmcnt(5)
	ds_write2_b32 v3, v30, v31 offset1:1
	v_add_u32_e32 v3, 0x1868, v46
	global_load_dwordx4 v[22:25], v[22:23], off nt
	v_lshlrev_b64 v[26:27], 14, v[26:27]
	v_or_b32_e32 v30, 56, v2
	ds_write2_b32 v3, v32, v33 offset1:1
	v_add_u32_e32 v3, 0x1c70, v46
	v_lshl_add_u64 v[26:27], v[0:1], 0, v[26:27]
	v_ashrrev_i32_e32 v31, 31, v30
	s_waitcnt vmcnt(5)
	ds_write2_b32 v3, v42, v43 offset1:1
	v_add_u32_e32 v3, 0x1c78, v46
	global_load_dwordx4 v[26:29], v[26:27], off nt
	v_lshlrev_b64 v[30:31], 14, v[30:31]
	v_or_b32_e32 v2, 60, v2
	ds_write2_b32 v3, v44, v45 offset1:1
	v_lshl_add_u64 v[30:31], v[0:1], 0, v[30:31]
	v_ashrrev_i32_e32 v3, 31, v2
	global_load_dwordx4 v[30:33], v[30:31], off nt
	v_lshlrev_b64 v[2:3], 14, v[2:3]
	v_lshl_add_u64 v[0:1], v[0:1], 0, v[2:3]
	global_load_dwordx4 v[0:3], v[0:1], off nt
	v_add_u32_e32 v42, 0x2080, v46
	s_waitcnt vmcnt(7)
	ds_write2_b32 v42, v4, v5 offset1:1
	v_add_u32_e32 v4, 0x2088, v46
	ds_write2_b32 v4, v6, v7 offset1:1
	v_add_u32_e32 v4, 0x2490, v46
	s_waitcnt vmcnt(6)
	ds_write2_b32 v4, v8, v9 offset1:1
	v_add_u32_e32 v4, 0x2498, v46
	ds_write2_b32 v4, v10, v11 offset1:1
	v_add_u32_e32 v4, 0x28a0, v46
	s_waitcnt vmcnt(5)
	ds_write2_b32 v4, v12, v13 offset1:1
	v_add_u32_e32 v4, 0x28a8, v46
	ds_write2_b32 v4, v14, v15 offset1:1
	v_add_u32_e32 v4, 0x2cb0, v46
	s_waitcnt vmcnt(4)
	ds_write2_b32 v4, v18, v19 offset1:1
	v_add_u32_e32 v4, 0x2cb8, v46
	ds_write2_b32 v4, v20, v21 offset1:1
	v_add_u32_e32 v4, 0x30c0, v46
	s_waitcnt vmcnt(3)
	ds_write2_b32 v4, v22, v23 offset1:1
	v_add_u32_e32 v4, 0x30c8, v46
	ds_write2_b32 v4, v24, v25 offset1:1
	v_add_u32_e32 v4, 0x34d0, v46
	s_waitcnt vmcnt(2)
	ds_write2_b32 v4, v26, v27 offset1:1
	v_add_u32_e32 v4, 0x34d8, v46
	ds_write2_b32 v4, v28, v29 offset1:1
	v_add_u32_e32 v4, 0x38e0, v46
	s_waitcnt vmcnt(1)
	ds_write2_b32 v4, v30, v31 offset1:1
	v_add_u32_e32 v4, 0x38e8, v46
	ds_write2_b32 v4, v32, v33 offset1:1
	v_add_u32_e32 v4, 0x3cf0, v46
	s_waitcnt vmcnt(0)
; __host__ __device__ __forceinline__ size_t blocked_off(int row, int col, int K) { return (((size_t)(row >> 8) * (K >> 6) + (col >> 6)) * 256 + (row & 255)) * 64 + (col & 63); }
; __device__ __forceinline__ unsigned cvt_pk_bf16(float lo, float hi) { const f32x2c_t v = {lo, hi}; return __builtin_bit_cast(unsigned, __builtin_convertvector(v, bf16x2c_t)); }
; #define LAS __attribute__((address_space(3)))
; #define LDS_WAIT() asm volatile("s_waitcnt lgkmcnt(0)" ::: "memory")
; __host__ __device__ __forceinline__ int win_phys_col(int n) { if (!win_rope_tile(n >> 8)) return n; const int cl = n & 255; return (n & ~255) | (cl & 63) | ((cl & 64) << 1) | ((cl & 128) >> 1); }
; template <bool PERMUTE, bool BLOCKED = false>
; __device__ __forceinline__ void cvt_tile64(const float* W, int K, int N, bf16* WT, int ldo, const float* gk, LAS float* scr, int tile, int lane) {
;     ...
;     const int kc = lane & 7, nrow0 = PERMUTE ? win_phys_col(n0) : n0;
; #pragma unroll
;     for (int j = 0; j < 8; ++j) { const int n = (lane >> 3) + 8 * j; const LAS float* s = scr + (8 * kc) * 65 + n;
;         v4u o; o[0] = cvt_pk_bf16(wrnd(s[0 * 65]), wrnd(s[1 * 65])); o[1] = cvt_pk_bf16(wrnd(s[2 * 65]), wrnd(s[3 * 65])); o[2] = cvt_pk_bf16(wrnd(s[4 * 65]), wrnd(s[5 * 65])); o[3] = cvt_pk_bf16(wrnd(s[6 * 65]), wrnd(s[7 * 65]));
;         *(v4u*)(WT + (BLOCKED ? pg8::blocked_off(nrow0 + n, k0 + 8 * kc, K) : (size_t)(nrow0 + n) * ldo + k0 + 8 * kc)) = o; }
;     LDS_WAIT(); asm volatile("" ::: "memory");
	ds_write2_b32 v4, v0, v1 offset1:1
	v_add_u32_e32 v0, 0x3cf8, v46
	ds_write2_b32 v0, v2, v3 offset1:1
	s_waitcnt lgkmcnt(0)
	ds_read2_b32 v[4:5], v51 offset1:8
	ds_read2_b32 v[10:11], v51 offset0:65 offset1:73
	ds_read2_b32 v[12:13], v51 offset0:130 offset1:138
	ds_read2_b32 v[14:15], v51 offset0:195 offset1:203
	v_lshl_add_u64 v[0:1], s[14:15], 1, v[40:41]
	s_waitcnt lgkmcnt(3)
	v_add_u32_e32 v2, 0x20000, v4
	v_add_u32_e32 v4, 0x400, v51
	ds_read2_b32 v[18:19], v4 offset0:4 offset1:12
	ds_read2_b32 v[20:21], v4 offset0:69 offset1:77
	s_waitcnt lgkmcnt(4)
	v_add_u32_e32 v3, 0x20000, v10
	v_and_b32_e32 v2, 0xfffc0000, v2
	v_and_b32_e32 v3, 0xfffc0000, v3
	ds_read2_b32 v[22:23], v4 offset0:134 offset1:142
	ds_read2_b32 v[24:25], v4 offset0:199 offset1:207
	v_cvt_pk_bf16_f32 v6, v2, v3
	s_waitcnt lgkmcnt(5)
	v_add_u32_e32 v2, 0x20000, v12
	s_waitcnt lgkmcnt(4)
	v_add_u32_e32 v3, 0x20000, v14
	v_and_b32_e32 v2, 0xfffc0000, v2
	v_and_b32_e32 v3, 0xfffc0000, v3
	v_cvt_pk_bf16_f32 v7, v2, v3
	s_waitcnt lgkmcnt(3)
	v_add_u32_e32 v2, 0x20000, v18
	s_waitcnt lgkmcnt(2)
	v_add_u32_e32 v3, 0x20000, v20
	v_and_b32_e32 v2, 0xfffc0000, v2
	v_and_b32_e32 v3, 0xfffc0000, v3
	v_cvt_pk_bf16_f32 v8, v2, v3
	s_waitcnt lgkmcnt(1)
	v_add_u32_e32 v2, 0x20000, v22
	s_waitcnt lgkmcnt(0)
	v_add_u32_e32 v3, 0x20000, v24
	v_and_b32_e32 v2, 0xfffc0000, v2
	v_and_b32_e32 v3, 0xfffc0000, v3
	v_cvt_pk_bf16_f32 v9, v2, v3
	v_add_u32_e32 v2, s6, v50
	v_ashrrev_i32_e32 v3, 31, v2
	v_lshlrev_b64 v[26:27], 13, v[2:3]
	v_add_u32_e32 v3, 0x20000, v5
	v_add_u32_e32 v5, 0x20000, v11
	v_lshl_add_u64 v[26:27], v[0:1], 0, v[26:27]
	v_and_b32_e32 v3, 0xfffc0000, v3
	v_and_b32_e32 v5, 0xfffc0000, v5
	global_store_dwordx4 v[26:27], v[6:9], off
	v_add_u32_e32 v10, 8, v2
	v_ashrrev_i32_e32 v11, 31, v10
	v_cvt_pk_bf16_f32 v6, v3, v5
	v_add_u32_e32 v3, 0x20000, v13
	v_add_u32_e32 v5, 0x20000, v15
	v_and_b32_e32 v3, 0xfffc0000, v3
	v_and_b32_e32 v5, 0xfffc0000, v5
	v_cvt_pk_bf16_f32 v7, v3, v5
	v_add_u32_e32 v3, 0x20000, v19
	v_add_u32_e32 v5, 0x20000, v21
	v_and_b32_e32 v3, 0xfffc0000, v3
	v_and_b32_e32 v5, 0xfffc0000, v5
	v_cvt_pk_bf16_f32 v8, v3, v5
	v_add_u32_e32 v3, 0x20000, v23
	v_add_u32_e32 v5, 0x20000, v25
	v_and_b32_e32 v3, 0xfffc0000, v3
	v_and_b32_e32 v5, 0xfffc0000, v5
	v_lshlrev_b64 v[10:11], 13, v[10:11]
	v_cvt_pk_bf16_f32 v9, v3, v5
	v_lshl_add_u64 v[10:11], v[0:1], 0, v[10:11]
	global_store_dwordx4 v[10:11], v[6:9], off
	ds_read2_b32 v[10:11], v51 offset0:16 offset1:24
	ds_read2_b32 v[12:13], v51 offset0:81 offset1:89
	ds_read2_b32 v[14:15], v51 offset0:146 offset1:154
	ds_read2_b32 v[18:19], v51 offset0:211 offset1:219
	ds_read2_b32 v[20:21], v4 offset0:20 offset1:28
	ds_read2_b32 v[22:23], v4 offset0:85 offset1:93
	s_waitcnt lgkmcnt(5)
	v_add_u32_e32 v3, 0x20000, v10
	s_waitcnt lgkmcnt(4)
	v_add_u32_e32 v5, 0x20000, v12
	v_and_b32_e32 v3, 0xfffc0000, v3
	v_and_b32_e32 v5, 0xfffc0000, v5
	ds_read2_b32 v[24:25], v4 offset0:150 offset1:158
	ds_read2_b32 v[26:27], v4 offset0:215 offset1:223
	v_cvt_pk_bf16_f32 v6, v3, v5
	s_waitcnt lgkmcnt(5)
	v_add_u32_e32 v3, 0x20000, v14
	s_waitcnt lgkmcnt(4)
	v_add_u32_e32 v5, 0x20000, v18
	v_and_b32_e32 v3, 0xfffc0000, v3
	v_and_b32_e32 v5, 0xfffc0000, v5
	v_cvt_pk_bf16_f32 v7, v3, v5
	s_waitcnt lgkmcnt(3)
	v_add_u32_e32 v3, 0x20000, v20
	s_waitcnt lgkmcnt(2)
	v_add_u32_e32 v5, 0x20000, v22
	v_and_b32_e32 v3, 0xfffc0000, v3
	v_and_b32_e32 v5, 0xfffc0000, v5
	v_cvt_pk_bf16_f32 v8, v3, v5
	s_waitcnt lgkmcnt(1)
	v_add_u32_e32 v3, 0x20000, v24
	s_waitcnt lgkmcnt(0)
	v_add_u32_e32 v5, 0x20000, v26
	v_add_u32_e32 v28, 16, v2
	v_and_b32_e32 v3, 0xfffc0000, v3
	v_and_b32_e32 v5, 0xfffc0000, v5
	v_ashrrev_i32_e32 v29, 31, v28
	v_cvt_pk_bf16_f32 v9, v3, v5
	v_lshlrev_b64 v[28:29], 13, v[28:29]
	v_add_u32_e32 v3, 0x20000, v11
	v_add_u32_e32 v5, 0x20000, v13
	v_lshl_add_u64 v[28:29], v[0:1], 0, v[28:29]
	v_and_b32_e32 v3, 0xfffc0000, v3
	v_and_b32_e32 v5, 0xfffc0000, v5
	global_store_dwordx4 v[28:29], v[6:9], off
	v_add_u32_e32 v10, 24, v2
	v_ashrrev_i32_e32 v11, 31, v10
	v_cvt_pk_bf16_f32 v6, v3, v5
	v_add_u32_e32 v3, 0x20000, v15
	v_add_u32_e32 v5, 0x20000, v19
	v_and_b32_e32 v3, 0xfffc0000, v3
	v_and_b32_e32 v5, 0xfffc0000, v5
	v_cvt_pk_bf16_f32 v7, v3, v5
	v_add_u32_e32 v3, 0x20000, v21
	v_add_u32_e32 v5, 0x20000, v23
	v_and_b32_e32 v3, 0xfffc0000, v3
	v_and_b32_e32 v5, 0xfffc0000, v5
	v_cvt_pk_bf16_f32 v8, v3, v5
	v_add_u32_e32 v3, 0x20000, v25
	v_add_u32_e32 v5, 0x20000, v27
	v_and_b32_e32 v3, 0xfffc0000, v3
	v_and_b32_e32 v5, 0xfffc0000, v5
	v_lshlrev_b64 v[10:11], 13, v[10:11]
	v_cvt_pk_bf16_f32 v9, v3, v5
	v_lshl_add_u64 v[10:11], v[0:1], 0, v[10:11]
	global_store_dwordx4 v[10:11], v[6:9], off
	ds_read2_b32 v[10:11], v51 offset0:32 offset1:40
	ds_read2_b32 v[12:13], v51 offset0:97 offset1:105
	ds_read2_b32 v[14:15], v51 offset0:162 offset1:170
	ds_read2_b32 v[18:19], v51 offset0:227 offset1:235
	ds_read2_b32 v[20:21], v4 offset0:36 offset1:44
	ds_read2_b32 v[22:23], v4 offset0:101 offset1:109
	s_waitcnt lgkmcnt(5)
; __host__ __device__ __forceinline__ size_t blocked_off(int row, int col, int K) { return (((size_t)(row >> 8) * (K >> 6) + (col >> 6)) * 256 + (row & 255)) * 64 + (col & 63); }
; __device__ __forceinline__ unsigned cvt_pk_bf16(float lo, float hi) { const f32x2c_t v = {lo, hi}; return __builtin_bit_cast(unsigned, __builtin_convertvector(v, bf16x2c_t)); }
; #define LAS __attribute__((address_space(3)))
; #define LDS_WAIT() asm volatile("s_waitcnt lgkmcnt(0)" ::: "memory")
; __host__ __device__ __forceinline__ int win_phys_col(int n) { if (!win_rope_tile(n >> 8)) return n; const int cl = n & 255; return (n & ~255) | (cl & 63) | ((cl & 64) << 1) | ((cl & 128) >> 1); }
; template <bool PERMUTE, bool BLOCKED = false>
; __device__ __forceinline__ void cvt_tile64(const float* W, int K, int N, bf16* WT, int ldo, const float* gk, LAS float* scr, int tile, int lane) {
;     ...
;     const int kc = lane & 7, nrow0 = PERMUTE ? win_phys_col(n0) : n0;
; #pragma unroll
;     for (int j = 0; j < 8; ++j) { const int n = (lane >> 3) + 8 * j; const LAS float* s = scr + (8 * kc) * 65 + n;
;         v4u o; o[0] = cvt_pk_bf16(wrnd(s[0 * 65]), wrnd(s[1 * 65])); o[1] = cvt_pk_bf16(wrnd(s[2 * 65]), wrnd(s[3 * 65])); o[2] = cvt_pk_bf16(wrnd(s[4 * 65]), wrnd(s[5 * 65])); o[3] = cvt_pk_bf16(wrnd(s[6 * 65]), wrnd(s[7 * 65]));
;         *(v4u*)(WT + (BLOCKED ? pg8::blocked_off(nrow0 + n, k0 + 8 * kc, K) : (size_t)(nrow0 + n) * ldo + k0 + 8 * kc)) = o; }
;     LDS_WAIT(); asm volatile("" ::: "memory");
	v_add_u32_e32 v3, 0x20000, v10
	s_waitcnt lgkmcnt(4)
	v_add_u32_e32 v5, 0x20000, v12
	v_and_b32_e32 v3, 0xfffc0000, v3
	v_and_b32_e32 v5, 0xfffc0000, v5
	ds_read2_b32 v[24:25], v4 offset0:166 offset1:174
	ds_read2_b32 v[26:27], v4 offset0:231 offset1:239
	v_cvt_pk_bf16_f32 v6, v3, v5
	s_waitcnt lgkmcnt(5)
	v_add_u32_e32 v3, 0x20000, v14
	s_waitcnt lgkmcnt(4)
	v_add_u32_e32 v5, 0x20000, v18
	v_and_b32_e32 v3, 0xfffc0000, v3
	v_and_b32_e32 v5, 0xfffc0000, v5
	v_cvt_pk_bf16_f32 v7, v3, v5
	s_waitcnt lgkmcnt(3)
	v_add_u32_e32 v3, 0x20000, v20
	s_waitcnt lgkmcnt(2)
	v_add_u32_e32 v5, 0x20000, v22
	v_and_b32_e32 v3, 0xfffc0000, v3
	v_and_b32_e32 v5, 0xfffc0000, v5
	v_cvt_pk_bf16_f32 v8, v3, v5
	s_waitcnt lgkmcnt(1)
	v_add_u32_e32 v3, 0x20000, v24
	s_waitcnt lgkmcnt(0)
	v_add_u32_e32 v5, 0x20000, v26
	v_add_u32_e32 v28, 32, v2
	v_and_b32_e32 v3, 0xfffc0000, v3
	v_and_b32_e32 v5, 0xfffc0000, v5
	v_ashrrev_i32_e32 v29, 31, v28
	v_cvt_pk_bf16_f32 v9, v3, v5
	v_lshlrev_b64 v[28:29], 13, v[28:29]
	v_add_u32_e32 v3, 0x20000, v11
	v_add_u32_e32 v5, 0x20000, v13
	v_lshl_add_u64 v[28:29], v[0:1], 0, v[28:29]
	v_and_b32_e32 v3, 0xfffc0000, v3
	v_and_b32_e32 v5, 0xfffc0000, v5
	global_store_dwordx4 v[28:29], v[6:9], off
	v_add_u32_e32 v10, 40, v2
	v_ashrrev_i32_e32 v11, 31, v10
	v_cvt_pk_bf16_f32 v6, v3, v5
	v_add_u32_e32 v3, 0x20000, v15
	v_add_u32_e32 v5, 0x20000, v19
	v_and_b32_e32 v3, 0xfffc0000, v3
	v_and_b32_e32 v5, 0xfffc0000, v5
	v_cvt_pk_bf16_f32 v7, v3, v5
	v_add_u32_e32 v3, 0x20000, v21
	v_add_u32_e32 v5, 0x20000, v23
	v_and_b32_e32 v3, 0xfffc0000, v3
	v_and_b32_e32 v5, 0xfffc0000, v5
	v_cvt_pk_bf16_f32 v8, v3, v5
	v_add_u32_e32 v3, 0x20000, v25
	v_add_u32_e32 v5, 0x20000, v27
	v_and_b32_e32 v3, 0xfffc0000, v3
	v_and_b32_e32 v5, 0xfffc0000, v5
	v_lshlrev_b64 v[10:11], 13, v[10:11]
	v_cvt_pk_bf16_f32 v9, v3, v5
	v_lshl_add_u64 v[10:11], v[0:1], 0, v[10:11]
	global_store_dwordx4 v[10:11], v[6:9], off
	ds_read2_b32 v[10:11], v51 offset0:48 offset1:56
	ds_read2_b32 v[12:13], v51 offset0:113 offset1:121
	ds_read2_b32 v[14:15], v51 offset0:178 offset1:186
	ds_read2_b32 v[18:19], v51 offset0:243 offset1:251
	ds_read2_b32 v[20:21], v4 offset0:52 offset1:60
	ds_read2_b32 v[22:23], v4 offset0:117 offset1:125
	s_waitcnt lgkmcnt(5)
	v_add_u32_e32 v3, 0x20000, v10
	s_waitcnt lgkmcnt(4)
	v_add_u32_e32 v5, 0x20000, v12
	v_and_b32_e32 v3, 0xfffc0000, v3
	v_and_b32_e32 v5, 0xfffc0000, v5
	ds_read2_b32 v[24:25], v4 offset0:182 offset1:190
	ds_read2_b32 v[26:27], v4 offset0:247 offset1:255
	v_cvt_pk_bf16_f32 v6, v3, v5
	s_waitcnt lgkmcnt(5)
	v_add_u32_e32 v3, 0x20000, v14
	s_waitcnt lgkmcnt(4)
	v_add_u32_e32 v5, 0x20000, v18
	v_and_b32_e32 v3, 0xfffc0000, v3
	v_and_b32_e32 v5, 0xfffc0000, v5
	v_cvt_pk_bf16_f32 v7, v3, v5
	s_waitcnt lgkmcnt(3)
	v_add_u32_e32 v3, 0x20000, v20
	s_waitcnt lgkmcnt(2)
	v_add_u32_e32 v5, 0x20000, v22
	v_and_b32_e32 v3, 0xfffc0000, v3
	v_and_b32_e32 v5, 0xfffc0000, v5
	v_cvt_pk_bf16_f32 v8, v3, v5
	s_waitcnt lgkmcnt(1)
	v_add_u32_e32 v3, 0x20000, v24
	s_waitcnt lgkmcnt(0)
	v_add_u32_e32 v4, 0x20000, v26
	v_and_b32_e32 v3, 0xfffc0000, v3
	v_and_b32_e32 v4, 0xfffc0000, v4
	v_cvt_pk_bf16_f32 v9, v3, v4
	v_add_u32_e32 v4, 48, v2
	v_ashrrev_i32_e32 v5, 31, v4
	v_lshlrev_b64 v[4:5], 13, v[4:5]
	v_lshl_add_u64 v[4:5], v[0:1], 0, v[4:5]
	global_store_dwordx4 v[4:5], v[6:9], off
	v_add_u32_e32 v3, 0x20000, v11
	v_add_u32_e32 v4, 0x20000, v13
	v_and_b32_e32 v3, 0xfffc0000, v3
	v_and_b32_e32 v4, 0xfffc0000, v4
	v_cvt_pk_bf16_f32 v4, v3, v4
	v_add_u32_e32 v3, 0x20000, v15
	v_add_u32_e32 v5, 0x20000, v19
	v_and_b32_e32 v3, 0xfffc0000, v3
	v_and_b32_e32 v5, 0xfffc0000, v5
	v_cvt_pk_bf16_f32 v5, v3, v5
	v_add_u32_e32 v3, 0x20000, v21
	v_add_u32_e32 v6, 0x20000, v23
	v_and_b32_e32 v3, 0xfffc0000, v3
	v_and_b32_e32 v6, 0xfffc0000, v6
	v_cvt_pk_bf16_f32 v6, v3, v6
	v_add_u32_e32 v3, 0x20000, v25
	v_add_u32_e32 v7, 0x20000, v27
	v_and_b32_e32 v3, 0xfffc0000, v3
	v_and_b32_e32 v7, 0xfffc0000, v7
	v_add_u32_e32 v2, 56, v2
	v_cvt_pk_bf16_f32 v7, v3, v7
	v_ashrrev_i32_e32 v3, 31, v2
	v_lshlrev_b64 v[2:3], 13, v[2:3]
	v_lshl_add_u64 v[0:1], v[0:1], 0, v[2:3]
	global_store_dwordx4 v[0:1], v[4:7], off
	s_waitcnt lgkmcnt(0)
	s_branch .LBB0_215

; #define LAS __attribute__((address_space(3)))
; #define LDS_WAIT() asm volatile("s_waitcnt lgkmcnt(0)" ::: "memory")
; template <bool PERMUTE, bool BLOCKED = false>
; __device__ __forceinline__ void cvt_tile64(const float* W, int K, int N, bf16* WT, int ldo, const float* gk, LAS float* scr, int tile, int lane) {
;     const int nblk = N >> 6, kb = tile / nblk, nb = tile - kb * nblk, k0 = 64 * kb, n0 = 64 * nb;
;     const int lk = lane >> 4, ln = (lane & 15) * 4;
;     ...
;     {
;         f32x4 v[16];
; #pragma unroll
;         for (int i = 0; i < 16; ++i) v[i] = *(const f32x4*)(W + (size_t)(k0 + 4 * i + lk) * N + n0 + ln);
; #pragma unroll
;         for (int i = 0; i < 16; ++i) { const int kk = 4 * i + lk; const float g = gk ? gk[k0 + kk] : 1.0f; LAS float* d = scr + kk * 65 + ln;
;             d[0] = v[i][0] * g; d[1] = v[i][1] * g; d[2] = v[i][2] * g; d[3] = v[i][3] * g; }
;     }
;     ...
; #pragma unroll
;     for (int hh = 0; hh < 2; ++hh) {
;         f32x4 v[8];
; #pragma unroll
;         for (int i = 0; i < 8; ++i) v[i] = *(const f32x4*)(W + (size_t)(k0 + 32 * hh + 4 * i + lk) * N + n0 + ln);
; #pragma unroll
;         for (int i = 0; i < 8; ++i) { const int kk = 32 * hh + 4 * i + lk; const float g = gk ? gk[k0 + kk] : 1.0f; LAS float* d = scr + kk * 65 + ln;
;             d[0] = v[i][0] * g; d[1] = v[i][1] * g; d[2] = v[i][2] * g; d[3] = v[i][3] * g; }
;     }
;     ...
;     LDS_WAIT(); asm volatile("" ::: "memory");
.LBB0_521:
	s_addk_i32 s13, 0x100
	s_cmpk_gt_i32 s13, 0x1ff
	s_mov_b64 s[0:1], -1
	s_cbranch_scc0 .LBB0_545
	s_cmpk_gt_u32 s13, 0x9ff
	s_cbranch_scc0 .LBB0_524
	s_add_i32 s0, s5, 0xffffb000
	s_ashr_i32 s1, s0, 31
	s_lshr_b32 s1, s1, 26
	s_add_i32 s0, s0, s1
	s_ashr_i32 s6, s0, 6
	s_add_i32 s7, s4, s12
	s_lshl_b32 s16, s6, 12
	s_andn2_b32 s0, s0, 63
	s_add_i32 s1, s7, 0xfff74000
	s_sub_i32 s7, s7, s16
	s_add_i32 s20, s7, 0xfff74000
	v_or_b32_e32 v2, s0, v16
	s_ashr_i32 s21, s20, 31
	v_ashrrev_i32_e32 v3, 31, v2
	v_lshl_add_u64 v[0:1], s[20:21], 2, v[34:35]
	v_lshlrev_b64 v[4:5], 14, v[2:3]
	v_or_b32_e32 v8, 4, v2
	v_lshl_add_u64 v[4:5], v[0:1], 0, v[4:5]
	v_ashrrev_i32_e32 v9, 31, v8
	global_load_dwordx4 v[4:7], v[4:5], off nt
	v_lshlrev_b64 v[8:9], 14, v[8:9]
	v_or_b32_e32 v12, 8, v2
	v_lshl_add_u64 v[8:9], v[0:1], 0, v[8:9]
	v_ashrrev_i32_e32 v13, 31, v12
	global_load_dwordx4 v[8:11], v[8:9], off nt
	v_lshlrev_b64 v[12:13], 14, v[12:13]
	v_or_b32_e32 v18, 12, v2
	v_lshl_add_u64 v[12:13], v[0:1], 0, v[12:13]
	v_ashrrev_i32_e32 v19, 31, v18
	global_load_dwordx4 v[12:15], v[12:13], off nt
	v_lshlrev_b64 v[18:19], 14, v[18:19]
	v_or_b32_e32 v22, 16, v2
	v_lshl_add_u64 v[18:19], v[0:1], 0, v[18:19]
	v_ashrrev_i32_e32 v23, 31, v22
	global_load_dwordx4 v[18:21], v[18:19], off nt
	v_lshlrev_b64 v[22:23], 14, v[22:23]
	v_or_b32_e32 v26, 20, v2
	v_lshl_add_u64 v[22:23], v[0:1], 0, v[22:23]
	v_ashrrev_i32_e32 v27, 31, v26
	global_load_dwordx4 v[22:25], v[22:23], off nt
	v_lshlrev_b64 v[26:27], 14, v[26:27]
	v_or_b32_e32 v30, 24, v2
	v_lshl_add_u64 v[26:27], v[0:1], 0, v[26:27]
	v_ashrrev_i32_e32 v31, 31, v30
	global_load_dwordx4 v[26:29], v[26:27], off nt
	v_lshlrev_b64 v[30:31], 14, v[30:31]
	v_or_b32_e32 v46, 28, v2
	v_lshl_add_u64 v[30:31], v[0:1], 0, v[30:31]
	v_ashrrev_i32_e32 v47, 31, v46
	global_load_dwordx4 v[30:33], v[30:31], off nt
	v_lshlrev_b64 v[46:47], 14, v[46:47]
	v_lshl_add_u64 v[46:47], v[0:1], 0, v[46:47]
	global_load_dwordx4 v[46:49], v[46:47], off nt
	v_add_u32_e32 v50, v51, v53
	v_add_u32_e32 v3, 0x410, v50
	s_ashr_i32 s16, s20, 8
	s_ashr_i32 s17, s16, 31
	s_ashr_i32 s7, s6, 31
	s_lshl_b64 s[16:17], s[16:17], 16
	s_lshl_b64 s[6:7], s[6:7], 8
	s_add_u32 s0, s16, s6
	s_addc_u32 s6, s17, s7
	s_and_b32 s1, s1, 0xc0
	s_waitcnt vmcnt(7)
	ds_write2_b32 v50, v4, v5 offset1:1
	ds_write2_b32 v50, v6, v7 offset0:2 offset1:3
	v_or_b32_e32 v4, 32, v2
	v_ashrrev_i32_e32 v5, 31, v4
	v_lshlrev_b64 v[4:5], 14, v[4:5]
	v_lshl_add_u64 v[4:5], v[0:1], 0, v[4:5]
	s_waitcnt vmcnt(6)
	ds_write2_b32 v3, v8, v9 offset1:1
	v_add_u32_e32 v3, 0x418, v50
	v_or_b32_e32 v8, 36, v2
	ds_write2_b32 v3, v10, v11 offset1:1
	v_add_u32_e32 v3, 0x820, v50
	v_ashrrev_i32_e32 v9, 31, v8
	s_waitcnt vmcnt(5)
	ds_write2_b32 v3, v12, v13 offset1:1
	v_add_u32_e32 v3, 0x828, v50
	global_load_dwordx4 v[4:7], v[4:5], off nt
	v_lshlrev_b64 v[8:9], 14, v[8:9]
	v_or_b32_e32 v12, 40, v2
	ds_write2_b32 v3, v14, v15 offset1:1
	v_add_u32_e32 v3, 0xc30, v50
	v_lshl_add_u64 v[8:9], v[0:1], 0, v[8:9]
	v_ashrrev_i32_e32 v13, 31, v12
	s_waitcnt vmcnt(5)
	ds_write2_b32 v3, v18, v19 offset1:1
	v_add_u32_e32 v3, 0xc38, v50
	global_load_dwordx4 v[8:11], v[8:9], off nt
	v_lshlrev_b64 v[12:13], 14, v[12:13]
	v_or_b32_e32 v18, 44, v2
	ds_write2_b32 v3, v20, v21 offset1:1
	v_add_u32_e32 v3, 0x1040, v50
	v_lshl_add_u64 v[12:13], v[0:1], 0, v[12:13]
	v_ashrrev_i32_e32 v19, 31, v18
	s_waitcnt vmcnt(5)
	ds_write2_b32 v3, v22, v23 offset1:1
	v_add_u32_e32 v3, 0x1048, v50
	global_load_dwordx4 v[12:15], v[12:13], off nt
	v_lshlrev_b64 v[18:19], 14, v[18:19]
	v_or_b32_e32 v22, 48, v2
	ds_write2_b32 v3, v24, v25 offset1:1
	v_add_u32_e32 v3, 0x1450, v50
	v_lshl_add_u64 v[18:19], v[0:1], 0, v[18:19]
	v_ashrrev_i32_e32 v23, 31, v22
	s_waitcnt vmcnt(5)
	ds_write2_b32 v3, v26, v27 offset1:1
	v_add_u32_e32 v3, 0x1458, v50
	global_load_dwordx4 v[18:21], v[18:19], off nt
	v_lshlrev_b64 v[22:23], 14, v[22:23]
	v_or_b32_e32 v26, 52, v2
	ds_write2_b32 v3, v28, v29 offset1:1
	v_add_u32_e32 v3, 0x1860, v50
	v_lshl_add_u64 v[22:23], v[0:1], 0, v[22:23]
	v_ashrrev_i32_e32 v27, 31, v26
	s_waitcnt vmcnt(5)
	ds_write2_b32 v3, v30, v31 offset1:1
	v_add_u32_e32 v3, 0x1868, v50
	global_load_dwordx4 v[22:25], v[22:23], off nt
	v_lshlrev_b64 v[26:27], 14, v[26:27]
	v_or_b32_e32 v30, 56, v2
	ds_write2_b32 v3, v32, v33 offset1:1
	v_add_u32_e32 v3, 0x1c70, v50
	v_lshl_add_u64 v[26:27], v[0:1], 0, v[26:27]
	v_ashrrev_i32_e32 v31, 31, v30
	s_waitcnt vmcnt(5)
	ds_write2_b32 v3, v46, v47 offset1:1
	v_add_u32_e32 v3, 0x1c78, v50
	global_load_dwordx4 v[26:29], v[26:27], off nt
	v_lshlrev_b64 v[30:31], 14, v[30:31]
	v_or_b32_e32 v2, 60, v2
	ds_write2_b32 v3, v48, v49 offset1:1
	v_lshl_add_u64 v[30:31], v[0:1], 0, v[30:31]
	v_ashrrev_i32_e32 v3, 31, v2
	global_load_dwordx4 v[30:33], v[30:31], off nt
	v_lshlrev_b64 v[2:3], 14, v[2:3]
	v_lshl_add_u64 v[0:1], v[0:1], 0, v[2:3]
	global_load_dwordx4 v[0:3], v[0:1], off nt
	v_add_u32_e32 v46, 0x2080, v50
	s_waitcnt vmcnt(7)
	ds_write2_b32 v46, v4, v5 offset1:1
	v_add_u32_e32 v4, 0x2088, v50
	ds_write2_b32 v4, v6, v7 offset1:1
	v_add_u32_e32 v4, 0x2490, v50
	s_waitcnt vmcnt(6)
	ds_write2_b32 v4, v8, v9 offset1:1
	v_add_u32_e32 v4, 0x2498, v50
	ds_write2_b32 v4, v10, v11 offset1:1
	v_add_u32_e32 v4, 0x28a0, v50
	s_waitcnt vmcnt(5)
	ds_write2_b32 v4, v12, v13 offset1:1
	v_add_u32_e32 v4, 0x28a8, v50
	ds_write2_b32 v4, v14, v15 offset1:1
	v_add_u32_e32 v4, 0x2cb0, v50
	s_waitcnt vmcnt(4)
	ds_write2_b32 v4, v18, v19 offset1:1
	v_add_u32_e32 v4, 0x2cb8, v50
	ds_write2_b32 v4, v20, v21 offset1:1
	v_add_u32_e32 v4, 0x30c0, v50
	s_waitcnt vmcnt(3)
; __device__ __forceinline__ unsigned cvt_pk_bf16(float lo, float hi) { const f32x2c_t v = {lo, hi}; return __builtin_bit_cast(unsigned, __builtin_convertvector(v, bf16x2c_t)); }
; #define LAS __attribute__((address_space(3)))
; #define LDS_WAIT() asm volatile("s_waitcnt lgkmcnt(0)" ::: "memory")
; __host__ __device__ __forceinline__ int win_phys_col(int n) { if (!win_rope_tile(n >> 8)) return n; const int cl = n & 255; return (n & ~255) | (cl & 63) | ((cl & 64) << 1) | ((cl & 128) >> 1); }
; __host__ __device__ __forceinline__ size_t blocked_off(int row, int col, int K) { return (((size_t)(row >> 8) * (K >> 6) + (col >> 6)) * 256 + (row & 255)) * 64 + (col & 63); }
; template <bool PERMUTE, bool BLOCKED = false>
; __device__ __forceinline__ void cvt_tile64(const float* W, int K, int N, bf16* WT, int ldo, const float* gk, LAS float* scr, int tile, int lane) {
;     ...
;     const int kc = lane & 7, nrow0 = PERMUTE ? win_phys_col(n0) : n0;
; #pragma unroll
;     for (int j = 0; j < 8; ++j) { const int n = (lane >> 3) + 8 * j; const LAS float* s = scr + (8 * kc) * 65 + n;
;         v4u o; o[0] = cvt_pk_bf16(wrnd(s[0 * 65]), wrnd(s[1 * 65])); o[1] = cvt_pk_bf16(wrnd(s[2 * 65]), wrnd(s[3 * 65])); o[2] = cvt_pk_bf16(wrnd(s[4 * 65]), wrnd(s[5 * 65])); o[3] = cvt_pk_bf16(wrnd(s[6 * 65]), wrnd(s[7 * 65]));
;         *(v4u*)(WT + (BLOCKED ? pg8::blocked_off(nrow0 + n, k0 + 8 * kc, K) : (size_t)(nrow0 + n) * ldo + k0 + 8 * kc)) = o; }
;     LDS_WAIT(); asm volatile("" ::: "memory");
	ds_write2_b32 v4, v22, v23 offset1:1
	v_add_u32_e32 v4, 0x30c8, v50
	ds_write2_b32 v4, v24, v25 offset1:1
	v_add_u32_e32 v4, 0x34d0, v50
	s_waitcnt vmcnt(2)
	ds_write2_b32 v4, v26, v27 offset1:1
	v_add_u32_e32 v4, 0x34d8, v50
	ds_write2_b32 v4, v28, v29 offset1:1
	v_add_u32_e32 v4, 0x38e0, v50
	s_waitcnt vmcnt(1)
	ds_write2_b32 v4, v30, v31 offset1:1
	v_add_u32_e32 v4, 0x38e8, v50
	ds_write2_b32 v4, v32, v33 offset1:1
	v_add_u32_e32 v4, 0x3cf0, v50
	s_waitcnt vmcnt(0)
	ds_write2_b32 v4, v0, v1 offset1:1
	v_add_u32_e32 v0, 0x3cf8, v50
	ds_write2_b32 v0, v2, v3 offset1:1
	s_waitcnt lgkmcnt(0)
	ds_read2_b32 v[2:3], v55 offset1:8
	ds_read2_b32 v[8:9], v55 offset0:65 offset1:73
	ds_read2_b32 v[10:11], v55 offset0:130 offset1:138
	ds_read2_b32 v[12:13], v55 offset0:195 offset1:203
	s_waitcnt lgkmcnt(3)
	v_add_u32_e32 v0, 0x20000, v2
	v_add_u32_e32 v2, 0x400, v55
	ds_read2_b32 v[14:15], v2 offset0:4 offset1:12
	ds_read2_b32 v[18:19], v2 offset0:69 offset1:77
	s_waitcnt lgkmcnt(4)
	v_add_u32_e32 v1, 0x20000, v8
	v_and_b32_e32 v0, 0xfffc0000, v0
	v_and_b32_e32 v1, 0xfffc0000, v1
	ds_read2_b32 v[20:21], v2 offset0:134 offset1:142
	ds_read2_b32 v[22:23], v2 offset0:199 offset1:207
	v_cvt_pk_bf16_f32 v4, v0, v1
	s_waitcnt lgkmcnt(5)
	v_add_u32_e32 v0, 0x20000, v10
	s_waitcnt lgkmcnt(4)
	v_add_u32_e32 v1, 0x20000, v12
	v_and_b32_e32 v0, 0xfffc0000, v0
	v_and_b32_e32 v1, 0xfffc0000, v1
	v_cvt_pk_bf16_f32 v5, v0, v1
	s_waitcnt lgkmcnt(3)
	v_add_u32_e32 v0, 0x20000, v14
	s_waitcnt lgkmcnt(2)
	v_add_u32_e32 v1, 0x20000, v18
	v_and_b32_e32 v0, 0xfffc0000, v0
	v_and_b32_e32 v1, 0xfffc0000, v1
	v_cvt_pk_bf16_f32 v6, v0, v1
	s_waitcnt lgkmcnt(1)
	v_add_u32_e32 v0, 0x20000, v20
	s_waitcnt lgkmcnt(0)
	v_add_u32_e32 v1, 0x20000, v22
	v_and_b32_e32 v0, 0xfffc0000, v0
	v_and_b32_e32 v1, 0xfffc0000, v1
	v_cvt_pk_bf16_f32 v7, v0, v1
	v_or_b32_e32 v0, s1, v54
	v_or_b32_e32 v0, s0, v0
	v_mov_b32_e32 v1, s6
	v_lshlrev_b64 v[24:25], 7, v[0:1]
	v_add_u32_e32 v0, 0x20000, v3
	v_add_u32_e32 v3, 0x20000, v9
	v_lshl_add_u64 v[24:25], v[36:37], 0, v[24:25]
	v_and_b32_e32 v0, 0xfffc0000, v0
	v_and_b32_e32 v3, 0xfffc0000, v3
	global_store_dwordx4 v[24:25], v[4:7], off
	ds_read2_b32 v[24:25], v2 offset0:215 offset1:223
	s_nop 0
	v_cvt_pk_bf16_f32 v4, v0, v3
	v_add_u32_e32 v0, 0x20000, v11
	v_add_u32_e32 v3, 0x20000, v13
	v_and_b32_e32 v0, 0xfffc0000, v0
	v_and_b32_e32 v3, 0xfffc0000, v3
	v_cvt_pk_bf16_f32 v5, v0, v3
	v_add_u32_e32 v0, 0x20000, v15
	v_add_u32_e32 v3, 0x20000, v19
	v_and_b32_e32 v0, 0xfffc0000, v0
	v_and_b32_e32 v3, 0xfffc0000, v3
	v_cvt_pk_bf16_f32 v6, v0, v3
	v_add_u32_e32 v0, 0x20000, v21
	v_add_u32_e32 v3, 0x20000, v23
	v_and_b32_e32 v0, 0xfffc0000, v0
	v_and_b32_e32 v3, 0xfffc0000, v3
	v_cvt_pk_bf16_f32 v7, v0, v3
	v_or_b32_e32 v0, s1, v56
	v_or_b32_e32 v0, s0, v0
	v_lshlrev_b64 v[8:9], 7, v[0:1]
	v_lshl_add_u64 v[8:9], v[36:37], 0, v[8:9]
	global_store_dwordx4 v[8:9], v[4:7], off
	ds_read2_b32 v[8:9], v55 offset0:16 offset1:24
	ds_read2_b32 v[10:11], v55 offset0:81 offset1:89
	ds_read2_b32 v[12:13], v55 offset0:146 offset1:154
	ds_read2_b32 v[14:15], v55 offset0:211 offset1:219
	ds_read2_b32 v[18:19], v2 offset0:20 offset1:28
	ds_read2_b32 v[20:21], v2 offset0:85 offset1:93
	s_waitcnt lgkmcnt(5)
	v_add_u32_e32 v0, 0x20000, v8
	s_waitcnt lgkmcnt(4)
	v_add_u32_e32 v3, 0x20000, v10
	v_and_b32_e32 v0, 0xfffc0000, v0
	v_and_b32_e32 v3, 0xfffc0000, v3
	ds_read2_b32 v[22:23], v2 offset0:150 offset1:158
	v_cvt_pk_bf16_f32 v4, v0, v3
	s_waitcnt lgkmcnt(4)
	v_add_u32_e32 v0, 0x20000, v12
	s_waitcnt lgkmcnt(3)
	v_add_u32_e32 v3, 0x20000, v14
	v_and_b32_e32 v0, 0xfffc0000, v0
	v_and_b32_e32 v3, 0xfffc0000, v3
	v_cvt_pk_bf16_f32 v5, v0, v3
	s_waitcnt lgkmcnt(2)
	v_add_u32_e32 v0, 0x20000, v18
	s_waitcnt lgkmcnt(1)
	v_add_u32_e32 v3, 0x20000, v20
	v_and_b32_e32 v0, 0xfffc0000, v0
	v_and_b32_e32 v3, 0xfffc0000, v3
	v_cvt_pk_bf16_f32 v6, v0, v3
	s_waitcnt lgkmcnt(0)
	v_add_u32_e32 v0, 0x20000, v22
	v_add_u32_e32 v3, 0x20000, v24
	v_and_b32_e32 v0, 0xfffc0000, v0
	v_and_b32_e32 v3, 0xfffc0000, v3
	v_cvt_pk_bf16_f32 v7, v0, v3
	v_or_b32_e32 v0, s1, v57
	v_or_b32_e32 v0, s0, v0
	v_lshlrev_b64 v[26:27], 7, v[0:1]
	v_add_u32_e32 v0, 0x20000, v9
	v_add_u32_e32 v3, 0x20000, v11
	v_lshl_add_u64 v[26:27], v[36:37], 0, v[26:27]
	v_and_b32_e32 v0, 0xfffc0000, v0
	v_and_b32_e32 v3, 0xfffc0000, v3
	global_store_dwordx4 v[26:27], v[4:7], off
	ds_read2_b32 v[10:11], v55 offset0:97 offset1:105
	s_nop 0
	v_cvt_pk_bf16_f32 v4, v0, v3
	v_add_u32_e32 v0, 0x20000, v13
	v_add_u32_e32 v3, 0x20000, v15
	v_and_b32_e32 v0, 0xfffc0000, v0
	v_and_b32_e32 v3, 0xfffc0000, v3
	v_cvt_pk_bf16_f32 v5, v0, v3
	v_add_u32_e32 v0, 0x20000, v19
	v_add_u32_e32 v3, 0x20000, v21
	v_and_b32_e32 v0, 0xfffc0000, v0
	v_and_b32_e32 v3, 0xfffc0000, v3
	v_cvt_pk_bf16_f32 v6, v0, v3
	v_add_u32_e32 v0, 0x20000, v23
	v_add_u32_e32 v3, 0x20000, v25
	v_and_b32_e32 v0, 0xfffc0000, v0
	v_and_b32_e32 v3, 0xfffc0000, v3
	v_cvt_pk_bf16_f32 v7, v0, v3
	v_or_b32_e32 v0, s1, v58
	v_or_b32_e32 v0, s0, v0
	v_lshlrev_b64 v[8:9], 7, v[0:1]
	v_lshl_add_u64 v[8:9], v[36:37], 0, v[8:9]
	global_store_dwordx4 v[8:9], v[4:7], off
	ds_read2_b32 v[8:9], v55 offset0:32 offset1:40
	ds_read2_b32 v[12:13], v55 offset0:162 offset1:170
	ds_read2_b32 v[14:15], v55 offset0:227 offset1:235
	ds_read2_b32 v[18:19], v2 offset0:36 offset1:44
	ds_read2_b32 v[20:21], v2 offset0:101 offset1:109
	s_waitcnt lgkmcnt(4)
	v_add_u32_e32 v0, 0x20000, v8
	v_add_u32_e32 v3, 0x20000, v10
	v_and_b32_e32 v0, 0xfffc0000, v0
	v_and_b32_e32 v3, 0xfffc0000, v3
	ds_read2_b32 v[22:23], v2 offset0:166 offset1:174
	ds_read2_b32 v[24:25], v2 offset0:231 offset1:239
	v_cvt_pk_bf16_f32 v4, v0, v3
	s_waitcnt lgkmcnt(5)
; __host__ __device__ __forceinline__ size_t blocked_off(int row, int col, int K) { return (((size_t)(row >> 8) * (K >> 6) + (col >> 6)) * 256 + (row & 255)) * 64 + (col & 63); }
; __device__ __forceinline__ unsigned cvt_pk_bf16(float lo, float hi) { const f32x2c_t v = {lo, hi}; return __builtin_bit_cast(unsigned, __builtin_convertvector(v, bf16x2c_t)); }
; #define LAS __attribute__((address_space(3)))
; #define LDS_WAIT() asm volatile("s_waitcnt lgkmcnt(0)" ::: "memory")
; template <bool PERMUTE, bool BLOCKED = false>
; __device__ __forceinline__ void cvt_tile64(const float* W, int K, int N, bf16* WT, int ldo, const float* gk, LAS float* scr, int tile, int lane) {
;     const int nblk = N >> 6, kb = tile / nblk, nb = tile - kb * nblk, k0 = 64 * kb, n0 = 64 * nb;
;     const int lk = lane >> 4, ln = (lane & 15) * 4;
;     ...
;     {
;         f32x4 v[16];
; #pragma unroll
;         for (int i = 0; i < 16; ++i) v[i] = *(const f32x4*)(W + (size_t)(k0 + 4 * i + lk) * N + n0 + ln);
; #pragma unroll
;         for (int i = 0; i < 16; ++i) { const int kk = 4 * i + lk; const float g = gk ? gk[k0 + kk] : 1.0f; LAS float* d = scr + kk * 65 + ln;
;             d[0] = v[i][0] * g; d[1] = v[i][1] * g; d[2] = v[i][2] * g; d[3] = v[i][3] * g; }
;     }
;     ...
; #pragma unroll
;     for (int hh = 0; hh < 2; ++hh) {
;         f32x4 v[8];
; #pragma unroll
;         for (int i = 0; i < 8; ++i) v[i] = *(const f32x4*)(W + (size_t)(k0 + 32 * hh + 4 * i + lk) * N + n0 + ln);
; #pragma unroll
;         for (int i = 0; i < 8; ++i) { const int kk = 32 * hh + 4 * i + lk; const float g = gk ? gk[k0 + kk] : 1.0f; LAS float* d = scr + kk * 65 + ln;
;             d[0] = v[i][0] * g; d[1] = v[i][1] * g; d[2] = v[i][2] * g; d[3] = v[i][3] * g; }
;     ...
;     const int kc = lane & 7, nrow0 = PERMUTE ? win_phys_col(n0) : n0;
; #pragma unroll
;     for (int j = 0; j < 8; ++j) { const int n = (lane >> 3) + 8 * j; const LAS float* s = scr + (8 * kc) * 65 + n;
;         v4u o; o[0] = cvt_pk_bf16(wrnd(s[0 * 65]), wrnd(s[1 * 65])); o[1] = cvt_pk_bf16(wrnd(s[2 * 65]), wrnd(s[3 * 65])); o[2] = cvt_pk_bf16(wrnd(s[4 * 65]), wrnd(s[5 * 65])); o[3] = cvt_pk_bf16(wrnd(s[6 * 65]), wrnd(s[7 * 65]));
;         *(v4u*)(WT + (BLOCKED ? pg8::blocked_off(nrow0 + n, k0 + 8 * kc, K) : (size_t)(nrow0 + n) * ldo + k0 + 8 * kc)) = o; }
;     LDS_WAIT(); asm volatile("" ::: "memory");
	v_add_u32_e32 v0, 0x20000, v12
	s_waitcnt lgkmcnt(4)
	v_add_u32_e32 v3, 0x20000, v14
	v_and_b32_e32 v0, 0xfffc0000, v0
	v_and_b32_e32 v3, 0xfffc0000, v3
	v_cvt_pk_bf16_f32 v5, v0, v3
	s_waitcnt lgkmcnt(3)
	v_add_u32_e32 v0, 0x20000, v18
	s_waitcnt lgkmcnt(2)
	v_add_u32_e32 v3, 0x20000, v20
	v_and_b32_e32 v0, 0xfffc0000, v0
	v_and_b32_e32 v3, 0xfffc0000, v3
	v_cvt_pk_bf16_f32 v6, v0, v3
	s_waitcnt lgkmcnt(1)
	v_add_u32_e32 v0, 0x20000, v22
	s_waitcnt lgkmcnt(0)
	v_add_u32_e32 v3, 0x20000, v24
	v_and_b32_e32 v0, 0xfffc0000, v0
	v_and_b32_e32 v3, 0xfffc0000, v3
	v_cvt_pk_bf16_f32 v7, v0, v3
	v_or_b32_e32 v0, s1, v59
	v_or_b32_e32 v0, s0, v0
	v_lshlrev_b64 v[26:27], 7, v[0:1]
	v_add_u32_e32 v0, 0x20000, v9
	v_add_u32_e32 v3, 0x20000, v11
	v_lshl_add_u64 v[26:27], v[36:37], 0, v[26:27]
	v_and_b32_e32 v0, 0xfffc0000, v0
	v_and_b32_e32 v3, 0xfffc0000, v3
	global_store_dwordx4 v[26:27], v[4:7], off
	ds_read2_b32 v[10:11], v55 offset0:113 offset1:121
	s_nop 0
	v_cvt_pk_bf16_f32 v4, v0, v3
	v_add_u32_e32 v0, 0x20000, v13
	v_add_u32_e32 v3, 0x20000, v15
	v_and_b32_e32 v0, 0xfffc0000, v0
	v_and_b32_e32 v3, 0xfffc0000, v3
	v_cvt_pk_bf16_f32 v5, v0, v3
	v_add_u32_e32 v0, 0x20000, v19
	v_add_u32_e32 v3, 0x20000, v21
	v_and_b32_e32 v0, 0xfffc0000, v0
	v_and_b32_e32 v3, 0xfffc0000, v3
	v_cvt_pk_bf16_f32 v6, v0, v3
	v_add_u32_e32 v0, 0x20000, v23
	v_add_u32_e32 v3, 0x20000, v25
	v_and_b32_e32 v0, 0xfffc0000, v0
	v_and_b32_e32 v3, 0xfffc0000, v3
	v_cvt_pk_bf16_f32 v7, v0, v3
	v_or_b32_e32 v0, s1, v60
	v_or_b32_e32 v0, s0, v0
	v_lshlrev_b64 v[8:9], 7, v[0:1]
	v_lshl_add_u64 v[8:9], v[36:37], 0, v[8:9]
	global_store_dwordx4 v[8:9], v[4:7], off
	ds_read2_b32 v[8:9], v55 offset0:48 offset1:56
	ds_read2_b32 v[12:13], v55 offset0:178 offset1:186
	ds_read2_b32 v[14:15], v55 offset0:243 offset1:251
	ds_read2_b32 v[18:19], v2 offset0:52 offset1:60
	ds_read2_b32 v[20:21], v2 offset0:117 offset1:125
	s_waitcnt lgkmcnt(4)
	v_add_u32_e32 v0, 0x20000, v8
	v_add_u32_e32 v3, 0x20000, v10
	v_and_b32_e32 v0, 0xfffc0000, v0
	v_and_b32_e32 v3, 0xfffc0000, v3
	ds_read2_b32 v[22:23], v2 offset0:182 offset1:190
	ds_read2_b32 v[24:25], v2 offset0:247 offset1:255
	v_cvt_pk_bf16_f32 v4, v0, v3
	s_waitcnt lgkmcnt(5)
	v_add_u32_e32 v0, 0x20000, v12
	s_waitcnt lgkmcnt(4)
	v_add_u32_e32 v3, 0x20000, v14
	v_and_b32_e32 v0, 0xfffc0000, v0
	v_and_b32_e32 v3, 0xfffc0000, v3
	v_cvt_pk_bf16_f32 v5, v0, v3
	s_waitcnt lgkmcnt(3)
	v_add_u32_e32 v0, 0x20000, v18
	s_waitcnt lgkmcnt(2)
	v_add_u32_e32 v3, 0x20000, v20
	v_and_b32_e32 v0, 0xfffc0000, v0
	v_and_b32_e32 v3, 0xfffc0000, v3
	v_cvt_pk_bf16_f32 v6, v0, v3
	s_waitcnt lgkmcnt(1)
	v_add_u32_e32 v0, 0x20000, v22
	s_waitcnt lgkmcnt(0)
	v_add_u32_e32 v2, 0x20000, v24
	v_and_b32_e32 v0, 0xfffc0000, v0
	v_and_b32_e32 v2, 0xfffc0000, v2
	v_cvt_pk_bf16_f32 v7, v0, v2
	v_or_b32_e32 v0, s1, v61
	v_or_b32_e32 v0, s0, v0
	v_lshlrev_b64 v[2:3], 7, v[0:1]
	v_lshl_add_u64 v[2:3], v[36:37], 0, v[2:3]
	global_store_dwordx4 v[2:3], v[4:7], off
	v_add_u32_e32 v0, 0x20000, v9
	v_add_u32_e32 v2, 0x20000, v11
	v_and_b32_e32 v0, 0xfffc0000, v0
	v_and_b32_e32 v2, 0xfffc0000, v2
	v_cvt_pk_bf16_f32 v2, v0, v2
	v_add_u32_e32 v0, 0x20000, v13
	v_add_u32_e32 v3, 0x20000, v15
	v_and_b32_e32 v0, 0xfffc0000, v0
	v_and_b32_e32 v3, 0xfffc0000, v3
	v_cvt_pk_bf16_f32 v3, v0, v3
	v_add_u32_e32 v0, 0x20000, v19
	v_add_u32_e32 v4, 0x20000, v21
	v_and_b32_e32 v0, 0xfffc0000, v0
	v_and_b32_e32 v4, 0xfffc0000, v4
	v_cvt_pk_bf16_f32 v4, v0, v4
	v_add_u32_e32 v0, 0x20000, v23
	v_add_u32_e32 v5, 0x20000, v25
	v_and_b32_e32 v0, 0xfffc0000, v0
	v_and_b32_e32 v5, 0xfffc0000, v5
	v_cvt_pk_bf16_f32 v5, v0, v5
	v_or_b32_e32 v0, s1, v62
	v_or_b32_e32 v0, s0, v0
	v_lshlrev_b64 v[0:1], 7, v[0:1]
	v_lshl_add_u64 v[0:1], v[36:37], 0, v[0:1]
	global_store_dwordx4 v[0:1], v[2:5], off
	s_waitcnt lgkmcnt(0)
	s_mov_b64 s[0:1], 0
.LBB0_524:
	s_andn2_b64 vcc, exec, s[0:1]
	s_cbranch_vccnz .LBB0_544
	s_add_i32 s0, s5, 0xfffff000
	s_ashr_i32 s1, s0, 31
	s_lshr_b32 s1, s1, 24
	s_add_i32 s0, s0, s1
	s_ashr_i32 s0, s0, 8
	s_lshl_b32 s20, s0, 6
	s_lshl_b32 s16, s0, 14
	s_add_i32 s0, s4, s12
	s_sub_i32 s0, s0, s16
	v_or_b32_e32 v48, s20, v16
	s_add_i32 s0, s0, 0x74000
	v_or_b32_e32 v2, 4, v48
	s_ashr_i32 s1, s0, 31
	v_ashrrev_i32_e32 v49, 31, v48
	v_ashrrev_i32_e32 v3, 31, v2
	v_lshl_add_u64 v[46:47], s[0:1], 2, v[38:39]
	v_lshlrev_b64 v[0:1], 16, v[48:49]
	v_lshlrev_b64 v[2:3], 16, v[2:3]
	v_lshl_add_u64 v[0:1], v[46:47], 0, v[0:1]
	v_lshl_add_u64 v[2:3], v[46:47], 0, v[2:3]
	global_load_dwordx4 v[30:33], v[0:1], off nt
	global_load_dwordx4 v[26:29], v[2:3], off nt
	v_or_b32_e32 v0, 8, v48
	v_or_b32_e32 v2, 12, v48
	v_ashrrev_i32_e32 v1, 31, v0
	v_ashrrev_i32_e32 v3, 31, v2
	v_lshlrev_b64 v[0:1], 16, v[0:1]
	v_lshlrev_b64 v[2:3], 16, v[2:3]
	v_lshl_add_u64 v[0:1], v[46:47], 0, v[0:1]
	v_lshl_add_u64 v[2:3], v[46:47], 0, v[2:3]
	global_load_dwordx4 v[22:25], v[0:1], off nt
	global_load_dwordx4 v[18:21], v[2:3], off nt
	v_or_b32_e32 v0, 16, v48
	v_or_b32_e32 v2, 20, v48
	v_ashrrev_i32_e32 v1, 31, v0
	v_ashrrev_i32_e32 v3, 31, v2
	v_lshlrev_b64 v[0:1], 16, v[0:1]
	v_lshlrev_b64 v[2:3], 16, v[2:3]
	v_lshl_add_u64 v[0:1], v[46:47], 0, v[0:1]
	v_lshl_add_u64 v[2:3], v[46:47], 0, v[2:3]
	global_load_dwordx4 v[12:15], v[0:1], off nt
	global_load_dwordx4 v[8:11], v[2:3], off nt
	v_or_b32_e32 v0, 24, v48
	v_or_b32_e32 v2, 28, v48
	v_ashrrev_i32_e32 v1, 31, v0
	v_ashrrev_i32_e32 v3, 31, v2
	v_lshlrev_b64 v[0:1], 16, v[0:1]
	v_lshlrev_b64 v[2:3], 16, v[2:3]
	v_lshl_add_u64 v[0:1], v[46:47], 0, v[0:1]
	v_lshl_add_u64 v[2:3], v[46:47], 0, v[2:3]
	global_load_dwordx4 v[4:7], v[0:1], off nt
	s_nop 0
	global_load_dwordx4 v[0:3], v[2:3], off nt
	v_cndmask_b32_e64 v52, 0, 1, s[14:15]
	v_mov_b32_e32 v50, 1.0
	v_cmp_ne_u32_e64 s[6:7], 1, v52
	s_andn2_b64 vcc, exec, s[14:15]
	v_mov_b32_e32 v52, 1.0
	s_cbranch_vccnz .LBB0_527
	v_lshl_add_u64 v[64:65], v[48:49], 2, s[10:11]
	global_load_dword v110, v[64:65], off offset:16
	global_load_dword v124, v[64:65], off offset:32
	global_load_dword v125, v[64:65], off offset:48
	global_load_dword v126, v[64:65], off offset:64
	global_load_dword v127, v[64:65], off offset:80
	global_load_dword v178, v[64:65], off offset:96
	global_load_dword v179, v[64:65], off offset:112
	global_load_dword v180, v[64:65], off offset:128
	global_load_dword v181, v[64:65], off offset:144
	global_load_dword v182, v[64:65], off offset:160
	global_load_dword v183, v[64:65], off offset:176
	global_load_dword v184, v[64:65], off offset:192
	global_load_dword v185, v[64:65], off offset:208
	global_load_dword v186, v[64:65], off offset:224
	global_load_dword v187, v[64:65], off offset:240
	global_load_dword v52, v[64:65], off
	s_waitcnt vmcnt(0)
	s_ashr_i32 s21, s20, 31
	v_lshl_add_u64 v[64:65], s[20:21], 0, v[16:17]
	v_lshl_add_u64 v[64:65], v[64:65], 2, s[10:11]
	s_waitcnt vmcnt(0)
	v_pk_mul_f32 v[30:31], v[30:31], v[52:53] op_sel_hi:[1,0]
	v_pk_mul_f32 v[32:33], v[32:33], v[52:53] op_sel_hi:[1,0]
	v_mov_b32_e32 v52, v110

; #define LAS __attribute__((address_space(3)))
; template <bool PERMUTE, bool BLOCKED = false>
; __device__ __forceinline__ void cvt_tile64(const float* W, int K, int N, bf16* WT, int ldo, const float* gk, LAS float* scr, int tile, int lane) {
;     ...
;     for (int hh = 0; hh < 2; ++hh) {
;         f32x4 v[8];
; #pragma unroll
;         for (int i = 0; i < 8; ++i) v[i] = *(const f32x4*)(W + (size_t)(k0 + 32 * hh + 4 * i + lk) * N + n0 + ln);
; #pragma unroll
;         for (int i = 0; i < 8; ++i) { const int kk = 32 * hh + 4 * i + lk; const float g = gk ? gk[k0 + kk] : 1.0f; LAS float* d = scr + kk * 65 + ln;
;             d[0] = v[i][0] * g; d[1] = v[i][1] * g; d[2] = v[i][2] * g; d[3] = v[i][3] * g; }
.LBB0_533:
	v_add_u32_e32 v8, 0x1860, v49
	ds_write2_b32 v8, v4, v5 offset1:1
	v_add_u32_e32 v4, 0x1868, v49
	ds_write2_b32 v4, v6, v7 offset1:1
	s_waitcnt vmcnt(0)
	v_pk_mul_f32 v[0:1], v[0:1], v[18:19] op_sel_hi:[1,0]
	v_add_u32_e32 v4, 0x1c70, v49
	ds_write2_b32 v4, v0, v1 offset1:1
	v_pk_mul_f32 v[0:1], v[2:3], v[18:19] op_sel_hi:[1,0]
	v_add_u32_e32 v2, 0x1c78, v49
	ds_write2_b32 v2, v0, v1 offset1:1
	v_or_b32_e32 v0, 32, v48
	v_or_b32_e32 v4, 60, v48
	v_ashrrev_i32_e32 v1, 31, v0
	v_ashrrev_i32_e32 v5, 31, v4
	v_lshlrev_b64 v[0:1], 16, v[0:1]
	v_lshlrev_b64 v[4:5], 16, v[4:5]
	v_lshl_add_u64 v[0:1], v[46:47], 0, v[0:1]
	v_lshl_add_u64 v[4:5], v[46:47], 0, v[4:5]
	global_load_dwordx4 v[26:29], v[0:1], off nt
	s_and_b64 vcc, exec, s[6:7]
	global_load_dwordx4 v[4:7], v[4:5], off nt
	v_or_b32_e32 v0, 36, v48
	v_ashrrev_i32_e32 v1, 31, v0
	v_lshlrev_b64 v[0:1], 16, v[0:1]
	v_lshl_add_u64 v[0:1], v[46:47], 0, v[0:1]
	global_load_dwordx4 v[30:33], v[0:1], off nt
	v_or_b32_e32 v0, 40, v48
	v_ashrrev_i32_e32 v1, 31, v0
	v_lshlrev_b64 v[0:1], 16, v[0:1]
	v_lshl_add_u64 v[0:1], v[46:47], 0, v[0:1]
	global_load_dwordx4 v[18:21], v[0:1], off nt
	v_or_b32_e32 v0, 44, v48
	v_ashrrev_i32_e32 v1, 31, v0
	v_lshlrev_b64 v[0:1], 16, v[0:1]
	v_lshl_add_u64 v[0:1], v[46:47], 0, v[0:1]
	global_load_dwordx4 v[22:25], v[0:1], off nt
	v_or_b32_e32 v0, 48, v48
	v_ashrrev_i32_e32 v1, 31, v0
	v_lshlrev_b64 v[0:1], 16, v[0:1]
	v_lshl_add_u64 v[0:1], v[46:47], 0, v[0:1]
	global_load_dwordx4 v[8:11], v[0:1], off nt
	v_or_b32_e32 v0, 52, v48
	v_ashrrev_i32_e32 v1, 31, v0
	v_lshlrev_b64 v[0:1], 16, v[0:1]
	v_lshl_add_u64 v[0:1], v[46:47], 0, v[0:1]
	global_load_dwordx4 v[12:15], v[0:1], off nt
	v_or_b32_e32 v0, 56, v48
	v_ashrrev_i32_e32 v1, 31, v0
	v_lshlrev_b64 v[0:1], 16, v[0:1]
	v_lshl_add_u64 v[0:1], v[46:47], 0, v[0:1]
	global_load_dwordx4 v[0:3], v[0:1], off nt
	v_mov_b32_e32 v46, 1.0
	v_mov_b32_e32 v48, 1.0
	s_cbranch_vccnz .LBB0_535
	s_ashr_i32 s21, s20, 31
	v_lshl_add_u64 v[64:65], s[20:21], 0, v[16:17]
	v_lshl_add_u64 v[64:65], v[64:65], 2, s[10:11]
	v_mov_b32_e32 v48, v180
	s_waitcnt vmcnt(0)
	v_pk_mul_f32 v[26:27], v[26:27], v[48:49] op_sel_hi:[1,0]
	v_pk_mul_f32 v[28:29], v[28:29], v[48:49] op_sel_hi:[1,0]
	v_mov_b32_e32 v48, v181

; #define LAS __attribute__((address_space(3)))
; #define LDS_WAIT() asm volatile("s_waitcnt lgkmcnt(0)" ::: "memory")
; template <bool PERMUTE, bool BLOCKED = false>
; __device__ __forceinline__ void cvt_tile64(const float* W, int K, int N, bf16* WT, int ldo, const float* gk, LAS float* scr, int tile, int lane) {
;     const int nblk = N >> 6, kb = tile / nblk, nb = tile - kb * nblk, k0 = 64 * kb, n0 = 64 * nb;
;     const int lk = lane >> 4, ln = (lane & 15) * 4;
;     ...
;     {
;         f32x4 v[16];
; #pragma unroll
;         for (int i = 0; i < 16; ++i) v[i] = *(const f32x4*)(W + (size_t)(k0 + 4 * i + lk) * N + n0 + ln);
; #pragma unroll
;         for (int i = 0; i < 16; ++i) { const int kk = 4 * i + lk; const float g = gk ? gk[k0 + kk] : 1.0f; LAS float* d = scr + kk * 65 + ln;
;             d[0] = v[i][0] * g; d[1] = v[i][1] * g; d[2] = v[i][2] * g; d[3] = v[i][3] * g; }
;     }
;     ...
; #pragma unroll
;     for (int hh = 0; hh < 2; ++hh) {
;         f32x4 v[8];
; #pragma unroll
;         for (int i = 0; i < 8; ++i) v[i] = *(const f32x4*)(W + (size_t)(k0 + 32 * hh + 4 * i + lk) * N + n0 + ln);
; #pragma unroll
;         for (int i = 0; i < 8; ++i) { const int kk = 32 * hh + 4 * i + lk; const float g = gk ? gk[k0 + kk] : 1.0f; LAS float* d = scr + kk * 65 + ln;
;             d[0] = v[i][0] * g; d[1] = v[i][1] * g; d[2] = v[i][2] * g; d[3] = v[i][3] * g; }
;     }
;     ...
;     LDS_WAIT(); asm volatile("" ::: "memory");
.LBB0_545:
	s_andn2_b64 vcc, exec, s[0:1]
	s_cbranch_vccnz .LBB0_520
	s_ashr_i32 s0, s5, 31
	s_lshr_b32 s0, s0, 26
	s_add_i32 s0, s5, s0
	s_and_b32 s6, s0, 0xffffffc0
	s_lshl_b32 s0, s0, 6
	s_and_b32 s0, s0, 0xfffff000
	s_add_i32 s1, s4, s12
	s_sub_i32 s1, s1, s0
	s_add_i32 s16, s1, 0xb4000
	v_or_b32_e32 v2, s6, v16
	s_ashr_i32 s17, s16, 31
	v_ashrrev_i32_e32 v3, 31, v2
	v_lshl_add_u64 v[0:1], s[16:17], 2, v[42:43]
	v_lshlrev_b64 v[4:5], 14, v[2:3]
	v_or_b32_e32 v8, 4, v2
	v_lshl_add_u64 v[4:5], v[0:1], 0, v[4:5]
	v_ashrrev_i32_e32 v9, 31, v8
	global_load_dwordx4 v[4:7], v[4:5], off nt
	v_lshlrev_b64 v[8:9], 14, v[8:9]
	v_or_b32_e32 v12, 8, v2
	v_lshl_add_u64 v[8:9], v[0:1], 0, v[8:9]
	v_ashrrev_i32_e32 v13, 31, v12
	global_load_dwordx4 v[8:11], v[8:9], off nt
	v_lshlrev_b64 v[12:13], 14, v[12:13]
	v_or_b32_e32 v18, 12, v2
	v_lshl_add_u64 v[12:13], v[0:1], 0, v[12:13]
	v_ashrrev_i32_e32 v19, 31, v18
	global_load_dwordx4 v[12:15], v[12:13], off nt
	v_lshlrev_b64 v[18:19], 14, v[18:19]
	v_or_b32_e32 v22, 16, v2
	v_lshl_add_u64 v[18:19], v[0:1], 0, v[18:19]
	v_ashrrev_i32_e32 v23, 31, v22
	global_load_dwordx4 v[18:21], v[18:19], off nt
	v_lshlrev_b64 v[22:23], 14, v[22:23]
	v_or_b32_e32 v26, 20, v2
	v_lshl_add_u64 v[22:23], v[0:1], 0, v[22:23]
	v_ashrrev_i32_e32 v27, 31, v26
	global_load_dwordx4 v[22:25], v[22:23], off nt
	v_lshlrev_b64 v[26:27], 14, v[26:27]
	v_or_b32_e32 v30, 24, v2
	v_lshl_add_u64 v[26:27], v[0:1], 0, v[26:27]
	v_ashrrev_i32_e32 v31, 31, v30
	global_load_dwordx4 v[26:29], v[26:27], off nt
	v_lshlrev_b64 v[30:31], 14, v[30:31]
	v_or_b32_e32 v46, 28, v2
	v_lshl_add_u64 v[30:31], v[0:1], 0, v[30:31]
	v_ashrrev_i32_e32 v47, 31, v46
	global_load_dwordx4 v[30:33], v[30:31], off nt
	v_lshlrev_b64 v[46:47], 14, v[46:47]
	v_lshl_add_u64 v[46:47], v[0:1], 0, v[46:47]
	global_load_dwordx4 v[46:49], v[46:47], off nt
	v_add_u32_e32 v50, v51, v53
	v_add_u32_e32 v3, 0x410, v50
	s_sub_i32 s0, s4, s0
	s_ashr_i32 s7, s6, 31
	s_waitcnt vmcnt(7)
	ds_write2_b32 v50, v4, v5 offset1:1
	ds_write2_b32 v50, v6, v7 offset0:2 offset1:3
	v_or_b32_e32 v4, 32, v2
	v_ashrrev_i32_e32 v5, 31, v4
	v_lshlrev_b64 v[4:5], 14, v[4:5]
	v_lshl_add_u64 v[4:5], v[0:1], 0, v[4:5]
	s_waitcnt vmcnt(6)
	ds_write2_b32 v3, v8, v9 offset1:1
	v_add_u32_e32 v3, 0x418, v50
	v_or_b32_e32 v8, 36, v2
	ds_write2_b32 v3, v10, v11 offset1:1
	v_add_u32_e32 v3, 0x820, v50
	v_ashrrev_i32_e32 v9, 31, v8
	s_waitcnt vmcnt(5)
	ds_write2_b32 v3, v12, v13 offset1:1
	v_add_u32_e32 v3, 0x828, v50
	global_load_dwordx4 v[4:7], v[4:5], off nt
	v_lshlrev_b64 v[8:9], 14, v[8:9]
	v_or_b32_e32 v12, 40, v2
	ds_write2_b32 v3, v14, v15 offset1:1
	v_add_u32_e32 v3, 0xc30, v50
	v_lshl_add_u64 v[8:9], v[0:1], 0, v[8:9]
	v_ashrrev_i32_e32 v13, 31, v12
	s_waitcnt vmcnt(5)
	ds_write2_b32 v3, v18, v19 offset1:1
	v_add_u32_e32 v3, 0xc38, v50
	global_load_dwordx4 v[8:11], v[8:9], off nt
	v_lshlrev_b64 v[12:13], 14, v[12:13]
	v_or_b32_e32 v18, 44, v2
	ds_write2_b32 v3, v20, v21 offset1:1
	v_add_u32_e32 v3, 0x1040, v50
	v_lshl_add_u64 v[12:13], v[0:1], 0, v[12:13]
	v_ashrrev_i32_e32 v19, 31, v18
	s_waitcnt vmcnt(5)
	ds_write2_b32 v3, v22, v23 offset1:1
	v_add_u32_e32 v3, 0x1048, v50
	global_load_dwordx4 v[12:15], v[12:13], off nt
	v_lshlrev_b64 v[18:19], 14, v[18:19]
	v_or_b32_e32 v22, 48, v2
	ds_write2_b32 v3, v24, v25 offset1:1
	v_add_u32_e32 v3, 0x1450, v50
	v_lshl_add_u64 v[18:19], v[0:1], 0, v[18:19]
	v_ashrrev_i32_e32 v23, 31, v22
	s_waitcnt vmcnt(5)
	ds_write2_b32 v3, v26, v27 offset1:1
	v_add_u32_e32 v3, 0x1458, v50
	global_load_dwordx4 v[18:21], v[18:19], off nt
	v_lshlrev_b64 v[22:23], 14, v[22:23]
	v_or_b32_e32 v26, 52, v2
	ds_write2_b32 v3, v28, v29 offset1:1
	v_add_u32_e32 v3, 0x1860, v50
	v_lshl_add_u64 v[22:23], v[0:1], 0, v[22:23]
	v_ashrrev_i32_e32 v27, 31, v26
	s_waitcnt vmcnt(5)
	ds_write2_b32 v3, v30, v31 offset1:1
	v_add_u32_e32 v3, 0x1868, v50
	global_load_dwordx4 v[22:25], v[22:23], off nt
	v_lshlrev_b64 v[26:27], 14, v[26:27]
	v_or_b32_e32 v30, 56, v2
	ds_write2_b32 v3, v32, v33 offset1:1
	v_add_u32_e32 v3, 0x1c70, v50
	v_lshl_add_u64 v[26:27], v[0:1], 0, v[26:27]
	v_ashrrev_i32_e32 v31, 31, v30
	s_waitcnt vmcnt(5)
	ds_write2_b32 v3, v46, v47 offset1:1
	v_add_u32_e32 v3, 0x1c78, v50
	global_load_dwordx4 v[26:29], v[26:27], off nt
	v_lshlrev_b64 v[30:31], 14, v[30:31]
	v_or_b32_e32 v2, 60, v2
	ds_write2_b32 v3, v48, v49 offset1:1
	v_lshl_add_u64 v[30:31], v[0:1], 0, v[30:31]
	v_ashrrev_i32_e32 v3, 31, v2
	global_load_dwordx4 v[30:33], v[30:31], off nt
	v_lshlrev_b64 v[2:3], 14, v[2:3]
	v_lshl_add_u64 v[0:1], v[0:1], 0, v[2:3]
	global_load_dwordx4 v[0:3], v[0:1], off nt
	v_add_u32_e32 v46, 0x2080, v50
	s_waitcnt vmcnt(7)
	ds_write2_b32 v46, v4, v5 offset1:1
	v_add_u32_e32 v4, 0x2088, v50
	ds_write2_b32 v4, v6, v7 offset1:1
	v_add_u32_e32 v4, 0x2490, v50
	s_waitcnt vmcnt(6)
	ds_write2_b32 v4, v8, v9 offset1:1
	v_add_u32_e32 v4, 0x2498, v50
	ds_write2_b32 v4, v10, v11 offset1:1
	v_add_u32_e32 v4, 0x28a0, v50
	s_waitcnt vmcnt(5)
	ds_write2_b32 v4, v12, v13 offset1:1
	v_add_u32_e32 v4, 0x28a8, v50
	ds_write2_b32 v4, v14, v15 offset1:1
	v_add_u32_e32 v4, 0x2cb0, v50
	s_waitcnt vmcnt(4)
	ds_write2_b32 v4, v18, v19 offset1:1
	v_add_u32_e32 v4, 0x2cb8, v50
	ds_write2_b32 v4, v20, v21 offset1:1
	v_add_u32_e32 v4, 0x30c0, v50
	s_waitcnt vmcnt(3)
	ds_write2_b32 v4, v22, v23 offset1:1
	v_add_u32_e32 v4, 0x30c8, v50
	ds_write2_b32 v4, v24, v25 offset1:1
	v_add_u32_e32 v4, 0x34d0, v50
	s_waitcnt vmcnt(2)
	ds_write2_b32 v4, v26, v27 offset1:1
	v_add_u32_e32 v4, 0x34d8, v50
	ds_write2_b32 v4, v28, v29 offset1:1
	v_add_u32_e32 v4, 0x38e0, v50
	s_waitcnt vmcnt(1)
; __host__ __device__ __forceinline__ size_t blocked_off(int row, int col, int K) { return (((size_t)(row >> 8) * (K >> 6) + (col >> 6)) * 256 + (row & 255)) * 64 + (col & 63); }
; __device__ __forceinline__ unsigned cvt_pk_bf16(float lo, float hi) { const f32x2c_t v = {lo, hi}; return __builtin_bit_cast(unsigned, __builtin_convertvector(v, bf16x2c_t)); }
; #define LAS __attribute__((address_space(3)))
; #define LDS_WAIT() asm volatile("s_waitcnt lgkmcnt(0)" ::: "memory")
; __host__ __device__ __forceinline__ int win_phys_col(int n) { if (!win_rope_tile(n >> 8)) return n; const int cl = n & 255; return (n & ~255) | (cl & 63) | ((cl & 64) << 1) | ((cl & 128) >> 1); }
; template <bool PERMUTE, bool BLOCKED = false>
; __device__ __forceinline__ void cvt_tile64(const float* W, int K, int N, bf16* WT, int ldo, const float* gk, LAS float* scr, int tile, int lane) {
;     ...
;     const int kc = lane & 7, nrow0 = PERMUTE ? win_phys_col(n0) : n0;
; #pragma unroll
;     for (int j = 0; j < 8; ++j) { const int n = (lane >> 3) + 8 * j; const LAS float* s = scr + (8 * kc) * 65 + n;
;         v4u o; o[0] = cvt_pk_bf16(wrnd(s[0 * 65]), wrnd(s[1 * 65])); o[1] = cvt_pk_bf16(wrnd(s[2 * 65]), wrnd(s[3 * 65])); o[2] = cvt_pk_bf16(wrnd(s[4 * 65]), wrnd(s[5 * 65])); o[3] = cvt_pk_bf16(wrnd(s[6 * 65]), wrnd(s[7 * 65]));
;         *(v4u*)(WT + (BLOCKED ? pg8::blocked_off(nrow0 + n, k0 + 8 * kc, K) : (size_t)(nrow0 + n) * ldo + k0 + 8 * kc)) = o; }
;     LDS_WAIT(); asm volatile("" ::: "memory");
	ds_write2_b32 v4, v30, v31 offset1:1
	v_add_u32_e32 v4, 0x38e8, v50
	ds_write2_b32 v4, v32, v33 offset1:1
	v_add_u32_e32 v4, 0x3cf0, v50
	s_waitcnt vmcnt(0)
	ds_write2_b32 v4, v0, v1 offset1:1
	v_add_u32_e32 v0, 0x3cf8, v50
	ds_write2_b32 v0, v2, v3 offset1:1
	s_waitcnt lgkmcnt(0)
	ds_read2_b32 v[8:9], v55 offset1:8
	ds_read2_b32 v[10:11], v55 offset0:65 offset1:73
	ds_read2_b32 v[12:13], v55 offset0:130 offset1:138
	ds_read2_b32 v[14:15], v55 offset0:195 offset1:203
	v_lshl_add_u64 v[0:1], s[6:7], 1, v[44:45]
	s_waitcnt lgkmcnt(3)
	v_add_u32_e32 v2, 0x20000, v8
	s_waitcnt lgkmcnt(2)
	v_add_u32_e32 v3, 0x20000, v10
	v_and_b32_e32 v2, 0xfffc0000, v2
	v_and_b32_e32 v3, 0xfffc0000, v3
	v_cvt_pk_bf16_f32 v4, v2, v3
	s_waitcnt lgkmcnt(1)
	v_add_u32_e32 v2, 0x20000, v12
	s_waitcnt lgkmcnt(0)
	v_add_u32_e32 v3, 0x20000, v14
	v_and_b32_e32 v2, 0xfffc0000, v2
	v_and_b32_e32 v3, 0xfffc0000, v3
	v_cvt_pk_bf16_f32 v5, v2, v3
	v_add_u32_e32 v2, 0x400, v55
	ds_read2_b32 v[18:19], v2 offset0:4 offset1:12
	ds_read2_b32 v[20:21], v2 offset0:69 offset1:77
	ds_read2_b32 v[22:23], v2 offset0:134 offset1:142
	ds_read2_b32 v[24:25], v2 offset0:199 offset1:207
	s_waitcnt lgkmcnt(3)
	v_add_u32_e32 v3, 0x20000, v18
	s_waitcnt lgkmcnt(2)
	v_add_u32_e32 v6, 0x20000, v20
	v_and_b32_e32 v3, 0xfffc0000, v3
	v_and_b32_e32 v6, 0xfffc0000, v6
	v_cvt_pk_bf16_f32 v6, v3, v6
	s_waitcnt lgkmcnt(1)
	v_add_u32_e32 v3, 0x20000, v22
	s_waitcnt lgkmcnt(0)
	v_add_u32_e32 v7, 0x20000, v24
	v_and_b32_e32 v3, 0xfffc0000, v3
	v_and_b32_e32 v7, 0xfffc0000, v7
	v_cvt_pk_bf16_f32 v7, v3, v7
	v_add_u32_e32 v3, s0, v63
	v_add_u32_e32 v26, 0xb4000, v3
	v_ashrrev_i32_e32 v27, 31, v26
	v_lshlrev_b64 v[26:27], 13, v[26:27]
	v_lshl_add_u64 v[26:27], v[0:1], 0, v[26:27]
	global_store_dwordx4 v[26:27], v[4:7], off
	v_add_u32_e32 v8, 0x20000, v25
	v_and_b32_e32 v8, 0xfffc0000, v8
	v_add_u32_e32 v4, 0x20000, v9
	v_add_u32_e32 v5, 0x20000, v11
	v_and_b32_e32 v4, 0xfffc0000, v4
	v_and_b32_e32 v5, 0xfffc0000, v5
	v_cvt_pk_bf16_f32 v4, v4, v5
	v_add_u32_e32 v5, 0x20000, v13
	v_add_u32_e32 v6, 0x20000, v15
	v_and_b32_e32 v5, 0xfffc0000, v5
	v_and_b32_e32 v6, 0xfffc0000, v6
	v_cvt_pk_bf16_f32 v5, v5, v6
	v_add_u32_e32 v6, 0x20000, v19
	v_add_u32_e32 v7, 0x20000, v21
	v_and_b32_e32 v6, 0xfffc0000, v6
	v_and_b32_e32 v7, 0xfffc0000, v7
	v_cvt_pk_bf16_f32 v6, v6, v7
	v_add_u32_e32 v7, 0x20000, v23
	v_and_b32_e32 v7, 0xfffc0000, v7
	v_cvt_pk_bf16_f32 v7, v7, v8
	v_add_u32_e32 v8, 0xb4008, v3
	v_ashrrev_i32_e32 v9, 31, v8
	v_lshlrev_b64 v[8:9], 13, v[8:9]
	v_lshl_add_u64 v[8:9], v[0:1], 0, v[8:9]
	global_store_dwordx4 v[8:9], v[4:7], off
	ds_read2_b32 v[8:9], v55 offset0:16 offset1:24
	ds_read2_b32 v[10:11], v55 offset0:81 offset1:89
	ds_read2_b32 v[12:13], v55 offset0:146 offset1:154
	ds_read2_b32 v[14:15], v55 offset0:211 offset1:219
	ds_read2_b32 v[18:19], v2 offset0:20 offset1:28
	ds_read2_b32 v[20:21], v2 offset0:85 offset1:93
	s_waitcnt lgkmcnt(5)
	v_add_u32_e32 v4, 0x20000, v8
	s_waitcnt lgkmcnt(4)
	v_add_u32_e32 v5, 0x20000, v10
	v_and_b32_e32 v4, 0xfffc0000, v4
	v_and_b32_e32 v5, 0xfffc0000, v5
	ds_read2_b32 v[22:23], v2 offset0:150 offset1:158
	ds_read2_b32 v[24:25], v2 offset0:215 offset1:223
	v_cvt_pk_bf16_f32 v4, v4, v5
	s_waitcnt lgkmcnt(5)
	v_add_u32_e32 v5, 0x20000, v12
	s_waitcnt lgkmcnt(4)
	v_add_u32_e32 v6, 0x20000, v14
	v_and_b32_e32 v5, 0xfffc0000, v5
	v_and_b32_e32 v6, 0xfffc0000, v6
	v_cvt_pk_bf16_f32 v5, v5, v6
	s_waitcnt lgkmcnt(3)
	v_add_u32_e32 v6, 0x20000, v18
	s_waitcnt lgkmcnt(2)
	v_add_u32_e32 v7, 0x20000, v20
	v_and_b32_e32 v6, 0xfffc0000, v6
	v_and_b32_e32 v7, 0xfffc0000, v7
	v_add_u32_e32 v26, 0xb4010, v3
	v_cvt_pk_bf16_f32 v6, v6, v7
	s_waitcnt lgkmcnt(1)
	v_add_u32_e32 v7, 0x20000, v22
	s_waitcnt lgkmcnt(0)
	v_add_u32_e32 v8, 0x20000, v24
	v_ashrrev_i32_e32 v27, 31, v26
	v_and_b32_e32 v7, 0xfffc0000, v7
	v_and_b32_e32 v8, 0xfffc0000, v8
	v_lshlrev_b64 v[26:27], 13, v[26:27]
	v_cvt_pk_bf16_f32 v7, v7, v8
	v_lshl_add_u64 v[26:27], v[0:1], 0, v[26:27]
	global_store_dwordx4 v[26:27], v[4:7], off
	v_add_u32_e32 v8, 0x20000, v25
	v_and_b32_e32 v8, 0xfffc0000, v8
	v_add_u32_e32 v4, 0x20000, v9
	v_add_u32_e32 v5, 0x20000, v11
	v_and_b32_e32 v4, 0xfffc0000, v4
	v_and_b32_e32 v5, 0xfffc0000, v5
	v_cvt_pk_bf16_f32 v4, v4, v5
	v_add_u32_e32 v5, 0x20000, v13
	v_add_u32_e32 v6, 0x20000, v15
	v_and_b32_e32 v5, 0xfffc0000, v5
	v_and_b32_e32 v6, 0xfffc0000, v6
	v_cvt_pk_bf16_f32 v5, v5, v6
	v_add_u32_e32 v6, 0x20000, v19
	v_add_u32_e32 v7, 0x20000, v21
	v_and_b32_e32 v6, 0xfffc0000, v6
	v_and_b32_e32 v7, 0xfffc0000, v7
	v_cvt_pk_bf16_f32 v6, v6, v7
	v_add_u32_e32 v7, 0x20000, v23
	v_and_b32_e32 v7, 0xfffc0000, v7
	v_cvt_pk_bf16_f32 v7, v7, v8
	v_add_u32_e32 v8, 0xb4018, v3
	v_ashrrev_i32_e32 v9, 31, v8
	v_lshlrev_b64 v[8:9], 13, v[8:9]
	v_lshl_add_u64 v[8:9], v[0:1], 0, v[8:9]
	global_store_dwordx4 v[8:9], v[4:7], off
	ds_read2_b32 v[8:9], v55 offset0:32 offset1:40
	ds_read2_b32 v[10:11], v55 offset0:97 offset1:105
	ds_read2_b32 v[12:13], v55 offset0:162 offset1:170
	ds_read2_b32 v[14:15], v55 offset0:227 offset1:235
	ds_read2_b32 v[18:19], v2 offset0:36 offset1:44
	ds_read2_b32 v[20:21], v2 offset0:101 offset1:109
	s_waitcnt lgkmcnt(5)
; __host__ __device__ __forceinline__ size_t blocked_off(int row, int col, int K) { return (((size_t)(row >> 8) * (K >> 6) + (col >> 6)) * 256 + (row & 255)) * 64 + (col & 63); }
; __device__ __forceinline__ unsigned cvt_pk_bf16(float lo, float hi) { const f32x2c_t v = {lo, hi}; return __builtin_bit_cast(unsigned, __builtin_convertvector(v, bf16x2c_t)); }
; #define LAS __attribute__((address_space(3)))
; #define LDS_WAIT() asm volatile("s_waitcnt lgkmcnt(0)" ::: "memory")
; __host__ __device__ __forceinline__ int win_phys_col(int n) { if (!win_rope_tile(n >> 8)) return n; const int cl = n & 255; return (n & ~255) | (cl & 63) | ((cl & 64) << 1) | ((cl & 128) >> 1); }
; template <bool PERMUTE, bool BLOCKED = false>
; __device__ __forceinline__ void cvt_tile64(const float* W, int K, int N, bf16* WT, int ldo, const float* gk, LAS float* scr, int tile, int lane) {
;     ...
;     const int kc = lane & 7, nrow0 = PERMUTE ? win_phys_col(n0) : n0;
; #pragma unroll
;     for (int j = 0; j < 8; ++j) { const int n = (lane >> 3) + 8 * j; const LAS float* s = scr + (8 * kc) * 65 + n;
;         v4u o; o[0] = cvt_pk_bf16(wrnd(s[0 * 65]), wrnd(s[1 * 65])); o[1] = cvt_pk_bf16(wrnd(s[2 * 65]), wrnd(s[3 * 65])); o[2] = cvt_pk_bf16(wrnd(s[4 * 65]), wrnd(s[5 * 65])); o[3] = cvt_pk_bf16(wrnd(s[6 * 65]), wrnd(s[7 * 65]));
;         *(v4u*)(WT + (BLOCKED ? pg8::blocked_off(nrow0 + n, k0 + 8 * kc, K) : (size_t)(nrow0 + n) * ldo + k0 + 8 * kc)) = o; }
;     LDS_WAIT(); asm volatile("" ::: "memory");
	v_add_u32_e32 v4, 0x20000, v8
	s_waitcnt lgkmcnt(4)
	v_add_u32_e32 v5, 0x20000, v10
	v_and_b32_e32 v4, 0xfffc0000, v4
	v_and_b32_e32 v5, 0xfffc0000, v5
	ds_read2_b32 v[22:23], v2 offset0:166 offset1:174
	ds_read2_b32 v[24:25], v2 offset0:231 offset1:239
	v_cvt_pk_bf16_f32 v4, v4, v5
	s_waitcnt lgkmcnt(5)
	v_add_u32_e32 v5, 0x20000, v12
	s_waitcnt lgkmcnt(4)
	v_add_u32_e32 v6, 0x20000, v14
	v_and_b32_e32 v5, 0xfffc0000, v5
	v_and_b32_e32 v6, 0xfffc0000, v6
	v_cvt_pk_bf16_f32 v5, v5, v6
	s_waitcnt lgkmcnt(3)
	v_add_u32_e32 v6, 0x20000, v18
	s_waitcnt lgkmcnt(2)
	v_add_u32_e32 v7, 0x20000, v20
	v_and_b32_e32 v6, 0xfffc0000, v6
	v_and_b32_e32 v7, 0xfffc0000, v7
	v_add_u32_e32 v26, 0xb4020, v3
	v_cvt_pk_bf16_f32 v6, v6, v7
	s_waitcnt lgkmcnt(1)
	v_add_u32_e32 v7, 0x20000, v22
	s_waitcnt lgkmcnt(0)
	v_add_u32_e32 v8, 0x20000, v24
	v_ashrrev_i32_e32 v27, 31, v26
	v_and_b32_e32 v7, 0xfffc0000, v7
	v_and_b32_e32 v8, 0xfffc0000, v8
	v_lshlrev_b64 v[26:27], 13, v[26:27]
	v_cvt_pk_bf16_f32 v7, v7, v8
	v_lshl_add_u64 v[26:27], v[0:1], 0, v[26:27]
	global_store_dwordx4 v[26:27], v[4:7], off
	v_add_u32_e32 v8, 0x20000, v25
	v_and_b32_e32 v8, 0xfffc0000, v8
	v_add_u32_e32 v4, 0x20000, v9
	v_add_u32_e32 v5, 0x20000, v11
	v_and_b32_e32 v4, 0xfffc0000, v4
	v_and_b32_e32 v5, 0xfffc0000, v5
	v_cvt_pk_bf16_f32 v4, v4, v5
	v_add_u32_e32 v5, 0x20000, v13
	v_add_u32_e32 v6, 0x20000, v15
	v_and_b32_e32 v5, 0xfffc0000, v5
	v_and_b32_e32 v6, 0xfffc0000, v6
	v_cvt_pk_bf16_f32 v5, v5, v6
	v_add_u32_e32 v6, 0x20000, v19
	v_add_u32_e32 v7, 0x20000, v21
	v_and_b32_e32 v6, 0xfffc0000, v6
	v_and_b32_e32 v7, 0xfffc0000, v7
	v_cvt_pk_bf16_f32 v6, v6, v7
	v_add_u32_e32 v7, 0x20000, v23
	v_and_b32_e32 v7, 0xfffc0000, v7
	v_cvt_pk_bf16_f32 v7, v7, v8
	v_add_u32_e32 v8, 0xb4028, v3
	v_ashrrev_i32_e32 v9, 31, v8
	v_lshlrev_b64 v[8:9], 13, v[8:9]
	v_lshl_add_u64 v[8:9], v[0:1], 0, v[8:9]
	global_store_dwordx4 v[8:9], v[4:7], off
	ds_read2_b32 v[8:9], v55 offset0:48 offset1:56
	ds_read2_b32 v[10:11], v55 offset0:113 offset1:121
	ds_read2_b32 v[12:13], v55 offset0:178 offset1:186
	ds_read2_b32 v[14:15], v55 offset0:243 offset1:251
	ds_read2_b32 v[18:19], v2 offset0:52 offset1:60
	ds_read2_b32 v[20:21], v2 offset0:117 offset1:125
	s_waitcnt lgkmcnt(5)
	v_add_u32_e32 v4, 0x20000, v8
	s_waitcnt lgkmcnt(4)
	v_add_u32_e32 v5, 0x20000, v10
	v_and_b32_e32 v4, 0xfffc0000, v4
	v_and_b32_e32 v5, 0xfffc0000, v5
	ds_read2_b32 v[22:23], v2 offset0:182 offset1:190
	ds_read2_b32 v[24:25], v2 offset0:247 offset1:255
	v_cvt_pk_bf16_f32 v4, v4, v5
	s_waitcnt lgkmcnt(5)
	v_add_u32_e32 v5, 0x20000, v12
	s_waitcnt lgkmcnt(4)
	v_add_u32_e32 v6, 0x20000, v14
	v_and_b32_e32 v5, 0xfffc0000, v5
	v_and_b32_e32 v6, 0xfffc0000, v6
	v_cvt_pk_bf16_f32 v5, v5, v6
	s_waitcnt lgkmcnt(3)
	v_add_u32_e32 v6, 0x20000, v18
	s_waitcnt lgkmcnt(2)
	v_add_u32_e32 v7, 0x20000, v20
	v_and_b32_e32 v6, 0xfffc0000, v6
	v_and_b32_e32 v7, 0xfffc0000, v7
	v_add_u32_e32 v26, 0xb4030, v3
	v_cvt_pk_bf16_f32 v6, v6, v7
	s_waitcnt lgkmcnt(1)
	v_add_u32_e32 v7, 0x20000, v22
	s_waitcnt lgkmcnt(0)
	v_add_u32_e32 v2, 0x20000, v24
	v_ashrrev_i32_e32 v27, 31, v26
	v_and_b32_e32 v7, 0xfffc0000, v7
	v_and_b32_e32 v2, 0xfffc0000, v2
	v_lshlrev_b64 v[26:27], 13, v[26:27]
	v_cvt_pk_bf16_f32 v7, v7, v2
	v_lshl_add_u64 v[26:27], v[0:1], 0, v[26:27]
	global_store_dwordx4 v[26:27], v[4:7], off
	v_add_u32_e32 v2, 0x20000, v9
	v_and_b32_e32 v2, 0xfffc0000, v2
	v_add_u32_e32 v4, 0x20000, v11
	v_and_b32_e32 v4, 0xfffc0000, v4
	v_cvt_pk_bf16_f32 v4, v2, v4
	v_add_u32_e32 v2, 0x20000, v13
	v_add_u32_e32 v5, 0x20000, v15
	v_and_b32_e32 v2, 0xfffc0000, v2
	v_and_b32_e32 v5, 0xfffc0000, v5
	v_cvt_pk_bf16_f32 v5, v2, v5
	v_add_u32_e32 v2, 0x20000, v19
	v_add_u32_e32 v6, 0x20000, v21
	v_and_b32_e32 v2, 0xfffc0000, v2
	v_and_b32_e32 v6, 0xfffc0000, v6
	v_cvt_pk_bf16_f32 v6, v2, v6
	v_add_u32_e32 v2, 0x20000, v23
	v_add_u32_e32 v7, 0x20000, v25
	v_and_b32_e32 v2, 0xfffc0000, v2
	v_and_b32_e32 v7, 0xfffc0000, v7
	v_cvt_pk_bf16_f32 v7, v2, v7
	v_add_u32_e32 v2, 0xb4038, v3
	v_ashrrev_i32_e32 v3, 31, v2
	v_lshlrev_b64 v[2:3], 13, v[2:3]
	v_lshl_add_u64 v[0:1], v[0:1], 0, v[2:3]
	global_store_dwordx4 v[0:1], v[4:7], off
	s_waitcnt lgkmcnt(0)
	s_branch .LBB0_520

; #define LAS __attribute__((address_space(3)))
; template <bool PERMUTE, bool BLOCKED = false>
; __device__ __forceinline__ void cvt_tile64(const float* W, int K, int N, bf16* WT, int ldo, const float* gk, LAS float* scr, int tile, int lane) {
;     ...
;     for (int hh = 0; hh < 2; ++hh) {
;         f32x4 v[8];
; #pragma unroll
;         for (int i = 0; i < 8; ++i) v[i] = *(const f32x4*)(W + (size_t)(k0 + 32 * hh + 4 * i + lk) * N + n0 + ln);
; #pragma unroll
;         for (int i = 0; i < 8; ++i) { const int kk = 32 * hh + 4 * i + lk; const float g = gk ? gk[k0 + kk] : 1.0f; LAS float* d = scr + kk * 65 + ln;
;             d[0] = v[i][0] * g; d[1] = v[i][1] * g; d[2] = v[i][2] * g; d[3] = v[i][3] * g; }
;     }
; __device__ __forceinline__ void cvt_item(const CvtCtx& c, int batch, int wi, LAS float* scr, int wave, int lane) {
;     const int l = batch;
;     if (wi < CVT_OUT) { cvt_tile64<false>(c.w_out + (size_t)l * DM * DM, DM, DM, c.WoutT + (size_t)l * DM * DM, DM, nullptr, scr, 8 * wi + wave, lane); return; } wi -= CVT_OUT;
;     if (wi < CVT_UP) { cvt_tile64<false>(c.w_up + (size_t)l * DM * DFF, DM, DFF, c.WupT + (size_t)l * DFF * DM, DM, c.g_mlp + l * DM, scr, 8 * wi + wave, lane); return; } wi -= CVT_UP;
;     if (wi < CVT_DN) { cvt_tile64<false, true>(c.w_down + (size_t)l * DFF * DM, DFF, DM, c.WdnT + (size_t)l * DM * DFF, 0, nullptr, scr, 8 * wi + wave, lane); return; } wi -= CVT_DN;
.LBB0_585:
	s_addk_i32 s17, 0x100
	s_cmpk_gt_i32 s17, 0x1ff
	s_mov_b64 s[0:1], -1
	s_cbranch_scc0 .LBB0_609
	s_cmpk_gt_u32 s17, 0x9ff
	s_cbranch_scc0 .LBB0_588
	s_add_i32 s0, s13, 0xffffb000
	s_ashr_i32 s1, s0, 31
	s_lshr_b32 s1, s1, 26
	s_add_i32 s0, s0, s1
	s_ashr_i32 s4, s0, 6
	s_add_i32 s5, s12, s16
	s_lshl_b32 s6, s4, 12
	s_andn2_b32 s0, s0, 63
	s_add_i32 s1, s5, 0xfff74000
	s_sub_i32 s5, s5, s6
	s_add_i32 s18, s5, 0xfff74000
	v_or_b32_e32 v2, s0, v16
	s_ashr_i32 s19, s18, 31
	v_ashrrev_i32_e32 v3, 31, v2
	v_lshl_add_u64 v[0:1], s[18:19], 2, v[34:35]
	v_lshlrev_b64 v[4:5], 14, v[2:3]
	v_or_b32_e32 v8, 4, v2
	v_lshl_add_u64 v[4:5], v[0:1], 0, v[4:5]
	v_ashrrev_i32_e32 v9, 31, v8
	global_load_dwordx4 v[4:7], v[4:5], off nt
	v_lshlrev_b64 v[8:9], 14, v[8:9]
	v_or_b32_e32 v12, 8, v2
	v_lshl_add_u64 v[8:9], v[0:1], 0, v[8:9]
	v_ashrrev_i32_e32 v13, 31, v12
	global_load_dwordx4 v[8:11], v[8:9], off nt
	v_lshlrev_b64 v[12:13], 14, v[12:13]
	v_or_b32_e32 v18, 12, v2
	v_lshl_add_u64 v[12:13], v[0:1], 0, v[12:13]
	v_ashrrev_i32_e32 v19, 31, v18
	global_load_dwordx4 v[12:15], v[12:13], off nt
	v_lshlrev_b64 v[18:19], 14, v[18:19]
	v_or_b32_e32 v22, 16, v2
	v_lshl_add_u64 v[18:19], v[0:1], 0, v[18:19]
	v_ashrrev_i32_e32 v23, 31, v22
	global_load_dwordx4 v[18:21], v[18:19], off nt
	v_lshlrev_b64 v[22:23], 14, v[22:23]
	v_or_b32_e32 v26, 20, v2
	v_lshl_add_u64 v[22:23], v[0:1], 0, v[22:23]
	v_ashrrev_i32_e32 v27, 31, v26
	global_load_dwordx4 v[22:25], v[22:23], off nt
	v_lshlrev_b64 v[26:27], 14, v[26:27]
	v_or_b32_e32 v30, 24, v2
	v_lshl_add_u64 v[26:27], v[0:1], 0, v[26:27]
	v_ashrrev_i32_e32 v31, 31, v30
	global_load_dwordx4 v[26:29], v[26:27], off nt
	v_lshlrev_b64 v[30:31], 14, v[30:31]
	v_or_b32_e32 v46, 28, v2
	v_lshl_add_u64 v[30:31], v[0:1], 0, v[30:31]
	v_ashrrev_i32_e32 v47, 31, v46
	global_load_dwordx4 v[30:33], v[30:31], off nt
	v_lshlrev_b64 v[46:47], 14, v[46:47]
	v_lshl_add_u64 v[46:47], v[0:1], 0, v[46:47]
	global_load_dwordx4 v[46:49], v[46:47], off nt
	v_add_u32_e32 v50, v51, v53
	v_add_u32_e32 v3, 0x410, v50
	s_ashr_i32 s6, s18, 8
	s_ashr_i32 s7, s6, 31
	s_ashr_i32 s5, s4, 31
	s_lshl_b64 s[6:7], s[6:7], 16
	s_lshl_b64 s[4:5], s[4:5], 8
	s_add_u32 s0, s6, s4
	s_addc_u32 s4, s7, s5
	s_and_b32 s1, s1, 0xc0
	s_waitcnt vmcnt(7)
	ds_write2_b32 v50, v4, v5 offset1:1
	ds_write2_b32 v50, v6, v7 offset0:2 offset1:3
	v_or_b32_e32 v4, 32, v2
	v_ashrrev_i32_e32 v5, 31, v4
	v_lshlrev_b64 v[4:5], 14, v[4:5]
	v_lshl_add_u64 v[4:5], v[0:1], 0, v[4:5]
	s_waitcnt vmcnt(6)
	ds_write2_b32 v3, v8, v9 offset1:1
	v_add_u32_e32 v3, 0x418, v50
	v_or_b32_e32 v8, 36, v2
	ds_write2_b32 v3, v10, v11 offset1:1
	v_add_u32_e32 v3, 0x820, v50
	v_ashrrev_i32_e32 v9, 31, v8
	s_waitcnt vmcnt(5)
	ds_write2_b32 v3, v12, v13 offset1:1
	v_add_u32_e32 v3, 0x828, v50
	global_load_dwordx4 v[4:7], v[4:5], off nt
	v_lshlrev_b64 v[8:9], 14, v[8:9]
	v_or_b32_e32 v12, 40, v2
	ds_write2_b32 v3, v14, v15 offset1:1
	v_add_u32_e32 v3, 0xc30, v50
	v_lshl_add_u64 v[8:9], v[0:1], 0, v[8:9]
	v_ashrrev_i32_e32 v13, 31, v12
	s_waitcnt vmcnt(5)
	ds_write2_b32 v3, v18, v19 offset1:1
	v_add_u32_e32 v3, 0xc38, v50
	global_load_dwordx4 v[8:11], v[8:9], off nt
	v_lshlrev_b64 v[12:13], 14, v[12:13]
	v_or_b32_e32 v18, 44, v2
	ds_write2_b32 v3, v20, v21 offset1:1
	v_add_u32_e32 v3, 0x1040, v50
	v_lshl_add_u64 v[12:13], v[0:1], 0, v[12:13]
	v_ashrrev_i32_e32 v19, 31, v18
	s_waitcnt vmcnt(5)
	ds_write2_b32 v3, v22, v23 offset1:1
	v_add_u32_e32 v3, 0x1048, v50
	global_load_dwordx4 v[12:15], v[12:13], off nt
	v_lshlrev_b64 v[18:19], 14, v[18:19]
	v_or_b32_e32 v22, 48, v2
	ds_write2_b32 v3, v24, v25 offset1:1
	v_add_u32_e32 v3, 0x1450, v50
	v_lshl_add_u64 v[18:19], v[0:1], 0, v[18:19]
	v_ashrrev_i32_e32 v23, 31, v22
	s_waitcnt vmcnt(5)
	ds_write2_b32 v3, v26, v27 offset1:1
	v_add_u32_e32 v3, 0x1458, v50
	global_load_dwordx4 v[18:21], v[18:19], off nt
	v_lshlrev_b64 v[22:23], 14, v[22:23]
	v_or_b32_e32 v26, 52, v2
	ds_write2_b32 v3, v28, v29 offset1:1
	v_add_u32_e32 v3, 0x1860, v50
	v_lshl_add_u64 v[22:23], v[0:1], 0, v[22:23]
	v_ashrrev_i32_e32 v27, 31, v26
	s_waitcnt vmcnt(5)
	ds_write2_b32 v3, v30, v31 offset1:1
	v_add_u32_e32 v3, 0x1868, v50
	global_load_dwordx4 v[22:25], v[22:23], off nt
	v_lshlrev_b64 v[26:27], 14, v[26:27]
	v_or_b32_e32 v30, 56, v2
	ds_write2_b32 v3, v32, v33 offset1:1
	v_add_u32_e32 v3, 0x1c70, v50
	v_lshl_add_u64 v[26:27], v[0:1], 0, v[26:27]
	v_ashrrev_i32_e32 v31, 31, v30
	s_waitcnt vmcnt(5)
	ds_write2_b32 v3, v46, v47 offset1:1
	v_add_u32_e32 v3, 0x1c78, v50
	global_load_dwordx4 v[26:29], v[26:27], off nt
	v_lshlrev_b64 v[30:31], 14, v[30:31]
	v_or_b32_e32 v2, 60, v2
	ds_write2_b32 v3, v48, v49 offset1:1
	v_lshl_add_u64 v[30:31], v[0:1], 0, v[30:31]
	v_ashrrev_i32_e32 v3, 31, v2
	global_load_dwordx4 v[30:33], v[30:31], off nt
	v_lshlrev_b64 v[2:3], 14, v[2:3]
	v_lshl_add_u64 v[0:1], v[0:1], 0, v[2:3]
	global_load_dwordx4 v[0:3], v[0:1], off nt
	v_add_u32_e32 v46, 0x2080, v50
	s_waitcnt vmcnt(7)
	ds_write2_b32 v46, v4, v5 offset1:1
	v_add_u32_e32 v4, 0x2088, v50
	ds_write2_b32 v4, v6, v7 offset1:1
	v_add_u32_e32 v4, 0x2490, v50
	s_waitcnt vmcnt(6)
	ds_write2_b32 v4, v8, v9 offset1:1
	v_add_u32_e32 v4, 0x2498, v50
	ds_write2_b32 v4, v10, v11 offset1:1
	v_add_u32_e32 v4, 0x28a0, v50
	s_waitcnt vmcnt(5)
	ds_write2_b32 v4, v12, v13 offset1:1
	v_add_u32_e32 v4, 0x28a8, v50
	ds_write2_b32 v4, v14, v15 offset1:1
	v_add_u32_e32 v4, 0x2cb0, v50
	s_waitcnt vmcnt(4)
	ds_write2_b32 v4, v18, v19 offset1:1
	v_add_u32_e32 v4, 0x2cb8, v50
	ds_write2_b32 v4, v20, v21 offset1:1
	v_add_u32_e32 v4, 0x30c0, v50
	s_waitcnt vmcnt(3)
; __host__ __device__ __forceinline__ size_t blocked_off(int row, int col, int K) { return (((size_t)(row >> 8) * (K >> 6) + (col >> 6)) * 256 + (row & 255)) * 64 + (col & 63); }
; __device__ __forceinline__ unsigned cvt_pk_bf16(float lo, float hi) { const f32x2c_t v = {lo, hi}; return __builtin_bit_cast(unsigned, __builtin_convertvector(v, bf16x2c_t)); }
; #define LAS __attribute__((address_space(3)))
; #define LDS_WAIT() asm volatile("s_waitcnt lgkmcnt(0)" ::: "memory")
; __host__ __device__ __forceinline__ int win_phys_col(int n) { if (!win_rope_tile(n >> 8)) return n; const int cl = n & 255; return (n & ~255) | (cl & 63) | ((cl & 64) << 1) | ((cl & 128) >> 1); }
; template <bool PERMUTE, bool BLOCKED = false>
; __device__ __forceinline__ void cvt_tile64(const float* W, int K, int N, bf16* WT, int ldo, const float* gk, LAS float* scr, int tile, int lane) {
;     ...
;     LDS_WAIT(); asm volatile("" ::: "memory");
;     const int kc = lane & 7, nrow0 = PERMUTE ? win_phys_col(n0) : n0;
; #pragma unroll
;     for (int j = 0; j < 8; ++j) { const int n = (lane >> 3) + 8 * j; const LAS float* s = scr + (8 * kc) * 65 + n;
;         v4u o; o[0] = cvt_pk_bf16(wrnd(s[0 * 65]), wrnd(s[1 * 65])); o[1] = cvt_pk_bf16(wrnd(s[2 * 65]), wrnd(s[3 * 65])); o[2] = cvt_pk_bf16(wrnd(s[4 * 65]), wrnd(s[5 * 65])); o[3] = cvt_pk_bf16(wrnd(s[6 * 65]), wrnd(s[7 * 65]));
;         *(v4u*)(WT + (BLOCKED ? pg8::blocked_off(nrow0 + n, k0 + 8 * kc, K) : (size_t)(nrow0 + n) * ldo + k0 + 8 * kc)) = o; }
	ds_write2_b32 v4, v22, v23 offset1:1
	v_add_u32_e32 v4, 0x30c8, v50
	ds_write2_b32 v4, v24, v25 offset1:1
	v_add_u32_e32 v4, 0x34d0, v50
	s_waitcnt vmcnt(2)
	ds_write2_b32 v4, v26, v27 offset1:1
	v_add_u32_e32 v4, 0x34d8, v50
	ds_write2_b32 v4, v28, v29 offset1:1
	v_add_u32_e32 v4, 0x38e0, v50
	s_waitcnt vmcnt(1)
	ds_write2_b32 v4, v30, v31 offset1:1
	v_add_u32_e32 v4, 0x38e8, v50
	ds_write2_b32 v4, v32, v33 offset1:1
	v_add_u32_e32 v4, 0x3cf0, v50
	s_waitcnt vmcnt(0)
	ds_write2_b32 v4, v0, v1 offset1:1
	v_add_u32_e32 v0, 0x3cf8, v50
	ds_write2_b32 v0, v2, v3 offset1:1
	s_waitcnt lgkmcnt(0)
	ds_read2_b32 v[2:3], v55 offset1:8
	ds_read2_b32 v[8:9], v55 offset0:65 offset1:73
	ds_read2_b32 v[10:11], v55 offset0:130 offset1:138
	ds_read2_b32 v[12:13], v55 offset0:195 offset1:203
	s_waitcnt lgkmcnt(3)
	v_add_u32_e32 v0, 0x20000, v2
	v_add_u32_e32 v2, 0x400, v55
	ds_read2_b32 v[14:15], v2 offset0:4 offset1:12
	ds_read2_b32 v[18:19], v2 offset0:69 offset1:77
	s_waitcnt lgkmcnt(4)
	v_add_u32_e32 v1, 0x20000, v8
	v_and_b32_e32 v0, 0xfffc0000, v0
	v_and_b32_e32 v1, 0xfffc0000, v1
	ds_read2_b32 v[20:21], v2 offset0:134 offset1:142
	ds_read2_b32 v[22:23], v2 offset0:199 offset1:207
	v_cvt_pk_bf16_f32 v4, v0, v1
	s_waitcnt lgkmcnt(5)
	v_add_u32_e32 v0, 0x20000, v10
	s_waitcnt lgkmcnt(4)
	v_add_u32_e32 v1, 0x20000, v12
	v_and_b32_e32 v0, 0xfffc0000, v0
	v_and_b32_e32 v1, 0xfffc0000, v1
	v_cvt_pk_bf16_f32 v5, v0, v1
	s_waitcnt lgkmcnt(3)
	v_add_u32_e32 v0, 0x20000, v14
	s_waitcnt lgkmcnt(2)
	v_add_u32_e32 v1, 0x20000, v18
	v_and_b32_e32 v0, 0xfffc0000, v0
	v_and_b32_e32 v1, 0xfffc0000, v1
	v_cvt_pk_bf16_f32 v6, v0, v1
	s_waitcnt lgkmcnt(1)
	v_add_u32_e32 v0, 0x20000, v20
	s_waitcnt lgkmcnt(0)
	v_add_u32_e32 v1, 0x20000, v22
	v_and_b32_e32 v0, 0xfffc0000, v0
	v_and_b32_e32 v1, 0xfffc0000, v1
	v_cvt_pk_bf16_f32 v7, v0, v1
	v_or_b32_e32 v0, s1, v54
	v_or_b32_e32 v0, s0, v0
	v_mov_b32_e32 v1, s4
	v_lshlrev_b64 v[24:25], 7, v[0:1]
	v_add_u32_e32 v0, 0x20000, v3
	v_add_u32_e32 v3, 0x20000, v9
	v_lshl_add_u64 v[24:25], v[36:37], 0, v[24:25]
	v_and_b32_e32 v0, 0xfffc0000, v0
	v_and_b32_e32 v3, 0xfffc0000, v3
	global_store_dwordx4 v[24:25], v[4:7], off
	ds_read2_b32 v[24:25], v2 offset0:215 offset1:223
	s_nop 0
	v_cvt_pk_bf16_f32 v4, v0, v3
	v_add_u32_e32 v0, 0x20000, v11
	v_add_u32_e32 v3, 0x20000, v13
	v_and_b32_e32 v0, 0xfffc0000, v0
	v_and_b32_e32 v3, 0xfffc0000, v3
	v_cvt_pk_bf16_f32 v5, v0, v3
	v_add_u32_e32 v0, 0x20000, v15
	v_add_u32_e32 v3, 0x20000, v19
	v_and_b32_e32 v0, 0xfffc0000, v0
	v_and_b32_e32 v3, 0xfffc0000, v3
	v_cvt_pk_bf16_f32 v6, v0, v3
	v_add_u32_e32 v0, 0x20000, v21
	v_add_u32_e32 v3, 0x20000, v23
	v_and_b32_e32 v0, 0xfffc0000, v0
	v_and_b32_e32 v3, 0xfffc0000, v3
	v_cvt_pk_bf16_f32 v7, v0, v3
	v_or_b32_e32 v0, s1, v56
	v_or_b32_e32 v0, s0, v0
	v_lshlrev_b64 v[8:9], 7, v[0:1]
	v_lshl_add_u64 v[8:9], v[36:37], 0, v[8:9]
	global_store_dwordx4 v[8:9], v[4:7], off
	ds_read2_b32 v[8:9], v55 offset0:16 offset1:24
	ds_read2_b32 v[10:11], v55 offset0:81 offset1:89
	ds_read2_b32 v[12:13], v55 offset0:146 offset1:154
	ds_read2_b32 v[14:15], v55 offset0:211 offset1:219
	ds_read2_b32 v[18:19], v2 offset0:20 offset1:28
	ds_read2_b32 v[20:21], v2 offset0:85 offset1:93
	s_waitcnt lgkmcnt(5)
	v_add_u32_e32 v0, 0x20000, v8
	s_waitcnt lgkmcnt(4)
	v_add_u32_e32 v3, 0x20000, v10
	v_and_b32_e32 v0, 0xfffc0000, v0
	v_and_b32_e32 v3, 0xfffc0000, v3
	ds_read2_b32 v[22:23], v2 offset0:150 offset1:158
	v_cvt_pk_bf16_f32 v4, v0, v3
	s_waitcnt lgkmcnt(4)
	v_add_u32_e32 v0, 0x20000, v12
	s_waitcnt lgkmcnt(3)
	v_add_u32_e32 v3, 0x20000, v14
	v_and_b32_e32 v0, 0xfffc0000, v0
	v_and_b32_e32 v3, 0xfffc0000, v3
	v_cvt_pk_bf16_f32 v5, v0, v3
	s_waitcnt lgkmcnt(2)
	v_add_u32_e32 v0, 0x20000, v18
	s_waitcnt lgkmcnt(1)
	v_add_u32_e32 v3, 0x20000, v20
	v_and_b32_e32 v0, 0xfffc0000, v0
	v_and_b32_e32 v3, 0xfffc0000, v3
	v_cvt_pk_bf16_f32 v6, v0, v3
	s_waitcnt lgkmcnt(0)
	v_add_u32_e32 v0, 0x20000, v22
	v_add_u32_e32 v3, 0x20000, v24
	v_and_b32_e32 v0, 0xfffc0000, v0
	v_and_b32_e32 v3, 0xfffc0000, v3
	v_cvt_pk_bf16_f32 v7, v0, v3
	v_or_b32_e32 v0, s1, v57
	v_or_b32_e32 v0, s0, v0
	v_lshlrev_b64 v[26:27], 7, v[0:1]
	v_add_u32_e32 v0, 0x20000, v9
	v_add_u32_e32 v3, 0x20000, v11
	v_lshl_add_u64 v[26:27], v[36:37], 0, v[26:27]
	v_and_b32_e32 v0, 0xfffc0000, v0
	v_and_b32_e32 v3, 0xfffc0000, v3
	global_store_dwordx4 v[26:27], v[4:7], off
	ds_read2_b32 v[10:11], v55 offset0:97 offset1:105
	s_nop 0
	v_cvt_pk_bf16_f32 v4, v0, v3
	v_add_u32_e32 v0, 0x20000, v13
	v_add_u32_e32 v3, 0x20000, v15
	v_and_b32_e32 v0, 0xfffc0000, v0
	v_and_b32_e32 v3, 0xfffc0000, v3
	v_cvt_pk_bf16_f32 v5, v0, v3
	v_add_u32_e32 v0, 0x20000, v19
	v_add_u32_e32 v3, 0x20000, v21
	v_and_b32_e32 v0, 0xfffc0000, v0
	v_and_b32_e32 v3, 0xfffc0000, v3
	v_cvt_pk_bf16_f32 v6, v0, v3
	v_add_u32_e32 v0, 0x20000, v23
	v_add_u32_e32 v3, 0x20000, v25
	v_and_b32_e32 v0, 0xfffc0000, v0
	v_and_b32_e32 v3, 0xfffc0000, v3
	v_cvt_pk_bf16_f32 v7, v0, v3
	v_or_b32_e32 v0, s1, v58
	v_or_b32_e32 v0, s0, v0
	v_lshlrev_b64 v[8:9], 7, v[0:1]
	v_lshl_add_u64 v[8:9], v[36:37], 0, v[8:9]
	global_store_dwordx4 v[8:9], v[4:7], off
	ds_read2_b32 v[8:9], v55 offset0:32 offset1:40
	ds_read2_b32 v[12:13], v55 offset0:162 offset1:170
	ds_read2_b32 v[14:15], v55 offset0:227 offset1:235
	ds_read2_b32 v[18:19], v2 offset0:36 offset1:44
	ds_read2_b32 v[20:21], v2 offset0:101 offset1:109
	s_waitcnt lgkmcnt(4)
	v_add_u32_e32 v0, 0x20000, v8
	v_add_u32_e32 v3, 0x20000, v10
	v_and_b32_e32 v0, 0xfffc0000, v0
	v_and_b32_e32 v3, 0xfffc0000, v3
	ds_read2_b32 v[22:23], v2 offset0:166 offset1:174
	ds_read2_b32 v[24:25], v2 offset0:231 offset1:239
	v_cvt_pk_bf16_f32 v4, v0, v3
	s_waitcnt lgkmcnt(5)
; __host__ __device__ __forceinline__ size_t blocked_off(int row, int col, int K) { return (((size_t)(row >> 8) * (K >> 6) + (col >> 6)) * 256 + (row & 255)) * 64 + (col & 63); }
; __device__ __forceinline__ unsigned cvt_pk_bf16(float lo, float hi) { const f32x2c_t v = {lo, hi}; return __builtin_bit_cast(unsigned, __builtin_convertvector(v, bf16x2c_t)); }
; #define LAS __attribute__((address_space(3)))
; #define LDS_WAIT() asm volatile("s_waitcnt lgkmcnt(0)" ::: "memory")
; __host__ __device__ __forceinline__ int win_phys_col(int n) { if (!win_rope_tile(n >> 8)) return n; const int cl = n & 255; return (n & ~255) | (cl & 63) | ((cl & 64) << 1) | ((cl & 128) >> 1); }
; template <bool PERMUTE, bool BLOCKED = false>
; __device__ __forceinline__ void cvt_tile64(const float* W, int K, int N, bf16* WT, int ldo, const float* gk, LAS float* scr, int tile, int lane) {
;     ...
;     for (int hh = 0; hh < 2; ++hh) {
;         f32x4 v[8];
; #pragma unroll
;         for (int i = 0; i < 8; ++i) v[i] = *(const f32x4*)(W + (size_t)(k0 + 32 * hh + 4 * i + lk) * N + n0 + ln);
; #pragma unroll
;         for (int i = 0; i < 8; ++i) { const int kk = 32 * hh + 4 * i + lk; const float g = gk ? gk[k0 + kk] : 1.0f; LAS float* d = scr + kk * 65 + ln;
;             d[0] = v[i][0] * g; d[1] = v[i][1] * g; d[2] = v[i][2] * g; d[3] = v[i][3] * g; }
;     }
;     ...
;     LDS_WAIT(); asm volatile("" ::: "memory");
;     const int kc = lane & 7, nrow0 = PERMUTE ? win_phys_col(n0) : n0;
; #pragma unroll
;     for (int j = 0; j < 8; ++j) { const int n = (lane >> 3) + 8 * j; const LAS float* s = scr + (8 * kc) * 65 + n;
;         v4u o; o[0] = cvt_pk_bf16(wrnd(s[0 * 65]), wrnd(s[1 * 65])); o[1] = cvt_pk_bf16(wrnd(s[2 * 65]), wrnd(s[3 * 65])); o[2] = cvt_pk_bf16(wrnd(s[4 * 65]), wrnd(s[5 * 65])); o[3] = cvt_pk_bf16(wrnd(s[6 * 65]), wrnd(s[7 * 65]));
;         *(v4u*)(WT + (BLOCKED ? pg8::blocked_off(nrow0 + n, k0 + 8 * kc, K) : (size_t)(nrow0 + n) * ldo + k0 + 8 * kc)) = o; }
	v_add_u32_e32 v0, 0x20000, v12
	s_waitcnt lgkmcnt(4)
	v_add_u32_e32 v3, 0x20000, v14
	v_and_b32_e32 v0, 0xfffc0000, v0
	v_and_b32_e32 v3, 0xfffc0000, v3
	v_cvt_pk_bf16_f32 v5, v0, v3
	s_waitcnt lgkmcnt(3)
	v_add_u32_e32 v0, 0x20000, v18
	s_waitcnt lgkmcnt(2)
	v_add_u32_e32 v3, 0x20000, v20
	v_and_b32_e32 v0, 0xfffc0000, v0
	v_and_b32_e32 v3, 0xfffc0000, v3
	v_cvt_pk_bf16_f32 v6, v0, v3
	s_waitcnt lgkmcnt(1)
	v_add_u32_e32 v0, 0x20000, v22
	s_waitcnt lgkmcnt(0)
	v_add_u32_e32 v3, 0x20000, v24
	v_and_b32_e32 v0, 0xfffc0000, v0
	v_and_b32_e32 v3, 0xfffc0000, v3
	v_cvt_pk_bf16_f32 v7, v0, v3
	v_or_b32_e32 v0, s1, v59
	v_or_b32_e32 v0, s0, v0
	v_lshlrev_b64 v[26:27], 7, v[0:1]
	v_add_u32_e32 v0, 0x20000, v9
	v_add_u32_e32 v3, 0x20000, v11
	v_lshl_add_u64 v[26:27], v[36:37], 0, v[26:27]
	v_and_b32_e32 v0, 0xfffc0000, v0
	v_and_b32_e32 v3, 0xfffc0000, v3
	global_store_dwordx4 v[26:27], v[4:7], off
	ds_read2_b32 v[10:11], v55 offset0:113 offset1:121
	s_nop 0
	v_cvt_pk_bf16_f32 v4, v0, v3
	v_add_u32_e32 v0, 0x20000, v13
	v_add_u32_e32 v3, 0x20000, v15
	v_and_b32_e32 v0, 0xfffc0000, v0
	v_and_b32_e32 v3, 0xfffc0000, v3
	v_cvt_pk_bf16_f32 v5, v0, v3
	v_add_u32_e32 v0, 0x20000, v19
	v_add_u32_e32 v3, 0x20000, v21
	v_and_b32_e32 v0, 0xfffc0000, v0
	v_and_b32_e32 v3, 0xfffc0000, v3
	v_cvt_pk_bf16_f32 v6, v0, v3
	v_add_u32_e32 v0, 0x20000, v23
	v_add_u32_e32 v3, 0x20000, v25
	v_and_b32_e32 v0, 0xfffc0000, v0
	v_and_b32_e32 v3, 0xfffc0000, v3
	v_cvt_pk_bf16_f32 v7, v0, v3
	v_or_b32_e32 v0, s1, v60
	v_or_b32_e32 v0, s0, v0
	v_lshlrev_b64 v[8:9], 7, v[0:1]
	v_lshl_add_u64 v[8:9], v[36:37], 0, v[8:9]
	global_store_dwordx4 v[8:9], v[4:7], off
	ds_read2_b32 v[8:9], v55 offset0:48 offset1:56
	ds_read2_b32 v[12:13], v55 offset0:178 offset1:186
	ds_read2_b32 v[14:15], v55 offset0:243 offset1:251
	ds_read2_b32 v[18:19], v2 offset0:52 offset1:60
	ds_read2_b32 v[20:21], v2 offset0:117 offset1:125
	s_waitcnt lgkmcnt(4)
	v_add_u32_e32 v0, 0x20000, v8
	v_add_u32_e32 v3, 0x20000, v10
	v_and_b32_e32 v0, 0xfffc0000, v0
	v_and_b32_e32 v3, 0xfffc0000, v3
	ds_read2_b32 v[22:23], v2 offset0:182 offset1:190
	ds_read2_b32 v[24:25], v2 offset0:247 offset1:255
	v_cvt_pk_bf16_f32 v4, v0, v3
	s_waitcnt lgkmcnt(5)
	v_add_u32_e32 v0, 0x20000, v12
	s_waitcnt lgkmcnt(4)
	v_add_u32_e32 v3, 0x20000, v14
	v_and_b32_e32 v0, 0xfffc0000, v0
	v_and_b32_e32 v3, 0xfffc0000, v3
	v_cvt_pk_bf16_f32 v5, v0, v3
	s_waitcnt lgkmcnt(3)
	v_add_u32_e32 v0, 0x20000, v18
	s_waitcnt lgkmcnt(2)
	v_add_u32_e32 v3, 0x20000, v20
	v_and_b32_e32 v0, 0xfffc0000, v0
	v_and_b32_e32 v3, 0xfffc0000, v3
	v_cvt_pk_bf16_f32 v6, v0, v3
	s_waitcnt lgkmcnt(1)
	v_add_u32_e32 v0, 0x20000, v22
	s_waitcnt lgkmcnt(0)
	v_add_u32_e32 v2, 0x20000, v24
	v_and_b32_e32 v0, 0xfffc0000, v0
	v_and_b32_e32 v2, 0xfffc0000, v2
	v_cvt_pk_bf16_f32 v7, v0, v2
	v_or_b32_e32 v0, s1, v61
	v_or_b32_e32 v0, s0, v0
	v_lshlrev_b64 v[2:3], 7, v[0:1]
	v_lshl_add_u64 v[2:3], v[36:37], 0, v[2:3]
	global_store_dwordx4 v[2:3], v[4:7], off
	v_add_u32_e32 v0, 0x20000, v9
	v_add_u32_e32 v2, 0x20000, v11
	v_and_b32_e32 v0, 0xfffc0000, v0
	v_and_b32_e32 v2, 0xfffc0000, v2
	v_cvt_pk_bf16_f32 v2, v0, v2
	v_add_u32_e32 v0, 0x20000, v13
	v_add_u32_e32 v3, 0x20000, v15
	v_and_b32_e32 v0, 0xfffc0000, v0
	v_and_b32_e32 v3, 0xfffc0000, v3
	v_cvt_pk_bf16_f32 v3, v0, v3
	v_add_u32_e32 v0, 0x20000, v19
	v_add_u32_e32 v4, 0x20000, v21
	v_and_b32_e32 v0, 0xfffc0000, v0
	v_and_b32_e32 v4, 0xfffc0000, v4
	v_cvt_pk_bf16_f32 v4, v0, v4
	v_add_u32_e32 v0, 0x20000, v23
	v_add_u32_e32 v5, 0x20000, v25
	v_and_b32_e32 v0, 0xfffc0000, v0
	v_and_b32_e32 v5, 0xfffc0000, v5
	v_cvt_pk_bf16_f32 v5, v0, v5
	v_or_b32_e32 v0, s1, v62
	v_or_b32_e32 v0, s0, v0
	v_lshlrev_b64 v[0:1], 7, v[0:1]
	v_lshl_add_u64 v[0:1], v[36:37], 0, v[0:1]
	global_store_dwordx4 v[0:1], v[2:5], off
	s_waitcnt lgkmcnt(0)
	s_mov_b64 s[0:1], 0
.LBB0_588:
	s_andn2_b64 vcc, exec, s[0:1]
	s_cbranch_vccnz .LBB0_608
	s_add_i32 s0, s13, 0xfffff000
	s_ashr_i32 s1, s0, 31
	s_lshr_b32 s1, s1, 24
	s_add_i32 s0, s0, s1
	s_ashr_i32 s0, s0, 8
	s_lshl_b32 s18, s0, 6
	s_lshl_b32 s20, s0, 14
	s_add_i32 s0, s12, s16
	s_sub_i32 s0, s0, s20
	v_or_b32_e32 v48, s18, v16
	s_add_i32 s0, s0, 0x74000
	v_or_b32_e32 v2, 4, v48
	s_ashr_i32 s1, s0, 31
	v_ashrrev_i32_e32 v49, 31, v48
	v_ashrrev_i32_e32 v3, 31, v2
	v_lshl_add_u64 v[46:47], s[0:1], 2, v[38:39]
	v_lshlrev_b64 v[0:1], 16, v[48:49]
	v_lshlrev_b64 v[2:3], 16, v[2:3]
	v_lshl_add_u64 v[0:1], v[46:47], 0, v[0:1]
	v_lshl_add_u64 v[2:3], v[46:47], 0, v[2:3]
	global_load_dwordx4 v[30:33], v[0:1], off nt
	global_load_dwordx4 v[26:29], v[2:3], off nt
	v_or_b32_e32 v0, 8, v48
	v_or_b32_e32 v2, 12, v48
	v_ashrrev_i32_e32 v1, 31, v0
	v_ashrrev_i32_e32 v3, 31, v2
	v_lshlrev_b64 v[0:1], 16, v[0:1]
	v_lshlrev_b64 v[2:3], 16, v[2:3]
	v_lshl_add_u64 v[0:1], v[46:47], 0, v[0:1]
	v_lshl_add_u64 v[2:3], v[46:47], 0, v[2:3]
	global_load_dwordx4 v[22:25], v[0:1], off nt
	global_load_dwordx4 v[18:21], v[2:3], off nt
	v_or_b32_e32 v0, 16, v48
	v_or_b32_e32 v2, 20, v48
	v_ashrrev_i32_e32 v1, 31, v0
	v_ashrrev_i32_e32 v3, 31, v2
	v_lshlrev_b64 v[0:1], 16, v[0:1]
	v_lshlrev_b64 v[2:3], 16, v[2:3]
	v_lshl_add_u64 v[0:1], v[46:47], 0, v[0:1]
	v_lshl_add_u64 v[2:3], v[46:47], 0, v[2:3]
	global_load_dwordx4 v[12:15], v[0:1], off nt
	global_load_dwordx4 v[8:11], v[2:3], off nt
	v_or_b32_e32 v0, 24, v48
	v_or_b32_e32 v2, 28, v48
	v_ashrrev_i32_e32 v1, 31, v0
	v_ashrrev_i32_e32 v3, 31, v2
	v_lshlrev_b64 v[0:1], 16, v[0:1]
	v_lshlrev_b64 v[2:3], 16, v[2:3]
	v_lshl_add_u64 v[0:1], v[46:47], 0, v[0:1]
	v_lshl_add_u64 v[2:3], v[46:47], 0, v[2:3]
	global_load_dwordx4 v[4:7], v[0:1], off nt
	s_nop 0
	global_load_dwordx4 v[0:3], v[2:3], off nt
	v_cndmask_b32_e64 v52, 0, 1, s[14:15]
	v_mov_b32_e32 v50, 1.0
	v_cmp_ne_u32_e64 s[4:5], 1, v52
	s_andn2_b64 vcc, exec, s[14:15]
	v_mov_b32_e32 v52, 1.0
	s_cbranch_vccnz .LBB0_591
	v_lshl_add_u64 v[64:65], v[48:49], 2, s[10:11]
	global_load_dword v110, v[64:65], off offset:16
	global_load_dword v124, v[64:65], off offset:32
	global_load_dword v125, v[64:65], off offset:48
	global_load_dword v126, v[64:65], off offset:64
	global_load_dword v127, v[64:65], off offset:80
	global_load_dword v178, v[64:65], off offset:96
	global_load_dword v179, v[64:65], off offset:112
	global_load_dword v180, v[64:65], off offset:128
	global_load_dword v181, v[64:65], off offset:144
	global_load_dword v182, v[64:65], off offset:160
	global_load_dword v183, v[64:65], off offset:176
	global_load_dword v184, v[64:65], off offset:192
	global_load_dword v185, v[64:65], off offset:208
	global_load_dword v186, v[64:65], off offset:224
	global_load_dword v187, v[64:65], off offset:240
	global_load_dword v52, v[64:65], off
	s_waitcnt vmcnt(0)
	s_ashr_i32 s19, s18, 31
	v_lshl_add_u64 v[64:65], s[18:19], 0, v[16:17]
	v_lshl_add_u64 v[64:65], v[64:65], 2, s[10:11]
	s_waitcnt vmcnt(0)
	v_pk_mul_f32 v[30:31], v[30:31], v[52:53] op_sel_hi:[1,0]
	v_pk_mul_f32 v[32:33], v[32:33], v[52:53] op_sel_hi:[1,0]
	v_mov_b32_e32 v52, v110

; #define LAS __attribute__((address_space(3)))
; template <bool PERMUTE, bool BLOCKED = false>
; __device__ __forceinline__ void cvt_tile64(const float* W, int K, int N, bf16* WT, int ldo, const float* gk, LAS float* scr, int tile, int lane) {
;     ...
;     for (int hh = 0; hh < 2; ++hh) {
;         f32x4 v[8];
; #pragma unroll
;         for (int i = 0; i < 8; ++i) v[i] = *(const f32x4*)(W + (size_t)(k0 + 32 * hh + 4 * i + lk) * N + n0 + ln);
; #pragma unroll
;         for (int i = 0; i < 8; ++i) { const int kk = 32 * hh + 4 * i + lk; const float g = gk ? gk[k0 + kk] : 1.0f; LAS float* d = scr + kk * 65 + ln;
;             d[0] = v[i][0] * g; d[1] = v[i][1] * g; d[2] = v[i][2] * g; d[3] = v[i][3] * g; }
;     }
.LBB0_597:
	v_add_u32_e32 v8, 0x1860, v49
	ds_write2_b32 v8, v4, v5 offset1:1
	v_add_u32_e32 v4, 0x1868, v49
	ds_write2_b32 v4, v6, v7 offset1:1
	s_waitcnt vmcnt(0)
	v_pk_mul_f32 v[0:1], v[0:1], v[18:19] op_sel_hi:[1,0]
	v_add_u32_e32 v4, 0x1c70, v49
	ds_write2_b32 v4, v0, v1 offset1:1
	v_pk_mul_f32 v[0:1], v[2:3], v[18:19] op_sel_hi:[1,0]
	v_add_u32_e32 v2, 0x1c78, v49
	ds_write2_b32 v2, v0, v1 offset1:1
	v_or_b32_e32 v0, 32, v48
	v_or_b32_e32 v4, 60, v48
	v_ashrrev_i32_e32 v1, 31, v0
	v_ashrrev_i32_e32 v5, 31, v4
	v_lshlrev_b64 v[0:1], 16, v[0:1]
	v_lshlrev_b64 v[4:5], 16, v[4:5]
	v_lshl_add_u64 v[0:1], v[46:47], 0, v[0:1]
	v_lshl_add_u64 v[4:5], v[46:47], 0, v[4:5]
	global_load_dwordx4 v[26:29], v[0:1], off nt
	s_and_b64 vcc, exec, s[4:5]
	global_load_dwordx4 v[4:7], v[4:5], off nt
	v_or_b32_e32 v0, 36, v48
	v_ashrrev_i32_e32 v1, 31, v0
	v_lshlrev_b64 v[0:1], 16, v[0:1]
	v_lshl_add_u64 v[0:1], v[46:47], 0, v[0:1]
	global_load_dwordx4 v[30:33], v[0:1], off nt
	v_or_b32_e32 v0, 40, v48
	v_ashrrev_i32_e32 v1, 31, v0
	v_lshlrev_b64 v[0:1], 16, v[0:1]
	v_lshl_add_u64 v[0:1], v[46:47], 0, v[0:1]
	global_load_dwordx4 v[18:21], v[0:1], off nt
	v_or_b32_e32 v0, 44, v48
	v_ashrrev_i32_e32 v1, 31, v0
	v_lshlrev_b64 v[0:1], 16, v[0:1]
	v_lshl_add_u64 v[0:1], v[46:47], 0, v[0:1]
	global_load_dwordx4 v[22:25], v[0:1], off nt
	v_or_b32_e32 v0, 48, v48
	v_ashrrev_i32_e32 v1, 31, v0
	v_lshlrev_b64 v[0:1], 16, v[0:1]
	v_lshl_add_u64 v[0:1], v[46:47], 0, v[0:1]
	global_load_dwordx4 v[8:11], v[0:1], off nt
	v_or_b32_e32 v0, 52, v48
	v_ashrrev_i32_e32 v1, 31, v0
	v_lshlrev_b64 v[0:1], 16, v[0:1]
	v_lshl_add_u64 v[0:1], v[46:47], 0, v[0:1]
	global_load_dwordx4 v[12:15], v[0:1], off nt
	v_or_b32_e32 v0, 56, v48
	v_ashrrev_i32_e32 v1, 31, v0
	v_lshlrev_b64 v[0:1], 16, v[0:1]
	v_lshl_add_u64 v[0:1], v[46:47], 0, v[0:1]
	global_load_dwordx4 v[0:3], v[0:1], off nt
	v_mov_b32_e32 v46, 1.0
	v_mov_b32_e32 v48, 1.0
	s_cbranch_vccnz .LBB0_599
	s_ashr_i32 s19, s18, 31
	v_lshl_add_u64 v[64:65], s[18:19], 0, v[16:17]
	v_lshl_add_u64 v[64:65], v[64:65], 2, s[10:11]
	v_mov_b32_e32 v48, v180
	s_waitcnt vmcnt(0)
	v_pk_mul_f32 v[26:27], v[26:27], v[48:49] op_sel_hi:[1,0]
	v_pk_mul_f32 v[28:29], v[28:29], v[48:49] op_sel_hi:[1,0]
	v_mov_b32_e32 v48, v181

; #define LAS __attribute__((address_space(3)))
; template <bool PERMUTE, bool BLOCKED = false>
; __device__ __forceinline__ void cvt_tile64(const float* W, int K, int N, bf16* WT, int ldo, const float* gk, LAS float* scr, int tile, int lane) {
;     ...
;     for (int hh = 0; hh < 2; ++hh) {
;         f32x4 v[8];
; #pragma unroll
;         for (int i = 0; i < 8; ++i) v[i] = *(const f32x4*)(W + (size_t)(k0 + 32 * hh + 4 * i + lk) * N + n0 + ln);
; #pragma unroll
;         for (int i = 0; i < 8; ++i) { const int kk = 32 * hh + 4 * i + lk; const float g = gk ? gk[k0 + kk] : 1.0f; LAS float* d = scr + kk * 65 + ln;
;             d[0] = v[i][0] * g; d[1] = v[i][1] * g; d[2] = v[i][2] * g; d[3] = v[i][3] * g; }
;     }
; __device__ __forceinline__ void cvt_item(const CvtCtx& c, int batch, int wi, LAS float* scr, int wave, int lane) {
;     ...
;     if (wi < CVT_OUT) { cvt_tile64<false>(c.w_out + (size_t)l * DM * DM, DM, DM, c.WoutT + (size_t)l * DM * DM, DM, nullptr, scr, 8 * wi + wave, lane); return; } wi -= CVT_OUT;
.LBB0_609:
	s_andn2_b64 vcc, exec, s[0:1]
	s_cbranch_vccnz .LBB0_584
	s_ashr_i32 s0, s13, 31
	s_lshr_b32 s0, s0, 26
	s_add_i32 s0, s13, s0
	s_and_b32 s4, s0, 0xffffffc0
	s_lshl_b32 s0, s0, 6
	s_and_b32 s0, s0, 0xfffff000
	s_add_i32 s1, s12, s16
	s_sub_i32 s1, s1, s0
	s_add_i32 s6, s1, 0xb4000
	v_or_b32_e32 v2, s4, v16
	s_ashr_i32 s7, s6, 31
	v_ashrrev_i32_e32 v3, 31, v2
	v_lshl_add_u64 v[0:1], s[6:7], 2, v[42:43]
	v_lshlrev_b64 v[4:5], 14, v[2:3]
	v_or_b32_e32 v8, 4, v2
	v_lshl_add_u64 v[4:5], v[0:1], 0, v[4:5]
	v_ashrrev_i32_e32 v9, 31, v8
	global_load_dwordx4 v[4:7], v[4:5], off nt
	v_lshlrev_b64 v[8:9], 14, v[8:9]
	v_or_b32_e32 v12, 8, v2
	v_lshl_add_u64 v[8:9], v[0:1], 0, v[8:9]
	v_ashrrev_i32_e32 v13, 31, v12
	global_load_dwordx4 v[8:11], v[8:9], off nt
	v_lshlrev_b64 v[12:13], 14, v[12:13]
	v_or_b32_e32 v18, 12, v2
	v_lshl_add_u64 v[12:13], v[0:1], 0, v[12:13]
	v_ashrrev_i32_e32 v19, 31, v18
	global_load_dwordx4 v[12:15], v[12:13], off nt
	v_lshlrev_b64 v[18:19], 14, v[18:19]
	v_or_b32_e32 v22, 16, v2
	v_lshl_add_u64 v[18:19], v[0:1], 0, v[18:19]
	v_ashrrev_i32_e32 v23, 31, v22
	global_load_dwordx4 v[18:21], v[18:19], off nt
	v_lshlrev_b64 v[22:23], 14, v[22:23]
	v_or_b32_e32 v26, 20, v2
	v_lshl_add_u64 v[22:23], v[0:1], 0, v[22:23]
	v_ashrrev_i32_e32 v27, 31, v26
	global_load_dwordx4 v[22:25], v[22:23], off nt
	v_lshlrev_b64 v[26:27], 14, v[26:27]
	v_or_b32_e32 v30, 24, v2
	v_lshl_add_u64 v[26:27], v[0:1], 0, v[26:27]
	v_ashrrev_i32_e32 v31, 31, v30
	global_load_dwordx4 v[26:29], v[26:27], off nt
	v_lshlrev_b64 v[30:31], 14, v[30:31]
	v_or_b32_e32 v46, 28, v2
	v_lshl_add_u64 v[30:31], v[0:1], 0, v[30:31]
	v_ashrrev_i32_e32 v47, 31, v46
	global_load_dwordx4 v[30:33], v[30:31], off nt
	v_lshlrev_b64 v[46:47], 14, v[46:47]
	v_lshl_add_u64 v[46:47], v[0:1], 0, v[46:47]
	global_load_dwordx4 v[46:49], v[46:47], off nt
	v_add_u32_e32 v50, v51, v53
	v_add_u32_e32 v3, 0x410, v50
	s_sub_i32 s0, s12, s0
	s_ashr_i32 s5, s4, 31
	s_waitcnt vmcnt(7)
	ds_write2_b32 v50, v4, v5 offset1:1
	ds_write2_b32 v50, v6, v7 offset0:2 offset1:3
	v_or_b32_e32 v4, 32, v2
	v_ashrrev_i32_e32 v5, 31, v4
	v_lshlrev_b64 v[4:5], 14, v[4:5]
	v_lshl_add_u64 v[4:5], v[0:1], 0, v[4:5]
	s_waitcnt vmcnt(6)
	ds_write2_b32 v3, v8, v9 offset1:1
	v_add_u32_e32 v3, 0x418, v50
	v_or_b32_e32 v8, 36, v2
	ds_write2_b32 v3, v10, v11 offset1:1
	v_add_u32_e32 v3, 0x820, v50
	v_ashrrev_i32_e32 v9, 31, v8
	s_waitcnt vmcnt(5)
	ds_write2_b32 v3, v12, v13 offset1:1
	v_add_u32_e32 v3, 0x828, v50
	global_load_dwordx4 v[4:7], v[4:5], off nt
	v_lshlrev_b64 v[8:9], 14, v[8:9]
	v_or_b32_e32 v12, 40, v2
	ds_write2_b32 v3, v14, v15 offset1:1
	v_add_u32_e32 v3, 0xc30, v50
	v_lshl_add_u64 v[8:9], v[0:1], 0, v[8:9]
	v_ashrrev_i32_e32 v13, 31, v12
	s_waitcnt vmcnt(5)
	ds_write2_b32 v3, v18, v19 offset1:1
	v_add_u32_e32 v3, 0xc38, v50
	global_load_dwordx4 v[8:11], v[8:9], off nt
	v_lshlrev_b64 v[12:13], 14, v[12:13]
	v_or_b32_e32 v18, 44, v2
	ds_write2_b32 v3, v20, v21 offset1:1
	v_add_u32_e32 v3, 0x1040, v50
	v_lshl_add_u64 v[12:13], v[0:1], 0, v[12:13]
	v_ashrrev_i32_e32 v19, 31, v18
	s_waitcnt vmcnt(5)
	ds_write2_b32 v3, v22, v23 offset1:1
	v_add_u32_e32 v3, 0x1048, v50
	global_load_dwordx4 v[12:15], v[12:13], off nt
	v_lshlrev_b64 v[18:19], 14, v[18:19]
	v_or_b32_e32 v22, 48, v2
	ds_write2_b32 v3, v24, v25 offset1:1
	v_add_u32_e32 v3, 0x1450, v50
	v_lshl_add_u64 v[18:19], v[0:1], 0, v[18:19]
	v_ashrrev_i32_e32 v23, 31, v22
	s_waitcnt vmcnt(5)
	ds_write2_b32 v3, v26, v27 offset1:1
	v_add_u32_e32 v3, 0x1458, v50
	global_load_dwordx4 v[18:21], v[18:19], off nt
	v_lshlrev_b64 v[22:23], 14, v[22:23]
	v_or_b32_e32 v26, 52, v2
	ds_write2_b32 v3, v28, v29 offset1:1
	v_add_u32_e32 v3, 0x1860, v50
	v_lshl_add_u64 v[22:23], v[0:1], 0, v[22:23]
	v_ashrrev_i32_e32 v27, 31, v26
	s_waitcnt vmcnt(5)
	ds_write2_b32 v3, v30, v31 offset1:1
	v_add_u32_e32 v3, 0x1868, v50
	global_load_dwordx4 v[22:25], v[22:23], off nt
	v_lshlrev_b64 v[26:27], 14, v[26:27]
	v_or_b32_e32 v30, 56, v2
	ds_write2_b32 v3, v32, v33 offset1:1
	v_add_u32_e32 v3, 0x1c70, v50
	v_lshl_add_u64 v[26:27], v[0:1], 0, v[26:27]
	v_ashrrev_i32_e32 v31, 31, v30
	s_waitcnt vmcnt(5)
	ds_write2_b32 v3, v46, v47 offset1:1
	v_add_u32_e32 v3, 0x1c78, v50
	global_load_dwordx4 v[26:29], v[26:27], off nt
	v_lshlrev_b64 v[30:31], 14, v[30:31]
	v_or_b32_e32 v2, 60, v2
	ds_write2_b32 v3, v48, v49 offset1:1
	v_lshl_add_u64 v[30:31], v[0:1], 0, v[30:31]
	v_ashrrev_i32_e32 v3, 31, v2
	global_load_dwordx4 v[30:33], v[30:31], off nt
	v_lshlrev_b64 v[2:3], 14, v[2:3]
	v_lshl_add_u64 v[0:1], v[0:1], 0, v[2:3]
	global_load_dwordx4 v[0:3], v[0:1], off nt
	v_add_u32_e32 v46, 0x2080, v50
	s_waitcnt vmcnt(7)
	ds_write2_b32 v46, v4, v5 offset1:1
	v_add_u32_e32 v4, 0x2088, v50
	ds_write2_b32 v4, v6, v7 offset1:1
	v_add_u32_e32 v4, 0x2490, v50
	s_waitcnt vmcnt(6)
	ds_write2_b32 v4, v8, v9 offset1:1
	v_add_u32_e32 v4, 0x2498, v50
	ds_write2_b32 v4, v10, v11 offset1:1
	v_add_u32_e32 v4, 0x28a0, v50
	s_waitcnt vmcnt(5)
	ds_write2_b32 v4, v12, v13 offset1:1
	v_add_u32_e32 v4, 0x28a8, v50
	ds_write2_b32 v4, v14, v15 offset1:1
	v_add_u32_e32 v4, 0x2cb0, v50
	s_waitcnt vmcnt(4)
	ds_write2_b32 v4, v18, v19 offset1:1
	v_add_u32_e32 v4, 0x2cb8, v50
	ds_write2_b32 v4, v20, v21 offset1:1
	v_add_u32_e32 v4, 0x30c0, v50
	s_waitcnt vmcnt(3)
	ds_write2_b32 v4, v22, v23 offset1:1
	v_add_u32_e32 v4, 0x30c8, v50
	ds_write2_b32 v4, v24, v25 offset1:1
	v_add_u32_e32 v4, 0x34d0, v50
	s_waitcnt vmcnt(2)
	ds_write2_b32 v4, v26, v27 offset1:1
	v_add_u32_e32 v4, 0x34d8, v50
	ds_write2_b32 v4, v28, v29 offset1:1
	v_add_u32_e32 v4, 0x38e0, v50
	s_waitcnt vmcnt(1)
; __host__ __device__ __forceinline__ size_t blocked_off(int row, int col, int K) { return (((size_t)(row >> 8) * (K >> 6) + (col >> 6)) * 256 + (row & 255)) * 64 + (col & 63); }
; __device__ __forceinline__ unsigned cvt_pk_bf16(float lo, float hi) { const f32x2c_t v = {lo, hi}; return __builtin_bit_cast(unsigned, __builtin_convertvector(v, bf16x2c_t)); }
; #define LAS __attribute__((address_space(3)))
; #define LDS_WAIT() asm volatile("s_waitcnt lgkmcnt(0)" ::: "memory")
; __host__ __device__ __forceinline__ int win_phys_col(int n) { if (!win_rope_tile(n >> 8)) return n; const int cl = n & 255; return (n & ~255) | (cl & 63) | ((cl & 64) << 1) | ((cl & 128) >> 1); }
; template <bool PERMUTE, bool BLOCKED = false>
; __device__ __forceinline__ void cvt_tile64(const float* W, int K, int N, bf16* WT, int ldo, const float* gk, LAS float* scr, int tile, int lane) {
;     ...
;     LDS_WAIT(); asm volatile("" ::: "memory");
;     const int kc = lane & 7, nrow0 = PERMUTE ? win_phys_col(n0) : n0;
; #pragma unroll
;     for (int j = 0; j < 8; ++j) { const int n = (lane >> 3) + 8 * j; const LAS float* s = scr + (8 * kc) * 65 + n;
;         v4u o; o[0] = cvt_pk_bf16(wrnd(s[0 * 65]), wrnd(s[1 * 65])); o[1] = cvt_pk_bf16(wrnd(s[2 * 65]), wrnd(s[3 * 65])); o[2] = cvt_pk_bf16(wrnd(s[4 * 65]), wrnd(s[5 * 65])); o[3] = cvt_pk_bf16(wrnd(s[6 * 65]), wrnd(s[7 * 65]));
;         *(v4u*)(WT + (BLOCKED ? pg8::blocked_off(nrow0 + n, k0 + 8 * kc, K) : (size_t)(nrow0 + n) * ldo + k0 + 8 * kc)) = o; }
;     LDS_WAIT(); asm volatile("" ::: "memory");
	ds_write2_b32 v4, v30, v31 offset1:1
	v_add_u32_e32 v4, 0x38e8, v50
	ds_write2_b32 v4, v32, v33 offset1:1
	v_add_u32_e32 v4, 0x3cf0, v50
	s_waitcnt vmcnt(0)
	ds_write2_b32 v4, v0, v1 offset1:1
	v_add_u32_e32 v0, 0x3cf8, v50
	ds_write2_b32 v0, v2, v3 offset1:1
	s_waitcnt lgkmcnt(0)
	ds_read2_b32 v[8:9], v55 offset1:8
	ds_read2_b32 v[10:11], v55 offset0:65 offset1:73
	ds_read2_b32 v[12:13], v55 offset0:130 offset1:138
	ds_read2_b32 v[14:15], v55 offset0:195 offset1:203
	v_lshl_add_u64 v[0:1], s[4:5], 1, v[44:45]
	s_waitcnt lgkmcnt(3)
	v_add_u32_e32 v2, 0x20000, v8
	s_waitcnt lgkmcnt(2)
	v_add_u32_e32 v3, 0x20000, v10
	v_and_b32_e32 v2, 0xfffc0000, v2
	v_and_b32_e32 v3, 0xfffc0000, v3
	v_cvt_pk_bf16_f32 v4, v2, v3
	s_waitcnt lgkmcnt(1)
	v_add_u32_e32 v2, 0x20000, v12
	s_waitcnt lgkmcnt(0)
	v_add_u32_e32 v3, 0x20000, v14
	v_and_b32_e32 v2, 0xfffc0000, v2
	v_and_b32_e32 v3, 0xfffc0000, v3
	v_cvt_pk_bf16_f32 v5, v2, v3
	v_add_u32_e32 v2, 0x400, v55
	ds_read2_b32 v[18:19], v2 offset0:4 offset1:12
	ds_read2_b32 v[20:21], v2 offset0:69 offset1:77
	ds_read2_b32 v[22:23], v2 offset0:134 offset1:142
	ds_read2_b32 v[24:25], v2 offset0:199 offset1:207
	s_waitcnt lgkmcnt(3)
	v_add_u32_e32 v3, 0x20000, v18
	s_waitcnt lgkmcnt(2)
	v_add_u32_e32 v6, 0x20000, v20
	v_and_b32_e32 v3, 0xfffc0000, v3
	v_and_b32_e32 v6, 0xfffc0000, v6
	v_cvt_pk_bf16_f32 v6, v3, v6
	s_waitcnt lgkmcnt(1)
	v_add_u32_e32 v3, 0x20000, v22
	s_waitcnt lgkmcnt(0)
	v_add_u32_e32 v7, 0x20000, v24
	v_and_b32_e32 v3, 0xfffc0000, v3
	v_and_b32_e32 v7, 0xfffc0000, v7
	v_cvt_pk_bf16_f32 v7, v3, v7
	v_add_u32_e32 v3, s0, v63
	v_add_u32_e32 v26, 0xb4000, v3
	v_ashrrev_i32_e32 v27, 31, v26
	v_lshlrev_b64 v[26:27], 13, v[26:27]
	v_lshl_add_u64 v[26:27], v[0:1], 0, v[26:27]
	global_store_dwordx4 v[26:27], v[4:7], off
	v_add_u32_e32 v8, 0x20000, v25
	v_and_b32_e32 v8, 0xfffc0000, v8
	v_add_u32_e32 v4, 0x20000, v9
	v_add_u32_e32 v5, 0x20000, v11
	v_and_b32_e32 v4, 0xfffc0000, v4
	v_and_b32_e32 v5, 0xfffc0000, v5
	v_cvt_pk_bf16_f32 v4, v4, v5
	v_add_u32_e32 v5, 0x20000, v13
	v_add_u32_e32 v6, 0x20000, v15
	v_and_b32_e32 v5, 0xfffc0000, v5
	v_and_b32_e32 v6, 0xfffc0000, v6
	v_cvt_pk_bf16_f32 v5, v5, v6
	v_add_u32_e32 v6, 0x20000, v19
	v_add_u32_e32 v7, 0x20000, v21
	v_and_b32_e32 v6, 0xfffc0000, v6
	v_and_b32_e32 v7, 0xfffc0000, v7
	v_cvt_pk_bf16_f32 v6, v6, v7
	v_add_u32_e32 v7, 0x20000, v23
	v_and_b32_e32 v7, 0xfffc0000, v7
	v_cvt_pk_bf16_f32 v7, v7, v8
	v_add_u32_e32 v8, 0xb4008, v3
	v_ashrrev_i32_e32 v9, 31, v8
	v_lshlrev_b64 v[8:9], 13, v[8:9]
	v_lshl_add_u64 v[8:9], v[0:1], 0, v[8:9]
	global_store_dwordx4 v[8:9], v[4:7], off
	ds_read2_b32 v[8:9], v55 offset0:16 offset1:24
	ds_read2_b32 v[10:11], v55 offset0:81 offset1:89
	ds_read2_b32 v[12:13], v55 offset0:146 offset1:154
	ds_read2_b32 v[14:15], v55 offset0:211 offset1:219
	ds_read2_b32 v[18:19], v2 offset0:20 offset1:28
	ds_read2_b32 v[20:21], v2 offset0:85 offset1:93
	s_waitcnt lgkmcnt(5)
	v_add_u32_e32 v4, 0x20000, v8
	s_waitcnt lgkmcnt(4)
	v_add_u32_e32 v5, 0x20000, v10
	v_and_b32_e32 v4, 0xfffc0000, v4
	v_and_b32_e32 v5, 0xfffc0000, v5
	ds_read2_b32 v[22:23], v2 offset0:150 offset1:158
	ds_read2_b32 v[24:25], v2 offset0:215 offset1:223
	v_cvt_pk_bf16_f32 v4, v4, v5
	s_waitcnt lgkmcnt(5)
	v_add_u32_e32 v5, 0x20000, v12
	s_waitcnt lgkmcnt(4)
	v_add_u32_e32 v6, 0x20000, v14
	v_and_b32_e32 v5, 0xfffc0000, v5
	v_and_b32_e32 v6, 0xfffc0000, v6
	v_cvt_pk_bf16_f32 v5, v5, v6
	s_waitcnt lgkmcnt(3)
	v_add_u32_e32 v6, 0x20000, v18
	s_waitcnt lgkmcnt(2)
	v_add_u32_e32 v7, 0x20000, v20
	v_and_b32_e32 v6, 0xfffc0000, v6
	v_and_b32_e32 v7, 0xfffc0000, v7
	v_add_u32_e32 v26, 0xb4010, v3
	v_cvt_pk_bf16_f32 v6, v6, v7
	s_waitcnt lgkmcnt(1)
	v_add_u32_e32 v7, 0x20000, v22
	s_waitcnt lgkmcnt(0)
	v_add_u32_e32 v8, 0x20000, v24
	v_ashrrev_i32_e32 v27, 31, v26
	v_and_b32_e32 v7, 0xfffc0000, v7
	v_and_b32_e32 v8, 0xfffc0000, v8
	v_lshlrev_b64 v[26:27], 13, v[26:27]
	v_cvt_pk_bf16_f32 v7, v7, v8
	v_lshl_add_u64 v[26:27], v[0:1], 0, v[26:27]
	global_store_dwordx4 v[26:27], v[4:7], off
	v_add_u32_e32 v8, 0x20000, v25
	v_and_b32_e32 v8, 0xfffc0000, v8
	v_add_u32_e32 v4, 0x20000, v9
	v_add_u32_e32 v5, 0x20000, v11
	v_and_b32_e32 v4, 0xfffc0000, v4
	v_and_b32_e32 v5, 0xfffc0000, v5
	v_cvt_pk_bf16_f32 v4, v4, v5
	v_add_u32_e32 v5, 0x20000, v13
	v_add_u32_e32 v6, 0x20000, v15
	v_and_b32_e32 v5, 0xfffc0000, v5
	v_and_b32_e32 v6, 0xfffc0000, v6
	v_cvt_pk_bf16_f32 v5, v5, v6
	v_add_u32_e32 v6, 0x20000, v19
	v_add_u32_e32 v7, 0x20000, v21
	v_and_b32_e32 v6, 0xfffc0000, v6
	v_and_b32_e32 v7, 0xfffc0000, v7
	v_cvt_pk_bf16_f32 v6, v6, v7
	v_add_u32_e32 v7, 0x20000, v23
	v_and_b32_e32 v7, 0xfffc0000, v7
	v_cvt_pk_bf16_f32 v7, v7, v8
	v_add_u32_e32 v8, 0xb4018, v3
	v_ashrrev_i32_e32 v9, 31, v8
	v_lshlrev_b64 v[8:9], 13, v[8:9]
	v_lshl_add_u64 v[8:9], v[0:1], 0, v[8:9]
	global_store_dwordx4 v[8:9], v[4:7], off
	ds_read2_b32 v[8:9], v55 offset0:32 offset1:40
	ds_read2_b32 v[10:11], v55 offset0:97 offset1:105
	ds_read2_b32 v[12:13], v55 offset0:162 offset1:170
	ds_read2_b32 v[14:15], v55 offset0:227 offset1:235
	ds_read2_b32 v[18:19], v2 offset0:36 offset1:44
	ds_read2_b32 v[20:21], v2 offset0:101 offset1:109
	s_waitcnt lgkmcnt(5)
; __host__ __device__ __forceinline__ size_t blocked_off(int row, int col, int K) { return (((size_t)(row >> 8) * (K >> 6) + (col >> 6)) * 256 + (row & 255)) * 64 + (col & 63); }
; __device__ __forceinline__ unsigned cvt_pk_bf16(float lo, float hi) { const f32x2c_t v = {lo, hi}; return __builtin_bit_cast(unsigned, __builtin_convertvector(v, bf16x2c_t)); }
; #define LAS __attribute__((address_space(3)))
; #define LDS_WAIT() asm volatile("s_waitcnt lgkmcnt(0)" ::: "memory")
; __host__ __device__ __forceinline__ int win_phys_col(int n) { if (!win_rope_tile(n >> 8)) return n; const int cl = n & 255; return (n & ~255) | (cl & 63) | ((cl & 64) << 1) | ((cl & 128) >> 1); }
; template <bool PERMUTE, bool BLOCKED = false>
; __device__ __forceinline__ void cvt_tile64(const float* W, int K, int N, bf16* WT, int ldo, const float* gk, LAS float* scr, int tile, int lane) {
;     ...
;     LDS_WAIT(); asm volatile("" ::: "memory");
;     const int kc = lane & 7, nrow0 = PERMUTE ? win_phys_col(n0) : n0;
; #pragma unroll
;     for (int j = 0; j < 8; ++j) { const int n = (lane >> 3) + 8 * j; const LAS float* s = scr + (8 * kc) * 65 + n;
;         v4u o; o[0] = cvt_pk_bf16(wrnd(s[0 * 65]), wrnd(s[1 * 65])); o[1] = cvt_pk_bf16(wrnd(s[2 * 65]), wrnd(s[3 * 65])); o[2] = cvt_pk_bf16(wrnd(s[4 * 65]), wrnd(s[5 * 65])); o[3] = cvt_pk_bf16(wrnd(s[6 * 65]), wrnd(s[7 * 65]));
;         *(v4u*)(WT + (BLOCKED ? pg8::blocked_off(nrow0 + n, k0 + 8 * kc, K) : (size_t)(nrow0 + n) * ldo + k0 + 8 * kc)) = o; }
;     LDS_WAIT(); asm volatile("" ::: "memory");
	v_add_u32_e32 v4, 0x20000, v8
	s_waitcnt lgkmcnt(4)
	v_add_u32_e32 v5, 0x20000, v10
	v_and_b32_e32 v4, 0xfffc0000, v4
	v_and_b32_e32 v5, 0xfffc0000, v5
	ds_read2_b32 v[22:23], v2 offset0:166 offset1:174
	ds_read2_b32 v[24:25], v2 offset0:231 offset1:239
	v_cvt_pk_bf16_f32 v4, v4, v5
	s_waitcnt lgkmcnt(5)
	v_add_u32_e32 v5, 0x20000, v12
	s_waitcnt lgkmcnt(4)
	v_add_u32_e32 v6, 0x20000, v14
	v_and_b32_e32 v5, 0xfffc0000, v5
	v_and_b32_e32 v6, 0xfffc0000, v6
	v_cvt_pk_bf16_f32 v5, v5, v6
	s_waitcnt lgkmcnt(3)
	v_add_u32_e32 v6, 0x20000, v18
	s_waitcnt lgkmcnt(2)
	v_add_u32_e32 v7, 0x20000, v20
	v_and_b32_e32 v6, 0xfffc0000, v6
	v_and_b32_e32 v7, 0xfffc0000, v7
	v_add_u32_e32 v26, 0xb4020, v3
	v_cvt_pk_bf16_f32 v6, v6, v7
	s_waitcnt lgkmcnt(1)
	v_add_u32_e32 v7, 0x20000, v22
	s_waitcnt lgkmcnt(0)
	v_add_u32_e32 v8, 0x20000, v24
	v_ashrrev_i32_e32 v27, 31, v26
	v_and_b32_e32 v7, 0xfffc0000, v7
	v_and_b32_e32 v8, 0xfffc0000, v8
	v_lshlrev_b64 v[26:27], 13, v[26:27]
	v_cvt_pk_bf16_f32 v7, v7, v8
	v_lshl_add_u64 v[26:27], v[0:1], 0, v[26:27]
	global_store_dwordx4 v[26:27], v[4:7], off
	v_add_u32_e32 v8, 0x20000, v25
	v_and_b32_e32 v8, 0xfffc0000, v8
	v_add_u32_e32 v4, 0x20000, v9
	v_add_u32_e32 v5, 0x20000, v11
	v_and_b32_e32 v4, 0xfffc0000, v4
	v_and_b32_e32 v5, 0xfffc0000, v5
	v_cvt_pk_bf16_f32 v4, v4, v5
	v_add_u32_e32 v5, 0x20000, v13
	v_add_u32_e32 v6, 0x20000, v15
	v_and_b32_e32 v5, 0xfffc0000, v5
	v_and_b32_e32 v6, 0xfffc0000, v6
	v_cvt_pk_bf16_f32 v5, v5, v6
	v_add_u32_e32 v6, 0x20000, v19
	v_add_u32_e32 v7, 0x20000, v21
	v_and_b32_e32 v6, 0xfffc0000, v6
	v_and_b32_e32 v7, 0xfffc0000, v7
	v_cvt_pk_bf16_f32 v6, v6, v7
	v_add_u32_e32 v7, 0x20000, v23
	v_and_b32_e32 v7, 0xfffc0000, v7
	v_cvt_pk_bf16_f32 v7, v7, v8
	v_add_u32_e32 v8, 0xb4028, v3
	v_ashrrev_i32_e32 v9, 31, v8
	v_lshlrev_b64 v[8:9], 13, v[8:9]
	v_lshl_add_u64 v[8:9], v[0:1], 0, v[8:9]
	global_store_dwordx4 v[8:9], v[4:7], off
	ds_read2_b32 v[8:9], v55 offset0:48 offset1:56
	ds_read2_b32 v[10:11], v55 offset0:113 offset1:121
	ds_read2_b32 v[12:13], v55 offset0:178 offset1:186
	ds_read2_b32 v[14:15], v55 offset0:243 offset1:251
	ds_read2_b32 v[18:19], v2 offset0:52 offset1:60
	ds_read2_b32 v[20:21], v2 offset0:117 offset1:125
	s_waitcnt lgkmcnt(5)
	v_add_u32_e32 v4, 0x20000, v8
	s_waitcnt lgkmcnt(4)
	v_add_u32_e32 v5, 0x20000, v10
	v_and_b32_e32 v4, 0xfffc0000, v4
	v_and_b32_e32 v5, 0xfffc0000, v5
	ds_read2_b32 v[22:23], v2 offset0:182 offset1:190
	ds_read2_b32 v[24:25], v2 offset0:247 offset1:255
	v_cvt_pk_bf16_f32 v4, v4, v5
	s_waitcnt lgkmcnt(5)
	v_add_u32_e32 v5, 0x20000, v12
	s_waitcnt lgkmcnt(4)
	v_add_u32_e32 v6, 0x20000, v14
	v_and_b32_e32 v5, 0xfffc0000, v5
	v_and_b32_e32 v6, 0xfffc0000, v6
	v_cvt_pk_bf16_f32 v5, v5, v6
	s_waitcnt lgkmcnt(3)
	v_add_u32_e32 v6, 0x20000, v18
	s_waitcnt lgkmcnt(2)
	v_add_u32_e32 v7, 0x20000, v20
	v_and_b32_e32 v6, 0xfffc0000, v6
	v_and_b32_e32 v7, 0xfffc0000, v7
	v_add_u32_e32 v26, 0xb4030, v3
	v_cvt_pk_bf16_f32 v6, v6, v7
	s_waitcnt lgkmcnt(1)
	v_add_u32_e32 v7, 0x20000, v22
	s_waitcnt lgkmcnt(0)
	v_add_u32_e32 v2, 0x20000, v24
	v_ashrrev_i32_e32 v27, 31, v26
	v_and_b32_e32 v7, 0xfffc0000, v7
	v_and_b32_e32 v2, 0xfffc0000, v2
	v_lshlrev_b64 v[26:27], 13, v[26:27]
	v_cvt_pk_bf16_f32 v7, v7, v2
	v_lshl_add_u64 v[26:27], v[0:1], 0, v[26:27]
	global_store_dwordx4 v[26:27], v[4:7], off
	v_add_u32_e32 v2, 0x20000, v9
	v_and_b32_e32 v2, 0xfffc0000, v2
	v_add_u32_e32 v4, 0x20000, v11
	v_and_b32_e32 v4, 0xfffc0000, v4
	v_cvt_pk_bf16_f32 v4, v2, v4
	v_add_u32_e32 v2, 0x20000, v13
	v_add_u32_e32 v5, 0x20000, v15
	v_and_b32_e32 v2, 0xfffc0000, v2
	v_and_b32_e32 v5, 0xfffc0000, v5
	v_cvt_pk_bf16_f32 v5, v2, v5
	v_add_u32_e32 v2, 0x20000, v19
	v_add_u32_e32 v6, 0x20000, v21
	v_and_b32_e32 v2, 0xfffc0000, v2
	v_and_b32_e32 v6, 0xfffc0000, v6
	v_cvt_pk_bf16_f32 v6, v2, v6
	v_add_u32_e32 v2, 0x20000, v23
	v_add_u32_e32 v7, 0x20000, v25
	v_and_b32_e32 v2, 0xfffc0000, v2
	v_and_b32_e32 v7, 0xfffc0000, v7
	v_cvt_pk_bf16_f32 v7, v2, v7
	v_add_u32_e32 v2, 0xb4038, v3
	v_ashrrev_i32_e32 v3, 31, v2
	v_lshlrev_b64 v[2:3], 13, v[2:3]
	v_lshl_add_u64 v[0:1], v[0:1], 0, v[2:3]
	global_store_dwordx4 v[0:1], v[4:7], off
	s_waitcnt lgkmcnt(0)
	s_branch .LBB0_584

; #define LAS __attribute__((address_space(3)))
; template <bool PERMUTE, bool BLOCKED = false>
; __device__ __forceinline__ void cvt_tile64(const float* W, int K, int N, bf16* WT, int ldo, const float* gk, LAS float* scr, int tile, int lane) {
;     ...
;     for (int hh = 0; hh < 2; ++hh) {
;         f32x4 v[8];
; #pragma unroll
;         for (int i = 0; i < 8; ++i) v[i] = *(const f32x4*)(W + (size_t)(k0 + 32 * hh + 4 * i + lk) * N + n0 + ln);
; #pragma unroll
;         for (int i = 0; i < 8; ++i) { const int kk = 32 * hh + 4 * i + lk; const float g = gk ? gk[k0 + kk] : 1.0f; LAS float* d = scr + kk * 65 + ln;
;             d[0] = v[i][0] * g; d[1] = v[i][1] * g; d[2] = v[i][2] * g; d[3] = v[i][3] * g; }
;     }
; __device__ __forceinline__ void cvt_item(const CvtCtx& c, int batch, int wi, LAS float* scr, int wave, int lane) {
;     const int l = batch;
;     if (wi < CVT_OUT) { cvt_tile64<false>(c.w_out + (size_t)l * DM * DM, DM, DM, c.WoutT + (size_t)l * DM * DM, DM, nullptr, scr, 8 * wi + wave, lane); return; } wi -= CVT_OUT;
;     if (wi < CVT_UP) { cvt_tile64<false>(c.w_up + (size_t)l * DM * DFF, DM, DFF, c.WupT + (size_t)l * DFF * DM, DM, c.g_mlp + l * DM, scr, 8 * wi + wave, lane); return; } wi -= CVT_UP;
;     if (wi < CVT_DN) { cvt_tile64<false, true>(c.w_down + (size_t)l * DFF * DM, DFF, DM, c.WdnT + (size_t)l * DM * DFF, 0, nullptr, scr, 8 * wi + wave, lane); return; } wi -= CVT_DN;
.LBB0_669:
	s_addk_i32 s17, 0x100
	s_cmpk_gt_i32 s17, 0x1ff
	s_mov_b64 s[0:1], -1
	s_cbranch_scc0 .LBB0_693
	s_cmpk_gt_u32 s17, 0x9ff
	s_cbranch_scc0 .LBB0_672
	s_add_i32 s0, s13, 0xffffb000
	s_ashr_i32 s1, s0, 31
	s_lshr_b32 s1, s1, 26
	s_add_i32 s0, s0, s1
	s_ashr_i32 s10, s0, 6
	s_add_i32 s6, s12, s16
	s_lshl_b32 s7, s10, 12
	s_andn2_b32 s0, s0, 63
	s_add_i32 s1, s6, 0x28000
	s_sub_i32 s6, s6, s7
	s_add_i32 s20, s6, 0x28000
	v_or_b32_e32 v2, s0, v16
	s_ashr_i32 s21, s20, 31
	v_ashrrev_i32_e32 v3, 31, v2
	v_lshl_add_u64 v[0:1], s[20:21], 2, v[34:35]
	v_lshlrev_b64 v[4:5], 14, v[2:3]
	v_or_b32_e32 v8, 4, v2
	v_lshl_add_u64 v[4:5], v[0:1], 0, v[4:5]
	v_ashrrev_i32_e32 v9, 31, v8
	global_load_dwordx4 v[4:7], v[4:5], off nt
	v_lshlrev_b64 v[8:9], 14, v[8:9]
	v_or_b32_e32 v12, 8, v2
	v_lshl_add_u64 v[8:9], v[0:1], 0, v[8:9]
	v_ashrrev_i32_e32 v13, 31, v12
	global_load_dwordx4 v[8:11], v[8:9], off nt
	v_lshlrev_b64 v[12:13], 14, v[12:13]
	v_or_b32_e32 v18, 12, v2
	v_lshl_add_u64 v[12:13], v[0:1], 0, v[12:13]
	v_ashrrev_i32_e32 v19, 31, v18
	global_load_dwordx4 v[12:15], v[12:13], off nt
	v_lshlrev_b64 v[18:19], 14, v[18:19]
	v_or_b32_e32 v22, 16, v2
	v_lshl_add_u64 v[18:19], v[0:1], 0, v[18:19]
	v_ashrrev_i32_e32 v23, 31, v22
	global_load_dwordx4 v[18:21], v[18:19], off nt
	v_lshlrev_b64 v[22:23], 14, v[22:23]
	v_or_b32_e32 v26, 20, v2
	v_lshl_add_u64 v[22:23], v[0:1], 0, v[22:23]
	v_ashrrev_i32_e32 v27, 31, v26
	global_load_dwordx4 v[22:25], v[22:23], off nt
	v_lshlrev_b64 v[26:27], 14, v[26:27]
	v_or_b32_e32 v30, 24, v2
	v_lshl_add_u64 v[26:27], v[0:1], 0, v[26:27]
	v_ashrrev_i32_e32 v31, 31, v30
	global_load_dwordx4 v[26:29], v[26:27], off nt
	v_lshlrev_b64 v[30:31], 14, v[30:31]
	v_or_b32_e32 v46, 28, v2
	v_lshl_add_u64 v[30:31], v[0:1], 0, v[30:31]
	v_ashrrev_i32_e32 v47, 31, v46
	global_load_dwordx4 v[30:33], v[30:31], off nt
	v_lshlrev_b64 v[46:47], 14, v[46:47]
	v_lshl_add_u64 v[46:47], v[0:1], 0, v[46:47]
	global_load_dwordx4 v[46:49], v[46:47], off nt
	v_add_u32_e32 v50, v51, v53
	v_add_u32_e32 v3, 0x410, v50
	s_ashr_i32 s6, s20, 8
	s_ashr_i32 s7, s6, 31
	s_ashr_i32 s11, s10, 31
	s_lshl_b64 s[6:7], s[6:7], 16
	s_lshl_b64 s[10:11], s[10:11], 8
	s_add_u32 s0, s6, s10
	s_addc_u32 s6, s7, s11
	s_and_b32 s1, s1, 0xc0
	s_waitcnt vmcnt(7)
	ds_write2_b32 v50, v4, v5 offset1:1
	ds_write2_b32 v50, v6, v7 offset0:2 offset1:3
	v_or_b32_e32 v4, 32, v2
	v_ashrrev_i32_e32 v5, 31, v4
	v_lshlrev_b64 v[4:5], 14, v[4:5]
	v_lshl_add_u64 v[4:5], v[0:1], 0, v[4:5]
	s_waitcnt vmcnt(6)
	ds_write2_b32 v3, v8, v9 offset1:1
	v_add_u32_e32 v3, 0x418, v50
	v_or_b32_e32 v8, 36, v2
	ds_write2_b32 v3, v10, v11 offset1:1
	v_add_u32_e32 v3, 0x820, v50
	v_ashrrev_i32_e32 v9, 31, v8
	s_waitcnt vmcnt(5)
	ds_write2_b32 v3, v12, v13 offset1:1
	v_add_u32_e32 v3, 0x828, v50
	global_load_dwordx4 v[4:7], v[4:5], off nt
	v_lshlrev_b64 v[8:9], 14, v[8:9]
	v_or_b32_e32 v12, 40, v2
	ds_write2_b32 v3, v14, v15 offset1:1
	v_add_u32_e32 v3, 0xc30, v50
	v_lshl_add_u64 v[8:9], v[0:1], 0, v[8:9]
	v_ashrrev_i32_e32 v13, 31, v12
	s_waitcnt vmcnt(5)
	ds_write2_b32 v3, v18, v19 offset1:1
	v_add_u32_e32 v3, 0xc38, v50
	global_load_dwordx4 v[8:11], v[8:9], off nt
	v_lshlrev_b64 v[12:13], 14, v[12:13]
	v_or_b32_e32 v18, 44, v2
	ds_write2_b32 v3, v20, v21 offset1:1
	v_add_u32_e32 v3, 0x1040, v50
	v_lshl_add_u64 v[12:13], v[0:1], 0, v[12:13]
	v_ashrrev_i32_e32 v19, 31, v18
	s_waitcnt vmcnt(5)
	ds_write2_b32 v3, v22, v23 offset1:1
	v_add_u32_e32 v3, 0x1048, v50
	global_load_dwordx4 v[12:15], v[12:13], off nt
	v_lshlrev_b64 v[18:19], 14, v[18:19]
	v_or_b32_e32 v22, 48, v2
	ds_write2_b32 v3, v24, v25 offset1:1
	v_add_u32_e32 v3, 0x1450, v50
	v_lshl_add_u64 v[18:19], v[0:1], 0, v[18:19]
	v_ashrrev_i32_e32 v23, 31, v22
	s_waitcnt vmcnt(5)
	ds_write2_b32 v3, v26, v27 offset1:1
	v_add_u32_e32 v3, 0x1458, v50
	global_load_dwordx4 v[18:21], v[18:19], off nt
	v_lshlrev_b64 v[22:23], 14, v[22:23]
	v_or_b32_e32 v26, 52, v2
	ds_write2_b32 v3, v28, v29 offset1:1
	v_add_u32_e32 v3, 0x1860, v50
	v_lshl_add_u64 v[22:23], v[0:1], 0, v[22:23]
	v_ashrrev_i32_e32 v27, 31, v26
	s_waitcnt vmcnt(5)
	ds_write2_b32 v3, v30, v31 offset1:1
	v_add_u32_e32 v3, 0x1868, v50
	global_load_dwordx4 v[22:25], v[22:23], off nt
	v_lshlrev_b64 v[26:27], 14, v[26:27]
	v_or_b32_e32 v30, 56, v2
	ds_write2_b32 v3, v32, v33 offset1:1
	v_add_u32_e32 v3, 0x1c70, v50
	v_lshl_add_u64 v[26:27], v[0:1], 0, v[26:27]
	v_ashrrev_i32_e32 v31, 31, v30
	s_waitcnt vmcnt(5)
	ds_write2_b32 v3, v46, v47 offset1:1
	v_add_u32_e32 v3, 0x1c78, v50
	global_load_dwordx4 v[26:29], v[26:27], off nt
	v_lshlrev_b64 v[30:31], 14, v[30:31]
	v_or_b32_e32 v2, 60, v2
	ds_write2_b32 v3, v48, v49 offset1:1
	v_lshl_add_u64 v[30:31], v[0:1], 0, v[30:31]
	v_ashrrev_i32_e32 v3, 31, v2
	global_load_dwordx4 v[30:33], v[30:31], off nt
	v_lshlrev_b64 v[2:3], 14, v[2:3]
	v_lshl_add_u64 v[0:1], v[0:1], 0, v[2:3]
	global_load_dwordx4 v[0:3], v[0:1], off nt
	v_add_u32_e32 v46, 0x2080, v50
	s_waitcnt vmcnt(7)
	ds_write2_b32 v46, v4, v5 offset1:1
	v_add_u32_e32 v4, 0x2088, v50
	ds_write2_b32 v4, v6, v7 offset1:1
	v_add_u32_e32 v4, 0x2490, v50
	s_waitcnt vmcnt(6)
	ds_write2_b32 v4, v8, v9 offset1:1
	v_add_u32_e32 v4, 0x2498, v50
	ds_write2_b32 v4, v10, v11 offset1:1
	v_add_u32_e32 v4, 0x28a0, v50
	s_waitcnt vmcnt(5)
	ds_write2_b32 v4, v12, v13 offset1:1
	v_add_u32_e32 v4, 0x28a8, v50
	ds_write2_b32 v4, v14, v15 offset1:1
	v_add_u32_e32 v4, 0x2cb0, v50
	s_waitcnt vmcnt(4)
	ds_write2_b32 v4, v18, v19 offset1:1
	v_add_u32_e32 v4, 0x2cb8, v50
	ds_write2_b32 v4, v20, v21 offset1:1
	v_add_u32_e32 v4, 0x30c0, v50
	s_waitcnt vmcnt(3)
; __host__ __device__ __forceinline__ size_t blocked_off(int row, int col, int K) { return (((size_t)(row >> 8) * (K >> 6) + (col >> 6)) * 256 + (row & 255)) * 64 + (col & 63); }
; __device__ __forceinline__ unsigned cvt_pk_bf16(float lo, float hi) { const f32x2c_t v = {lo, hi}; return __builtin_bit_cast(unsigned, __builtin_convertvector(v, bf16x2c_t)); }
; #define LAS __attribute__((address_space(3)))
; #define LDS_WAIT() asm volatile("s_waitcnt lgkmcnt(0)" ::: "memory")
; __host__ __device__ __forceinline__ int win_phys_col(int n) { if (!win_rope_tile(n >> 8)) return n; const int cl = n & 255; return (n & ~255) | (cl & 63) | ((cl & 64) << 1) | ((cl & 128) >> 1); }
; template <bool PERMUTE, bool BLOCKED = false>
; __device__ __forceinline__ void cvt_tile64(const float* W, int K, int N, bf16* WT, int ldo, const float* gk, LAS float* scr, int tile, int lane) {
;     ...
;     LDS_WAIT(); asm volatile("" ::: "memory");
;     const int kc = lane & 7, nrow0 = PERMUTE ? win_phys_col(n0) : n0;
; #pragma unroll
;     for (int j = 0; j < 8; ++j) { const int n = (lane >> 3) + 8 * j; const LAS float* s = scr + (8 * kc) * 65 + n;
;         v4u o; o[0] = cvt_pk_bf16(wrnd(s[0 * 65]), wrnd(s[1 * 65])); o[1] = cvt_pk_bf16(wrnd(s[2 * 65]), wrnd(s[3 * 65])); o[2] = cvt_pk_bf16(wrnd(s[4 * 65]), wrnd(s[5 * 65])); o[3] = cvt_pk_bf16(wrnd(s[6 * 65]), wrnd(s[7 * 65]));
;         *(v4u*)(WT + (BLOCKED ? pg8::blocked_off(nrow0 + n, k0 + 8 * kc, K) : (size_t)(nrow0 + n) * ldo + k0 + 8 * kc)) = o; }
	ds_write2_b32 v4, v22, v23 offset1:1
	v_add_u32_e32 v4, 0x30c8, v50
	ds_write2_b32 v4, v24, v25 offset1:1
	v_add_u32_e32 v4, 0x34d0, v50
	s_waitcnt vmcnt(2)
	ds_write2_b32 v4, v26, v27 offset1:1
	v_add_u32_e32 v4, 0x34d8, v50
	ds_write2_b32 v4, v28, v29 offset1:1
	v_add_u32_e32 v4, 0x38e0, v50
	s_waitcnt vmcnt(1)
	ds_write2_b32 v4, v30, v31 offset1:1
	v_add_u32_e32 v4, 0x38e8, v50
	ds_write2_b32 v4, v32, v33 offset1:1
	v_add_u32_e32 v4, 0x3cf0, v50
	s_waitcnt vmcnt(0)
	ds_write2_b32 v4, v0, v1 offset1:1
	v_add_u32_e32 v0, 0x3cf8, v50
	ds_write2_b32 v0, v2, v3 offset1:1
	s_waitcnt lgkmcnt(0)
	ds_read2_b32 v[2:3], v55 offset1:8
	ds_read2_b32 v[8:9], v55 offset0:65 offset1:73
	ds_read2_b32 v[10:11], v55 offset0:130 offset1:138
	ds_read2_b32 v[12:13], v55 offset0:195 offset1:203
	s_waitcnt lgkmcnt(3)
	v_add_u32_e32 v0, 0x20000, v2
	v_add_u32_e32 v2, 0x400, v55
	ds_read2_b32 v[14:15], v2 offset0:4 offset1:12
	ds_read2_b32 v[18:19], v2 offset0:69 offset1:77
	s_waitcnt lgkmcnt(4)
	v_add_u32_e32 v1, 0x20000, v8
	v_and_b32_e32 v0, 0xfffc0000, v0
	v_and_b32_e32 v1, 0xfffc0000, v1
	ds_read2_b32 v[20:21], v2 offset0:134 offset1:142
	ds_read2_b32 v[22:23], v2 offset0:199 offset1:207
	v_cvt_pk_bf16_f32 v4, v0, v1
	s_waitcnt lgkmcnt(5)
	v_add_u32_e32 v0, 0x20000, v10
	s_waitcnt lgkmcnt(4)
	v_add_u32_e32 v1, 0x20000, v12
	v_and_b32_e32 v0, 0xfffc0000, v0
	v_and_b32_e32 v1, 0xfffc0000, v1
	v_cvt_pk_bf16_f32 v5, v0, v1
	s_waitcnt lgkmcnt(3)
	v_add_u32_e32 v0, 0x20000, v14
	s_waitcnt lgkmcnt(2)
	v_add_u32_e32 v1, 0x20000, v18
	v_and_b32_e32 v0, 0xfffc0000, v0
	v_and_b32_e32 v1, 0xfffc0000, v1
	v_cvt_pk_bf16_f32 v6, v0, v1
	s_waitcnt lgkmcnt(1)
	v_add_u32_e32 v0, 0x20000, v20
	s_waitcnt lgkmcnt(0)
	v_add_u32_e32 v1, 0x20000, v22
	v_and_b32_e32 v0, 0xfffc0000, v0
	v_and_b32_e32 v1, 0xfffc0000, v1
	v_cvt_pk_bf16_f32 v7, v0, v1
	v_or_b32_e32 v0, s1, v54
	v_or_b32_e32 v0, s0, v0
	v_mov_b32_e32 v1, s6
	v_lshlrev_b64 v[24:25], 7, v[0:1]
	v_add_u32_e32 v0, 0x20000, v3
	v_add_u32_e32 v3, 0x20000, v9
	v_lshl_add_u64 v[24:25], v[36:37], 0, v[24:25]
	v_and_b32_e32 v0, 0xfffc0000, v0
	v_and_b32_e32 v3, 0xfffc0000, v3
	global_store_dwordx4 v[24:25], v[4:7], off
	ds_read2_b32 v[24:25], v2 offset0:215 offset1:223
	s_nop 0
	v_cvt_pk_bf16_f32 v4, v0, v3
	v_add_u32_e32 v0, 0x20000, v11
	v_add_u32_e32 v3, 0x20000, v13
	v_and_b32_e32 v0, 0xfffc0000, v0
	v_and_b32_e32 v3, 0xfffc0000, v3
	v_cvt_pk_bf16_f32 v5, v0, v3
	v_add_u32_e32 v0, 0x20000, v15
	v_add_u32_e32 v3, 0x20000, v19
	v_and_b32_e32 v0, 0xfffc0000, v0
	v_and_b32_e32 v3, 0xfffc0000, v3
	v_cvt_pk_bf16_f32 v6, v0, v3
	v_add_u32_e32 v0, 0x20000, v21
	v_add_u32_e32 v3, 0x20000, v23
	v_and_b32_e32 v0, 0xfffc0000, v0
	v_and_b32_e32 v3, 0xfffc0000, v3
	v_cvt_pk_bf16_f32 v7, v0, v3
	v_or_b32_e32 v0, s1, v56
	v_or_b32_e32 v0, s0, v0
	v_lshlrev_b64 v[8:9], 7, v[0:1]
	v_lshl_add_u64 v[8:9], v[36:37], 0, v[8:9]
	global_store_dwordx4 v[8:9], v[4:7], off
	ds_read2_b32 v[8:9], v55 offset0:16 offset1:24
	ds_read2_b32 v[10:11], v55 offset0:81 offset1:89
	ds_read2_b32 v[12:13], v55 offset0:146 offset1:154
	ds_read2_b32 v[14:15], v55 offset0:211 offset1:219
	ds_read2_b32 v[18:19], v2 offset0:20 offset1:28
	ds_read2_b32 v[20:21], v2 offset0:85 offset1:93
	s_waitcnt lgkmcnt(5)
	v_add_u32_e32 v0, 0x20000, v8
	s_waitcnt lgkmcnt(4)
	v_add_u32_e32 v3, 0x20000, v10
	v_and_b32_e32 v0, 0xfffc0000, v0
	v_and_b32_e32 v3, 0xfffc0000, v3
	ds_read2_b32 v[22:23], v2 offset0:150 offset1:158
	v_cvt_pk_bf16_f32 v4, v0, v3
	s_waitcnt lgkmcnt(4)
	v_add_u32_e32 v0, 0x20000, v12
	s_waitcnt lgkmcnt(3)
	v_add_u32_e32 v3, 0x20000, v14
	v_and_b32_e32 v0, 0xfffc0000, v0
	v_and_b32_e32 v3, 0xfffc0000, v3
	v_cvt_pk_bf16_f32 v5, v0, v3
	s_waitcnt lgkmcnt(2)
	v_add_u32_e32 v0, 0x20000, v18
	s_waitcnt lgkmcnt(1)
	v_add_u32_e32 v3, 0x20000, v20
	v_and_b32_e32 v0, 0xfffc0000, v0
	v_and_b32_e32 v3, 0xfffc0000, v3
	v_cvt_pk_bf16_f32 v6, v0, v3
	s_waitcnt lgkmcnt(0)
	v_add_u32_e32 v0, 0x20000, v22
	v_add_u32_e32 v3, 0x20000, v24
	v_and_b32_e32 v0, 0xfffc0000, v0
	v_and_b32_e32 v3, 0xfffc0000, v3
	v_cvt_pk_bf16_f32 v7, v0, v3
	v_or_b32_e32 v0, s1, v57
	v_or_b32_e32 v0, s0, v0
	v_lshlrev_b64 v[26:27], 7, v[0:1]
	v_add_u32_e32 v0, 0x20000, v9
	v_add_u32_e32 v3, 0x20000, v11
	v_lshl_add_u64 v[26:27], v[36:37], 0, v[26:27]
	v_and_b32_e32 v0, 0xfffc0000, v0
	v_and_b32_e32 v3, 0xfffc0000, v3
	global_store_dwordx4 v[26:27], v[4:7], off
	ds_read2_b32 v[10:11], v55 offset0:97 offset1:105
	s_nop 0
	v_cvt_pk_bf16_f32 v4, v0, v3
	v_add_u32_e32 v0, 0x20000, v13
	v_add_u32_e32 v3, 0x20000, v15
	v_and_b32_e32 v0, 0xfffc0000, v0
	v_and_b32_e32 v3, 0xfffc0000, v3
	v_cvt_pk_bf16_f32 v5, v0, v3
	v_add_u32_e32 v0, 0x20000, v19
	v_add_u32_e32 v3, 0x20000, v21
	v_and_b32_e32 v0, 0xfffc0000, v0
	v_and_b32_e32 v3, 0xfffc0000, v3
	v_cvt_pk_bf16_f32 v6, v0, v3
	v_add_u32_e32 v0, 0x20000, v23
	v_add_u32_e32 v3, 0x20000, v25
	v_and_b32_e32 v0, 0xfffc0000, v0
	v_and_b32_e32 v3, 0xfffc0000, v3
	v_cvt_pk_bf16_f32 v7, v0, v3
	v_or_b32_e32 v0, s1, v58
	v_or_b32_e32 v0, s0, v0
	v_lshlrev_b64 v[8:9], 7, v[0:1]
	v_lshl_add_u64 v[8:9], v[36:37], 0, v[8:9]
	global_store_dwordx4 v[8:9], v[4:7], off
	ds_read2_b32 v[8:9], v55 offset0:32 offset1:40
	ds_read2_b32 v[12:13], v55 offset0:162 offset1:170
	ds_read2_b32 v[14:15], v55 offset0:227 offset1:235
	ds_read2_b32 v[18:19], v2 offset0:36 offset1:44
	ds_read2_b32 v[20:21], v2 offset0:101 offset1:109
	s_waitcnt lgkmcnt(4)
	v_add_u32_e32 v0, 0x20000, v8
	v_add_u32_e32 v3, 0x20000, v10
	v_and_b32_e32 v0, 0xfffc0000, v0
	v_and_b32_e32 v3, 0xfffc0000, v3
	ds_read2_b32 v[22:23], v2 offset0:166 offset1:174
	ds_read2_b32 v[24:25], v2 offset0:231 offset1:239
	v_cvt_pk_bf16_f32 v4, v0, v3
	s_waitcnt lgkmcnt(5)
; __host__ __device__ __forceinline__ size_t blocked_off(int row, int col, int K) { return (((size_t)(row >> 8) * (K >> 6) + (col >> 6)) * 256 + (row & 255)) * 64 + (col & 63); }
; __device__ __forceinline__ unsigned cvt_pk_bf16(float lo, float hi) { const f32x2c_t v = {lo, hi}; return __builtin_bit_cast(unsigned, __builtin_convertvector(v, bf16x2c_t)); }
; #define LAS __attribute__((address_space(3)))
; #define LDS_WAIT() asm volatile("s_waitcnt lgkmcnt(0)" ::: "memory")
; __host__ __device__ __forceinline__ int win_phys_col(int n) { if (!win_rope_tile(n >> 8)) return n; const int cl = n & 255; return (n & ~255) | (cl & 63) | ((cl & 64) << 1) | ((cl & 128) >> 1); }
; template <bool PERMUTE, bool BLOCKED = false>
; __device__ __forceinline__ void cvt_tile64(const float* W, int K, int N, bf16* WT, int ldo, const float* gk, LAS float* scr, int tile, int lane) {
;     ...
;     for (int hh = 0; hh < 2; ++hh) {
;         f32x4 v[8];
; #pragma unroll
;         for (int i = 0; i < 8; ++i) v[i] = *(const f32x4*)(W + (size_t)(k0 + 32 * hh + 4 * i + lk) * N + n0 + ln);
; #pragma unroll
;         for (int i = 0; i < 8; ++i) { const int kk = 32 * hh + 4 * i + lk; const float g = gk ? gk[k0 + kk] : 1.0f; LAS float* d = scr + kk * 65 + ln;
;             d[0] = v[i][0] * g; d[1] = v[i][1] * g; d[2] = v[i][2] * g; d[3] = v[i][3] * g; }
;     }
;     ...
;     LDS_WAIT(); asm volatile("" ::: "memory");
;     const int kc = lane & 7, nrow0 = PERMUTE ? win_phys_col(n0) : n0;
; #pragma unroll
;     for (int j = 0; j < 8; ++j) { const int n = (lane >> 3) + 8 * j; const LAS float* s = scr + (8 * kc) * 65 + n;
;         v4u o; o[0] = cvt_pk_bf16(wrnd(s[0 * 65]), wrnd(s[1 * 65])); o[1] = cvt_pk_bf16(wrnd(s[2 * 65]), wrnd(s[3 * 65])); o[2] = cvt_pk_bf16(wrnd(s[4 * 65]), wrnd(s[5 * 65])); o[3] = cvt_pk_bf16(wrnd(s[6 * 65]), wrnd(s[7 * 65]));
;         *(v4u*)(WT + (BLOCKED ? pg8::blocked_off(nrow0 + n, k0 + 8 * kc, K) : (size_t)(nrow0 + n) * ldo + k0 + 8 * kc)) = o; }
	v_add_u32_e32 v0, 0x20000, v12
	s_waitcnt lgkmcnt(4)
	v_add_u32_e32 v3, 0x20000, v14
	v_and_b32_e32 v0, 0xfffc0000, v0
	v_and_b32_e32 v3, 0xfffc0000, v3
	v_cvt_pk_bf16_f32 v5, v0, v3
	s_waitcnt lgkmcnt(3)
	v_add_u32_e32 v0, 0x20000, v18
	s_waitcnt lgkmcnt(2)
	v_add_u32_e32 v3, 0x20000, v20
	v_and_b32_e32 v0, 0xfffc0000, v0
	v_and_b32_e32 v3, 0xfffc0000, v3
	v_cvt_pk_bf16_f32 v6, v0, v3
	s_waitcnt lgkmcnt(1)
	v_add_u32_e32 v0, 0x20000, v22
	s_waitcnt lgkmcnt(0)
	v_add_u32_e32 v3, 0x20000, v24
	v_and_b32_e32 v0, 0xfffc0000, v0
	v_and_b32_e32 v3, 0xfffc0000, v3
	v_cvt_pk_bf16_f32 v7, v0, v3
	v_or_b32_e32 v0, s1, v59
	v_or_b32_e32 v0, s0, v0
	v_lshlrev_b64 v[26:27], 7, v[0:1]
	v_add_u32_e32 v0, 0x20000, v9
	v_add_u32_e32 v3, 0x20000, v11
	v_lshl_add_u64 v[26:27], v[36:37], 0, v[26:27]
	v_and_b32_e32 v0, 0xfffc0000, v0
	v_and_b32_e32 v3, 0xfffc0000, v3
	global_store_dwordx4 v[26:27], v[4:7], off
	ds_read2_b32 v[10:11], v55 offset0:113 offset1:121
	s_nop 0
	v_cvt_pk_bf16_f32 v4, v0, v3
	v_add_u32_e32 v0, 0x20000, v13
	v_add_u32_e32 v3, 0x20000, v15
	v_and_b32_e32 v0, 0xfffc0000, v0
	v_and_b32_e32 v3, 0xfffc0000, v3
	v_cvt_pk_bf16_f32 v5, v0, v3
	v_add_u32_e32 v0, 0x20000, v19
	v_add_u32_e32 v3, 0x20000, v21
	v_and_b32_e32 v0, 0xfffc0000, v0
	v_and_b32_e32 v3, 0xfffc0000, v3
	v_cvt_pk_bf16_f32 v6, v0, v3
	v_add_u32_e32 v0, 0x20000, v23
	v_add_u32_e32 v3, 0x20000, v25
	v_and_b32_e32 v0, 0xfffc0000, v0
	v_and_b32_e32 v3, 0xfffc0000, v3
	v_cvt_pk_bf16_f32 v7, v0, v3
	v_or_b32_e32 v0, s1, v60
	v_or_b32_e32 v0, s0, v0
	v_lshlrev_b64 v[8:9], 7, v[0:1]
	v_lshl_add_u64 v[8:9], v[36:37], 0, v[8:9]
	global_store_dwordx4 v[8:9], v[4:7], off
	ds_read2_b32 v[8:9], v55 offset0:48 offset1:56
	ds_read2_b32 v[12:13], v55 offset0:178 offset1:186
	ds_read2_b32 v[14:15], v55 offset0:243 offset1:251
	ds_read2_b32 v[18:19], v2 offset0:52 offset1:60
	ds_read2_b32 v[20:21], v2 offset0:117 offset1:125
	s_waitcnt lgkmcnt(4)
	v_add_u32_e32 v0, 0x20000, v8
	v_add_u32_e32 v3, 0x20000, v10
	v_and_b32_e32 v0, 0xfffc0000, v0
	v_and_b32_e32 v3, 0xfffc0000, v3
	ds_read2_b32 v[22:23], v2 offset0:182 offset1:190
	ds_read2_b32 v[24:25], v2 offset0:247 offset1:255
	v_cvt_pk_bf16_f32 v4, v0, v3
	s_waitcnt lgkmcnt(5)
	v_add_u32_e32 v0, 0x20000, v12
	s_waitcnt lgkmcnt(4)
	v_add_u32_e32 v3, 0x20000, v14
	v_and_b32_e32 v0, 0xfffc0000, v0
	v_and_b32_e32 v3, 0xfffc0000, v3
	v_cvt_pk_bf16_f32 v5, v0, v3
	s_waitcnt lgkmcnt(3)
	v_add_u32_e32 v0, 0x20000, v18
	s_waitcnt lgkmcnt(2)
	v_add_u32_e32 v3, 0x20000, v20
	v_and_b32_e32 v0, 0xfffc0000, v0
	v_and_b32_e32 v3, 0xfffc0000, v3
	v_cvt_pk_bf16_f32 v6, v0, v3
	s_waitcnt lgkmcnt(1)
	v_add_u32_e32 v0, 0x20000, v22
	s_waitcnt lgkmcnt(0)
	v_add_u32_e32 v2, 0x20000, v24
	v_and_b32_e32 v0, 0xfffc0000, v0
	v_and_b32_e32 v2, 0xfffc0000, v2
	v_cvt_pk_bf16_f32 v7, v0, v2
	v_or_b32_e32 v0, s1, v61
	v_or_b32_e32 v0, s0, v0
	v_lshlrev_b64 v[2:3], 7, v[0:1]
	v_lshl_add_u64 v[2:3], v[36:37], 0, v[2:3]
	global_store_dwordx4 v[2:3], v[4:7], off
	v_add_u32_e32 v0, 0x20000, v9
	v_add_u32_e32 v2, 0x20000, v11
	v_and_b32_e32 v0, 0xfffc0000, v0
	v_and_b32_e32 v2, 0xfffc0000, v2
	v_cvt_pk_bf16_f32 v2, v0, v2
	v_add_u32_e32 v0, 0x20000, v13
	v_add_u32_e32 v3, 0x20000, v15
	v_and_b32_e32 v0, 0xfffc0000, v0
	v_and_b32_e32 v3, 0xfffc0000, v3
	v_cvt_pk_bf16_f32 v3, v0, v3
	v_add_u32_e32 v0, 0x20000, v19
	v_add_u32_e32 v4, 0x20000, v21
	v_and_b32_e32 v0, 0xfffc0000, v0
	v_and_b32_e32 v4, 0xfffc0000, v4
	v_cvt_pk_bf16_f32 v4, v0, v4
	v_add_u32_e32 v0, 0x20000, v23
	v_add_u32_e32 v5, 0x20000, v25
	v_and_b32_e32 v0, 0xfffc0000, v0
	v_and_b32_e32 v5, 0xfffc0000, v5
	v_cvt_pk_bf16_f32 v5, v0, v5
	v_or_b32_e32 v0, s1, v62
	v_or_b32_e32 v0, s0, v0
	v_lshlrev_b64 v[0:1], 7, v[0:1]
	v_lshl_add_u64 v[0:1], v[36:37], 0, v[0:1]
	global_store_dwordx4 v[0:1], v[2:5], off
	s_waitcnt lgkmcnt(0)
	s_mov_b64 s[0:1], 0
.LBB0_672:
	s_andn2_b64 vcc, exec, s[0:1]
	s_cbranch_vccnz .LBB0_692
	s_add_i32 s0, s13, 0xfffff000
	s_ashr_i32 s1, s0, 31
	s_lshr_b32 s1, s1, 24
	s_add_i32 s0, s0, s1
	s_ashr_i32 s0, s0, 8
	s_lshl_b32 s20, s0, 6
	s_lshl_b32 s22, s0, 14
	s_add_i32 s0, s12, s16
	s_sub_i32 s0, s0, s22
	v_or_b32_e32 v48, s20, v16
	s_add_i32 s0, s0, 0x128000
	v_or_b32_e32 v2, 4, v48
	s_ashr_i32 s1, s0, 31
	v_ashrrev_i32_e32 v49, 31, v48
	v_ashrrev_i32_e32 v3, 31, v2
	v_lshl_add_u64 v[46:47], s[0:1], 2, v[38:39]
	v_lshlrev_b64 v[0:1], 16, v[48:49]
	v_lshlrev_b64 v[2:3], 16, v[2:3]
	v_lshl_add_u64 v[0:1], v[46:47], 0, v[0:1]
	v_lshl_add_u64 v[2:3], v[46:47], 0, v[2:3]
	global_load_dwordx4 v[30:33], v[0:1], off nt
	global_load_dwordx4 v[26:29], v[2:3], off nt
	v_or_b32_e32 v0, 8, v48
	v_or_b32_e32 v2, 12, v48
	v_ashrrev_i32_e32 v1, 31, v0
	v_ashrrev_i32_e32 v3, 31, v2
	v_lshlrev_b64 v[0:1], 16, v[0:1]
	v_lshlrev_b64 v[2:3], 16, v[2:3]
	v_lshl_add_u64 v[0:1], v[46:47], 0, v[0:1]
	v_lshl_add_u64 v[2:3], v[46:47], 0, v[2:3]
	global_load_dwordx4 v[22:25], v[0:1], off nt
	global_load_dwordx4 v[18:21], v[2:3], off nt
	v_or_b32_e32 v0, 16, v48
	v_or_b32_e32 v2, 20, v48
	v_ashrrev_i32_e32 v1, 31, v0
	v_ashrrev_i32_e32 v3, 31, v2
	v_lshlrev_b64 v[0:1], 16, v[0:1]
	v_lshlrev_b64 v[2:3], 16, v[2:3]
	v_lshl_add_u64 v[0:1], v[46:47], 0, v[0:1]
	v_lshl_add_u64 v[2:3], v[46:47], 0, v[2:3]
	global_load_dwordx4 v[12:15], v[0:1], off nt
	global_load_dwordx4 v[8:11], v[2:3], off nt
	v_or_b32_e32 v0, 24, v48
	v_or_b32_e32 v2, 28, v48
	v_ashrrev_i32_e32 v1, 31, v0
	v_ashrrev_i32_e32 v3, 31, v2
	v_lshlrev_b64 v[0:1], 16, v[0:1]
	v_lshlrev_b64 v[2:3], 16, v[2:3]
	v_lshl_add_u64 v[0:1], v[46:47], 0, v[0:1]
	v_lshl_add_u64 v[2:3], v[46:47], 0, v[2:3]
	global_load_dwordx4 v[4:7], v[0:1], off nt
	s_nop 0
	global_load_dwordx4 v[0:3], v[2:3], off nt
	v_cndmask_b32_e64 v52, 0, 1, s[18:19]
	v_mov_b32_e32 v50, 1.0
	v_cmp_ne_u32_e64 s[10:11], 1, v52
	s_andn2_b64 vcc, exec, s[18:19]
	v_mov_b32_e32 v52, 1.0
	s_cbranch_vccnz .LBB0_675
	v_lshl_add_u64 v[64:65], v[48:49], 2, s[14:15]
	global_load_dword v110, v[64:65], off offset:16
	global_load_dword v124, v[64:65], off offset:32
	global_load_dword v125, v[64:65], off offset:48
	global_load_dword v126, v[64:65], off offset:64
	global_load_dword v127, v[64:65], off offset:80
	global_load_dword v178, v[64:65], off offset:96
	global_load_dword v179, v[64:65], off offset:112
	global_load_dword v180, v[64:65], off offset:128
	global_load_dword v181, v[64:65], off offset:144
	global_load_dword v182, v[64:65], off offset:160
	global_load_dword v183, v[64:65], off offset:176
	global_load_dword v184, v[64:65], off offset:192
	global_load_dword v185, v[64:65], off offset:208
	global_load_dword v186, v[64:65], off offset:224
	global_load_dword v187, v[64:65], off offset:240
	global_load_dword v52, v[64:65], off
	s_waitcnt vmcnt(0)
	s_ashr_i32 s21, s20, 31
	v_lshl_add_u64 v[64:65], s[20:21], 0, v[16:17]
	v_lshl_add_u64 v[64:65], v[64:65], 2, s[14:15]
	s_waitcnt vmcnt(0)
	v_pk_mul_f32 v[30:31], v[30:31], v[52:53] op_sel_hi:[1,0]
	v_pk_mul_f32 v[32:33], v[32:33], v[52:53] op_sel_hi:[1,0]
	v_mov_b32_e32 v52, v110

; #define LAS __attribute__((address_space(3)))
; template <bool PERMUTE, bool BLOCKED = false>
; __device__ __forceinline__ void cvt_tile64(const float* W, int K, int N, bf16* WT, int ldo, const float* gk, LAS float* scr, int tile, int lane) {
;     ...
;     for (int hh = 0; hh < 2; ++hh) {
;         f32x4 v[8];
; #pragma unroll
;         for (int i = 0; i < 8; ++i) v[i] = *(const f32x4*)(W + (size_t)(k0 + 32 * hh + 4 * i + lk) * N + n0 + ln);
; #pragma unroll
;         for (int i = 0; i < 8; ++i) { const int kk = 32 * hh + 4 * i + lk; const float g = gk ? gk[k0 + kk] : 1.0f; LAS float* d = scr + kk * 65 + ln;
;             d[0] = v[i][0] * g; d[1] = v[i][1] * g; d[2] = v[i][2] * g; d[3] = v[i][3] * g; }
;     }
.LBB0_681:
	v_add_u32_e32 v8, 0x1860, v49
	ds_write2_b32 v8, v4, v5 offset1:1
	v_add_u32_e32 v4, 0x1868, v49
	ds_write2_b32 v4, v6, v7 offset1:1
	s_waitcnt vmcnt(0)
	v_pk_mul_f32 v[0:1], v[0:1], v[18:19] op_sel_hi:[1,0]
	v_add_u32_e32 v4, 0x1c70, v49
	ds_write2_b32 v4, v0, v1 offset1:1
	v_pk_mul_f32 v[0:1], v[2:3], v[18:19] op_sel_hi:[1,0]
	v_add_u32_e32 v2, 0x1c78, v49
	ds_write2_b32 v2, v0, v1 offset1:1
	v_or_b32_e32 v0, 32, v48
	v_or_b32_e32 v4, 60, v48
	v_ashrrev_i32_e32 v1, 31, v0
	v_ashrrev_i32_e32 v5, 31, v4
	v_lshlrev_b64 v[0:1], 16, v[0:1]
	v_lshlrev_b64 v[4:5], 16, v[4:5]
	v_lshl_add_u64 v[0:1], v[46:47], 0, v[0:1]
	v_lshl_add_u64 v[4:5], v[46:47], 0, v[4:5]
	global_load_dwordx4 v[26:29], v[0:1], off nt
	s_and_b64 vcc, exec, s[10:11]
	global_load_dwordx4 v[4:7], v[4:5], off nt
	v_or_b32_e32 v0, 36, v48
	v_ashrrev_i32_e32 v1, 31, v0
	v_lshlrev_b64 v[0:1], 16, v[0:1]
	v_lshl_add_u64 v[0:1], v[46:47], 0, v[0:1]
	global_load_dwordx4 v[30:33], v[0:1], off nt
	v_or_b32_e32 v0, 40, v48
	v_ashrrev_i32_e32 v1, 31, v0
	v_lshlrev_b64 v[0:1], 16, v[0:1]
	v_lshl_add_u64 v[0:1], v[46:47], 0, v[0:1]
	global_load_dwordx4 v[18:21], v[0:1], off nt
	v_or_b32_e32 v0, 44, v48
	v_ashrrev_i32_e32 v1, 31, v0
	v_lshlrev_b64 v[0:1], 16, v[0:1]
	v_lshl_add_u64 v[0:1], v[46:47], 0, v[0:1]
	global_load_dwordx4 v[22:25], v[0:1], off nt
	v_or_b32_e32 v0, 48, v48
	v_ashrrev_i32_e32 v1, 31, v0
	v_lshlrev_b64 v[0:1], 16, v[0:1]
	v_lshl_add_u64 v[0:1], v[46:47], 0, v[0:1]
	global_load_dwordx4 v[8:11], v[0:1], off nt
	v_or_b32_e32 v0, 52, v48
	v_ashrrev_i32_e32 v1, 31, v0
	v_lshlrev_b64 v[0:1], 16, v[0:1]
	v_lshl_add_u64 v[0:1], v[46:47], 0, v[0:1]
	global_load_dwordx4 v[12:15], v[0:1], off nt
	v_or_b32_e32 v0, 56, v48
	v_ashrrev_i32_e32 v1, 31, v0
	v_lshlrev_b64 v[0:1], 16, v[0:1]
	v_lshl_add_u64 v[0:1], v[46:47], 0, v[0:1]
	global_load_dwordx4 v[0:3], v[0:1], off nt
	v_mov_b32_e32 v46, 1.0
	v_mov_b32_e32 v48, 1.0
	s_cbranch_vccnz .LBB0_683
	s_ashr_i32 s21, s20, 31
	v_lshl_add_u64 v[64:65], s[20:21], 0, v[16:17]
	v_lshl_add_u64 v[64:65], v[64:65], 2, s[14:15]
	v_mov_b32_e32 v48, v180
	s_waitcnt vmcnt(0)
	v_pk_mul_f32 v[26:27], v[26:27], v[48:49] op_sel_hi:[1,0]
	v_pk_mul_f32 v[28:29], v[28:29], v[48:49] op_sel_hi:[1,0]
	v_mov_b32_e32 v48, v181

; #define LAS __attribute__((address_space(3)))
; template <bool PERMUTE, bool BLOCKED = false>
; __device__ __forceinline__ void cvt_tile64(const float* W, int K, int N, bf16* WT, int ldo, const float* gk, LAS float* scr, int tile, int lane) {
;     ...
;     for (int hh = 0; hh < 2; ++hh) {
;         f32x4 v[8];
; #pragma unroll
;         for (int i = 0; i < 8; ++i) v[i] = *(const f32x4*)(W + (size_t)(k0 + 32 * hh + 4 * i + lk) * N + n0 + ln);
; #pragma unroll
;         for (int i = 0; i < 8; ++i) { const int kk = 32 * hh + 4 * i + lk; const float g = gk ? gk[k0 + kk] : 1.0f; LAS float* d = scr + kk * 65 + ln;
;             d[0] = v[i][0] * g; d[1] = v[i][1] * g; d[2] = v[i][2] * g; d[3] = v[i][3] * g; }
;     }
; __device__ __forceinline__ void cvt_item(const CvtCtx& c, int batch, int wi, LAS float* scr, int wave, int lane) {
;     ...
;     if (wi < CVT_OUT) { cvt_tile64<false>(c.w_out + (size_t)l * DM * DM, DM, DM, c.WoutT + (size_t)l * DM * DM, DM, nullptr, scr, 8 * wi + wave, lane); return; } wi -= CVT_OUT;
.LBB0_693:
	s_andn2_b64 vcc, exec, s[0:1]
	s_cbranch_vccnz .LBB0_668
	s_ashr_i32 s0, s13, 31
	s_lshr_b32 s0, s0, 26
	s_add_i32 s0, s13, s0
	s_and_b32 s10, s0, 0xffffffc0
	s_lshl_b32 s0, s0, 6
	s_and_b32 s0, s0, 0xfffff000
	s_add_i32 s1, s12, s16
	s_sub_i32 s1, s1, s0
	s_add_i32 s6, s1, 0x168000
	v_or_b32_e32 v2, s10, v16
	s_ashr_i32 s7, s6, 31
	v_ashrrev_i32_e32 v3, 31, v2
	v_lshl_add_u64 v[0:1], s[6:7], 2, v[42:43]
	v_lshlrev_b64 v[4:5], 14, v[2:3]
	v_or_b32_e32 v8, 4, v2
	v_lshl_add_u64 v[4:5], v[0:1], 0, v[4:5]
	v_ashrrev_i32_e32 v9, 31, v8
	global_load_dwordx4 v[4:7], v[4:5], off nt
	v_lshlrev_b64 v[8:9], 14, v[8:9]
	v_or_b32_e32 v12, 8, v2
	v_lshl_add_u64 v[8:9], v[0:1], 0, v[8:9]
	v_ashrrev_i32_e32 v13, 31, v12
	global_load_dwordx4 v[8:11], v[8:9], off nt
	v_lshlrev_b64 v[12:13], 14, v[12:13]
	v_or_b32_e32 v18, 12, v2
	v_lshl_add_u64 v[12:13], v[0:1], 0, v[12:13]
	v_ashrrev_i32_e32 v19, 31, v18
	global_load_dwordx4 v[12:15], v[12:13], off nt
	v_lshlrev_b64 v[18:19], 14, v[18:19]
	v_or_b32_e32 v22, 16, v2
	v_lshl_add_u64 v[18:19], v[0:1], 0, v[18:19]
	v_ashrrev_i32_e32 v23, 31, v22
	global_load_dwordx4 v[18:21], v[18:19], off nt
	v_lshlrev_b64 v[22:23], 14, v[22:23]
	v_or_b32_e32 v26, 20, v2
	v_lshl_add_u64 v[22:23], v[0:1], 0, v[22:23]
	v_ashrrev_i32_e32 v27, 31, v26
	global_load_dwordx4 v[22:25], v[22:23], off nt
	v_lshlrev_b64 v[26:27], 14, v[26:27]
	v_or_b32_e32 v30, 24, v2
	v_lshl_add_u64 v[26:27], v[0:1], 0, v[26:27]
	v_ashrrev_i32_e32 v31, 31, v30
	global_load_dwordx4 v[26:29], v[26:27], off nt
	v_lshlrev_b64 v[30:31], 14, v[30:31]
	v_or_b32_e32 v46, 28, v2
	v_lshl_add_u64 v[30:31], v[0:1], 0, v[30:31]
	v_ashrrev_i32_e32 v47, 31, v46
	global_load_dwordx4 v[30:33], v[30:31], off nt
	v_lshlrev_b64 v[46:47], 14, v[46:47]
	v_lshl_add_u64 v[46:47], v[0:1], 0, v[46:47]
	global_load_dwordx4 v[46:49], v[46:47], off nt
	v_add_u32_e32 v50, v51, v53
	v_add_u32_e32 v3, 0x410, v50
	s_sub_i32 s0, s12, s0
	s_ashr_i32 s11, s10, 31
	s_waitcnt vmcnt(7)
	ds_write2_b32 v50, v4, v5 offset1:1
	ds_write2_b32 v50, v6, v7 offset0:2 offset1:3
	v_or_b32_e32 v4, 32, v2
	v_ashrrev_i32_e32 v5, 31, v4
	v_lshlrev_b64 v[4:5], 14, v[4:5]
	v_lshl_add_u64 v[4:5], v[0:1], 0, v[4:5]
	s_waitcnt vmcnt(6)
	ds_write2_b32 v3, v8, v9 offset1:1
	v_add_u32_e32 v3, 0x418, v50
	v_or_b32_e32 v8, 36, v2
	ds_write2_b32 v3, v10, v11 offset1:1
	v_add_u32_e32 v3, 0x820, v50
	v_ashrrev_i32_e32 v9, 31, v8
	s_waitcnt vmcnt(5)
	ds_write2_b32 v3, v12, v13 offset1:1
	v_add_u32_e32 v3, 0x828, v50
	global_load_dwordx4 v[4:7], v[4:5], off nt
	v_lshlrev_b64 v[8:9], 14, v[8:9]
	v_or_b32_e32 v12, 40, v2
	ds_write2_b32 v3, v14, v15 offset1:1
	v_add_u32_e32 v3, 0xc30, v50
	v_lshl_add_u64 v[8:9], v[0:1], 0, v[8:9]
	v_ashrrev_i32_e32 v13, 31, v12
	s_waitcnt vmcnt(5)
	ds_write2_b32 v3, v18, v19 offset1:1
	v_add_u32_e32 v3, 0xc38, v50
	global_load_dwordx4 v[8:11], v[8:9], off nt
	v_lshlrev_b64 v[12:13], 14, v[12:13]
	v_or_b32_e32 v18, 44, v2
	ds_write2_b32 v3, v20, v21 offset1:1
	v_add_u32_e32 v3, 0x1040, v50
	v_lshl_add_u64 v[12:13], v[0:1], 0, v[12:13]
	v_ashrrev_i32_e32 v19, 31, v18
	s_waitcnt vmcnt(5)
	ds_write2_b32 v3, v22, v23 offset1:1
	v_add_u32_e32 v3, 0x1048, v50
	global_load_dwordx4 v[12:15], v[12:13], off nt
	v_lshlrev_b64 v[18:19], 14, v[18:19]
	v_or_b32_e32 v22, 48, v2
	ds_write2_b32 v3, v24, v25 offset1:1
	v_add_u32_e32 v3, 0x1450, v50
	v_lshl_add_u64 v[18:19], v[0:1], 0, v[18:19]
	v_ashrrev_i32_e32 v23, 31, v22
	s_waitcnt vmcnt(5)
	ds_write2_b32 v3, v26, v27 offset1:1
	v_add_u32_e32 v3, 0x1458, v50
	global_load_dwordx4 v[18:21], v[18:19], off nt
	v_lshlrev_b64 v[22:23], 14, v[22:23]
	v_or_b32_e32 v26, 52, v2
	ds_write2_b32 v3, v28, v29 offset1:1
	v_add_u32_e32 v3, 0x1860, v50
	v_lshl_add_u64 v[22:23], v[0:1], 0, v[22:23]
	v_ashrrev_i32_e32 v27, 31, v26
	s_waitcnt vmcnt(5)
	ds_write2_b32 v3, v30, v31 offset1:1
	v_add_u32_e32 v3, 0x1868, v50
	global_load_dwordx4 v[22:25], v[22:23], off nt
	v_lshlrev_b64 v[26:27], 14, v[26:27]
	v_or_b32_e32 v30, 56, v2
	ds_write2_b32 v3, v32, v33 offset1:1
	v_add_u32_e32 v3, 0x1c70, v50
	v_lshl_add_u64 v[26:27], v[0:1], 0, v[26:27]
	v_ashrrev_i32_e32 v31, 31, v30
	s_waitcnt vmcnt(5)
	ds_write2_b32 v3, v46, v47 offset1:1
	v_add_u32_e32 v3, 0x1c78, v50
	global_load_dwordx4 v[26:29], v[26:27], off nt
	v_lshlrev_b64 v[30:31], 14, v[30:31]
	v_or_b32_e32 v2, 60, v2
	ds_write2_b32 v3, v48, v49 offset1:1
	v_lshl_add_u64 v[30:31], v[0:1], 0, v[30:31]
	v_ashrrev_i32_e32 v3, 31, v2
	global_load_dwordx4 v[30:33], v[30:31], off nt
	v_lshlrev_b64 v[2:3], 14, v[2:3]
	v_lshl_add_u64 v[0:1], v[0:1], 0, v[2:3]
	global_load_dwordx4 v[0:3], v[0:1], off nt
	v_add_u32_e32 v46, 0x2080, v50
	s_waitcnt vmcnt(7)
	ds_write2_b32 v46, v4, v5 offset1:1
	v_add_u32_e32 v4, 0x2088, v50
	ds_write2_b32 v4, v6, v7 offset1:1
	v_add_u32_e32 v4, 0x2490, v50
	s_waitcnt vmcnt(6)
	ds_write2_b32 v4, v8, v9 offset1:1
	v_add_u32_e32 v4, 0x2498, v50
	ds_write2_b32 v4, v10, v11 offset1:1
	v_add_u32_e32 v4, 0x28a0, v50
	s_waitcnt vmcnt(5)
	ds_write2_b32 v4, v12, v13 offset1:1
	v_add_u32_e32 v4, 0x28a8, v50
	ds_write2_b32 v4, v14, v15 offset1:1
	v_add_u32_e32 v4, 0x2cb0, v50
	s_waitcnt vmcnt(4)
	ds_write2_b32 v4, v18, v19 offset1:1
	v_add_u32_e32 v4, 0x2cb8, v50
	ds_write2_b32 v4, v20, v21 offset1:1
	v_add_u32_e32 v4, 0x30c0, v50
	s_waitcnt vmcnt(3)
	ds_write2_b32 v4, v22, v23 offset1:1
	v_add_u32_e32 v4, 0x30c8, v50
	ds_write2_b32 v4, v24, v25 offset1:1
	v_add_u32_e32 v4, 0x34d0, v50
	s_waitcnt vmcnt(2)
	ds_write2_b32 v4, v26, v27 offset1:1
	v_add_u32_e32 v4, 0x34d8, v50
	ds_write2_b32 v4, v28, v29 offset1:1
	v_add_u32_e32 v4, 0x38e0, v50
	s_waitcnt vmcnt(1)
; __host__ __device__ __forceinline__ size_t blocked_off(int row, int col, int K) { return (((size_t)(row >> 8) * (K >> 6) + (col >> 6)) * 256 + (row & 255)) * 64 + (col & 63); }
; __device__ __forceinline__ unsigned cvt_pk_bf16(float lo, float hi) { const f32x2c_t v = {lo, hi}; return __builtin_bit_cast(unsigned, __builtin_convertvector(v, bf16x2c_t)); }
; #define LAS __attribute__((address_space(3)))
; #define LDS_WAIT() asm volatile("s_waitcnt lgkmcnt(0)" ::: "memory")
; __host__ __device__ __forceinline__ int win_phys_col(int n) { if (!win_rope_tile(n >> 8)) return n; const int cl = n & 255; return (n & ~255) | (cl & 63) | ((cl & 64) << 1) | ((cl & 128) >> 1); }
; template <bool PERMUTE, bool BLOCKED = false>
; __device__ __forceinline__ void cvt_tile64(const float* W, int K, int N, bf16* WT, int ldo, const float* gk, LAS float* scr, int tile, int lane) {
;     ...
;     LDS_WAIT(); asm volatile("" ::: "memory");
;     const int kc = lane & 7, nrow0 = PERMUTE ? win_phys_col(n0) : n0;
; #pragma unroll
;     for (int j = 0; j < 8; ++j) { const int n = (lane >> 3) + 8 * j; const LAS float* s = scr + (8 * kc) * 65 + n;
;         v4u o; o[0] = cvt_pk_bf16(wrnd(s[0 * 65]), wrnd(s[1 * 65])); o[1] = cvt_pk_bf16(wrnd(s[2 * 65]), wrnd(s[3 * 65])); o[2] = cvt_pk_bf16(wrnd(s[4 * 65]), wrnd(s[5 * 65])); o[3] = cvt_pk_bf16(wrnd(s[6 * 65]), wrnd(s[7 * 65]));
;         *(v4u*)(WT + (BLOCKED ? pg8::blocked_off(nrow0 + n, k0 + 8 * kc, K) : (size_t)(nrow0 + n) * ldo + k0 + 8 * kc)) = o; }
;     LDS_WAIT(); asm volatile("" ::: "memory");
	ds_write2_b32 v4, v30, v31 offset1:1
	v_add_u32_e32 v4, 0x38e8, v50
	ds_write2_b32 v4, v32, v33 offset1:1
	v_add_u32_e32 v4, 0x3cf0, v50
	s_waitcnt vmcnt(0)
	ds_write2_b32 v4, v0, v1 offset1:1
	v_add_u32_e32 v0, 0x3cf8, v50
	ds_write2_b32 v0, v2, v3 offset1:1
	s_waitcnt lgkmcnt(0)
	ds_read2_b32 v[8:9], v55 offset1:8
	ds_read2_b32 v[10:11], v55 offset0:65 offset1:73
	ds_read2_b32 v[12:13], v55 offset0:130 offset1:138
	ds_read2_b32 v[14:15], v55 offset0:195 offset1:203
	v_lshl_add_u64 v[0:1], s[10:11], 1, v[44:45]
	s_waitcnt lgkmcnt(3)
	v_add_u32_e32 v2, 0x20000, v8
	s_waitcnt lgkmcnt(2)
	v_add_u32_e32 v3, 0x20000, v10
	v_and_b32_e32 v2, 0xfffc0000, v2
	v_and_b32_e32 v3, 0xfffc0000, v3
	v_cvt_pk_bf16_f32 v4, v2, v3
	s_waitcnt lgkmcnt(1)
	v_add_u32_e32 v2, 0x20000, v12
	s_waitcnt lgkmcnt(0)
	v_add_u32_e32 v3, 0x20000, v14
	v_and_b32_e32 v2, 0xfffc0000, v2
	v_and_b32_e32 v3, 0xfffc0000, v3
	v_cvt_pk_bf16_f32 v5, v2, v3
	v_add_u32_e32 v2, 0x400, v55
	ds_read2_b32 v[18:19], v2 offset0:4 offset1:12
	ds_read2_b32 v[20:21], v2 offset0:69 offset1:77
	ds_read2_b32 v[22:23], v2 offset0:134 offset1:142
	ds_read2_b32 v[24:25], v2 offset0:199 offset1:207
	s_waitcnt lgkmcnt(3)
	v_add_u32_e32 v3, 0x20000, v18
	s_waitcnt lgkmcnt(2)
	v_add_u32_e32 v6, 0x20000, v20
	v_and_b32_e32 v3, 0xfffc0000, v3
	v_and_b32_e32 v6, 0xfffc0000, v6
	v_cvt_pk_bf16_f32 v6, v3, v6
	s_waitcnt lgkmcnt(1)
	v_add_u32_e32 v3, 0x20000, v22
	s_waitcnt lgkmcnt(0)
	v_add_u32_e32 v7, 0x20000, v24
	v_and_b32_e32 v3, 0xfffc0000, v3
	v_and_b32_e32 v7, 0xfffc0000, v7
	v_cvt_pk_bf16_f32 v7, v3, v7
	v_add_u32_e32 v3, s0, v63
	v_add_u32_e32 v26, 0x168000, v3
	v_ashrrev_i32_e32 v27, 31, v26
	v_lshlrev_b64 v[26:27], 13, v[26:27]
	v_lshl_add_u64 v[26:27], v[0:1], 0, v[26:27]
	global_store_dwordx4 v[26:27], v[4:7], off
	v_add_u32_e32 v8, 0x20000, v25
	v_and_b32_e32 v8, 0xfffc0000, v8
	v_add_u32_e32 v4, 0x20000, v9
	v_add_u32_e32 v5, 0x20000, v11
	v_and_b32_e32 v4, 0xfffc0000, v4
	v_and_b32_e32 v5, 0xfffc0000, v5
	v_cvt_pk_bf16_f32 v4, v4, v5
	v_add_u32_e32 v5, 0x20000, v13
	v_add_u32_e32 v6, 0x20000, v15
	v_and_b32_e32 v5, 0xfffc0000, v5
	v_and_b32_e32 v6, 0xfffc0000, v6
	v_cvt_pk_bf16_f32 v5, v5, v6
	v_add_u32_e32 v6, 0x20000, v19
	v_add_u32_e32 v7, 0x20000, v21
	v_and_b32_e32 v6, 0xfffc0000, v6
	v_and_b32_e32 v7, 0xfffc0000, v7
	v_cvt_pk_bf16_f32 v6, v6, v7
	v_add_u32_e32 v7, 0x20000, v23
	v_and_b32_e32 v7, 0xfffc0000, v7
	v_cvt_pk_bf16_f32 v7, v7, v8
	v_add_u32_e32 v8, 0x168008, v3
	v_ashrrev_i32_e32 v9, 31, v8
	v_lshlrev_b64 v[8:9], 13, v[8:9]
	v_lshl_add_u64 v[8:9], v[0:1], 0, v[8:9]
	global_store_dwordx4 v[8:9], v[4:7], off
	ds_read2_b32 v[8:9], v55 offset0:16 offset1:24
	ds_read2_b32 v[10:11], v55 offset0:81 offset1:89
	ds_read2_b32 v[12:13], v55 offset0:146 offset1:154
	ds_read2_b32 v[14:15], v55 offset0:211 offset1:219
	ds_read2_b32 v[18:19], v2 offset0:20 offset1:28
	ds_read2_b32 v[20:21], v2 offset0:85 offset1:93
	s_waitcnt lgkmcnt(5)
	v_add_u32_e32 v4, 0x20000, v8
	s_waitcnt lgkmcnt(4)
	v_add_u32_e32 v5, 0x20000, v10
	v_and_b32_e32 v4, 0xfffc0000, v4
	v_and_b32_e32 v5, 0xfffc0000, v5
	ds_read2_b32 v[22:23], v2 offset0:150 offset1:158
	ds_read2_b32 v[24:25], v2 offset0:215 offset1:223
	v_cvt_pk_bf16_f32 v4, v4, v5
	s_waitcnt lgkmcnt(5)
	v_add_u32_e32 v5, 0x20000, v12
	s_waitcnt lgkmcnt(4)
	v_add_u32_e32 v6, 0x20000, v14
	v_and_b32_e32 v5, 0xfffc0000, v5
	v_and_b32_e32 v6, 0xfffc0000, v6
	v_cvt_pk_bf16_f32 v5, v5, v6
	s_waitcnt lgkmcnt(3)
	v_add_u32_e32 v6, 0x20000, v18
	s_waitcnt lgkmcnt(2)
	v_add_u32_e32 v7, 0x20000, v20
	v_and_b32_e32 v6, 0xfffc0000, v6
	v_and_b32_e32 v7, 0xfffc0000, v7
	v_add_u32_e32 v26, 0x168010, v3
	v_cvt_pk_bf16_f32 v6, v6, v7
	s_waitcnt lgkmcnt(1)
	v_add_u32_e32 v7, 0x20000, v22
	s_waitcnt lgkmcnt(0)
	v_add_u32_e32 v8, 0x20000, v24
	v_ashrrev_i32_e32 v27, 31, v26
	v_and_b32_e32 v7, 0xfffc0000, v7
	v_and_b32_e32 v8, 0xfffc0000, v8
	v_lshlrev_b64 v[26:27], 13, v[26:27]
	v_cvt_pk_bf16_f32 v7, v7, v8
	v_lshl_add_u64 v[26:27], v[0:1], 0, v[26:27]
	global_store_dwordx4 v[26:27], v[4:7], off
	v_add_u32_e32 v8, 0x20000, v25
	v_and_b32_e32 v8, 0xfffc0000, v8
	v_add_u32_e32 v4, 0x20000, v9
	v_add_u32_e32 v5, 0x20000, v11
	v_and_b32_e32 v4, 0xfffc0000, v4
	v_and_b32_e32 v5, 0xfffc0000, v5
	v_cvt_pk_bf16_f32 v4, v4, v5
	v_add_u32_e32 v5, 0x20000, v13
	v_add_u32_e32 v6, 0x20000, v15
	v_and_b32_e32 v5, 0xfffc0000, v5
	v_and_b32_e32 v6, 0xfffc0000, v6
	v_cvt_pk_bf16_f32 v5, v5, v6
	v_add_u32_e32 v6, 0x20000, v19
	v_add_u32_e32 v7, 0x20000, v21
	v_and_b32_e32 v6, 0xfffc0000, v6
	v_and_b32_e32 v7, 0xfffc0000, v7
	v_cvt_pk_bf16_f32 v6, v6, v7
	v_add_u32_e32 v7, 0x20000, v23
	v_and_b32_e32 v7, 0xfffc0000, v7
	v_cvt_pk_bf16_f32 v7, v7, v8
	v_add_u32_e32 v8, 0x168018, v3
	v_ashrrev_i32_e32 v9, 31, v8
	v_lshlrev_b64 v[8:9], 13, v[8:9]
	v_lshl_add_u64 v[8:9], v[0:1], 0, v[8:9]
	global_store_dwordx4 v[8:9], v[4:7], off
	ds_read2_b32 v[8:9], v55 offset0:32 offset1:40
	ds_read2_b32 v[10:11], v55 offset0:97 offset1:105
	ds_read2_b32 v[12:13], v55 offset0:162 offset1:170
	ds_read2_b32 v[14:15], v55 offset0:227 offset1:235
	ds_read2_b32 v[18:19], v2 offset0:36 offset1:44
	ds_read2_b32 v[20:21], v2 offset0:101 offset1:109
	s_waitcnt lgkmcnt(5)
; __host__ __device__ __forceinline__ size_t blocked_off(int row, int col, int K) { return (((size_t)(row >> 8) * (K >> 6) + (col >> 6)) * 256 + (row & 255)) * 64 + (col & 63); }
; __device__ __forceinline__ unsigned cvt_pk_bf16(float lo, float hi) { const f32x2c_t v = {lo, hi}; return __builtin_bit_cast(unsigned, __builtin_convertvector(v, bf16x2c_t)); }
; #define LAS __attribute__((address_space(3)))
; #define LDS_WAIT() asm volatile("s_waitcnt lgkmcnt(0)" ::: "memory")
; __host__ __device__ __forceinline__ int win_phys_col(int n) { if (!win_rope_tile(n >> 8)) return n; const int cl = n & 255; return (n & ~255) | (cl & 63) | ((cl & 64) << 1) | ((cl & 128) >> 1); }
; template <bool PERMUTE, bool BLOCKED = false>
; __device__ __forceinline__ void cvt_tile64(const float* W, int K, int N, bf16* WT, int ldo, const float* gk, LAS float* scr, int tile, int lane) {
;     ...
;     LDS_WAIT(); asm volatile("" ::: "memory");
;     const int kc = lane & 7, nrow0 = PERMUTE ? win_phys_col(n0) : n0;
; #pragma unroll
;     for (int j = 0; j < 8; ++j) { const int n = (lane >> 3) + 8 * j; const LAS float* s = scr + (8 * kc) * 65 + n;
;         v4u o; o[0] = cvt_pk_bf16(wrnd(s[0 * 65]), wrnd(s[1 * 65])); o[1] = cvt_pk_bf16(wrnd(s[2 * 65]), wrnd(s[3 * 65])); o[2] = cvt_pk_bf16(wrnd(s[4 * 65]), wrnd(s[5 * 65])); o[3] = cvt_pk_bf16(wrnd(s[6 * 65]), wrnd(s[7 * 65]));
;         *(v4u*)(WT + (BLOCKED ? pg8::blocked_off(nrow0 + n, k0 + 8 * kc, K) : (size_t)(nrow0 + n) * ldo + k0 + 8 * kc)) = o; }
;     LDS_WAIT(); asm volatile("" ::: "memory");
	v_add_u32_e32 v4, 0x20000, v8
	s_waitcnt lgkmcnt(4)
	v_add_u32_e32 v5, 0x20000, v10
	v_and_b32_e32 v4, 0xfffc0000, v4
	v_and_b32_e32 v5, 0xfffc0000, v5
	ds_read2_b32 v[22:23], v2 offset0:166 offset1:174
	ds_read2_b32 v[24:25], v2 offset0:231 offset1:239
	v_cvt_pk_bf16_f32 v4, v4, v5
	s_waitcnt lgkmcnt(5)
	v_add_u32_e32 v5, 0x20000, v12
	s_waitcnt lgkmcnt(4)
	v_add_u32_e32 v6, 0x20000, v14
	v_and_b32_e32 v5, 0xfffc0000, v5
	v_and_b32_e32 v6, 0xfffc0000, v6
	v_cvt_pk_bf16_f32 v5, v5, v6
	s_waitcnt lgkmcnt(3)
	v_add_u32_e32 v6, 0x20000, v18
	s_waitcnt lgkmcnt(2)
	v_add_u32_e32 v7, 0x20000, v20
	v_and_b32_e32 v6, 0xfffc0000, v6
	v_and_b32_e32 v7, 0xfffc0000, v7
	v_add_u32_e32 v26, 0x168020, v3
	v_cvt_pk_bf16_f32 v6, v6, v7
	s_waitcnt lgkmcnt(1)
	v_add_u32_e32 v7, 0x20000, v22
	s_waitcnt lgkmcnt(0)
	v_add_u32_e32 v8, 0x20000, v24
	v_ashrrev_i32_e32 v27, 31, v26
	v_and_b32_e32 v7, 0xfffc0000, v7
	v_and_b32_e32 v8, 0xfffc0000, v8
	v_lshlrev_b64 v[26:27], 13, v[26:27]
	v_cvt_pk_bf16_f32 v7, v7, v8
	v_lshl_add_u64 v[26:27], v[0:1], 0, v[26:27]
	global_store_dwordx4 v[26:27], v[4:7], off
	v_add_u32_e32 v8, 0x20000, v25
	v_and_b32_e32 v8, 0xfffc0000, v8
	v_add_u32_e32 v4, 0x20000, v9
	v_add_u32_e32 v5, 0x20000, v11
	v_and_b32_e32 v4, 0xfffc0000, v4
	v_and_b32_e32 v5, 0xfffc0000, v5
	v_cvt_pk_bf16_f32 v4, v4, v5
	v_add_u32_e32 v5, 0x20000, v13
	v_add_u32_e32 v6, 0x20000, v15
	v_and_b32_e32 v5, 0xfffc0000, v5
	v_and_b32_e32 v6, 0xfffc0000, v6
	v_cvt_pk_bf16_f32 v5, v5, v6
	v_add_u32_e32 v6, 0x20000, v19
	v_add_u32_e32 v7, 0x20000, v21
	v_and_b32_e32 v6, 0xfffc0000, v6
	v_and_b32_e32 v7, 0xfffc0000, v7
	v_cvt_pk_bf16_f32 v6, v6, v7
	v_add_u32_e32 v7, 0x20000, v23
	v_and_b32_e32 v7, 0xfffc0000, v7
	v_cvt_pk_bf16_f32 v7, v7, v8
	v_add_u32_e32 v8, 0x168028, v3
	v_ashrrev_i32_e32 v9, 31, v8
	v_lshlrev_b64 v[8:9], 13, v[8:9]
	v_lshl_add_u64 v[8:9], v[0:1], 0, v[8:9]
	global_store_dwordx4 v[8:9], v[4:7], off
	ds_read2_b32 v[8:9], v55 offset0:48 offset1:56
	ds_read2_b32 v[10:11], v55 offset0:113 offset1:121
	ds_read2_b32 v[12:13], v55 offset0:178 offset1:186
	ds_read2_b32 v[14:15], v55 offset0:243 offset1:251
	ds_read2_b32 v[18:19], v2 offset0:52 offset1:60
	ds_read2_b32 v[20:21], v2 offset0:117 offset1:125
	s_waitcnt lgkmcnt(5)
	v_add_u32_e32 v4, 0x20000, v8
	s_waitcnt lgkmcnt(4)
	v_add_u32_e32 v5, 0x20000, v10
	v_and_b32_e32 v4, 0xfffc0000, v4
	v_and_b32_e32 v5, 0xfffc0000, v5
	ds_read2_b32 v[22:23], v2 offset0:182 offset1:190
	ds_read2_b32 v[24:25], v2 offset0:247 offset1:255
	v_cvt_pk_bf16_f32 v4, v4, v5
	s_waitcnt lgkmcnt(5)
	v_add_u32_e32 v5, 0x20000, v12
	s_waitcnt lgkmcnt(4)
	v_add_u32_e32 v6, 0x20000, v14
	v_and_b32_e32 v5, 0xfffc0000, v5
	v_and_b32_e32 v6, 0xfffc0000, v6
	v_cvt_pk_bf16_f32 v5, v5, v6
	s_waitcnt lgkmcnt(3)
	v_add_u32_e32 v6, 0x20000, v18
	s_waitcnt lgkmcnt(2)
	v_add_u32_e32 v7, 0x20000, v20
	v_and_b32_e32 v6, 0xfffc0000, v6
	v_and_b32_e32 v7, 0xfffc0000, v7
	v_add_u32_e32 v26, 0x168030, v3
	v_cvt_pk_bf16_f32 v6, v6, v7
	s_waitcnt lgkmcnt(1)
	v_add_u32_e32 v7, 0x20000, v22
	s_waitcnt lgkmcnt(0)
	v_add_u32_e32 v2, 0x20000, v24
	v_ashrrev_i32_e32 v27, 31, v26
	v_and_b32_e32 v7, 0xfffc0000, v7
	v_and_b32_e32 v2, 0xfffc0000, v2
	v_lshlrev_b64 v[26:27], 13, v[26:27]
	v_cvt_pk_bf16_f32 v7, v7, v2
	v_lshl_add_u64 v[26:27], v[0:1], 0, v[26:27]
	global_store_dwordx4 v[26:27], v[4:7], off
	v_add_u32_e32 v2, 0x20000, v9
	v_and_b32_e32 v2, 0xfffc0000, v2
	v_add_u32_e32 v4, 0x20000, v11
	v_and_b32_e32 v4, 0xfffc0000, v4
	v_cvt_pk_bf16_f32 v4, v2, v4
	v_add_u32_e32 v2, 0x20000, v13
	v_add_u32_e32 v5, 0x20000, v15
	v_and_b32_e32 v2, 0xfffc0000, v2
	v_and_b32_e32 v5, 0xfffc0000, v5
	v_cvt_pk_bf16_f32 v5, v2, v5
	v_add_u32_e32 v2, 0x20000, v19
	v_add_u32_e32 v6, 0x20000, v21
	v_and_b32_e32 v2, 0xfffc0000, v2
	v_and_b32_e32 v6, 0xfffc0000, v6
	v_cvt_pk_bf16_f32 v6, v2, v6
	v_add_u32_e32 v2, 0x20000, v23
	v_add_u32_e32 v7, 0x20000, v25
	v_and_b32_e32 v2, 0xfffc0000, v2
	v_and_b32_e32 v7, 0xfffc0000, v7
	v_cvt_pk_bf16_f32 v7, v2, v7
	v_add_u32_e32 v2, 0x168038, v3
	v_ashrrev_i32_e32 v3, 31, v2
	v_lshlrev_b64 v[2:3], 13, v[2:3]
	v_lshl_add_u64 v[0:1], v[0:1], 0, v[2:3]
	global_store_dwordx4 v[0:1], v[4:7], off
	s_waitcnt lgkmcnt(0)
	s_branch .LBB0_668

; __device__ __forceinline__ unsigned hw_slot() { return (unsigned)__builtin_amdgcn_s_getreg((5 << 11) | 4) & 63u; }
; __device__ __forceinline__ int hw_lane() { int l; asm volatile("v_mbcnt_lo_u32_b32 %0, -1, 0\n\tv_mbcnt_hi_u32_b32 %0, -1, %0" : "=v"(l)); return l; }
; #define LAS __attribute__((address_space(3)))
; __device__ __forceinline__ int hw_tid(__attribute__((address_space(3))) unsigned char* lds) {
;     ...
;     const int wv = __builtin_amdgcn_readfirstlane(*(volatile __attribute__((address_space(3))) int*)(lds + HWTAB_OFF + 4u * hw_slot()));
;     return 64 * wv + hw_lane();
; __device__ __forceinline__ void build_rstd(LAS float* tab, const float* part, int pm, int tid) {
;     const f32x4* p = (const f32x4*)(part + ((size_t)pm * 256 + (tid >> 1)) * 64 + (tid & 1) * 32); float s = 0.f;
; #pragma unroll
;     for (int k = 0; k < 8; ++k) { const f32x4 v = p[k]; s += (v[0] + v[1]) + (v[2] + v[3]); }
;     s += __shfl_xor(s, 1);
;     if ((tid & 1) == 0) tab[tid >> 1] = 1.0f / sqrtf(s * (1.f / DM) + NORM_EPS);
;     __syncthreads();
; }
.LBB0_697:
	v_readlane_b32 s0, v253, 62
	v_readlane_b32 s1, v253, 63
	s_andn2_b64 vcc, exec, s[0:1]
	s_nop 0
	v_cndmask_b32_e64 v0, 0, 1, s[0:1]
	s_getreg_b32 s0, hwreg(HW_REG_HW_ID, 0, 6)
	s_lshl_b32 s0, s0, 2
	s_and_b32 s0, s0, 0xfc
	s_add_i32 s0, s0, 0
	s_add_i32 s0, s0, 0x22240
	v_cmp_ne_u32_e64 s[10:11], 1, v0
	v_mov_b32_e32 v0, s0
	ds_read_b32 v0, v0
	s_waitcnt lgkmcnt(0)
	v_readfirstlane_b32 s0, v0
	v_mbcnt_lo_u32_b32 v0, -1, 0
	v_mbcnt_hi_u32_b32 v0, -1, v0
	s_nop 1
	v_lshl_add_u32 v4, s0, 6, v0
	v_readlane_b32 s0, v254, 39
	v_readlane_b32 s1, v254, 40
	s_mov_b32 s6, s0
	s_ashr_i32 s7, s0, 31
	v_writelane_b32 v254, s0, 39
	s_nop 0
	v_ashrrev_i32_e32 v0, 1, v4
	v_writelane_b32 v254, s1, 40
	s_lshl_b64 s[0:1], s[6:7], 16
	v_ashrrev_i32_e32 v1, 31, v0
	s_add_u32 s0, s28, s0
	s_addc_u32 s1, s29, s1
	v_lshlrev_b64 v[2:3], 8, v[0:1]
	s_waitcnt vmcnt(15)
	v_and_b32_e32 v22, 1, v4
	v_lshl_add_u64 v[2:3], s[0:1], 0, v[2:3]
	v_lshlrev_b32_e32 v16, 7, v22
	v_lshl_add_u64 v[14:15], v[2:3], 0, v[16:17]
	global_load_dwordx4 v[2:5], v[14:15], off offset:48 nt
	global_load_dwordx4 v[6:9], v[14:15], off offset:32 nt
	global_load_dwordx4 v[10:13], v[14:15], off offset:16 nt
	global_load_dwordx4 v[18:21], v[14:15], off nt
	v_cmp_eq_u32_e32 vcc, 0, v22
	s_waitcnt vmcnt(3)
	v_add_f32_e32 v2, v2, v3
	s_waitcnt vmcnt(2)
	v_add_f32_e32 v6, v6, v7
	s_waitcnt vmcnt(1)
	v_add_f32_e32 v10, v10, v11
	s_waitcnt vmcnt(0)
	v_add_f32_e32 v1, v18, v19
	v_add_f32_e32 v16, v20, v21
	v_add_f32_e32 v1, v1, v16
	v_add_f32_e32 v11, v12, v13
	v_add_f32_e32 v1, 0, v1
	v_add_f32_e32 v10, v10, v11
	v_add_f32_e32 v7, v8, v9
	v_add_f32_e32 v1, v1, v10
	v_add_f32_e32 v6, v6, v7
	v_add_f32_e32 v3, v4, v5
	v_add_f32_e32 v1, v1, v6
	v_add_f32_e32 v2, v2, v3
	v_add_f32_e32 v1, v1, v2
	global_load_dwordx4 v[2:5], v[14:15], off offset:112 nt
	global_load_dwordx4 v[6:9], v[14:15], off offset:96 nt
	global_load_dwordx4 v[10:13], v[14:15], off offset:80 nt
	global_load_dwordx4 v[18:21], v[14:15], off offset:64 nt
	s_waitcnt vmcnt(3)
	v_add_f32_e32 v2, v2, v3
	s_waitcnt vmcnt(2)
	v_add_f32_e32 v6, v6, v7
	s_waitcnt vmcnt(1)
	v_add_f32_e32 v10, v10, v11
	s_waitcnt vmcnt(0)
	v_add_f32_e32 v14, v18, v19
	v_add_f32_e32 v15, v20, v21
	v_add_f32_e32 v14, v14, v15
	v_add_f32_e32 v11, v12, v13
	v_add_f32_e32 v1, v1, v14
	v_add_f32_e32 v10, v10, v11
	v_add_f32_e32 v7, v8, v9
	v_add_f32_e32 v1, v1, v10
	v_add_f32_e32 v6, v6, v7
	v_add_f32_e32 v3, v4, v5
	v_add_f32_e32 v1, v1, v6
	v_add_f32_e32 v2, v2, v3
	v_add_f32_e32 v1, v1, v2
	ds_bpermute_b32 v2, v244, v1
	s_and_saveexec_b64 s[0:1], vcc
	s_cbranch_execz .LBB0_699
	s_waitcnt lgkmcnt(0)
	v_add_f32_e32 v1, v1, v2
	v_fmamk_f32 v1, v1, 0x39800000, v234
	v_cmp_gt_f32_e32 vcc, s78, v1
	v_mul_f32_e32 v2, 0x4f800000, v1
	v_readlane_b32 s6, v254, 39
	v_cndmask_b32_e32 v1, v1, v2, vcc
	v_sqrt_f32_e32 v2, v1
	s_lshl_b32 s6, s6, 6
	s_and_b32 s6, s6, 0xfffffc00
	v_readlane_b32 s7, v254, 40
	v_add_u32_e32 v3, -1, v2
	v_fma_f32 v4, -v3, v2, v1
	v_cmp_ge_f32_e64 s[14:15], 0, v4
	v_add_u32_e32 v4, 1, v2
	s_add_i32 s6, s6, 0
	v_cndmask_b32_e64 v3, v2, v3, s[14:15]
	v_fma_f32 v2, -v4, v2, v1
	v_cmp_lt_f32_e64 s[14:15], 0, v2
	v_lshl_add_u32 v0, v0, 2, s6
	v_add_u32_e32 v0, 0x20000, v0
	v_cndmask_b32_e64 v2, v3, v4, s[14:15]
	v_mul_f32_e32 v3, 0x37800000, v2
	v_cndmask_b32_e32 v2, v2, v3, vcc
	v_cmp_class_f32_e32 vcc, v1, v229
	s_nop 1
	v_cndmask_b32_e32 v1, v2, v1, vcc
	v_div_scale_f32 v2, s[6:7], v1, v1, 1.0
	v_rcp_f32_e32 v3, v2
	s_nop 0
	v_fma_f32 v4, -v2, v3, 1.0
	v_fmac_f32_e32 v3, v4, v3
	v_div_scale_f32 v4, vcc, 1.0, v1, 1.0
	v_mul_f32_e32 v5, v4, v3
	v_fma_f32 v6, -v2, v5, v4
	v_fmac_f32_e32 v5, v6, v3
	v_fma_f32 v2, -v2, v5, v4
	v_div_fmas_f32 v2, v2, v3, v5
	v_div_fixup_f32 v1, v2, v1, 1.0
	ds_write_b32 v0, v1

; #define LAS __attribute__((address_space(3)))
; template <bool PERMUTE, bool BLOCKED = false>
; __device__ __forceinline__ void cvt_tile64(const float* W, int K, int N, bf16* WT, int ldo, const float* gk, LAS float* scr, int tile, int lane) {
;     ...
;     for (int hh = 0; hh < 2; ++hh) {
;         f32x4 v[8];
; #pragma unroll
;         for (int i = 0; i < 8; ++i) v[i] = *(const f32x4*)(W + (size_t)(k0 + 32 * hh + 4 * i + lk) * N + n0 + ln);
; #pragma unroll
;         for (int i = 0; i < 8; ++i) { const int kk = 32 * hh + 4 * i + lk; const float g = gk ? gk[k0 + kk] : 1.0f; LAS float* d = scr + kk * 65 + ln;
;             d[0] = v[i][0] * g; d[1] = v[i][1] * g; d[2] = v[i][2] * g; d[3] = v[i][3] * g; }
;     }
; __device__ __forceinline__ void cvt_item(const CvtCtx& c, int batch, int wi, LAS float* scr, int wave, int lane) {
;     const int l = batch;
;     if (wi < CVT_OUT) { cvt_tile64<false>(c.w_out + (size_t)l * DM * DM, DM, DM, c.WoutT + (size_t)l * DM * DM, DM, nullptr, scr, 8 * wi + wave, lane); return; } wi -= CVT_OUT;
;     if (wi < CVT_UP) { cvt_tile64<false>(c.w_up + (size_t)l * DM * DFF, DM, DFF, c.WupT + (size_t)l * DFF * DM, DM, c.g_mlp + l * DM, scr, 8 * wi + wave, lane); return; } wi -= CVT_UP;
;     if (wi < CVT_DN) { cvt_tile64<false, true>(c.w_down + (size_t)l * DFF * DM, DFF, DM, c.WdnT + (size_t)l * DM * DFF, 0, nullptr, scr, 8 * wi + wave, lane); return; } wi -= CVT_DN;
.LBB0_723:
	s_addk_i32 s17, 0x100
	s_cmpk_gt_i32 s17, 0x1ff
	s_mov_b64 s[0:1], -1
	s_cbranch_scc0 .LBB0_747
	s_cmpk_gt_u32 s17, 0x9ff
	s_cbranch_scc0 .LBB0_726
	s_add_i32 s0, s13, 0xffffb000
	s_ashr_i32 s1, s0, 31
	s_lshr_b32 s1, s1, 26
	s_add_i32 s0, s0, s1
	s_ashr_i32 s4, s0, 6
	s_add_i32 s5, s12, s16
	s_lshl_b32 s6, s4, 12
	s_andn2_b32 s0, s0, 63
	s_add_i32 s1, s5, 0x28000
	s_sub_i32 s5, s5, s6
	s_add_i32 s18, s5, 0x28000
	v_or_b32_e32 v2, s0, v16
	s_ashr_i32 s19, s18, 31
	v_ashrrev_i32_e32 v3, 31, v2
	v_lshl_add_u64 v[0:1], s[18:19], 2, v[34:35]
	v_lshlrev_b64 v[4:5], 14, v[2:3]
	v_or_b32_e32 v8, 4, v2
	v_lshl_add_u64 v[4:5], v[0:1], 0, v[4:5]
	v_ashrrev_i32_e32 v9, 31, v8
	global_load_dwordx4 v[4:7], v[4:5], off nt
	v_lshlrev_b64 v[8:9], 14, v[8:9]
	v_or_b32_e32 v12, 8, v2
	v_lshl_add_u64 v[8:9], v[0:1], 0, v[8:9]
	v_ashrrev_i32_e32 v13, 31, v12
	global_load_dwordx4 v[8:11], v[8:9], off nt
	v_lshlrev_b64 v[12:13], 14, v[12:13]
	v_or_b32_e32 v18, 12, v2
	v_lshl_add_u64 v[12:13], v[0:1], 0, v[12:13]
	v_ashrrev_i32_e32 v19, 31, v18
	global_load_dwordx4 v[12:15], v[12:13], off nt
	v_lshlrev_b64 v[18:19], 14, v[18:19]
	v_or_b32_e32 v22, 16, v2
	v_lshl_add_u64 v[18:19], v[0:1], 0, v[18:19]
	v_ashrrev_i32_e32 v23, 31, v22
	global_load_dwordx4 v[18:21], v[18:19], off nt
	v_lshlrev_b64 v[22:23], 14, v[22:23]
	v_or_b32_e32 v26, 20, v2
	v_lshl_add_u64 v[22:23], v[0:1], 0, v[22:23]
	v_ashrrev_i32_e32 v27, 31, v26
	global_load_dwordx4 v[22:25], v[22:23], off nt
	v_lshlrev_b64 v[26:27], 14, v[26:27]
	v_or_b32_e32 v30, 24, v2
	v_lshl_add_u64 v[26:27], v[0:1], 0, v[26:27]
	v_ashrrev_i32_e32 v31, 31, v30
	global_load_dwordx4 v[26:29], v[26:27], off nt
	v_lshlrev_b64 v[30:31], 14, v[30:31]
	v_or_b32_e32 v46, 28, v2
	v_lshl_add_u64 v[30:31], v[0:1], 0, v[30:31]
	v_ashrrev_i32_e32 v47, 31, v46
	global_load_dwordx4 v[30:33], v[30:31], off nt
	v_lshlrev_b64 v[46:47], 14, v[46:47]
	v_lshl_add_u64 v[46:47], v[0:1], 0, v[46:47]
	global_load_dwordx4 v[46:49], v[46:47], off nt
	v_add_u32_e32 v50, v51, v53
	v_add_u32_e32 v3, 0x410, v50
	s_ashr_i32 s6, s18, 8
	s_ashr_i32 s7, s6, 31
	s_ashr_i32 s5, s4, 31
	s_lshl_b64 s[6:7], s[6:7], 16
	s_lshl_b64 s[4:5], s[4:5], 8
	s_add_u32 s0, s6, s4
	s_addc_u32 s4, s7, s5
	s_and_b32 s1, s1, 0xc0
	s_waitcnt vmcnt(7)
	ds_write2_b32 v50, v4, v5 offset1:1
	ds_write2_b32 v50, v6, v7 offset0:2 offset1:3
	v_or_b32_e32 v4, 32, v2
	v_ashrrev_i32_e32 v5, 31, v4
	v_lshlrev_b64 v[4:5], 14, v[4:5]
	v_lshl_add_u64 v[4:5], v[0:1], 0, v[4:5]
	s_waitcnt vmcnt(6)
	ds_write2_b32 v3, v8, v9 offset1:1
	v_add_u32_e32 v3, 0x418, v50
	v_or_b32_e32 v8, 36, v2
	ds_write2_b32 v3, v10, v11 offset1:1
	v_add_u32_e32 v3, 0x820, v50
	v_ashrrev_i32_e32 v9, 31, v8
	s_waitcnt vmcnt(5)
	ds_write2_b32 v3, v12, v13 offset1:1
	v_add_u32_e32 v3, 0x828, v50
	global_load_dwordx4 v[4:7], v[4:5], off nt
	v_lshlrev_b64 v[8:9], 14, v[8:9]
	v_or_b32_e32 v12, 40, v2
	ds_write2_b32 v3, v14, v15 offset1:1
	v_add_u32_e32 v3, 0xc30, v50
	v_lshl_add_u64 v[8:9], v[0:1], 0, v[8:9]
	v_ashrrev_i32_e32 v13, 31, v12
	s_waitcnt vmcnt(5)
	ds_write2_b32 v3, v18, v19 offset1:1
	v_add_u32_e32 v3, 0xc38, v50
	global_load_dwordx4 v[8:11], v[8:9], off nt
	v_lshlrev_b64 v[12:13], 14, v[12:13]
	v_or_b32_e32 v18, 44, v2
	ds_write2_b32 v3, v20, v21 offset1:1
	v_add_u32_e32 v3, 0x1040, v50
	v_lshl_add_u64 v[12:13], v[0:1], 0, v[12:13]
	v_ashrrev_i32_e32 v19, 31, v18
	s_waitcnt vmcnt(5)
	ds_write2_b32 v3, v22, v23 offset1:1
	v_add_u32_e32 v3, 0x1048, v50
	global_load_dwordx4 v[12:15], v[12:13], off nt
	v_lshlrev_b64 v[18:19], 14, v[18:19]
	v_or_b32_e32 v22, 48, v2
	ds_write2_b32 v3, v24, v25 offset1:1
	v_add_u32_e32 v3, 0x1450, v50
	v_lshl_add_u64 v[18:19], v[0:1], 0, v[18:19]
	v_ashrrev_i32_e32 v23, 31, v22
	s_waitcnt vmcnt(5)
	ds_write2_b32 v3, v26, v27 offset1:1
	v_add_u32_e32 v3, 0x1458, v50
	global_load_dwordx4 v[18:21], v[18:19], off nt
	v_lshlrev_b64 v[22:23], 14, v[22:23]
	v_or_b32_e32 v26, 52, v2
	ds_write2_b32 v3, v28, v29 offset1:1
	v_add_u32_e32 v3, 0x1860, v50
	v_lshl_add_u64 v[22:23], v[0:1], 0, v[22:23]
	v_ashrrev_i32_e32 v27, 31, v26
	s_waitcnt vmcnt(5)
	ds_write2_b32 v3, v30, v31 offset1:1
	v_add_u32_e32 v3, 0x1868, v50
	global_load_dwordx4 v[22:25], v[22:23], off nt
	v_lshlrev_b64 v[26:27], 14, v[26:27]
	v_or_b32_e32 v30, 56, v2
	ds_write2_b32 v3, v32, v33 offset1:1
	v_add_u32_e32 v3, 0x1c70, v50
	v_lshl_add_u64 v[26:27], v[0:1], 0, v[26:27]
	v_ashrrev_i32_e32 v31, 31, v30
	s_waitcnt vmcnt(5)
	ds_write2_b32 v3, v46, v47 offset1:1
	v_add_u32_e32 v3, 0x1c78, v50
	global_load_dwordx4 v[26:29], v[26:27], off nt
	v_lshlrev_b64 v[30:31], 14, v[30:31]
	v_or_b32_e32 v2, 60, v2
	ds_write2_b32 v3, v48, v49 offset1:1
	v_lshl_add_u64 v[30:31], v[0:1], 0, v[30:31]
	v_ashrrev_i32_e32 v3, 31, v2
	global_load_dwordx4 v[30:33], v[30:31], off nt
	v_lshlrev_b64 v[2:3], 14, v[2:3]
	v_lshl_add_u64 v[0:1], v[0:1], 0, v[2:3]
	global_load_dwordx4 v[0:3], v[0:1], off nt
	v_add_u32_e32 v46, 0x2080, v50
	s_waitcnt vmcnt(7)
	ds_write2_b32 v46, v4, v5 offset1:1
	v_add_u32_e32 v4, 0x2088, v50
	ds_write2_b32 v4, v6, v7 offset1:1
	v_add_u32_e32 v4, 0x2490, v50
	s_waitcnt vmcnt(6)
	ds_write2_b32 v4, v8, v9 offset1:1
	v_add_u32_e32 v4, 0x2498, v50
	ds_write2_b32 v4, v10, v11 offset1:1
	v_add_u32_e32 v4, 0x28a0, v50
	s_waitcnt vmcnt(5)
	ds_write2_b32 v4, v12, v13 offset1:1
	v_add_u32_e32 v4, 0x28a8, v50
	ds_write2_b32 v4, v14, v15 offset1:1
	v_add_u32_e32 v4, 0x2cb0, v50
	s_waitcnt vmcnt(4)
	ds_write2_b32 v4, v18, v19 offset1:1
	v_add_u32_e32 v4, 0x2cb8, v50
	ds_write2_b32 v4, v20, v21 offset1:1
	v_add_u32_e32 v4, 0x30c0, v50
	s_waitcnt vmcnt(3)
; __host__ __device__ __forceinline__ size_t blocked_off(int row, int col, int K) { return (((size_t)(row >> 8) * (K >> 6) + (col >> 6)) * 256 + (row & 255)) * 64 + (col & 63); }
; __device__ __forceinline__ unsigned cvt_pk_bf16(float lo, float hi) { const f32x2c_t v = {lo, hi}; return __builtin_bit_cast(unsigned, __builtin_convertvector(v, bf16x2c_t)); }
; #define LAS __attribute__((address_space(3)))
; #define LDS_WAIT() asm volatile("s_waitcnt lgkmcnt(0)" ::: "memory")
; __host__ __device__ __forceinline__ int win_phys_col(int n) { if (!win_rope_tile(n >> 8)) return n; const int cl = n & 255; return (n & ~255) | (cl & 63) | ((cl & 64) << 1) | ((cl & 128) >> 1); }
; template <bool PERMUTE, bool BLOCKED = false>
; __device__ __forceinline__ void cvt_tile64(const float* W, int K, int N, bf16* WT, int ldo, const float* gk, LAS float* scr, int tile, int lane) {
;     ...
;     LDS_WAIT(); asm volatile("" ::: "memory");
;     const int kc = lane & 7, nrow0 = PERMUTE ? win_phys_col(n0) : n0;
; #pragma unroll
;     for (int j = 0; j < 8; ++j) { const int n = (lane >> 3) + 8 * j; const LAS float* s = scr + (8 * kc) * 65 + n;
;         v4u o; o[0] = cvt_pk_bf16(wrnd(s[0 * 65]), wrnd(s[1 * 65])); o[1] = cvt_pk_bf16(wrnd(s[2 * 65]), wrnd(s[3 * 65])); o[2] = cvt_pk_bf16(wrnd(s[4 * 65]), wrnd(s[5 * 65])); o[3] = cvt_pk_bf16(wrnd(s[6 * 65]), wrnd(s[7 * 65]));
;         *(v4u*)(WT + (BLOCKED ? pg8::blocked_off(nrow0 + n, k0 + 8 * kc, K) : (size_t)(nrow0 + n) * ldo + k0 + 8 * kc)) = o; }
	ds_write2_b32 v4, v22, v23 offset1:1
	v_add_u32_e32 v4, 0x30c8, v50
	ds_write2_b32 v4, v24, v25 offset1:1
	v_add_u32_e32 v4, 0x34d0, v50
	s_waitcnt vmcnt(2)
	ds_write2_b32 v4, v26, v27 offset1:1
	v_add_u32_e32 v4, 0x34d8, v50
	ds_write2_b32 v4, v28, v29 offset1:1
	v_add_u32_e32 v4, 0x38e0, v50
	s_waitcnt vmcnt(1)
	ds_write2_b32 v4, v30, v31 offset1:1
	v_add_u32_e32 v4, 0x38e8, v50
	ds_write2_b32 v4, v32, v33 offset1:1
	v_add_u32_e32 v4, 0x3cf0, v50
	s_waitcnt vmcnt(0)
	ds_write2_b32 v4, v0, v1 offset1:1
	v_add_u32_e32 v0, 0x3cf8, v50
	ds_write2_b32 v0, v2, v3 offset1:1
	s_waitcnt lgkmcnt(0)
	ds_read2_b32 v[2:3], v55 offset1:8
	ds_read2_b32 v[8:9], v55 offset0:65 offset1:73
	ds_read2_b32 v[10:11], v55 offset0:130 offset1:138
	ds_read2_b32 v[12:13], v55 offset0:195 offset1:203
	s_waitcnt lgkmcnt(3)
	v_add_u32_e32 v0, 0x20000, v2
	v_add_u32_e32 v2, 0x400, v55
	ds_read2_b32 v[14:15], v2 offset0:4 offset1:12
	ds_read2_b32 v[18:19], v2 offset0:69 offset1:77
	s_waitcnt lgkmcnt(4)
	v_add_u32_e32 v1, 0x20000, v8
	v_and_b32_e32 v0, 0xfffc0000, v0
	v_and_b32_e32 v1, 0xfffc0000, v1
	ds_read2_b32 v[20:21], v2 offset0:134 offset1:142
	ds_read2_b32 v[22:23], v2 offset0:199 offset1:207
	v_cvt_pk_bf16_f32 v4, v0, v1
	s_waitcnt lgkmcnt(5)
	v_add_u32_e32 v0, 0x20000, v10
	s_waitcnt lgkmcnt(4)
	v_add_u32_e32 v1, 0x20000, v12
	v_and_b32_e32 v0, 0xfffc0000, v0
	v_and_b32_e32 v1, 0xfffc0000, v1
	v_cvt_pk_bf16_f32 v5, v0, v1
	s_waitcnt lgkmcnt(3)
	v_add_u32_e32 v0, 0x20000, v14
	s_waitcnt lgkmcnt(2)
	v_add_u32_e32 v1, 0x20000, v18
	v_and_b32_e32 v0, 0xfffc0000, v0
	v_and_b32_e32 v1, 0xfffc0000, v1
	v_cvt_pk_bf16_f32 v6, v0, v1
	s_waitcnt lgkmcnt(1)
	v_add_u32_e32 v0, 0x20000, v20
	s_waitcnt lgkmcnt(0)
	v_add_u32_e32 v1, 0x20000, v22
	v_and_b32_e32 v0, 0xfffc0000, v0
	v_and_b32_e32 v1, 0xfffc0000, v1
	v_cvt_pk_bf16_f32 v7, v0, v1
	v_or_b32_e32 v0, s1, v54
	v_or_b32_e32 v0, s0, v0
	v_mov_b32_e32 v1, s4
	v_lshlrev_b64 v[24:25], 7, v[0:1]
	v_add_u32_e32 v0, 0x20000, v3
	v_add_u32_e32 v3, 0x20000, v9
	v_lshl_add_u64 v[24:25], v[36:37], 0, v[24:25]
	v_and_b32_e32 v0, 0xfffc0000, v0
	v_and_b32_e32 v3, 0xfffc0000, v3
	global_store_dwordx4 v[24:25], v[4:7], off
	ds_read2_b32 v[24:25], v2 offset0:215 offset1:223
	s_nop 0
	v_cvt_pk_bf16_f32 v4, v0, v3
	v_add_u32_e32 v0, 0x20000, v11
	v_add_u32_e32 v3, 0x20000, v13
	v_and_b32_e32 v0, 0xfffc0000, v0
	v_and_b32_e32 v3, 0xfffc0000, v3
	v_cvt_pk_bf16_f32 v5, v0, v3
	v_add_u32_e32 v0, 0x20000, v15
	v_add_u32_e32 v3, 0x20000, v19
	v_and_b32_e32 v0, 0xfffc0000, v0
	v_and_b32_e32 v3, 0xfffc0000, v3
	v_cvt_pk_bf16_f32 v6, v0, v3
	v_add_u32_e32 v0, 0x20000, v21
	v_add_u32_e32 v3, 0x20000, v23
	v_and_b32_e32 v0, 0xfffc0000, v0
	v_and_b32_e32 v3, 0xfffc0000, v3
	v_cvt_pk_bf16_f32 v7, v0, v3
	v_or_b32_e32 v0, s1, v56
	v_or_b32_e32 v0, s0, v0
	v_lshlrev_b64 v[8:9], 7, v[0:1]
	v_lshl_add_u64 v[8:9], v[36:37], 0, v[8:9]
	global_store_dwordx4 v[8:9], v[4:7], off
	ds_read2_b32 v[8:9], v55 offset0:16 offset1:24
	ds_read2_b32 v[10:11], v55 offset0:81 offset1:89
	ds_read2_b32 v[12:13], v55 offset0:146 offset1:154
	ds_read2_b32 v[14:15], v55 offset0:211 offset1:219
	ds_read2_b32 v[18:19], v2 offset0:20 offset1:28
	ds_read2_b32 v[20:21], v2 offset0:85 offset1:93
	s_waitcnt lgkmcnt(5)
	v_add_u32_e32 v0, 0x20000, v8
	s_waitcnt lgkmcnt(4)
	v_add_u32_e32 v3, 0x20000, v10
	v_and_b32_e32 v0, 0xfffc0000, v0
	v_and_b32_e32 v3, 0xfffc0000, v3
	ds_read2_b32 v[22:23], v2 offset0:150 offset1:158
	v_cvt_pk_bf16_f32 v4, v0, v3
	s_waitcnt lgkmcnt(4)
	v_add_u32_e32 v0, 0x20000, v12
	s_waitcnt lgkmcnt(3)
	v_add_u32_e32 v3, 0x20000, v14
	v_and_b32_e32 v0, 0xfffc0000, v0
	v_and_b32_e32 v3, 0xfffc0000, v3
	v_cvt_pk_bf16_f32 v5, v0, v3
	s_waitcnt lgkmcnt(2)
	v_add_u32_e32 v0, 0x20000, v18
	s_waitcnt lgkmcnt(1)
	v_add_u32_e32 v3, 0x20000, v20
	v_and_b32_e32 v0, 0xfffc0000, v0
	v_and_b32_e32 v3, 0xfffc0000, v3
	v_cvt_pk_bf16_f32 v6, v0, v3
	s_waitcnt lgkmcnt(0)
	v_add_u32_e32 v0, 0x20000, v22
	v_add_u32_e32 v3, 0x20000, v24
	v_and_b32_e32 v0, 0xfffc0000, v0
	v_and_b32_e32 v3, 0xfffc0000, v3
	v_cvt_pk_bf16_f32 v7, v0, v3
	v_or_b32_e32 v0, s1, v57
	v_or_b32_e32 v0, s0, v0
	v_lshlrev_b64 v[26:27], 7, v[0:1]
	v_add_u32_e32 v0, 0x20000, v9
	v_add_u32_e32 v3, 0x20000, v11
	v_lshl_add_u64 v[26:27], v[36:37], 0, v[26:27]
	v_and_b32_e32 v0, 0xfffc0000, v0
	v_and_b32_e32 v3, 0xfffc0000, v3
	global_store_dwordx4 v[26:27], v[4:7], off
	ds_read2_b32 v[10:11], v55 offset0:97 offset1:105
	s_nop 0
	v_cvt_pk_bf16_f32 v4, v0, v3
	v_add_u32_e32 v0, 0x20000, v13
	v_add_u32_e32 v3, 0x20000, v15
	v_and_b32_e32 v0, 0xfffc0000, v0
	v_and_b32_e32 v3, 0xfffc0000, v3
	v_cvt_pk_bf16_f32 v5, v0, v3
	v_add_u32_e32 v0, 0x20000, v19
	v_add_u32_e32 v3, 0x20000, v21
	v_and_b32_e32 v0, 0xfffc0000, v0
	v_and_b32_e32 v3, 0xfffc0000, v3
	v_cvt_pk_bf16_f32 v6, v0, v3
	v_add_u32_e32 v0, 0x20000, v23
	v_add_u32_e32 v3, 0x20000, v25
	v_and_b32_e32 v0, 0xfffc0000, v0
	v_and_b32_e32 v3, 0xfffc0000, v3
	v_cvt_pk_bf16_f32 v7, v0, v3
	v_or_b32_e32 v0, s1, v58
	v_or_b32_e32 v0, s0, v0
	v_lshlrev_b64 v[8:9], 7, v[0:1]
	v_lshl_add_u64 v[8:9], v[36:37], 0, v[8:9]
	global_store_dwordx4 v[8:9], v[4:7], off
	ds_read2_b32 v[8:9], v55 offset0:32 offset1:40
	ds_read2_b32 v[12:13], v55 offset0:162 offset1:170
	ds_read2_b32 v[14:15], v55 offset0:227 offset1:235
	ds_read2_b32 v[18:19], v2 offset0:36 offset1:44
	ds_read2_b32 v[20:21], v2 offset0:101 offset1:109
	s_waitcnt lgkmcnt(4)
	v_add_u32_e32 v0, 0x20000, v8
	v_add_u32_e32 v3, 0x20000, v10
	v_and_b32_e32 v0, 0xfffc0000, v0
	v_and_b32_e32 v3, 0xfffc0000, v3
	ds_read2_b32 v[22:23], v2 offset0:166 offset1:174
	ds_read2_b32 v[24:25], v2 offset0:231 offset1:239
	v_cvt_pk_bf16_f32 v4, v0, v3
	s_waitcnt lgkmcnt(5)
; __host__ __device__ __forceinline__ size_t blocked_off(int row, int col, int K) { return (((size_t)(row >> 8) * (K >> 6) + (col >> 6)) * 256 + (row & 255)) * 64 + (col & 63); }
; __device__ __forceinline__ unsigned cvt_pk_bf16(float lo, float hi) { const f32x2c_t v = {lo, hi}; return __builtin_bit_cast(unsigned, __builtin_convertvector(v, bf16x2c_t)); }
; #define LAS __attribute__((address_space(3)))
; #define LDS_WAIT() asm volatile("s_waitcnt lgkmcnt(0)" ::: "memory")
; __host__ __device__ __forceinline__ int win_phys_col(int n) { if (!win_rope_tile(n >> 8)) return n; const int cl = n & 255; return (n & ~255) | (cl & 63) | ((cl & 64) << 1) | ((cl & 128) >> 1); }
; template <bool PERMUTE, bool BLOCKED = false>
; __device__ __forceinline__ void cvt_tile64(const float* W, int K, int N, bf16* WT, int ldo, const float* gk, LAS float* scr, int tile, int lane) {
;     ...
;     for (int hh = 0; hh < 2; ++hh) {
;         f32x4 v[8];
; #pragma unroll
;         for (int i = 0; i < 8; ++i) v[i] = *(const f32x4*)(W + (size_t)(k0 + 32 * hh + 4 * i + lk) * N + n0 + ln);
; #pragma unroll
;         for (int i = 0; i < 8; ++i) { const int kk = 32 * hh + 4 * i + lk; const float g = gk ? gk[k0 + kk] : 1.0f; LAS float* d = scr + kk * 65 + ln;
;             d[0] = v[i][0] * g; d[1] = v[i][1] * g; d[2] = v[i][2] * g; d[3] = v[i][3] * g; }
;     }
;     ...
;     LDS_WAIT(); asm volatile("" ::: "memory");
;     const int kc = lane & 7, nrow0 = PERMUTE ? win_phys_col(n0) : n0;
; #pragma unroll
;     for (int j = 0; j < 8; ++j) { const int n = (lane >> 3) + 8 * j; const LAS float* s = scr + (8 * kc) * 65 + n;
;         v4u o; o[0] = cvt_pk_bf16(wrnd(s[0 * 65]), wrnd(s[1 * 65])); o[1] = cvt_pk_bf16(wrnd(s[2 * 65]), wrnd(s[3 * 65])); o[2] = cvt_pk_bf16(wrnd(s[4 * 65]), wrnd(s[5 * 65])); o[3] = cvt_pk_bf16(wrnd(s[6 * 65]), wrnd(s[7 * 65]));
;         *(v4u*)(WT + (BLOCKED ? pg8::blocked_off(nrow0 + n, k0 + 8 * kc, K) : (size_t)(nrow0 + n) * ldo + k0 + 8 * kc)) = o; }
	v_add_u32_e32 v0, 0x20000, v12
	s_waitcnt lgkmcnt(4)
	v_add_u32_e32 v3, 0x20000, v14
	v_and_b32_e32 v0, 0xfffc0000, v0
	v_and_b32_e32 v3, 0xfffc0000, v3
	v_cvt_pk_bf16_f32 v5, v0, v3
	s_waitcnt lgkmcnt(3)
	v_add_u32_e32 v0, 0x20000, v18
	s_waitcnt lgkmcnt(2)
	v_add_u32_e32 v3, 0x20000, v20
	v_and_b32_e32 v0, 0xfffc0000, v0
	v_and_b32_e32 v3, 0xfffc0000, v3
	v_cvt_pk_bf16_f32 v6, v0, v3
	s_waitcnt lgkmcnt(1)
	v_add_u32_e32 v0, 0x20000, v22
	s_waitcnt lgkmcnt(0)
	v_add_u32_e32 v3, 0x20000, v24
	v_and_b32_e32 v0, 0xfffc0000, v0
	v_and_b32_e32 v3, 0xfffc0000, v3
	v_cvt_pk_bf16_f32 v7, v0, v3
	v_or_b32_e32 v0, s1, v59
	v_or_b32_e32 v0, s0, v0
	v_lshlrev_b64 v[26:27], 7, v[0:1]
	v_add_u32_e32 v0, 0x20000, v9
	v_add_u32_e32 v3, 0x20000, v11
	v_lshl_add_u64 v[26:27], v[36:37], 0, v[26:27]
	v_and_b32_e32 v0, 0xfffc0000, v0
	v_and_b32_e32 v3, 0xfffc0000, v3
	global_store_dwordx4 v[26:27], v[4:7], off
	ds_read2_b32 v[10:11], v55 offset0:113 offset1:121
	s_nop 0
	v_cvt_pk_bf16_f32 v4, v0, v3
	v_add_u32_e32 v0, 0x20000, v13
	v_add_u32_e32 v3, 0x20000, v15
	v_and_b32_e32 v0, 0xfffc0000, v0
	v_and_b32_e32 v3, 0xfffc0000, v3
	v_cvt_pk_bf16_f32 v5, v0, v3
	v_add_u32_e32 v0, 0x20000, v19
	v_add_u32_e32 v3, 0x20000, v21
	v_and_b32_e32 v0, 0xfffc0000, v0
	v_and_b32_e32 v3, 0xfffc0000, v3
	v_cvt_pk_bf16_f32 v6, v0, v3
	v_add_u32_e32 v0, 0x20000, v23
	v_add_u32_e32 v3, 0x20000, v25
	v_and_b32_e32 v0, 0xfffc0000, v0
	v_and_b32_e32 v3, 0xfffc0000, v3
	v_cvt_pk_bf16_f32 v7, v0, v3
	v_or_b32_e32 v0, s1, v60
	v_or_b32_e32 v0, s0, v0
	v_lshlrev_b64 v[8:9], 7, v[0:1]
	v_lshl_add_u64 v[8:9], v[36:37], 0, v[8:9]
	global_store_dwordx4 v[8:9], v[4:7], off
	ds_read2_b32 v[8:9], v55 offset0:48 offset1:56
	ds_read2_b32 v[12:13], v55 offset0:178 offset1:186
	ds_read2_b32 v[14:15], v55 offset0:243 offset1:251
	ds_read2_b32 v[18:19], v2 offset0:52 offset1:60
	ds_read2_b32 v[20:21], v2 offset0:117 offset1:125
	s_waitcnt lgkmcnt(4)
	v_add_u32_e32 v0, 0x20000, v8
	v_add_u32_e32 v3, 0x20000, v10
	v_and_b32_e32 v0, 0xfffc0000, v0
	v_and_b32_e32 v3, 0xfffc0000, v3
	ds_read2_b32 v[22:23], v2 offset0:182 offset1:190
	ds_read2_b32 v[24:25], v2 offset0:247 offset1:255
	v_cvt_pk_bf16_f32 v4, v0, v3
	s_waitcnt lgkmcnt(5)
	v_add_u32_e32 v0, 0x20000, v12
	s_waitcnt lgkmcnt(4)
	v_add_u32_e32 v3, 0x20000, v14
	v_and_b32_e32 v0, 0xfffc0000, v0
	v_and_b32_e32 v3, 0xfffc0000, v3
	v_cvt_pk_bf16_f32 v5, v0, v3
	s_waitcnt lgkmcnt(3)
	v_add_u32_e32 v0, 0x20000, v18
	s_waitcnt lgkmcnt(2)
	v_add_u32_e32 v3, 0x20000, v20
	v_and_b32_e32 v0, 0xfffc0000, v0
	v_and_b32_e32 v3, 0xfffc0000, v3
	v_cvt_pk_bf16_f32 v6, v0, v3
	s_waitcnt lgkmcnt(1)
	v_add_u32_e32 v0, 0x20000, v22
	s_waitcnt lgkmcnt(0)
	v_add_u32_e32 v2, 0x20000, v24
	v_and_b32_e32 v0, 0xfffc0000, v0
	v_and_b32_e32 v2, 0xfffc0000, v2
	v_cvt_pk_bf16_f32 v7, v0, v2
	v_or_b32_e32 v0, s1, v61
	v_or_b32_e32 v0, s0, v0
	v_lshlrev_b64 v[2:3], 7, v[0:1]
	v_lshl_add_u64 v[2:3], v[36:37], 0, v[2:3]
	global_store_dwordx4 v[2:3], v[4:7], off
	v_add_u32_e32 v0, 0x20000, v9
	v_add_u32_e32 v2, 0x20000, v11
	v_and_b32_e32 v0, 0xfffc0000, v0
	v_and_b32_e32 v2, 0xfffc0000, v2
	v_cvt_pk_bf16_f32 v2, v0, v2
	v_add_u32_e32 v0, 0x20000, v13
	v_add_u32_e32 v3, 0x20000, v15
	v_and_b32_e32 v0, 0xfffc0000, v0
	v_and_b32_e32 v3, 0xfffc0000, v3
	v_cvt_pk_bf16_f32 v3, v0, v3
	v_add_u32_e32 v0, 0x20000, v19
	v_add_u32_e32 v4, 0x20000, v21
	v_and_b32_e32 v0, 0xfffc0000, v0
	v_and_b32_e32 v4, 0xfffc0000, v4
	v_cvt_pk_bf16_f32 v4, v0, v4
	v_add_u32_e32 v0, 0x20000, v23
	v_add_u32_e32 v5, 0x20000, v25
	v_and_b32_e32 v0, 0xfffc0000, v0
	v_and_b32_e32 v5, 0xfffc0000, v5
	v_cvt_pk_bf16_f32 v5, v0, v5
	v_or_b32_e32 v0, s1, v62
	v_or_b32_e32 v0, s0, v0
	v_lshlrev_b64 v[0:1], 7, v[0:1]
	v_lshl_add_u64 v[0:1], v[36:37], 0, v[0:1]
	global_store_dwordx4 v[0:1], v[2:5], off
	s_waitcnt lgkmcnt(0)
	s_mov_b64 s[0:1], 0
.LBB0_726:
	s_andn2_b64 vcc, exec, s[0:1]
	s_cbranch_vccnz .LBB0_746
	s_add_i32 s0, s13, 0xfffff000
	s_ashr_i32 s1, s0, 31
	s_lshr_b32 s1, s1, 24
	s_add_i32 s0, s0, s1
	s_ashr_i32 s0, s0, 8
	s_lshl_b32 s18, s0, 6
	s_lshl_b32 s20, s0, 14
	s_add_i32 s0, s12, s16
	s_sub_i32 s0, s0, s20
	v_or_b32_e32 v48, s18, v16
	s_add_i32 s0, s0, 0x128000
	v_or_b32_e32 v2, 4, v48
	s_ashr_i32 s1, s0, 31
	v_ashrrev_i32_e32 v49, 31, v48
	v_ashrrev_i32_e32 v3, 31, v2
	v_lshl_add_u64 v[46:47], s[0:1], 2, v[38:39]
	v_lshlrev_b64 v[0:1], 16, v[48:49]
	v_lshlrev_b64 v[2:3], 16, v[2:3]
	v_lshl_add_u64 v[0:1], v[46:47], 0, v[0:1]
	v_lshl_add_u64 v[2:3], v[46:47], 0, v[2:3]
	global_load_dwordx4 v[30:33], v[0:1], off nt
	global_load_dwordx4 v[26:29], v[2:3], off nt
	v_or_b32_e32 v0, 8, v48
	v_or_b32_e32 v2, 12, v48
	v_ashrrev_i32_e32 v1, 31, v0
	v_ashrrev_i32_e32 v3, 31, v2
	v_lshlrev_b64 v[0:1], 16, v[0:1]
	v_lshlrev_b64 v[2:3], 16, v[2:3]
	v_lshl_add_u64 v[0:1], v[46:47], 0, v[0:1]
	v_lshl_add_u64 v[2:3], v[46:47], 0, v[2:3]
	global_load_dwordx4 v[22:25], v[0:1], off nt
	global_load_dwordx4 v[18:21], v[2:3], off nt
	v_or_b32_e32 v0, 16, v48
	v_or_b32_e32 v2, 20, v48
	v_ashrrev_i32_e32 v1, 31, v0
	v_ashrrev_i32_e32 v3, 31, v2
	v_lshlrev_b64 v[0:1], 16, v[0:1]
	v_lshlrev_b64 v[2:3], 16, v[2:3]
	v_lshl_add_u64 v[0:1], v[46:47], 0, v[0:1]
	v_lshl_add_u64 v[2:3], v[46:47], 0, v[2:3]
	global_load_dwordx4 v[12:15], v[0:1], off nt
	global_load_dwordx4 v[8:11], v[2:3], off nt
	v_or_b32_e32 v0, 24, v48
	v_or_b32_e32 v2, 28, v48
	v_ashrrev_i32_e32 v1, 31, v0
	v_ashrrev_i32_e32 v3, 31, v2
	v_lshlrev_b64 v[0:1], 16, v[0:1]
	v_lshlrev_b64 v[2:3], 16, v[2:3]
	v_lshl_add_u64 v[0:1], v[46:47], 0, v[0:1]
	v_lshl_add_u64 v[2:3], v[46:47], 0, v[2:3]
	global_load_dwordx4 v[4:7], v[0:1], off nt
	s_nop 0
	global_load_dwordx4 v[0:3], v[2:3], off nt
	v_cndmask_b32_e64 v52, 0, 1, s[14:15]
	v_mov_b32_e32 v50, 1.0
	v_cmp_ne_u32_e64 s[4:5], 1, v52
	s_andn2_b64 vcc, exec, s[14:15]
	v_mov_b32_e32 v52, 1.0
	s_cbranch_vccnz .LBB0_729
	v_lshl_add_u64 v[64:65], v[48:49], 2, s[10:11]
	global_load_dword v110, v[64:65], off offset:16
	global_load_dword v124, v[64:65], off offset:32
	global_load_dword v125, v[64:65], off offset:48
	global_load_dword v126, v[64:65], off offset:64
	global_load_dword v127, v[64:65], off offset:80
	global_load_dword v178, v[64:65], off offset:96
	global_load_dword v179, v[64:65], off offset:112
	global_load_dword v180, v[64:65], off offset:128
	global_load_dword v181, v[64:65], off offset:144
	global_load_dword v182, v[64:65], off offset:160
	global_load_dword v183, v[64:65], off offset:176
	global_load_dword v184, v[64:65], off offset:192
	global_load_dword v185, v[64:65], off offset:208
	global_load_dword v186, v[64:65], off offset:224
	global_load_dword v187, v[64:65], off offset:240
	global_load_dword v52, v[64:65], off
	s_waitcnt vmcnt(0)
	s_ashr_i32 s19, s18, 31
	v_lshl_add_u64 v[64:65], s[18:19], 0, v[16:17]
	v_lshl_add_u64 v[64:65], v[64:65], 2, s[10:11]
	s_waitcnt vmcnt(0)
	v_pk_mul_f32 v[30:31], v[30:31], v[52:53] op_sel_hi:[1,0]
	v_pk_mul_f32 v[32:33], v[32:33], v[52:53] op_sel_hi:[1,0]
	v_mov_b32_e32 v52, v110

; #define LAS __attribute__((address_space(3)))
; template <bool PERMUTE, bool BLOCKED = false>
; __device__ __forceinline__ void cvt_tile64(const float* W, int K, int N, bf16* WT, int ldo, const float* gk, LAS float* scr, int tile, int lane) {
;     ...
;     for (int hh = 0; hh < 2; ++hh) {
;         f32x4 v[8];
; #pragma unroll
;         for (int i = 0; i < 8; ++i) v[i] = *(const f32x4*)(W + (size_t)(k0 + 32 * hh + 4 * i + lk) * N + n0 + ln);
; #pragma unroll
;         for (int i = 0; i < 8; ++i) { const int kk = 32 * hh + 4 * i + lk; const float g = gk ? gk[k0 + kk] : 1.0f; LAS float* d = scr + kk * 65 + ln;
;             d[0] = v[i][0] * g; d[1] = v[i][1] * g; d[2] = v[i][2] * g; d[3] = v[i][3] * g; }
;     }
; __device__ __forceinline__ void cvt_item(const CvtCtx& c, int batch, int wi, LAS float* scr, int wave, int lane) {
;     ...
;     if (wi < CVT_OUT) { cvt_tile64<false>(c.w_out + (size_t)l * DM * DM, DM, DM, c.WoutT + (size_t)l * DM * DM, DM, nullptr, scr, 8 * wi + wave, lane); return; } wi -= CVT_OUT;
.LBB0_747:
	s_andn2_b64 vcc, exec, s[0:1]
	s_cbranch_vccnz .LBB0_722
	s_ashr_i32 s0, s13, 31
	s_lshr_b32 s0, s0, 26
	s_add_i32 s0, s13, s0
	s_and_b32 s4, s0, 0xffffffc0
	s_lshl_b32 s0, s0, 6
	s_and_b32 s0, s0, 0xfffff000
	s_add_i32 s1, s12, s16
	s_sub_i32 s1, s1, s0
	s_add_i32 s6, s1, 0x168000
	v_or_b32_e32 v2, s4, v16
	s_ashr_i32 s7, s6, 31
	v_ashrrev_i32_e32 v3, 31, v2
	v_lshl_add_u64 v[0:1], s[6:7], 2, v[42:43]
	v_lshlrev_b64 v[4:5], 14, v[2:3]
	v_or_b32_e32 v8, 4, v2
	v_lshl_add_u64 v[4:5], v[0:1], 0, v[4:5]
	v_ashrrev_i32_e32 v9, 31, v8
	global_load_dwordx4 v[4:7], v[4:5], off nt
	v_lshlrev_b64 v[8:9], 14, v[8:9]
	v_or_b32_e32 v12, 8, v2
	v_lshl_add_u64 v[8:9], v[0:1], 0, v[8:9]
	v_ashrrev_i32_e32 v13, 31, v12
	global_load_dwordx4 v[8:11], v[8:9], off nt
	v_lshlrev_b64 v[12:13], 14, v[12:13]
	v_or_b32_e32 v18, 12, v2
	v_lshl_add_u64 v[12:13], v[0:1], 0, v[12:13]
	v_ashrrev_i32_e32 v19, 31, v18
	global_load_dwordx4 v[12:15], v[12:13], off nt
	v_lshlrev_b64 v[18:19], 14, v[18:19]
	v_or_b32_e32 v22, 16, v2
	v_lshl_add_u64 v[18:19], v[0:1], 0, v[18:19]
	v_ashrrev_i32_e32 v23, 31, v22
	global_load_dwordx4 v[18:21], v[18:19], off nt
	v_lshlrev_b64 v[22:23], 14, v[22:23]
	v_or_b32_e32 v26, 20, v2
	v_lshl_add_u64 v[22:23], v[0:1], 0, v[22:23]
	v_ashrrev_i32_e32 v27, 31, v26
	global_load_dwordx4 v[22:25], v[22:23], off nt
	v_lshlrev_b64 v[26:27], 14, v[26:27]
	v_or_b32_e32 v30, 24, v2
	v_lshl_add_u64 v[26:27], v[0:1], 0, v[26:27]
	v_ashrrev_i32_e32 v31, 31, v30
	global_load_dwordx4 v[26:29], v[26:27], off nt
	v_lshlrev_b64 v[30:31], 14, v[30:31]
	v_or_b32_e32 v46, 28, v2
	v_lshl_add_u64 v[30:31], v[0:1], 0, v[30:31]
	v_ashrrev_i32_e32 v47, 31, v46
	global_load_dwordx4 v[30:33], v[30:31], off nt
	v_lshlrev_b64 v[46:47], 14, v[46:47]
	v_lshl_add_u64 v[46:47], v[0:1], 0, v[46:47]
	global_load_dwordx4 v[46:49], v[46:47], off nt
	v_add_u32_e32 v50, v51, v53
	v_add_u32_e32 v3, 0x410, v50
	s_sub_i32 s0, s12, s0
	s_ashr_i32 s5, s4, 31
	s_waitcnt vmcnt(7)
	ds_write2_b32 v50, v4, v5 offset1:1
	ds_write2_b32 v50, v6, v7 offset0:2 offset1:3
	v_or_b32_e32 v4, 32, v2
	v_ashrrev_i32_e32 v5, 31, v4
	v_lshlrev_b64 v[4:5], 14, v[4:5]
	v_lshl_add_u64 v[4:5], v[0:1], 0, v[4:5]
	s_waitcnt vmcnt(6)
	ds_write2_b32 v3, v8, v9 offset1:1
	v_add_u32_e32 v3, 0x418, v50
	v_or_b32_e32 v8, 36, v2
	ds_write2_b32 v3, v10, v11 offset1:1
	v_add_u32_e32 v3, 0x820, v50
	v_ashrrev_i32_e32 v9, 31, v8
	s_waitcnt vmcnt(5)
	ds_write2_b32 v3, v12, v13 offset1:1
	v_add_u32_e32 v3, 0x828, v50
	global_load_dwordx4 v[4:7], v[4:5], off nt
	v_lshlrev_b64 v[8:9], 14, v[8:9]
	v_or_b32_e32 v12, 40, v2
	ds_write2_b32 v3, v14, v15 offset1:1
	v_add_u32_e32 v3, 0xc30, v50
	v_lshl_add_u64 v[8:9], v[0:1], 0, v[8:9]
	v_ashrrev_i32_e32 v13, 31, v12
	s_waitcnt vmcnt(5)
	ds_write2_b32 v3, v18, v19 offset1:1
	v_add_u32_e32 v3, 0xc38, v50
	global_load_dwordx4 v[8:11], v[8:9], off nt
	v_lshlrev_b64 v[12:13], 14, v[12:13]
	v_or_b32_e32 v18, 44, v2
	ds_write2_b32 v3, v20, v21 offset1:1
	v_add_u32_e32 v3, 0x1040, v50
	v_lshl_add_u64 v[12:13], v[0:1], 0, v[12:13]
	v_ashrrev_i32_e32 v19, 31, v18
	s_waitcnt vmcnt(5)
	ds_write2_b32 v3, v22, v23 offset1:1
	v_add_u32_e32 v3, 0x1048, v50
	global_load_dwordx4 v[12:15], v[12:13], off nt
	v_lshlrev_b64 v[18:19], 14, v[18:19]
	v_or_b32_e32 v22, 48, v2
	ds_write2_b32 v3, v24, v25 offset1:1
	v_add_u32_e32 v3, 0x1450, v50
	v_lshl_add_u64 v[18:19], v[0:1], 0, v[18:19]
	v_ashrrev_i32_e32 v23, 31, v22
	s_waitcnt vmcnt(5)
	ds_write2_b32 v3, v26, v27 offset1:1
	v_add_u32_e32 v3, 0x1458, v50
	global_load_dwordx4 v[18:21], v[18:19], off nt
	v_lshlrev_b64 v[22:23], 14, v[22:23]
	v_or_b32_e32 v26, 52, v2
	ds_write2_b32 v3, v28, v29 offset1:1
	v_add_u32_e32 v3, 0x1860, v50
	v_lshl_add_u64 v[22:23], v[0:1], 0, v[22:23]
	v_ashrrev_i32_e32 v27, 31, v26
	s_waitcnt vmcnt(5)
	ds_write2_b32 v3, v30, v31 offset1:1
	v_add_u32_e32 v3, 0x1868, v50
	global_load_dwordx4 v[22:25], v[22:23], off nt
	v_lshlrev_b64 v[26:27], 14, v[26:27]
	v_or_b32_e32 v30, 56, v2
	ds_write2_b32 v3, v32, v33 offset1:1
	v_add_u32_e32 v3, 0x1c70, v50
	v_lshl_add_u64 v[26:27], v[0:1], 0, v[26:27]
	v_ashrrev_i32_e32 v31, 31, v30
	s_waitcnt vmcnt(5)
	ds_write2_b32 v3, v46, v47 offset1:1
	v_add_u32_e32 v3, 0x1c78, v50
	global_load_dwordx4 v[26:29], v[26:27], off nt
	v_lshlrev_b64 v[30:31], 14, v[30:31]
	v_or_b32_e32 v2, 60, v2
	ds_write2_b32 v3, v48, v49 offset1:1
	v_lshl_add_u64 v[30:31], v[0:1], 0, v[30:31]
	v_ashrrev_i32_e32 v3, 31, v2
	global_load_dwordx4 v[30:33], v[30:31], off nt
	v_lshlrev_b64 v[2:3], 14, v[2:3]
	v_lshl_add_u64 v[0:1], v[0:1], 0, v[2:3]
	global_load_dwordx4 v[0:3], v[0:1], off nt
	v_add_u32_e32 v46, 0x2080, v50
	s_waitcnt vmcnt(7)
	ds_write2_b32 v46, v4, v5 offset1:1
	v_add_u32_e32 v4, 0x2088, v50
	ds_write2_b32 v4, v6, v7 offset1:1
	v_add_u32_e32 v4, 0x2490, v50
	s_waitcnt vmcnt(6)
	ds_write2_b32 v4, v8, v9 offset1:1
	v_add_u32_e32 v4, 0x2498, v50
	ds_write2_b32 v4, v10, v11 offset1:1
	v_add_u32_e32 v4, 0x28a0, v50
	s_waitcnt vmcnt(5)
	ds_write2_b32 v4, v12, v13 offset1:1
	v_add_u32_e32 v4, 0x28a8, v50
	ds_write2_b32 v4, v14, v15 offset1:1
	v_add_u32_e32 v4, 0x2cb0, v50
	s_waitcnt vmcnt(4)
	ds_write2_b32 v4, v18, v19 offset1:1
	v_add_u32_e32 v4, 0x2cb8, v50
	ds_write2_b32 v4, v20, v21 offset1:1
	v_add_u32_e32 v4, 0x30c0, v50
	s_waitcnt vmcnt(3)
	ds_write2_b32 v4, v22, v23 offset1:1
	v_add_u32_e32 v4, 0x30c8, v50
	ds_write2_b32 v4, v24, v25 offset1:1
	v_add_u32_e32 v4, 0x34d0, v50
	s_waitcnt vmcnt(2)
	ds_write2_b32 v4, v26, v27 offset1:1
	v_add_u32_e32 v4, 0x34d8, v50
	ds_write2_b32 v4, v28, v29 offset1:1
	v_add_u32_e32 v4, 0x38e0, v50
	s_waitcnt vmcnt(1)
; __host__ __device__ __forceinline__ size_t blocked_off(int row, int col, int K) { return (((size_t)(row >> 8) * (K >> 6) + (col >> 6)) * 256 + (row & 255)) * 64 + (col & 63); }
; __device__ __forceinline__ unsigned cvt_pk_bf16(float lo, float hi) { const f32x2c_t v = {lo, hi}; return __builtin_bit_cast(unsigned, __builtin_convertvector(v, bf16x2c_t)); }
; #define LAS __attribute__((address_space(3)))
; #define LDS_WAIT() asm volatile("s_waitcnt lgkmcnt(0)" ::: "memory")
; __host__ __device__ __forceinline__ int win_phys_col(int n) { if (!win_rope_tile(n >> 8)) return n; const int cl = n & 255; return (n & ~255) | (cl & 63) | ((cl & 64) << 1) | ((cl & 128) >> 1); }
; template <bool PERMUTE, bool BLOCKED = false>
; __device__ __forceinline__ void cvt_tile64(const float* W, int K, int N, bf16* WT, int ldo, const float* gk, LAS float* scr, int tile, int lane) {
;     ...
;     LDS_WAIT(); asm volatile("" ::: "memory");
;     const int kc = lane & 7, nrow0 = PERMUTE ? win_phys_col(n0) : n0;
; #pragma unroll
;     for (int j = 0; j < 8; ++j) { const int n = (lane >> 3) + 8 * j; const LAS float* s = scr + (8 * kc) * 65 + n;
;         v4u o; o[0] = cvt_pk_bf16(wrnd(s[0 * 65]), wrnd(s[1 * 65])); o[1] = cvt_pk_bf16(wrnd(s[2 * 65]), wrnd(s[3 * 65])); o[2] = cvt_pk_bf16(wrnd(s[4 * 65]), wrnd(s[5 * 65])); o[3] = cvt_pk_bf16(wrnd(s[6 * 65]), wrnd(s[7 * 65]));
;         *(v4u*)(WT + (BLOCKED ? pg8::blocked_off(nrow0 + n, k0 + 8 * kc, K) : (size_t)(nrow0 + n) * ldo + k0 + 8 * kc)) = o; }
;     LDS_WAIT(); asm volatile("" ::: "memory");
	ds_write2_b32 v4, v30, v31 offset1:1
	v_add_u32_e32 v4, 0x38e8, v50
	ds_write2_b32 v4, v32, v33 offset1:1
	v_add_u32_e32 v4, 0x3cf0, v50
	s_waitcnt vmcnt(0)
	ds_write2_b32 v4, v0, v1 offset1:1
	v_add_u32_e32 v0, 0x3cf8, v50
	ds_write2_b32 v0, v2, v3 offset1:1
	s_waitcnt lgkmcnt(0)
	ds_read2_b32 v[8:9], v55 offset1:8
	ds_read2_b32 v[10:11], v55 offset0:65 offset1:73
	ds_read2_b32 v[12:13], v55 offset0:130 offset1:138
	ds_read2_b32 v[14:15], v55 offset0:195 offset1:203
	v_lshl_add_u64 v[0:1], s[4:5], 1, v[44:45]
	s_waitcnt lgkmcnt(3)
	v_add_u32_e32 v2, 0x20000, v8
	s_waitcnt lgkmcnt(2)
	v_add_u32_e32 v3, 0x20000, v10
	v_and_b32_e32 v2, 0xfffc0000, v2
	v_and_b32_e32 v3, 0xfffc0000, v3
	v_cvt_pk_bf16_f32 v4, v2, v3
	s_waitcnt lgkmcnt(1)
	v_add_u32_e32 v2, 0x20000, v12
	s_waitcnt lgkmcnt(0)
	v_add_u32_e32 v3, 0x20000, v14
	v_and_b32_e32 v2, 0xfffc0000, v2
	v_and_b32_e32 v3, 0xfffc0000, v3
	v_cvt_pk_bf16_f32 v5, v2, v3
	v_add_u32_e32 v2, 0x400, v55
	ds_read2_b32 v[18:19], v2 offset0:4 offset1:12
	ds_read2_b32 v[20:21], v2 offset0:69 offset1:77
	ds_read2_b32 v[22:23], v2 offset0:134 offset1:142
	ds_read2_b32 v[24:25], v2 offset0:199 offset1:207
	s_waitcnt lgkmcnt(3)
	v_add_u32_e32 v3, 0x20000, v18
	s_waitcnt lgkmcnt(2)
	v_add_u32_e32 v6, 0x20000, v20
	v_and_b32_e32 v3, 0xfffc0000, v3
	v_and_b32_e32 v6, 0xfffc0000, v6
	v_cvt_pk_bf16_f32 v6, v3, v6
	s_waitcnt lgkmcnt(1)
	v_add_u32_e32 v3, 0x20000, v22
	s_waitcnt lgkmcnt(0)
	v_add_u32_e32 v7, 0x20000, v24
	v_and_b32_e32 v3, 0xfffc0000, v3
	v_and_b32_e32 v7, 0xfffc0000, v7
	v_cvt_pk_bf16_f32 v7, v3, v7
	v_add_u32_e32 v3, s0, v63
	v_add_u32_e32 v26, 0x168000, v3
	v_ashrrev_i32_e32 v27, 31, v26
	v_lshlrev_b64 v[26:27], 13, v[26:27]
	v_lshl_add_u64 v[26:27], v[0:1], 0, v[26:27]
	global_store_dwordx4 v[26:27], v[4:7], off
	v_add_u32_e32 v8, 0x20000, v25
	v_and_b32_e32 v8, 0xfffc0000, v8
	v_add_u32_e32 v4, 0x20000, v9
	v_add_u32_e32 v5, 0x20000, v11
	v_and_b32_e32 v4, 0xfffc0000, v4
	v_and_b32_e32 v5, 0xfffc0000, v5
	v_cvt_pk_bf16_f32 v4, v4, v5
	v_add_u32_e32 v5, 0x20000, v13
	v_add_u32_e32 v6, 0x20000, v15
	v_and_b32_e32 v5, 0xfffc0000, v5
	v_and_b32_e32 v6, 0xfffc0000, v6
	v_cvt_pk_bf16_f32 v5, v5, v6
	v_add_u32_e32 v6, 0x20000, v19
	v_add_u32_e32 v7, 0x20000, v21
	v_and_b32_e32 v6, 0xfffc0000, v6
	v_and_b32_e32 v7, 0xfffc0000, v7
	v_cvt_pk_bf16_f32 v6, v6, v7
	v_add_u32_e32 v7, 0x20000, v23
	v_and_b32_e32 v7, 0xfffc0000, v7
	v_cvt_pk_bf16_f32 v7, v7, v8
	v_add_u32_e32 v8, 0x168008, v3
	v_ashrrev_i32_e32 v9, 31, v8
	v_lshlrev_b64 v[8:9], 13, v[8:9]
	v_lshl_add_u64 v[8:9], v[0:1], 0, v[8:9]
	global_store_dwordx4 v[8:9], v[4:7], off
	ds_read2_b32 v[8:9], v55 offset0:16 offset1:24
	ds_read2_b32 v[10:11], v55 offset0:81 offset1:89
	ds_read2_b32 v[12:13], v55 offset0:146 offset1:154
	ds_read2_b32 v[14:15], v55 offset0:211 offset1:219
	ds_read2_b32 v[18:19], v2 offset0:20 offset1:28
	ds_read2_b32 v[20:21], v2 offset0:85 offset1:93
	s_waitcnt lgkmcnt(5)
	v_add_u32_e32 v4, 0x20000, v8
	s_waitcnt lgkmcnt(4)
	v_add_u32_e32 v5, 0x20000, v10
	v_and_b32_e32 v4, 0xfffc0000, v4
	v_and_b32_e32 v5, 0xfffc0000, v5
	ds_read2_b32 v[22:23], v2 offset0:150 offset1:158
	ds_read2_b32 v[24:25], v2 offset0:215 offset1:223
	v_cvt_pk_bf16_f32 v4, v4, v5
	s_waitcnt lgkmcnt(5)
	v_add_u32_e32 v5, 0x20000, v12
	s_waitcnt lgkmcnt(4)
	v_add_u32_e32 v6, 0x20000, v14
	v_and_b32_e32 v5, 0xfffc0000, v5
	v_and_b32_e32 v6, 0xfffc0000, v6
	v_cvt_pk_bf16_f32 v5, v5, v6
	s_waitcnt lgkmcnt(3)
	v_add_u32_e32 v6, 0x20000, v18
	s_waitcnt lgkmcnt(2)
	v_add_u32_e32 v7, 0x20000, v20
	v_and_b32_e32 v6, 0xfffc0000, v6
	v_and_b32_e32 v7, 0xfffc0000, v7
	v_add_u32_e32 v26, 0x168010, v3
	v_cvt_pk_bf16_f32 v6, v6, v7
	s_waitcnt lgkmcnt(1)
	v_add_u32_e32 v7, 0x20000, v22
	s_waitcnt lgkmcnt(0)
	v_add_u32_e32 v8, 0x20000, v24
	v_ashrrev_i32_e32 v27, 31, v26
	v_and_b32_e32 v7, 0xfffc0000, v7
	v_and_b32_e32 v8, 0xfffc0000, v8
	v_lshlrev_b64 v[26:27], 13, v[26:27]
	v_cvt_pk_bf16_f32 v7, v7, v8
	v_lshl_add_u64 v[26:27], v[0:1], 0, v[26:27]
	global_store_dwordx4 v[26:27], v[4:7], off
	v_add_u32_e32 v8, 0x20000, v25
	v_and_b32_e32 v8, 0xfffc0000, v8
	v_add_u32_e32 v4, 0x20000, v9
	v_add_u32_e32 v5, 0x20000, v11
	v_and_b32_e32 v4, 0xfffc0000, v4
	v_and_b32_e32 v5, 0xfffc0000, v5
	v_cvt_pk_bf16_f32 v4, v4, v5
	v_add_u32_e32 v5, 0x20000, v13
	v_add_u32_e32 v6, 0x20000, v15
	v_and_b32_e32 v5, 0xfffc0000, v5
	v_and_b32_e32 v6, 0xfffc0000, v6
	v_cvt_pk_bf16_f32 v5, v5, v6
	v_add_u32_e32 v6, 0x20000, v19
	v_add_u32_e32 v7, 0x20000, v21
	v_and_b32_e32 v6, 0xfffc0000, v6
	v_and_b32_e32 v7, 0xfffc0000, v7
	v_cvt_pk_bf16_f32 v6, v6, v7
	v_add_u32_e32 v7, 0x20000, v23
	v_and_b32_e32 v7, 0xfffc0000, v7
	v_cvt_pk_bf16_f32 v7, v7, v8
	v_add_u32_e32 v8, 0x168018, v3
	v_ashrrev_i32_e32 v9, 31, v8
	v_lshlrev_b64 v[8:9], 13, v[8:9]
	v_lshl_add_u64 v[8:9], v[0:1], 0, v[8:9]
	global_store_dwordx4 v[8:9], v[4:7], off
	ds_read2_b32 v[8:9], v55 offset0:32 offset1:40
	ds_read2_b32 v[10:11], v55 offset0:97 offset1:105
	ds_read2_b32 v[12:13], v55 offset0:162 offset1:170
	ds_read2_b32 v[14:15], v55 offset0:227 offset1:235
	ds_read2_b32 v[18:19], v2 offset0:36 offset1:44
	ds_read2_b32 v[20:21], v2 offset0:101 offset1:109
	s_waitcnt lgkmcnt(5)
; __host__ __device__ __forceinline__ size_t blocked_off(int row, int col, int K) { return (((size_t)(row >> 8) * (K >> 6) + (col >> 6)) * 256 + (row & 255)) * 64 + (col & 63); }
; __device__ __forceinline__ unsigned cvt_pk_bf16(float lo, float hi) { const f32x2c_t v = {lo, hi}; return __builtin_bit_cast(unsigned, __builtin_convertvector(v, bf16x2c_t)); }
; #define LAS __attribute__((address_space(3)))
; #define LDS_WAIT() asm volatile("s_waitcnt lgkmcnt(0)" ::: "memory")
; __host__ __device__ __forceinline__ int win_phys_col(int n) { if (!win_rope_tile(n >> 8)) return n; const int cl = n & 255; return (n & ~255) | (cl & 63) | ((cl & 64) << 1) | ((cl & 128) >> 1); }
; template <bool PERMUTE, bool BLOCKED = false>
; __device__ __forceinline__ void cvt_tile64(const float* W, int K, int N, bf16* WT, int ldo, const float* gk, LAS float* scr, int tile, int lane) {
;     ...
;     LDS_WAIT(); asm volatile("" ::: "memory");
;     const int kc = lane & 7, nrow0 = PERMUTE ? win_phys_col(n0) : n0;
; #pragma unroll
;     for (int j = 0; j < 8; ++j) { const int n = (lane >> 3) + 8 * j; const LAS float* s = scr + (8 * kc) * 65 + n;
;         v4u o; o[0] = cvt_pk_bf16(wrnd(s[0 * 65]), wrnd(s[1 * 65])); o[1] = cvt_pk_bf16(wrnd(s[2 * 65]), wrnd(s[3 * 65])); o[2] = cvt_pk_bf16(wrnd(s[4 * 65]), wrnd(s[5 * 65])); o[3] = cvt_pk_bf16(wrnd(s[6 * 65]), wrnd(s[7 * 65]));
;         *(v4u*)(WT + (BLOCKED ? pg8::blocked_off(nrow0 + n, k0 + 8 * kc, K) : (size_t)(nrow0 + n) * ldo + k0 + 8 * kc)) = o; }
;     LDS_WAIT(); asm volatile("" ::: "memory");
	v_add_u32_e32 v4, 0x20000, v8
	s_waitcnt lgkmcnt(4)
	v_add_u32_e32 v5, 0x20000, v10
	v_and_b32_e32 v4, 0xfffc0000, v4
	v_and_b32_e32 v5, 0xfffc0000, v5
	ds_read2_b32 v[22:23], v2 offset0:166 offset1:174
	ds_read2_b32 v[24:25], v2 offset0:231 offset1:239
	v_cvt_pk_bf16_f32 v4, v4, v5
	s_waitcnt lgkmcnt(5)
	v_add_u32_e32 v5, 0x20000, v12
	s_waitcnt lgkmcnt(4)
	v_add_u32_e32 v6, 0x20000, v14
	v_and_b32_e32 v5, 0xfffc0000, v5
	v_and_b32_e32 v6, 0xfffc0000, v6
	v_cvt_pk_bf16_f32 v5, v5, v6
	s_waitcnt lgkmcnt(3)
	v_add_u32_e32 v6, 0x20000, v18
	s_waitcnt lgkmcnt(2)
	v_add_u32_e32 v7, 0x20000, v20
	v_and_b32_e32 v6, 0xfffc0000, v6
	v_and_b32_e32 v7, 0xfffc0000, v7
	v_add_u32_e32 v26, 0x168020, v3
	v_cvt_pk_bf16_f32 v6, v6, v7
	s_waitcnt lgkmcnt(1)
	v_add_u32_e32 v7, 0x20000, v22
	s_waitcnt lgkmcnt(0)
	v_add_u32_e32 v8, 0x20000, v24
	v_ashrrev_i32_e32 v27, 31, v26
	v_and_b32_e32 v7, 0xfffc0000, v7
	v_and_b32_e32 v8, 0xfffc0000, v8
	v_lshlrev_b64 v[26:27], 13, v[26:27]
	v_cvt_pk_bf16_f32 v7, v7, v8
	v_lshl_add_u64 v[26:27], v[0:1], 0, v[26:27]
	global_store_dwordx4 v[26:27], v[4:7], off
	v_add_u32_e32 v8, 0x20000, v25
	v_and_b32_e32 v8, 0xfffc0000, v8
	v_add_u32_e32 v4, 0x20000, v9
	v_add_u32_e32 v5, 0x20000, v11
	v_and_b32_e32 v4, 0xfffc0000, v4
	v_and_b32_e32 v5, 0xfffc0000, v5
	v_cvt_pk_bf16_f32 v4, v4, v5
	v_add_u32_e32 v5, 0x20000, v13
	v_add_u32_e32 v6, 0x20000, v15
	v_and_b32_e32 v5, 0xfffc0000, v5
	v_and_b32_e32 v6, 0xfffc0000, v6
	v_cvt_pk_bf16_f32 v5, v5, v6
	v_add_u32_e32 v6, 0x20000, v19
	v_add_u32_e32 v7, 0x20000, v21
	v_and_b32_e32 v6, 0xfffc0000, v6
	v_and_b32_e32 v7, 0xfffc0000, v7
	v_cvt_pk_bf16_f32 v6, v6, v7
	v_add_u32_e32 v7, 0x20000, v23
	v_and_b32_e32 v7, 0xfffc0000, v7
	v_cvt_pk_bf16_f32 v7, v7, v8
	v_add_u32_e32 v8, 0x168028, v3
	v_ashrrev_i32_e32 v9, 31, v8
	v_lshlrev_b64 v[8:9], 13, v[8:9]
	v_lshl_add_u64 v[8:9], v[0:1], 0, v[8:9]
	global_store_dwordx4 v[8:9], v[4:7], off
	ds_read2_b32 v[8:9], v55 offset0:48 offset1:56
	ds_read2_b32 v[10:11], v55 offset0:113 offset1:121
	ds_read2_b32 v[12:13], v55 offset0:178 offset1:186
	ds_read2_b32 v[14:15], v55 offset0:243 offset1:251
	ds_read2_b32 v[18:19], v2 offset0:52 offset1:60
	ds_read2_b32 v[20:21], v2 offset0:117 offset1:125
	s_waitcnt lgkmcnt(5)
	v_add_u32_e32 v4, 0x20000, v8
	s_waitcnt lgkmcnt(4)
	v_add_u32_e32 v5, 0x20000, v10
	v_and_b32_e32 v4, 0xfffc0000, v4
	v_and_b32_e32 v5, 0xfffc0000, v5
	ds_read2_b32 v[22:23], v2 offset0:182 offset1:190
	ds_read2_b32 v[24:25], v2 offset0:247 offset1:255
	v_cvt_pk_bf16_f32 v4, v4, v5
	s_waitcnt lgkmcnt(5)
	v_add_u32_e32 v5, 0x20000, v12
	s_waitcnt lgkmcnt(4)
	v_add_u32_e32 v6, 0x20000, v14
	v_and_b32_e32 v5, 0xfffc0000, v5
	v_and_b32_e32 v6, 0xfffc0000, v6
	v_cvt_pk_bf16_f32 v5, v5, v6
	s_waitcnt lgkmcnt(3)
	v_add_u32_e32 v6, 0x20000, v18
	s_waitcnt lgkmcnt(2)
	v_add_u32_e32 v7, 0x20000, v20
	v_and_b32_e32 v6, 0xfffc0000, v6
	v_and_b32_e32 v7, 0xfffc0000, v7
	v_add_u32_e32 v26, 0x168030, v3
	v_cvt_pk_bf16_f32 v6, v6, v7
	s_waitcnt lgkmcnt(1)
	v_add_u32_e32 v7, 0x20000, v22
	s_waitcnt lgkmcnt(0)
	v_add_u32_e32 v2, 0x20000, v24
	v_ashrrev_i32_e32 v27, 31, v26
	v_and_b32_e32 v7, 0xfffc0000, v7
	v_and_b32_e32 v2, 0xfffc0000, v2
	v_lshlrev_b64 v[26:27], 13, v[26:27]
	v_cvt_pk_bf16_f32 v7, v7, v2
	v_lshl_add_u64 v[26:27], v[0:1], 0, v[26:27]
	global_store_dwordx4 v[26:27], v[4:7], off
	v_add_u32_e32 v2, 0x20000, v9
	v_and_b32_e32 v2, 0xfffc0000, v2
	v_add_u32_e32 v4, 0x20000, v11
	v_and_b32_e32 v4, 0xfffc0000, v4
	v_cvt_pk_bf16_f32 v4, v2, v4
	v_add_u32_e32 v2, 0x20000, v13
	v_add_u32_e32 v5, 0x20000, v15
	v_and_b32_e32 v2, 0xfffc0000, v2
	v_and_b32_e32 v5, 0xfffc0000, v5
	v_cvt_pk_bf16_f32 v5, v2, v5
	v_add_u32_e32 v2, 0x20000, v19
	v_add_u32_e32 v6, 0x20000, v21
	v_and_b32_e32 v2, 0xfffc0000, v2
	v_and_b32_e32 v6, 0xfffc0000, v6
	v_cvt_pk_bf16_f32 v6, v2, v6
	v_add_u32_e32 v2, 0x20000, v23
	v_add_u32_e32 v7, 0x20000, v25
	v_and_b32_e32 v2, 0xfffc0000, v2
	v_and_b32_e32 v7, 0xfffc0000, v7
	v_cvt_pk_bf16_f32 v7, v2, v7
	v_add_u32_e32 v2, 0x168038, v3
	v_ashrrev_i32_e32 v3, 31, v2
	v_lshlrev_b64 v[2:3], 13, v[2:3]
	v_lshl_add_u64 v[0:1], v[0:1], 0, v[2:3]
	global_store_dwordx4 v[0:1], v[4:7], off
	s_waitcnt lgkmcnt(0)
	s_branch .LBB0_722

; #define LAS __attribute__((address_space(3)))
; template <bool PERMUTE, bool BLOCKED = false>
; __device__ __forceinline__ void cvt_tile64(const float* W, int K, int N, bf16* WT, int ldo, const float* gk, LAS float* scr, int tile, int lane) {
;     ...
;     for (int hh = 0; hh < 2; ++hh) {
;         f32x4 v[8];
; #pragma unroll
;         for (int i = 0; i < 8; ++i) v[i] = *(const f32x4*)(W + (size_t)(k0 + 32 * hh + 4 * i + lk) * N + n0 + ln);
; #pragma unroll
;         for (int i = 0; i < 8; ++i) { const int kk = 32 * hh + 4 * i + lk; const float g = gk ? gk[k0 + kk] : 1.0f; LAS float* d = scr + kk * 65 + ln;
;             d[0] = v[i][0] * g; d[1] = v[i][1] * g; d[2] = v[i][2] * g; d[3] = v[i][3] * g; }
;     }
; __device__ __forceinline__ void cvt_item(const CvtCtx& c, int batch, int wi, LAS float* scr, int wave, int lane) {
;     const int l = batch;
;     if (wi < CVT_OUT) { cvt_tile64<false>(c.w_out + (size_t)l * DM * DM, DM, DM, c.WoutT + (size_t)l * DM * DM, DM, nullptr, scr, 8 * wi + wave, lane); return; } wi -= CVT_OUT;
;     if (wi < CVT_UP) { cvt_tile64<false>(c.w_up + (size_t)l * DM * DFF, DM, DFF, c.WupT + (size_t)l * DFF * DM, DM, c.g_mlp + l * DM, scr, 8 * wi + wave, lane); return; } wi -= CVT_UP;
;     if (wi < CVT_DN) { cvt_tile64<false, true>(c.w_down + (size_t)l * DFF * DM, DFF, DM, c.WdnT + (size_t)l * DM * DFF, 0, nullptr, scr, 8 * wi + wave, lane); return; } wi -= CVT_DN;
;     cvt_tile64<true>(c.w_in + (size_t)1 * DM * INW, DM, INW, c.WinT + (size_t)1 * INW * DM, DM, c.g_mix + 1 * DM, scr, 8 * wi + wave, lane);
.LBB0_807:
	s_cmpk_gt_i32 s17, 0x1ff
	s_mov_b64 s[0:1], -1
	s_cbranch_scc0 .LBB0_835
	s_cmpk_gt_u32 s17, 0x9ff
	s_cbranch_scc0 .LBB0_814
	s_cmpk_gt_u32 s17, 0x11ff
	s_cbranch_scc0 .LBB0_811
	s_mul_hi_i32 s0, s16, 0x38e38e39
	s_lshr_b32 s1, s0, 31
	s_ashr_i32 s0, s0, 5
	s_add_i32 s1, s0, s1
	s_mul_i32 s0, s1, 0xffffff70
	s_lshl_b32 s4, s1, 6
	s_mulk_i32 s1, 0xdc00
	s_add_i32 s18, s13, s1
	v_or_b32_e32 v18, s4, v16
	s_ashr_i32 s19, s18, 31
	v_lshl_add_u64 v[20:21], s[18:19], 2, v[34:35]
	v_ashrrev_i32_e32 v19, 31, v18
	s_mov_b32 s1, 0x9000
	v_mad_i64_i32 v[0:1], s[6:7], v18, s1, v[20:21]
	v_lshl_add_u64 v[86:87], v[18:19], 2, s[8:9]
	global_load_dwordx4 v[22:25], v[0:1], off nt
	global_load_dword v54, v[86:87], off
	v_add_u32_e32 v19, v55, v57
	v_or_b32_e32 v0, 4, v18
	v_mad_i64_i32 v[0:1], s[6:7], v0, s1, v[20:21]
	global_load_dwordx4 v[26:29], v[0:1], off nt
	v_or_b32_e32 v0, 8, v18
	v_mad_i64_i32 v[0:1], s[6:7], v0, s1, v[20:21]
	global_load_dwordx4 v[30:33], v[0:1], off nt
	v_or_b32_e32 v0, 12, v18
	v_mad_i64_i32 v[0:1], s[6:7], v0, s1, v[20:21]
	global_load_dwordx4 v[50:53], v[0:1], off nt
	v_or_b32_e32 v0, 16, v18
	v_mad_i64_i32 v[0:1], s[6:7], v0, s1, v[20:21]
	global_load_dwordx4 v[12:15], v[0:1], off nt
	v_or_b32_e32 v0, 20, v18
	v_mad_i64_i32 v[0:1], s[6:7], v0, s1, v[20:21]
	global_load_dwordx4 v[8:11], v[0:1], off nt
	v_or_b32_e32 v0, 24, v18
	v_mad_i64_i32 v[0:1], s[6:7], v0, s1, v[20:21]
	global_load_dwordx4 v[4:7], v[0:1], off nt
	v_or_b32_e32 v0, 28, v18
	v_mad_i64_i32 v[0:1], s[6:7], v0, s1, v[20:21]
	global_load_dwordx4 v[0:3], v[0:1], off nt
	s_add_i32 s0, s16, s0
	s_ashr_i32 s5, s0, 2
	s_and_b32 s0, s0, 0x3ffffe0
	s_cmp_eq_u32 s0, 32
	s_waitcnt vmcnt(7)
	v_pk_mul_f32 v[22:23], v[22:23], v[54:55] op_sel_hi:[1,0]
	ds_write2_b32 v19, v22, v23 offset1:1
	v_pk_mul_f32 v[22:23], v[24:25], v[54:55] op_sel_hi:[1,0]
	ds_write2_b32 v19, v22, v23 offset0:2 offset1:3
	v_or_b32_e32 v22, s4, v58
	v_ashrrev_i32_e32 v23, 31, v22
	v_lshl_add_u64 v[22:23], v[22:23], 2, s[8:9]
	global_load_dword v22, v[22:23], off
	s_waitcnt vmcnt(0)
	v_pk_mul_f32 v[24:25], v[26:27], v[22:23] op_sel_hi:[1,0]
	v_add_u32_e32 v23, 0x410, v19
	ds_write2_b32 v23, v24, v25 offset1:1
	v_pk_mul_f32 v[22:23], v[28:29], v[22:23] op_sel_hi:[1,0]
	v_add_u32_e32 v24, 0x418, v19
	ds_write2_b32 v24, v22, v23 offset1:1
	v_or_b32_e32 v22, s4, v59
	v_ashrrev_i32_e32 v23, 31, v22
	v_lshl_add_u64 v[22:23], v[22:23], 2, s[8:9]
	global_load_dword v22, v[22:23], off
	s_waitcnt vmcnt(0)
	v_pk_mul_f32 v[24:25], v[30:31], v[22:23] op_sel_hi:[1,0]
	v_add_u32_e32 v23, 0x820, v19
	ds_write2_b32 v23, v24, v25 offset1:1
	v_pk_mul_f32 v[22:23], v[32:33], v[22:23] op_sel_hi:[1,0]
	v_add_u32_e32 v24, 0x828, v19
	ds_write2_b32 v24, v22, v23 offset1:1
	v_or_b32_e32 v22, s4, v60
	v_ashrrev_i32_e32 v23, 31, v22
	v_lshl_add_u64 v[22:23], v[22:23], 2, s[8:9]
	global_load_dword v22, v[22:23], off
	s_waitcnt vmcnt(0)
	v_pk_mul_f32 v[24:25], v[50:51], v[22:23] op_sel_hi:[1,0]
	v_add_u32_e32 v23, 0xc30, v19
	ds_write2_b32 v23, v24, v25 offset1:1
	v_pk_mul_f32 v[22:23], v[52:53], v[22:23] op_sel_hi:[1,0]
	v_add_u32_e32 v24, 0xc38, v19
	ds_write2_b32 v24, v22, v23 offset1:1
	v_or_b32_e32 v22, s4, v61
	v_ashrrev_i32_e32 v23, 31, v22
	v_lshl_add_u64 v[22:23], v[22:23], 2, s[8:9]
	global_load_dword v22, v[22:23], off
	s_waitcnt vmcnt(0)
	v_pk_mul_f32 v[12:13], v[12:13], v[22:23] op_sel_hi:[1,0]
	v_add_u32_e32 v23, 0x1040, v19
	ds_write2_b32 v23, v12, v13 offset1:1
	v_pk_mul_f32 v[12:13], v[14:15], v[22:23] op_sel_hi:[1,0]
	v_add_u32_e32 v14, 0x1048, v19
	ds_write2_b32 v14, v12, v13 offset1:1
	v_or_b32_e32 v12, s4, v62
	v_ashrrev_i32_e32 v13, 31, v12
	v_lshl_add_u64 v[12:13], v[12:13], 2, s[8:9]
	global_load_dword v12, v[12:13], off
	v_or_b32_e32 v14, s4, v66
	v_ashrrev_i32_e32 v15, 31, v14
	v_lshl_add_u64 v[14:15], v[14:15], 2, s[8:9]
	global_load_dword v14, v[14:15], off
	s_waitcnt vmcnt(1)
	v_pk_mul_f32 v[8:9], v[8:9], v[12:13] op_sel_hi:[1,0]
	v_add_u32_e32 v13, 0x1450, v19
	ds_write2_b32 v13, v8, v9 offset1:1
	v_pk_mul_f32 v[8:9], v[10:11], v[12:13] op_sel_hi:[1,0]
	v_add_u32_e32 v12, v55, v63
	ds_write2_b32 v12, v8, v9 offset0:2 offset1:3
	v_or_b32_e32 v8, s4, v64
	v_ashrrev_i32_e32 v9, 31, v8
	v_lshl_add_u64 v[8:9], v[8:9], 2, s[8:9]
	global_load_dword v8, v[8:9], off
	v_add_u32_e32 v13, 0xc30, v12
	s_waitcnt vmcnt(0)
	v_pk_mul_f32 v[4:5], v[4:5], v[8:9] op_sel_hi:[1,0]
	v_add_u32_e32 v9, 0x410, v12
	ds_write2_b32 v9, v4, v5 offset1:1
	v_pk_mul_f32 v[4:5], v[6:7], v[8:9] op_sel_hi:[1,0]
	v_add_u32_e32 v6, 0x418, v12
	ds_write2_b32 v6, v4, v5 offset1:1
	v_or_b32_e32 v4, s4, v65
	v_ashrrev_i32_e32 v5, 31, v4
	v_lshl_add_u64 v[4:5], v[4:5], 2, s[8:9]
	global_load_dword v4, v[4:5], off
	s_waitcnt vmcnt(0)
	v_pk_mul_f32 v[0:1], v[0:1], v[4:5] op_sel_hi:[1,0]
	v_add_u32_e32 v5, 0x820, v12
	ds_write2_b32 v5, v0, v1 offset1:1
	v_pk_mul_f32 v[0:1], v[2:3], v[4:5] op_sel_hi:[1,0]
	v_add_u32_e32 v2, 0x828, v12
	ds_write2_b32 v2, v0, v1 offset1:1
	v_or_b32_e32 v0, 32, v18
	v_mad_i64_i32 v[0:1], s[6:7], v0, s1, v[20:21]
	global_load_dwordx4 v[22:25], v[0:1], off nt
	v_or_b32_e32 v0, 36, v18
	v_mad_i64_i32 v[0:1], s[6:7], v0, s1, v[20:21]
	global_load_dwordx4 v[26:29], v[0:1], off nt
	v_or_b32_e32 v0, 40, v18
	v_mad_i64_i32 v[0:1], s[6:7], v0, s1, v[20:21]
	global_load_dwordx4 v[30:33], v[0:1], off nt
	v_or_b32_e32 v0, 44, v18
	v_mad_i64_i32 v[0:1], s[6:7], v0, s1, v[20:21]
	global_load_dwordx4 v[50:53], v[0:1], off nt
	v_or_b32_e32 v0, 48, v18
	v_mad_i64_i32 v[0:1], s[6:7], v0, s1, v[20:21]
	global_load_dwordx4 v[86:89], v[0:1], off nt
	v_or_b32_e32 v0, 52, v18
	v_mad_i64_i32 v[0:1], s[6:7], v0, s1, v[20:21]
	global_load_dwordx4 v[8:11], v[0:1], off nt
	v_or_b32_e32 v0, 56, v18
	v_mad_i64_i32 v[0:1], s[6:7], v0, s1, v[20:21]
	global_load_dwordx4 v[4:7], v[0:1], off nt
	v_or_b32_e32 v0, 60, v18
	v_mad_i64_i32 v[0:1], s[6:7], v0, s1, v[20:21]
	global_load_dwordx4 v[0:3], v[0:1], off nt
	s_cselect_b64 s[0:1], -1, 0
	s_sub_i32 s5, s5, 24
	s_cmp_lt_u32 s5, 10
	s_cselect_b64 s[6:7], -1, 0
	s_or_b64 s[0:1], s[0:1], s[6:7]
	s_and_b32 s5, s18, 0xffffff00
	s_lshr_b32 s6, s18, 1
	s_or_b32 s5, s5, s12
	s_and_b32 s6, s6, 64
	s_or_b32 s5, s5, s6
	s_and_b64 s[0:1], s[0:1], exec
	s_cselect_b32 s0, s5, s18
	s_ashr_i32 s5, s4, 31
	s_waitcnt vmcnt(7)
; __host__ __device__ __forceinline__ size_t blocked_off(int row, int col, int K) { return (((size_t)(row >> 8) * (K >> 6) + (col >> 6)) * 256 + (row & 255)) * 64 + (col & 63); }
; __device__ __forceinline__ unsigned cvt_pk_bf16(float lo, float hi) { const f32x2c_t v = {lo, hi}; return __builtin_bit_cast(unsigned, __builtin_convertvector(v, bf16x2c_t)); }
; #define LAS __attribute__((address_space(3)))
; #define LDS_WAIT() asm volatile("s_waitcnt lgkmcnt(0)" ::: "memory")
; __host__ __device__ __forceinline__ int win_phys_col(int n) { if (!win_rope_tile(n >> 8)) return n; const int cl = n & 255; return (n & ~255) | (cl & 63) | ((cl & 64) << 1) | ((cl & 128) >> 1); }
; template <bool PERMUTE, bool BLOCKED = false>
; __device__ __forceinline__ void cvt_tile64(const float* W, int K, int N, bf16* WT, int ldo, const float* gk, LAS float* scr, int tile, int lane) {
;     ...
;         for (int i = 0; i < 8; ++i) { const int kk = 32 * hh + 4 * i + lk; const float g = gk ? gk[k0 + kk] : 1.0f; LAS float* d = scr + kk * 65 + ln;
;             d[0] = v[i][0] * g; d[1] = v[i][1] * g; d[2] = v[i][2] * g; d[3] = v[i][3] * g; }
;     }
;     ...
;     LDS_WAIT(); asm volatile("" ::: "memory");
;     const int kc = lane & 7, nrow0 = PERMUTE ? win_phys_col(n0) : n0;
; #pragma unroll
;     for (int j = 0; j < 8; ++j) { const int n = (lane >> 3) + 8 * j; const LAS float* s = scr + (8 * kc) * 65 + n;
;         v4u o; o[0] = cvt_pk_bf16(wrnd(s[0 * 65]), wrnd(s[1 * 65])); o[1] = cvt_pk_bf16(wrnd(s[2 * 65]), wrnd(s[3 * 65])); o[2] = cvt_pk_bf16(wrnd(s[4 * 65]), wrnd(s[5 * 65])); o[3] = cvt_pk_bf16(wrnd(s[6 * 65]), wrnd(s[7 * 65]));
;         *(v4u*)(WT + (BLOCKED ? pg8::blocked_off(nrow0 + n, k0 + 8 * kc, K) : (size_t)(nrow0 + n) * ldo + k0 + 8 * kc)) = o; }
	v_pk_mul_f32 v[18:19], v[22:23], v[14:15] op_sel_hi:[1,0]
	ds_write2_b32 v13, v18, v19 offset1:1
	v_pk_mul_f32 v[14:15], v[24:25], v[14:15] op_sel_hi:[1,0]
	v_add_u32_e32 v13, 0xc38, v12
	ds_write2_b32 v13, v14, v15 offset1:1
	v_or_b32_e32 v14, s4, v67
	v_ashrrev_i32_e32 v15, 31, v14
	v_lshl_add_u64 v[14:15], v[14:15], 2, s[8:9]
	global_load_dword v14, v[14:15], off
	v_add_u32_e32 v13, 0x1040, v12
	v_or_b32_e32 v24, s0, v74
	v_ashrrev_i32_e32 v25, 31, v24
	v_lshlrev_b64 v[24:25], 13, v[24:25]
	s_waitcnt vmcnt(0)
	v_pk_mul_f32 v[18:19], v[26:27], v[14:15] op_sel_hi:[1,0]
	ds_write2_b32 v13, v18, v19 offset1:1
	v_pk_mul_f32 v[14:15], v[28:29], v[14:15] op_sel_hi:[1,0]
	v_add_u32_e32 v13, 0x1048, v12
	ds_write2_b32 v13, v14, v15 offset1:1
	v_or_b32_e32 v14, s4, v68
	v_ashrrev_i32_e32 v15, 31, v14
	v_lshl_add_u64 v[14:15], v[14:15], 2, s[8:9]
	global_load_dword v14, v[14:15], off
	v_add_u32_e32 v13, 0x1450, v12
	v_or_b32_e32 v26, s0, v77
	v_ashrrev_i32_e32 v27, 31, v26
	v_lshlrev_b64 v[26:27], 13, v[26:27]
	s_waitcnt vmcnt(0)
	v_pk_mul_f32 v[18:19], v[30:31], v[14:15] op_sel_hi:[1,0]
	ds_write2_b32 v13, v18, v19 offset1:1
	v_pk_mul_f32 v[14:15], v[32:33], v[14:15] op_sel_hi:[1,0]
	v_add_u32_e32 v13, 0x1458, v12
	ds_write2_b32 v13, v14, v15 offset1:1
	v_or_b32_e32 v14, s4, v69
	v_ashrrev_i32_e32 v15, 31, v14
	v_lshl_add_u64 v[14:15], v[14:15], 2, s[8:9]
	global_load_dword v14, v[14:15], off
	v_add_u32_e32 v13, 0x1860, v12
	s_waitcnt vmcnt(0)
	v_pk_mul_f32 v[18:19], v[50:51], v[14:15] op_sel_hi:[1,0]
	ds_write2_b32 v13, v18, v19 offset1:1
	v_pk_mul_f32 v[14:15], v[52:53], v[14:15] op_sel_hi:[1,0]
	v_add_u32_e32 v13, 0x1868, v12
	ds_write2_b32 v13, v14, v15 offset1:1
	v_or_b32_e32 v14, s4, v70
	v_ashrrev_i32_e32 v15, 31, v14
	v_lshl_add_u64 v[14:15], v[14:15], 2, s[8:9]
	global_load_dword v14, v[14:15], off
	v_add_u32_e32 v13, 0x1c70, v12
	s_waitcnt vmcnt(0)
	v_pk_mul_f32 v[18:19], v[86:87], v[14:15] op_sel_hi:[1,0]
	ds_write2_b32 v13, v18, v19 offset1:1
	v_pk_mul_f32 v[14:15], v[88:89], v[14:15] op_sel_hi:[1,0]
	v_add_u32_e32 v13, 0x1c78, v12
	ds_write2_b32 v13, v14, v15 offset1:1
	v_or_b32_e32 v14, s4, v71
	v_ashrrev_i32_e32 v15, 31, v14
	v_lshl_add_u64 v[14:15], v[14:15], 2, s[8:9]
	global_load_dword v14, v[14:15], off
	v_add_u32_e32 v13, 0x2080, v12
	s_waitcnt vmcnt(0)
	v_pk_mul_f32 v[8:9], v[8:9], v[14:15] op_sel_hi:[1,0]
	ds_write2_b32 v13, v8, v9 offset1:1
	v_pk_mul_f32 v[8:9], v[10:11], v[14:15] op_sel_hi:[1,0]
	v_add_u32_e32 v10, 0x2088, v12
	ds_write2_b32 v10, v8, v9 offset1:1
	v_or_b32_e32 v8, s4, v72
	v_ashrrev_i32_e32 v9, 31, v8
	v_lshl_add_u64 v[8:9], v[8:9], 2, s[8:9]
	global_load_dword v8, v[8:9], off
	s_waitcnt vmcnt(0)
	v_pk_mul_f32 v[4:5], v[4:5], v[8:9] op_sel_hi:[1,0]
	v_add_u32_e32 v9, 0x2490, v12
	ds_write2_b32 v9, v4, v5 offset1:1
	v_pk_mul_f32 v[4:5], v[6:7], v[8:9] op_sel_hi:[1,0]
	v_add_u32_e32 v6, 0x2498, v12
	ds_write2_b32 v6, v4, v5 offset1:1
	v_or_b32_e32 v4, s4, v73
	v_ashrrev_i32_e32 v5, 31, v4
	v_lshl_add_u64 v[4:5], v[4:5], 2, s[8:9]
	global_load_dword v4, v[4:5], off
	s_waitcnt vmcnt(0)
	v_pk_mul_f32 v[0:1], v[0:1], v[4:5] op_sel_hi:[1,0]
	v_add_u32_e32 v5, 0x28a0, v12
	ds_write2_b32 v5, v0, v1 offset1:1
	v_pk_mul_f32 v[0:1], v[2:3], v[4:5] op_sel_hi:[1,0]
	v_add_u32_e32 v2, 0x28a8, v12
	ds_write2_b32 v2, v0, v1 offset1:1
	s_waitcnt lgkmcnt(0)
	ds_read2_b32 v[2:3], v75 offset1:8
	ds_read2_b32 v[8:9], v75 offset0:65 offset1:73
	ds_read2_b32 v[10:11], v75 offset0:130 offset1:138
	ds_read2_b32 v[12:13], v75 offset0:195 offset1:203
	v_lshl_add_u64 v[0:1], s[4:5], 1, v[36:37]
	s_waitcnt lgkmcnt(3)
	v_add_u32_e32 v2, 0x20000, v2
	s_waitcnt lgkmcnt(2)
	v_add_u32_e32 v4, 0x20000, v8
	v_and_b32_e32 v2, 0xfffc0000, v2
	v_and_b32_e32 v4, 0xfffc0000, v4
	v_cvt_pk_bf16_f32 v4, v2, v4
	s_waitcnt lgkmcnt(1)
	v_add_u32_e32 v2, 0x20000, v10
	s_waitcnt lgkmcnt(0)
	v_add_u32_e32 v5, 0x20000, v12
	v_and_b32_e32 v2, 0xfffc0000, v2
	v_and_b32_e32 v5, 0xfffc0000, v5
	v_cvt_pk_bf16_f32 v5, v2, v5
	v_add_u32_e32 v2, 0x400, v75
	ds_read2_b32 v[14:15], v2 offset0:4 offset1:12
	ds_read2_b32 v[18:19], v2 offset0:69 offset1:77
	ds_read2_b32 v[20:21], v2 offset0:134 offset1:142
	ds_read2_b32 v[22:23], v2 offset0:199 offset1:207
	v_lshl_add_u64 v[24:25], v[0:1], 0, v[24:25]
	s_waitcnt lgkmcnt(3)
	v_add_u32_e32 v6, 0x20000, v14
	s_waitcnt lgkmcnt(2)
	v_add_u32_e32 v7, 0x20000, v18
	v_and_b32_e32 v6, 0xfffc0000, v6
	v_and_b32_e32 v7, 0xfffc0000, v7
	v_cvt_pk_bf16_f32 v6, v6, v7
	s_waitcnt lgkmcnt(1)
	v_add_u32_e32 v7, 0x20000, v20
	s_waitcnt lgkmcnt(0)
	v_add_u32_e32 v8, 0x20000, v22
	v_and_b32_e32 v7, 0xfffc0000, v7
	v_and_b32_e32 v8, 0xfffc0000, v8
	v_cvt_pk_bf16_f32 v7, v7, v8
	global_store_dwordx4 v[24:25], v[4:7], off
	v_add_u32_e32 v3, 0x20000, v3
	v_and_b32_e32 v3, 0xfffc0000, v3
	v_add_u32_e32 v4, 0x20000, v9
	v_and_b32_e32 v4, 0xfffc0000, v4
	v_cvt_pk_bf16_f32 v4, v3, v4
	v_add_u32_e32 v3, 0x20000, v11
	v_add_u32_e32 v5, 0x20000, v13
	v_and_b32_e32 v3, 0xfffc0000, v3
	v_and_b32_e32 v5, 0xfffc0000, v5
	v_cvt_pk_bf16_f32 v5, v3, v5
	v_add_u32_e32 v3, 0x20000, v15
	v_add_u32_e32 v6, 0x20000, v19
	v_and_b32_e32 v3, 0xfffc0000, v3
	v_and_b32_e32 v6, 0xfffc0000, v6
	v_or_b32_e32 v8, s0, v76
	v_cvt_pk_bf16_f32 v6, v3, v6
	v_add_u32_e32 v3, 0x20000, v21
	v_add_u32_e32 v7, 0x20000, v23
	v_ashrrev_i32_e32 v9, 31, v8
	v_and_b32_e32 v3, 0xfffc0000, v3
	v_and_b32_e32 v7, 0xfffc0000, v7
	v_lshlrev_b64 v[8:9], 13, v[8:9]
	v_cvt_pk_bf16_f32 v7, v3, v7
	v_lshl_add_u64 v[8:9], v[0:1], 0, v[8:9]
	global_store_dwordx4 v[8:9], v[4:7], off
	ds_read2_b32 v[8:9], v75 offset0:16 offset1:24
	ds_read2_b32 v[10:11], v75 offset0:81 offset1:89
	ds_read2_b32 v[12:13], v75 offset0:146 offset1:154
	ds_read2_b32 v[14:15], v75 offset0:211 offset1:219
	ds_read2_b32 v[18:19], v2 offset0:20 offset1:28
	ds_read2_b32 v[20:21], v2 offset0:85 offset1:93
	s_waitcnt lgkmcnt(5)
; __host__ __device__ __forceinline__ size_t blocked_off(int row, int col, int K) { return (((size_t)(row >> 8) * (K >> 6) + (col >> 6)) * 256 + (row & 255)) * 64 + (col & 63); }
; __device__ __forceinline__ unsigned cvt_pk_bf16(float lo, float hi) { const f32x2c_t v = {lo, hi}; return __builtin_bit_cast(unsigned, __builtin_convertvector(v, bf16x2c_t)); }
; #define LAS __attribute__((address_space(3)))
; #define LDS_WAIT() asm volatile("s_waitcnt lgkmcnt(0)" ::: "memory")
; __host__ __device__ __forceinline__ int win_phys_col(int n) { if (!win_rope_tile(n >> 8)) return n; const int cl = n & 255; return (n & ~255) | (cl & 63) | ((cl & 64) << 1) | ((cl & 128) >> 1); }
; template <bool PERMUTE, bool BLOCKED = false>
; __device__ __forceinline__ void cvt_tile64(const float* W, int K, int N, bf16* WT, int ldo, const float* gk, LAS float* scr, int tile, int lane) {
;     ...
;     const int kc = lane & 7, nrow0 = PERMUTE ? win_phys_col(n0) : n0;
; #pragma unroll
;     for (int j = 0; j < 8; ++j) { const int n = (lane >> 3) + 8 * j; const LAS float* s = scr + (8 * kc) * 65 + n;
;         v4u o; o[0] = cvt_pk_bf16(wrnd(s[0 * 65]), wrnd(s[1 * 65])); o[1] = cvt_pk_bf16(wrnd(s[2 * 65]), wrnd(s[3 * 65])); o[2] = cvt_pk_bf16(wrnd(s[4 * 65]), wrnd(s[5 * 65])); o[3] = cvt_pk_bf16(wrnd(s[6 * 65]), wrnd(s[7 * 65]));
;         *(v4u*)(WT + (BLOCKED ? pg8::blocked_off(nrow0 + n, k0 + 8 * kc, K) : (size_t)(nrow0 + n) * ldo + k0 + 8 * kc)) = o; }
;     LDS_WAIT(); asm volatile("" ::: "memory");
	v_add_u32_e32 v3, 0x20000, v8
	s_waitcnt lgkmcnt(4)
	v_add_u32_e32 v4, 0x20000, v10
	v_and_b32_e32 v3, 0xfffc0000, v3
	v_and_b32_e32 v4, 0xfffc0000, v4
	ds_read2_b32 v[22:23], v2 offset0:150 offset1:158
	ds_read2_b32 v[24:25], v2 offset0:215 offset1:223
	v_cvt_pk_bf16_f32 v4, v3, v4
	s_waitcnt lgkmcnt(5)
	v_add_u32_e32 v3, 0x20000, v12
	s_waitcnt lgkmcnt(4)
	v_add_u32_e32 v5, 0x20000, v14
	v_and_b32_e32 v3, 0xfffc0000, v3
	v_and_b32_e32 v5, 0xfffc0000, v5
	v_cvt_pk_bf16_f32 v5, v3, v5
	s_waitcnt lgkmcnt(3)
	v_add_u32_e32 v3, 0x20000, v18
	s_waitcnt lgkmcnt(2)
	v_add_u32_e32 v6, 0x20000, v20
	v_and_b32_e32 v3, 0xfffc0000, v3
	v_and_b32_e32 v6, 0xfffc0000, v6
	v_cvt_pk_bf16_f32 v6, v3, v6
	s_waitcnt lgkmcnt(1)
	v_add_u32_e32 v3, 0x20000, v22
	s_waitcnt lgkmcnt(0)
	v_add_u32_e32 v7, 0x20000, v24
	v_and_b32_e32 v3, 0xfffc0000, v3
	v_and_b32_e32 v7, 0xfffc0000, v7
	v_cvt_pk_bf16_f32 v7, v3, v7
	v_lshl_add_u64 v[26:27], v[0:1], 0, v[26:27]
	global_store_dwordx4 v[26:27], v[4:7], off
	v_add_u32_e32 v3, 0x20000, v9
	v_and_b32_e32 v3, 0xfffc0000, v3
	v_add_u32_e32 v4, 0x20000, v11
	v_and_b32_e32 v4, 0xfffc0000, v4
	v_cvt_pk_bf16_f32 v4, v3, v4
	v_add_u32_e32 v3, 0x20000, v13
	v_add_u32_e32 v5, 0x20000, v15
	v_and_b32_e32 v3, 0xfffc0000, v3
	v_and_b32_e32 v5, 0xfffc0000, v5
	v_cvt_pk_bf16_f32 v5, v3, v5
	v_add_u32_e32 v3, 0x20000, v19
	v_add_u32_e32 v6, 0x20000, v21
	v_and_b32_e32 v3, 0xfffc0000, v3
	v_and_b32_e32 v6, 0xfffc0000, v6
	v_or_b32_e32 v8, s0, v78
	v_cvt_pk_bf16_f32 v6, v3, v6
	v_add_u32_e32 v3, 0x20000, v23
	v_add_u32_e32 v7, 0x20000, v25
	v_ashrrev_i32_e32 v9, 31, v8
	v_and_b32_e32 v3, 0xfffc0000, v3
	v_and_b32_e32 v7, 0xfffc0000, v7
	v_lshlrev_b64 v[8:9], 13, v[8:9]
	v_cvt_pk_bf16_f32 v7, v3, v7
	v_lshl_add_u64 v[8:9], v[0:1], 0, v[8:9]
	global_store_dwordx4 v[8:9], v[4:7], off
	ds_read2_b32 v[8:9], v75 offset0:32 offset1:40
	ds_read2_b32 v[10:11], v75 offset0:97 offset1:105
	ds_read2_b32 v[12:13], v75 offset0:162 offset1:170
	ds_read2_b32 v[14:15], v75 offset0:227 offset1:235
	ds_read2_b32 v[18:19], v2 offset0:36 offset1:44
	ds_read2_b32 v[20:21], v2 offset0:101 offset1:109
	s_waitcnt lgkmcnt(5)
	v_add_u32_e32 v3, 0x20000, v8
	s_waitcnt lgkmcnt(4)
	v_add_u32_e32 v4, 0x20000, v10
	v_and_b32_e32 v3, 0xfffc0000, v3
	v_and_b32_e32 v4, 0xfffc0000, v4
	ds_read2_b32 v[22:23], v2 offset0:166 offset1:174
	ds_read2_b32 v[24:25], v2 offset0:231 offset1:239
	v_cvt_pk_bf16_f32 v4, v3, v4
	s_waitcnt lgkmcnt(5)
	v_add_u32_e32 v3, 0x20000, v12
	s_waitcnt lgkmcnt(4)
	v_add_u32_e32 v5, 0x20000, v14
	v_and_b32_e32 v3, 0xfffc0000, v3
	v_and_b32_e32 v5, 0xfffc0000, v5
	v_cvt_pk_bf16_f32 v5, v3, v5
	s_waitcnt lgkmcnt(3)
	v_add_u32_e32 v3, 0x20000, v18
	s_waitcnt lgkmcnt(2)
	v_add_u32_e32 v6, 0x20000, v20
	v_and_b32_e32 v3, 0xfffc0000, v3
	v_and_b32_e32 v6, 0xfffc0000, v6
	v_or_b32_e32 v26, s0, v79
	v_cvt_pk_bf16_f32 v6, v3, v6
	s_waitcnt lgkmcnt(1)
	v_add_u32_e32 v3, 0x20000, v22
	s_waitcnt lgkmcnt(0)
	v_add_u32_e32 v7, 0x20000, v24
	v_ashrrev_i32_e32 v27, 31, v26
	v_and_b32_e32 v3, 0xfffc0000, v3
	v_and_b32_e32 v7, 0xfffc0000, v7
	v_lshlrev_b64 v[26:27], 13, v[26:27]
	v_cvt_pk_bf16_f32 v7, v3, v7
	v_lshl_add_u64 v[26:27], v[0:1], 0, v[26:27]
	global_store_dwordx4 v[26:27], v[4:7], off
	v_add_u32_e32 v3, 0x20000, v9
	v_and_b32_e32 v3, 0xfffc0000, v3
	v_add_u32_e32 v4, 0x20000, v11
	v_and_b32_e32 v4, 0xfffc0000, v4
	v_cvt_pk_bf16_f32 v4, v3, v4
	v_add_u32_e32 v3, 0x20000, v13
	v_add_u32_e32 v5, 0x20000, v15
	v_and_b32_e32 v3, 0xfffc0000, v3
	v_and_b32_e32 v5, 0xfffc0000, v5
	v_cvt_pk_bf16_f32 v5, v3, v5
	v_add_u32_e32 v3, 0x20000, v19
	v_add_u32_e32 v6, 0x20000, v21
	v_and_b32_e32 v3, 0xfffc0000, v3
	v_and_b32_e32 v6, 0xfffc0000, v6
	v_or_b32_e32 v8, s0, v80
	v_cvt_pk_bf16_f32 v6, v3, v6
	v_add_u32_e32 v3, 0x20000, v23
	v_add_u32_e32 v7, 0x20000, v25
	v_ashrrev_i32_e32 v9, 31, v8
	v_and_b32_e32 v3, 0xfffc0000, v3
	v_and_b32_e32 v7, 0xfffc0000, v7
	v_lshlrev_b64 v[8:9], 13, v[8:9]
	v_cvt_pk_bf16_f32 v7, v3, v7
	v_lshl_add_u64 v[8:9], v[0:1], 0, v[8:9]
	global_store_dwordx4 v[8:9], v[4:7], off
	ds_read2_b32 v[8:9], v75 offset0:48 offset1:56
	ds_read2_b32 v[10:11], v75 offset0:113 offset1:121
	ds_read2_b32 v[12:13], v75 offset0:178 offset1:186
	ds_read2_b32 v[14:15], v75 offset0:243 offset1:251
	ds_read2_b32 v[18:19], v2 offset0:52 offset1:60
	ds_read2_b32 v[20:21], v2 offset0:117 offset1:125
	s_waitcnt lgkmcnt(5)
	v_add_u32_e32 v3, 0x20000, v8
	s_waitcnt lgkmcnt(4)
	v_add_u32_e32 v4, 0x20000, v10
	v_and_b32_e32 v3, 0xfffc0000, v3
	v_and_b32_e32 v4, 0xfffc0000, v4
	ds_read2_b32 v[22:23], v2 offset0:182 offset1:190
	ds_read2_b32 v[24:25], v2 offset0:247 offset1:255
	v_cvt_pk_bf16_f32 v4, v3, v4
	s_waitcnt lgkmcnt(5)
	v_add_u32_e32 v3, 0x20000, v12
	s_waitcnt lgkmcnt(4)
	v_add_u32_e32 v5, 0x20000, v14
	v_and_b32_e32 v3, 0xfffc0000, v3
	v_and_b32_e32 v5, 0xfffc0000, v5
	v_cvt_pk_bf16_f32 v5, v3, v5
	s_waitcnt lgkmcnt(3)
	v_add_u32_e32 v3, 0x20000, v18
	s_waitcnt lgkmcnt(2)
	v_add_u32_e32 v6, 0x20000, v20
	v_and_b32_e32 v3, 0xfffc0000, v3
	v_and_b32_e32 v6, 0xfffc0000, v6
	v_cvt_pk_bf16_f32 v6, v3, v6
	s_waitcnt lgkmcnt(1)
	v_add_u32_e32 v3, 0x20000, v22
	s_waitcnt lgkmcnt(0)
	v_add_u32_e32 v2, 0x20000, v24
	v_and_b32_e32 v3, 0xfffc0000, v3
	v_and_b32_e32 v2, 0xfffc0000, v2
	v_cvt_pk_bf16_f32 v7, v3, v2
	v_or_b32_e32 v2, s0, v81
	v_ashrrev_i32_e32 v3, 31, v2
	v_lshlrev_b64 v[2:3], 13, v[2:3]
	v_lshl_add_u64 v[2:3], v[0:1], 0, v[2:3]
	global_store_dwordx4 v[2:3], v[4:7], off
	v_add_u32_e32 v2, 0x20000, v9
	v_add_u32_e32 v3, 0x20000, v11
	v_and_b32_e32 v2, 0xfffc0000, v2
	v_and_b32_e32 v3, 0xfffc0000, v3
	v_cvt_pk_bf16_f32 v2, v2, v3
	v_add_u32_e32 v3, 0x20000, v13
	v_add_u32_e32 v4, 0x20000, v15
	v_and_b32_e32 v3, 0xfffc0000, v3
	v_and_b32_e32 v4, 0xfffc0000, v4
	v_cvt_pk_bf16_f32 v3, v3, v4
	v_add_u32_e32 v4, 0x20000, v19
	v_add_u32_e32 v5, 0x20000, v21
	v_and_b32_e32 v4, 0xfffc0000, v4
	v_and_b32_e32 v5, 0xfffc0000, v5
	v_cvt_pk_bf16_f32 v4, v4, v5
	v_add_u32_e32 v5, 0x20000, v23
	v_add_u32_e32 v6, 0x20000, v25
	v_and_b32_e32 v5, 0xfffc0000, v5
	v_and_b32_e32 v6, 0xfffc0000, v6
	v_cvt_pk_bf16_f32 v5, v5, v6
	v_or_b32_e32 v6, s0, v82
	v_ashrrev_i32_e32 v7, 31, v6
	v_lshlrev_b64 v[6:7], 13, v[6:7]
	v_lshl_add_u64 v[0:1], v[0:1], 0, v[6:7]
	global_store_dwordx4 v[0:1], v[2:5], off
	s_waitcnt lgkmcnt(0)
	s_mov_b64 s[0:1], 0
; #define LAS __attribute__((address_space(3)))
; template <bool PERMUTE, bool BLOCKED = false>
; __device__ __forceinline__ void cvt_tile64(const float* W, int K, int N, bf16* WT, int ldo, const float* gk, LAS float* scr, int tile, int lane) {
;     ...
;     for (int hh = 0; hh < 2; ++hh) {
;         f32x4 v[8];
; #pragma unroll
;         for (int i = 0; i < 8; ++i) v[i] = *(const f32x4*)(W + (size_t)(k0 + 32 * hh + 4 * i + lk) * N + n0 + ln);
; #pragma unroll
;         for (int i = 0; i < 8; ++i) { const int kk = 32 * hh + 4 * i + lk; const float g = gk ? gk[k0 + kk] : 1.0f; LAS float* d = scr + kk * 65 + ln;
;             d[0] = v[i][0] * g; d[1] = v[i][1] * g; d[2] = v[i][2] * g; d[3] = v[i][3] * g; }
;     }
; __device__ __forceinline__ void cvt_item(const CvtCtx& c, int batch, int wi, LAS float* scr, int wave, int lane) {
;     ...
;     if (wi < CVT_DN) { cvt_tile64<false, true>(c.w_down + (size_t)l * DFF * DM, DFF, DM, c.WdnT + (size_t)l * DM * DFF, 0, nullptr, scr, 8 * wi + wave, lane); return; } wi -= CVT_DN;
.LBB0_811:
	s_andn2_b64 vcc, exec, s[0:1]
	s_cbranch_vccnz .LBB0_813
	s_add_i32 s0, s16, 0x4000
	s_ashr_i32 s1, s0, 31
	s_lshr_b32 s1, s1, 26
	s_add_i32 s0, s0, s1
	s_ashr_i32 s4, s0, 6
	s_lshl_b32 s5, s4, 12
	s_andn2_b32 s0, s0, 63
	s_sub_i32 s5, s13, s5
	s_add_i32 s18, s5, 0x100000
	v_or_b32_e32 v2, s0, v16
	s_ashr_i32 s19, s18, 31
	v_ashrrev_i32_e32 v3, 31, v2
	v_lshl_add_u64 v[0:1], s[18:19], 2, v[38:39]
	v_lshlrev_b64 v[4:5], 14, v[2:3]
	v_or_b32_e32 v8, 4, v2
	v_lshl_add_u64 v[4:5], v[0:1], 0, v[4:5]
	v_ashrrev_i32_e32 v9, 31, v8
	global_load_dwordx4 v[4:7], v[4:5], off nt
	v_lshlrev_b64 v[8:9], 14, v[8:9]
	v_or_b32_e32 v12, 8, v2
	v_lshl_add_u64 v[8:9], v[0:1], 0, v[8:9]
	v_ashrrev_i32_e32 v13, 31, v12
	global_load_dwordx4 v[8:11], v[8:9], off nt
	v_lshlrev_b64 v[12:13], 14, v[12:13]
	v_or_b32_e32 v18, 12, v2
	v_lshl_add_u64 v[12:13], v[0:1], 0, v[12:13]
	v_ashrrev_i32_e32 v19, 31, v18
	global_load_dwordx4 v[12:15], v[12:13], off nt
	v_lshlrev_b64 v[18:19], 14, v[18:19]
	v_or_b32_e32 v22, 16, v2
	v_lshl_add_u64 v[18:19], v[0:1], 0, v[18:19]
	v_ashrrev_i32_e32 v23, 31, v22
	global_load_dwordx4 v[18:21], v[18:19], off nt
	v_lshlrev_b64 v[22:23], 14, v[22:23]
	v_or_b32_e32 v26, 20, v2
	v_lshl_add_u64 v[22:23], v[0:1], 0, v[22:23]
	v_ashrrev_i32_e32 v27, 31, v26
	global_load_dwordx4 v[22:25], v[22:23], off nt
	v_lshlrev_b64 v[26:27], 14, v[26:27]
	v_or_b32_e32 v30, 24, v2
	v_lshl_add_u64 v[26:27], v[0:1], 0, v[26:27]
	v_ashrrev_i32_e32 v31, 31, v30
	global_load_dwordx4 v[26:29], v[26:27], off nt
	v_lshlrev_b64 v[30:31], 14, v[30:31]
	v_or_b32_e32 v50, 28, v2
	v_lshl_add_u64 v[30:31], v[0:1], 0, v[30:31]
	v_ashrrev_i32_e32 v51, 31, v50
	global_load_dwordx4 v[30:33], v[30:31], off nt
	v_lshlrev_b64 v[50:51], 14, v[50:51]
	v_lshl_add_u64 v[50:51], v[0:1], 0, v[50:51]
	global_load_dwordx4 v[50:53], v[50:51], off nt
	v_add_u32_e32 v54, v55, v57
	v_add_u32_e32 v3, 0x410, v54
	s_ashr_i32 s6, s18, 8
	s_ashr_i32 s7, s6, 31
	s_ashr_i32 s5, s4, 31
	s_add_i32 s1, s13, 0x100000
	s_lshl_b64 s[6:7], s[6:7], 16
	s_lshl_b64 s[4:5], s[4:5], 8
	s_add_u32 s0, s6, s4
	s_addc_u32 s4, s7, s5
	s_and_b32 s1, s1, 0xc0
	s_waitcnt vmcnt(7)
	ds_write2_b32 v54, v4, v5 offset1:1
	ds_write2_b32 v54, v6, v7 offset0:2 offset1:3
	v_or_b32_e32 v4, 32, v2
	v_ashrrev_i32_e32 v5, 31, v4
	v_lshlrev_b64 v[4:5], 14, v[4:5]
	v_lshl_add_u64 v[4:5], v[0:1], 0, v[4:5]
	s_waitcnt vmcnt(6)
	ds_write2_b32 v3, v8, v9 offset1:1
	v_add_u32_e32 v3, 0x418, v54
	v_or_b32_e32 v8, 36, v2
	ds_write2_b32 v3, v10, v11 offset1:1
	v_add_u32_e32 v3, 0x820, v54
	v_ashrrev_i32_e32 v9, 31, v8
	s_waitcnt vmcnt(5)
	ds_write2_b32 v3, v12, v13 offset1:1
	v_add_u32_e32 v3, 0x828, v54
	global_load_dwordx4 v[4:7], v[4:5], off nt
	v_lshlrev_b64 v[8:9], 14, v[8:9]
	v_or_b32_e32 v12, 40, v2
	ds_write2_b32 v3, v14, v15 offset1:1
	v_add_u32_e32 v3, 0xc30, v54
	v_lshl_add_u64 v[8:9], v[0:1], 0, v[8:9]
	v_ashrrev_i32_e32 v13, 31, v12
	s_waitcnt vmcnt(5)
	ds_write2_b32 v3, v18, v19 offset1:1
	v_add_u32_e32 v3, 0xc38, v54
	global_load_dwordx4 v[8:11], v[8:9], off nt
	v_lshlrev_b64 v[12:13], 14, v[12:13]
	v_or_b32_e32 v18, 44, v2
	ds_write2_b32 v3, v20, v21 offset1:1
	v_add_u32_e32 v3, 0x1040, v54
	v_lshl_add_u64 v[12:13], v[0:1], 0, v[12:13]
	v_ashrrev_i32_e32 v19, 31, v18
	s_waitcnt vmcnt(5)
	ds_write2_b32 v3, v22, v23 offset1:1
	v_add_u32_e32 v3, 0x1048, v54
	global_load_dwordx4 v[12:15], v[12:13], off nt
	v_lshlrev_b64 v[18:19], 14, v[18:19]
	v_or_b32_e32 v22, 48, v2
	ds_write2_b32 v3, v24, v25 offset1:1
	v_add_u32_e32 v3, 0x1450, v54
	v_lshl_add_u64 v[18:19], v[0:1], 0, v[18:19]
	v_ashrrev_i32_e32 v23, 31, v22
	s_waitcnt vmcnt(5)
	ds_write2_b32 v3, v26, v27 offset1:1
	v_add_u32_e32 v3, 0x1458, v54
	global_load_dwordx4 v[18:21], v[18:19], off nt
	v_lshlrev_b64 v[22:23], 14, v[22:23]
	v_or_b32_e32 v26, 52, v2
	ds_write2_b32 v3, v28, v29 offset1:1
	v_add_u32_e32 v3, 0x1860, v54
	v_lshl_add_u64 v[22:23], v[0:1], 0, v[22:23]
	v_ashrrev_i32_e32 v27, 31, v26
	s_waitcnt vmcnt(5)
	ds_write2_b32 v3, v30, v31 offset1:1
	v_add_u32_e32 v3, 0x1868, v54
	global_load_dwordx4 v[22:25], v[22:23], off nt
	v_lshlrev_b64 v[26:27], 14, v[26:27]
	v_or_b32_e32 v30, 56, v2
	ds_write2_b32 v3, v32, v33 offset1:1
	v_add_u32_e32 v3, 0x1c70, v54
	v_lshl_add_u64 v[26:27], v[0:1], 0, v[26:27]
	v_ashrrev_i32_e32 v31, 31, v30
	s_waitcnt vmcnt(5)
	ds_write2_b32 v3, v50, v51 offset1:1
	v_add_u32_e32 v3, 0x1c78, v54
	global_load_dwordx4 v[26:29], v[26:27], off nt
	v_lshlrev_b64 v[30:31], 14, v[30:31]
	v_or_b32_e32 v2, 60, v2
	ds_write2_b32 v3, v52, v53 offset1:1
	v_lshl_add_u64 v[30:31], v[0:1], 0, v[30:31]
	v_ashrrev_i32_e32 v3, 31, v2
	global_load_dwordx4 v[30:33], v[30:31], off nt
	v_lshlrev_b64 v[2:3], 14, v[2:3]
	v_lshl_add_u64 v[0:1], v[0:1], 0, v[2:3]
	global_load_dwordx4 v[0:3], v[0:1], off nt
	v_add_u32_e32 v50, 0x2080, v54
	s_waitcnt vmcnt(7)
	ds_write2_b32 v50, v4, v5 offset1:1
	v_add_u32_e32 v4, 0x2088, v54
	ds_write2_b32 v4, v6, v7 offset1:1
	v_add_u32_e32 v4, 0x2490, v54
	s_waitcnt vmcnt(6)
	ds_write2_b32 v4, v8, v9 offset1:1
	v_add_u32_e32 v4, 0x2498, v54
	ds_write2_b32 v4, v10, v11 offset1:1
	v_add_u32_e32 v4, 0x28a0, v54
	s_waitcnt vmcnt(5)
	ds_write2_b32 v4, v12, v13 offset1:1
	v_add_u32_e32 v4, 0x28a8, v54
	ds_write2_b32 v4, v14, v15 offset1:1
	v_add_u32_e32 v4, 0x2cb0, v54
	s_waitcnt vmcnt(4)
	ds_write2_b32 v4, v18, v19 offset1:1
	v_add_u32_e32 v4, 0x2cb8, v54
	ds_write2_b32 v4, v20, v21 offset1:1
	v_add_u32_e32 v4, 0x30c0, v54
	s_waitcnt vmcnt(3)
	ds_write2_b32 v4, v22, v23 offset1:1
	v_add_u32_e32 v4, 0x30c8, v54
	ds_write2_b32 v4, v24, v25 offset1:1
	v_add_u32_e32 v4, 0x34d0, v54
	s_waitcnt vmcnt(2)
; __host__ __device__ __forceinline__ size_t blocked_off(int row, int col, int K) { return (((size_t)(row >> 8) * (K >> 6) + (col >> 6)) * 256 + (row & 255)) * 64 + (col & 63); }
; __device__ __forceinline__ unsigned cvt_pk_bf16(float lo, float hi) { const f32x2c_t v = {lo, hi}; return __builtin_bit_cast(unsigned, __builtin_convertvector(v, bf16x2c_t)); }
; #define LAS __attribute__((address_space(3)))
; #define LDS_WAIT() asm volatile("s_waitcnt lgkmcnt(0)" ::: "memory")
; __host__ __device__ __forceinline__ int win_phys_col(int n) { if (!win_rope_tile(n >> 8)) return n; const int cl = n & 255; return (n & ~255) | (cl & 63) | ((cl & 64) << 1) | ((cl & 128) >> 1); }
; template <bool PERMUTE, bool BLOCKED = false>
; __device__ __forceinline__ void cvt_tile64(const float* W, int K, int N, bf16* WT, int ldo, const float* gk, LAS float* scr, int tile, int lane) {
;     ...
;         for (int i = 0; i < 8; ++i) { const int kk = 32 * hh + 4 * i + lk; const float g = gk ? gk[k0 + kk] : 1.0f; LAS float* d = scr + kk * 65 + ln;
;             d[0] = v[i][0] * g; d[1] = v[i][1] * g; d[2] = v[i][2] * g; d[3] = v[i][3] * g; }
;     }
;     ...
;     LDS_WAIT(); asm volatile("" ::: "memory");
;     const int kc = lane & 7, nrow0 = PERMUTE ? win_phys_col(n0) : n0;
; #pragma unroll
;     for (int j = 0; j < 8; ++j) { const int n = (lane >> 3) + 8 * j; const LAS float* s = scr + (8 * kc) * 65 + n;
;         v4u o; o[0] = cvt_pk_bf16(wrnd(s[0 * 65]), wrnd(s[1 * 65])); o[1] = cvt_pk_bf16(wrnd(s[2 * 65]), wrnd(s[3 * 65])); o[2] = cvt_pk_bf16(wrnd(s[4 * 65]), wrnd(s[5 * 65])); o[3] = cvt_pk_bf16(wrnd(s[6 * 65]), wrnd(s[7 * 65]));
;         *(v4u*)(WT + (BLOCKED ? pg8::blocked_off(nrow0 + n, k0 + 8 * kc, K) : (size_t)(nrow0 + n) * ldo + k0 + 8 * kc)) = o; }
	ds_write2_b32 v4, v26, v27 offset1:1
	v_add_u32_e32 v4, 0x34d8, v54
	ds_write2_b32 v4, v28, v29 offset1:1
	v_add_u32_e32 v4, 0x38e0, v54
	s_waitcnt vmcnt(1)
	ds_write2_b32 v4, v30, v31 offset1:1
	v_add_u32_e32 v4, 0x38e8, v54
	ds_write2_b32 v4, v32, v33 offset1:1
	v_add_u32_e32 v4, 0x3cf0, v54
	s_waitcnt vmcnt(0)
	ds_write2_b32 v4, v0, v1 offset1:1
	v_add_u32_e32 v0, 0x3cf8, v54
	ds_write2_b32 v0, v2, v3 offset1:1
	s_waitcnt lgkmcnt(0)
	ds_read2_b32 v[2:3], v75 offset1:8
	ds_read2_b32 v[8:9], v75 offset0:65 offset1:73
	ds_read2_b32 v[10:11], v75 offset0:130 offset1:138
	ds_read2_b32 v[12:13], v75 offset0:195 offset1:203
	s_waitcnt lgkmcnt(3)
	v_add_u32_e32 v0, 0x20000, v2
	v_add_u32_e32 v2, 0x400, v75
	ds_read2_b32 v[14:15], v2 offset0:4 offset1:12
	ds_read2_b32 v[18:19], v2 offset0:69 offset1:77
	s_waitcnt lgkmcnt(4)
	v_add_u32_e32 v1, 0x20000, v8
	v_and_b32_e32 v0, 0xfffc0000, v0
	v_and_b32_e32 v1, 0xfffc0000, v1
	ds_read2_b32 v[20:21], v2 offset0:134 offset1:142
	ds_read2_b32 v[22:23], v2 offset0:199 offset1:207
	v_cvt_pk_bf16_f32 v4, v0, v1
	s_waitcnt lgkmcnt(5)
	v_add_u32_e32 v0, 0x20000, v10
	s_waitcnt lgkmcnt(4)
	v_add_u32_e32 v1, 0x20000, v12
	v_and_b32_e32 v0, 0xfffc0000, v0
	v_and_b32_e32 v1, 0xfffc0000, v1
	v_cvt_pk_bf16_f32 v5, v0, v1
	s_waitcnt lgkmcnt(3)
	v_add_u32_e32 v0, 0x20000, v14
	s_waitcnt lgkmcnt(2)
	v_add_u32_e32 v1, 0x20000, v18
	v_and_b32_e32 v0, 0xfffc0000, v0
	v_and_b32_e32 v1, 0xfffc0000, v1
	v_cvt_pk_bf16_f32 v6, v0, v1
	s_waitcnt lgkmcnt(1)
	v_add_u32_e32 v0, 0x20000, v20
	s_waitcnt lgkmcnt(0)
	v_add_u32_e32 v1, 0x20000, v22
	v_and_b32_e32 v0, 0xfffc0000, v0
	v_and_b32_e32 v1, 0xfffc0000, v1
	v_cvt_pk_bf16_f32 v7, v0, v1
	v_or_b32_e32 v0, s1, v74
	v_or_b32_e32 v0, s0, v0
	v_mov_b32_e32 v1, s4
	v_lshlrev_b64 v[24:25], 7, v[0:1]
	v_add_u32_e32 v0, 0x20000, v3
	v_add_u32_e32 v3, 0x20000, v9
	v_lshl_add_u64 v[24:25], v[40:41], 0, v[24:25]
	v_and_b32_e32 v0, 0xfffc0000, v0
	v_and_b32_e32 v3, 0xfffc0000, v3
	global_store_dwordx4 v[24:25], v[4:7], off
	ds_read2_b32 v[24:25], v2 offset0:215 offset1:223
	s_nop 0
	v_cvt_pk_bf16_f32 v4, v0, v3
	v_add_u32_e32 v0, 0x20000, v11
	v_add_u32_e32 v3, 0x20000, v13
	v_and_b32_e32 v0, 0xfffc0000, v0
	v_and_b32_e32 v3, 0xfffc0000, v3
	v_cvt_pk_bf16_f32 v5, v0, v3
	v_add_u32_e32 v0, 0x20000, v15
	v_add_u32_e32 v3, 0x20000, v19
	v_and_b32_e32 v0, 0xfffc0000, v0
	v_and_b32_e32 v3, 0xfffc0000, v3
	v_cvt_pk_bf16_f32 v6, v0, v3
	v_add_u32_e32 v0, 0x20000, v21
	v_add_u32_e32 v3, 0x20000, v23
	v_and_b32_e32 v0, 0xfffc0000, v0
	v_and_b32_e32 v3, 0xfffc0000, v3
	v_cvt_pk_bf16_f32 v7, v0, v3
	v_or_b32_e32 v0, s1, v76
	v_or_b32_e32 v0, s0, v0
	v_lshlrev_b64 v[8:9], 7, v[0:1]
	v_lshl_add_u64 v[8:9], v[40:41], 0, v[8:9]
	global_store_dwordx4 v[8:9], v[4:7], off
	ds_read2_b32 v[8:9], v75 offset0:16 offset1:24
	ds_read2_b32 v[10:11], v75 offset0:81 offset1:89
	ds_read2_b32 v[12:13], v75 offset0:146 offset1:154
	ds_read2_b32 v[14:15], v75 offset0:211 offset1:219
	ds_read2_b32 v[18:19], v2 offset0:20 offset1:28
	ds_read2_b32 v[20:21], v2 offset0:85 offset1:93
	s_waitcnt lgkmcnt(5)
	v_add_u32_e32 v0, 0x20000, v8
	s_waitcnt lgkmcnt(4)
	v_add_u32_e32 v3, 0x20000, v10
	v_and_b32_e32 v0, 0xfffc0000, v0
	v_and_b32_e32 v3, 0xfffc0000, v3
	ds_read2_b32 v[22:23], v2 offset0:150 offset1:158
	v_cvt_pk_bf16_f32 v4, v0, v3
	s_waitcnt lgkmcnt(4)
	v_add_u32_e32 v0, 0x20000, v12
	s_waitcnt lgkmcnt(3)
	v_add_u32_e32 v3, 0x20000, v14
	v_and_b32_e32 v0, 0xfffc0000, v0
	v_and_b32_e32 v3, 0xfffc0000, v3
	v_cvt_pk_bf16_f32 v5, v0, v3
	s_waitcnt lgkmcnt(2)
	v_add_u32_e32 v0, 0x20000, v18
	s_waitcnt lgkmcnt(1)
	v_add_u32_e32 v3, 0x20000, v20
	v_and_b32_e32 v0, 0xfffc0000, v0
	v_and_b32_e32 v3, 0xfffc0000, v3
	v_cvt_pk_bf16_f32 v6, v0, v3
	s_waitcnt lgkmcnt(0)
	v_add_u32_e32 v0, 0x20000, v22
	v_add_u32_e32 v3, 0x20000, v24
	v_and_b32_e32 v0, 0xfffc0000, v0
	v_and_b32_e32 v3, 0xfffc0000, v3
	v_cvt_pk_bf16_f32 v7, v0, v3
	v_or_b32_e32 v0, s1, v77
	v_or_b32_e32 v0, s0, v0
	v_lshlrev_b64 v[26:27], 7, v[0:1]
	v_add_u32_e32 v0, 0x20000, v9
	v_add_u32_e32 v3, 0x20000, v11
	v_lshl_add_u64 v[26:27], v[40:41], 0, v[26:27]
	v_and_b32_e32 v0, 0xfffc0000, v0
	v_and_b32_e32 v3, 0xfffc0000, v3
	global_store_dwordx4 v[26:27], v[4:7], off
	ds_read2_b32 v[10:11], v75 offset0:97 offset1:105
	s_nop 0
	v_cvt_pk_bf16_f32 v4, v0, v3
	v_add_u32_e32 v0, 0x20000, v13
	v_add_u32_e32 v3, 0x20000, v15
	v_and_b32_e32 v0, 0xfffc0000, v0
	v_and_b32_e32 v3, 0xfffc0000, v3
	v_cvt_pk_bf16_f32 v5, v0, v3
	v_add_u32_e32 v0, 0x20000, v19
	v_add_u32_e32 v3, 0x20000, v21
	v_and_b32_e32 v0, 0xfffc0000, v0
	v_and_b32_e32 v3, 0xfffc0000, v3
	v_cvt_pk_bf16_f32 v6, v0, v3
	v_add_u32_e32 v0, 0x20000, v23
	v_add_u32_e32 v3, 0x20000, v25
	v_and_b32_e32 v0, 0xfffc0000, v0
	v_and_b32_e32 v3, 0xfffc0000, v3
	v_cvt_pk_bf16_f32 v7, v0, v3
	v_or_b32_e32 v0, s1, v78
	v_or_b32_e32 v0, s0, v0
	v_lshlrev_b64 v[8:9], 7, v[0:1]
	v_lshl_add_u64 v[8:9], v[40:41], 0, v[8:9]
	global_store_dwordx4 v[8:9], v[4:7], off
	ds_read2_b32 v[8:9], v75 offset0:32 offset1:40
	ds_read2_b32 v[12:13], v75 offset0:162 offset1:170
	ds_read2_b32 v[14:15], v75 offset0:227 offset1:235
	ds_read2_b32 v[18:19], v2 offset0:36 offset1:44
	ds_read2_b32 v[20:21], v2 offset0:101 offset1:109
	s_waitcnt lgkmcnt(4)
; __host__ __device__ __forceinline__ size_t blocked_off(int row, int col, int K) { return (((size_t)(row >> 8) * (K >> 6) + (col >> 6)) * 256 + (row & 255)) * 64 + (col & 63); }
; __device__ __forceinline__ unsigned cvt_pk_bf16(float lo, float hi) { const f32x2c_t v = {lo, hi}; return __builtin_bit_cast(unsigned, __builtin_convertvector(v, bf16x2c_t)); }
; #define LAS __attribute__((address_space(3)))
; #define LDS_WAIT() asm volatile("s_waitcnt lgkmcnt(0)" ::: "memory")
; __host__ __device__ __forceinline__ int win_phys_col(int n) { if (!win_rope_tile(n >> 8)) return n; const int cl = n & 255; return (n & ~255) | (cl & 63) | ((cl & 64) << 1) | ((cl & 128) >> 1); }
; template <bool PERMUTE, bool BLOCKED = false>
; __device__ __forceinline__ void cvt_tile64(const float* W, int K, int N, bf16* WT, int ldo, const float* gk, LAS float* scr, int tile, int lane) {
;     ...
;     const int kc = lane & 7, nrow0 = PERMUTE ? win_phys_col(n0) : n0;
; #pragma unroll
;     for (int j = 0; j < 8; ++j) { const int n = (lane >> 3) + 8 * j; const LAS float* s = scr + (8 * kc) * 65 + n;
;         v4u o; o[0] = cvt_pk_bf16(wrnd(s[0 * 65]), wrnd(s[1 * 65])); o[1] = cvt_pk_bf16(wrnd(s[2 * 65]), wrnd(s[3 * 65])); o[2] = cvt_pk_bf16(wrnd(s[4 * 65]), wrnd(s[5 * 65])); o[3] = cvt_pk_bf16(wrnd(s[6 * 65]), wrnd(s[7 * 65]));
;         *(v4u*)(WT + (BLOCKED ? pg8::blocked_off(nrow0 + n, k0 + 8 * kc, K) : (size_t)(nrow0 + n) * ldo + k0 + 8 * kc)) = o; }
;     LDS_WAIT(); asm volatile("" ::: "memory");
	v_add_u32_e32 v0, 0x20000, v8
	v_add_u32_e32 v3, 0x20000, v10
	v_and_b32_e32 v0, 0xfffc0000, v0
	v_and_b32_e32 v3, 0xfffc0000, v3
	ds_read2_b32 v[22:23], v2 offset0:166 offset1:174
	ds_read2_b32 v[24:25], v2 offset0:231 offset1:239
	v_cvt_pk_bf16_f32 v4, v0, v3
	s_waitcnt lgkmcnt(5)
	v_add_u32_e32 v0, 0x20000, v12
	s_waitcnt lgkmcnt(4)
	v_add_u32_e32 v3, 0x20000, v14
	v_and_b32_e32 v0, 0xfffc0000, v0
	v_and_b32_e32 v3, 0xfffc0000, v3
	v_cvt_pk_bf16_f32 v5, v0, v3
	s_waitcnt lgkmcnt(3)
	v_add_u32_e32 v0, 0x20000, v18
	s_waitcnt lgkmcnt(2)
	v_add_u32_e32 v3, 0x20000, v20
	v_and_b32_e32 v0, 0xfffc0000, v0
	v_and_b32_e32 v3, 0xfffc0000, v3
	v_cvt_pk_bf16_f32 v6, v0, v3
	s_waitcnt lgkmcnt(1)
	v_add_u32_e32 v0, 0x20000, v22
	s_waitcnt lgkmcnt(0)
	v_add_u32_e32 v3, 0x20000, v24
	v_and_b32_e32 v0, 0xfffc0000, v0
	v_and_b32_e32 v3, 0xfffc0000, v3
	v_cvt_pk_bf16_f32 v7, v0, v3
	v_or_b32_e32 v0, s1, v79
	v_or_b32_e32 v0, s0, v0
	v_lshlrev_b64 v[26:27], 7, v[0:1]
	v_add_u32_e32 v0, 0x20000, v9
	v_add_u32_e32 v3, 0x20000, v11
	v_lshl_add_u64 v[26:27], v[40:41], 0, v[26:27]
	v_and_b32_e32 v0, 0xfffc0000, v0
	v_and_b32_e32 v3, 0xfffc0000, v3
	global_store_dwordx4 v[26:27], v[4:7], off
	ds_read2_b32 v[10:11], v75 offset0:113 offset1:121
	s_nop 0
	v_cvt_pk_bf16_f32 v4, v0, v3
	v_add_u32_e32 v0, 0x20000, v13
	v_add_u32_e32 v3, 0x20000, v15
	v_and_b32_e32 v0, 0xfffc0000, v0
	v_and_b32_e32 v3, 0xfffc0000, v3
	v_cvt_pk_bf16_f32 v5, v0, v3
	v_add_u32_e32 v0, 0x20000, v19
	v_add_u32_e32 v3, 0x20000, v21
	v_and_b32_e32 v0, 0xfffc0000, v0
	v_and_b32_e32 v3, 0xfffc0000, v3
	v_cvt_pk_bf16_f32 v6, v0, v3
	v_add_u32_e32 v0, 0x20000, v23
	v_add_u32_e32 v3, 0x20000, v25
	v_and_b32_e32 v0, 0xfffc0000, v0
	v_and_b32_e32 v3, 0xfffc0000, v3
	v_cvt_pk_bf16_f32 v7, v0, v3
	v_or_b32_e32 v0, s1, v80
	v_or_b32_e32 v0, s0, v0
	v_lshlrev_b64 v[8:9], 7, v[0:1]
	v_lshl_add_u64 v[8:9], v[40:41], 0, v[8:9]
	global_store_dwordx4 v[8:9], v[4:7], off
	ds_read2_b32 v[8:9], v75 offset0:48 offset1:56
	ds_read2_b32 v[12:13], v75 offset0:178 offset1:186
	ds_read2_b32 v[14:15], v75 offset0:243 offset1:251
	ds_read2_b32 v[18:19], v2 offset0:52 offset1:60
	ds_read2_b32 v[20:21], v2 offset0:117 offset1:125
	s_waitcnt lgkmcnt(4)
	v_add_u32_e32 v0, 0x20000, v8
	v_add_u32_e32 v3, 0x20000, v10
	v_and_b32_e32 v0, 0xfffc0000, v0
	v_and_b32_e32 v3, 0xfffc0000, v3
	ds_read2_b32 v[22:23], v2 offset0:182 offset1:190
	ds_read2_b32 v[24:25], v2 offset0:247 offset1:255
	v_cvt_pk_bf16_f32 v4, v0, v3
	s_waitcnt lgkmcnt(5)
	v_add_u32_e32 v0, 0x20000, v12
	s_waitcnt lgkmcnt(4)
	v_add_u32_e32 v3, 0x20000, v14
	v_and_b32_e32 v0, 0xfffc0000, v0
	v_and_b32_e32 v3, 0xfffc0000, v3
	v_cvt_pk_bf16_f32 v5, v0, v3
	s_waitcnt lgkmcnt(3)
	v_add_u32_e32 v0, 0x20000, v18
	s_waitcnt lgkmcnt(2)
	v_add_u32_e32 v3, 0x20000, v20
	v_and_b32_e32 v0, 0xfffc0000, v0
	v_and_b32_e32 v3, 0xfffc0000, v3
	v_cvt_pk_bf16_f32 v6, v0, v3
	s_waitcnt lgkmcnt(1)
	v_add_u32_e32 v0, 0x20000, v22
	s_waitcnt lgkmcnt(0)
	v_add_u32_e32 v2, 0x20000, v24
	v_and_b32_e32 v0, 0xfffc0000, v0
	v_and_b32_e32 v2, 0xfffc0000, v2
	v_cvt_pk_bf16_f32 v7, v0, v2
	v_or_b32_e32 v0, s1, v81
	v_or_b32_e32 v0, s0, v0
	v_lshlrev_b64 v[2:3], 7, v[0:1]
	v_lshl_add_u64 v[2:3], v[40:41], 0, v[2:3]
	global_store_dwordx4 v[2:3], v[4:7], off
	v_add_u32_e32 v0, 0x20000, v9
	v_add_u32_e32 v2, 0x20000, v11
	v_and_b32_e32 v0, 0xfffc0000, v0
	v_and_b32_e32 v2, 0xfffc0000, v2
	v_cvt_pk_bf16_f32 v2, v0, v2
	v_add_u32_e32 v0, 0x20000, v13
	v_add_u32_e32 v3, 0x20000, v15
	v_and_b32_e32 v0, 0xfffc0000, v0
	v_and_b32_e32 v3, 0xfffc0000, v3
	v_cvt_pk_bf16_f32 v3, v0, v3
	v_add_u32_e32 v0, 0x20000, v19
	v_add_u32_e32 v4, 0x20000, v21
	v_and_b32_e32 v0, 0xfffc0000, v0
	v_and_b32_e32 v4, 0xfffc0000, v4
	v_cvt_pk_bf16_f32 v4, v0, v4
	v_add_u32_e32 v0, 0x20000, v23
	v_add_u32_e32 v5, 0x20000, v25
	v_and_b32_e32 v0, 0xfffc0000, v0
	v_and_b32_e32 v5, 0xfffc0000, v5
	v_cvt_pk_bf16_f32 v5, v0, v5
	v_or_b32_e32 v0, s1, v82
	v_or_b32_e32 v0, s0, v0
	v_lshlrev_b64 v[0:1], 7, v[0:1]
	v_lshl_add_u64 v[0:1], v[40:41], 0, v[0:1]
	global_store_dwordx4 v[0:1], v[2:5], off
	s_waitcnt lgkmcnt(0)

; #define LAS __attribute__((address_space(3)))
; template <bool PERMUTE, bool BLOCKED = false>
; __device__ __forceinline__ void cvt_tile64(const float* W, int K, int N, bf16* WT, int ldo, const float* gk, LAS float* scr, int tile, int lane) {
;     ...
;     for (int hh = 0; hh < 2; ++hh) {
;         f32x4 v[8];
; #pragma unroll
;         for (int i = 0; i < 8; ++i) v[i] = *(const f32x4*)(W + (size_t)(k0 + 32 * hh + 4 * i + lk) * N + n0 + ln);
; #pragma unroll
;         for (int i = 0; i < 8; ++i) { const int kk = 32 * hh + 4 * i + lk; const float g = gk ? gk[k0 + kk] : 1.0f; LAS float* d = scr + kk * 65 + ln;
;             d[0] = v[i][0] * g; d[1] = v[i][1] * g; d[2] = v[i][2] * g; d[3] = v[i][3] * g; }
; __device__ __forceinline__ void cvt_item(const CvtCtx& c, int batch, int wi, LAS float* scr, int wave, int lane) {
;     ...
;     if (wi < CVT_UP) { cvt_tile64<false>(c.w_up + (size_t)l * DM * DFF, DM, DFF, c.WupT + (size_t)l * DFF * DM, DM, c.g_mlp + l * DM, scr, 8 * wi + wave, lane); return; } wi -= CVT_UP;
.LBB0_814:
	s_andn2_b64 vcc, exec, s[0:1]
	s_cbranch_vccnz .LBB0_834
	s_add_i32 s0, s16, 0x8000
	s_ashr_i32 s1, s0, 31
	s_lshr_b32 s1, s1, 24
	s_add_i32 s0, s0, s1
	s_ashr_i32 s0, s0, 8
	s_lshl_b32 s18, s0, 6
	s_lshl_b32 s20, s0, 14
	s_sub_i32 s0, s13, s20
	v_or_b32_e32 v52, s18, v16
	s_add_i32 s0, s0, 0x200000
	v_or_b32_e32 v2, 4, v52
	s_ashr_i32 s1, s0, 31
	v_ashrrev_i32_e32 v53, 31, v52
	v_ashrrev_i32_e32 v3, 31, v2
	v_lshl_add_u64 v[50:51], s[0:1], 2, v[42:43]
	v_lshlrev_b64 v[0:1], 16, v[52:53]
	v_lshlrev_b64 v[2:3], 16, v[2:3]
	v_lshl_add_u64 v[0:1], v[50:51], 0, v[0:1]
	v_lshl_add_u64 v[2:3], v[50:51], 0, v[2:3]
	global_load_dwordx4 v[30:33], v[0:1], off nt
	global_load_dwordx4 v[26:29], v[2:3], off nt
	v_or_b32_e32 v0, 8, v52
	v_or_b32_e32 v2, 12, v52
	v_ashrrev_i32_e32 v1, 31, v0
	v_ashrrev_i32_e32 v3, 31, v2
	v_lshlrev_b64 v[0:1], 16, v[0:1]
	v_lshlrev_b64 v[2:3], 16, v[2:3]
	v_lshl_add_u64 v[0:1], v[50:51], 0, v[0:1]
	v_lshl_add_u64 v[2:3], v[50:51], 0, v[2:3]
	global_load_dwordx4 v[22:25], v[0:1], off nt
	global_load_dwordx4 v[18:21], v[2:3], off nt
	v_or_b32_e32 v0, 16, v52
	v_or_b32_e32 v2, 20, v52
	v_ashrrev_i32_e32 v1, 31, v0
	v_ashrrev_i32_e32 v3, 31, v2
	v_lshlrev_b64 v[0:1], 16, v[0:1]
	v_lshlrev_b64 v[2:3], 16, v[2:3]
	v_lshl_add_u64 v[0:1], v[50:51], 0, v[0:1]
	v_lshl_add_u64 v[2:3], v[50:51], 0, v[2:3]
	global_load_dwordx4 v[12:15], v[0:1], off nt
	global_load_dwordx4 v[8:11], v[2:3], off nt
	v_or_b32_e32 v0, 24, v52
	v_or_b32_e32 v2, 28, v52
	v_ashrrev_i32_e32 v1, 31, v0
	v_ashrrev_i32_e32 v3, 31, v2
	v_lshlrev_b64 v[0:1], 16, v[0:1]
	v_lshlrev_b64 v[2:3], 16, v[2:3]
	v_lshl_add_u64 v[0:1], v[50:51], 0, v[0:1]
	v_lshl_add_u64 v[2:3], v[50:51], 0, v[2:3]
	global_load_dwordx4 v[4:7], v[0:1], off nt
	s_nop 0
	global_load_dwordx4 v[0:3], v[2:3], off nt
	v_cndmask_b32_e64 v56, 0, 1, s[14:15]
	v_mov_b32_e32 v54, 1.0
	v_cmp_ne_u32_e64 s[4:5], 1, v56
	s_andn2_b64 vcc, exec, s[14:15]
	v_mov_b32_e32 v56, 1.0
	s_cbranch_vccnz .LBB0_817
	v_lshl_add_u64 v[86:87], v[52:53], 2, s[10:11]
	global_load_dword v110, v[86:87], off offset:16
	global_load_dword v124, v[86:87], off offset:32
	global_load_dword v125, v[86:87], off offset:48
	global_load_dword v126, v[86:87], off offset:64
	global_load_dword v127, v[86:87], off offset:80
	global_load_dword v178, v[86:87], off offset:96
	global_load_dword v179, v[86:87], off offset:112
	global_load_dword v180, v[86:87], off offset:128
	global_load_dword v181, v[86:87], off offset:144
	global_load_dword v182, v[86:87], off offset:160
	global_load_dword v183, v[86:87], off offset:176
	global_load_dword v184, v[86:87], off offset:192
	global_load_dword v185, v[86:87], off offset:208
	global_load_dword v186, v[86:87], off offset:224
	global_load_dword v187, v[86:87], off offset:240
	global_load_dword v56, v[86:87], off
	s_waitcnt vmcnt(0)
	s_ashr_i32 s19, s18, 31
	v_lshl_add_u64 v[86:87], s[18:19], 0, v[16:17]
	v_lshl_add_u64 v[86:87], v[86:87], 2, s[10:11]
	s_waitcnt vmcnt(0)
	v_pk_mul_f32 v[30:31], v[30:31], v[56:57] op_sel_hi:[1,0]
	v_pk_mul_f32 v[32:33], v[32:33], v[56:57] op_sel_hi:[1,0]
	v_mov_b32_e32 v56, v110

; #define LAS __attribute__((address_space(3)))
; template <bool PERMUTE, bool BLOCKED = false>
; __device__ __forceinline__ void cvt_tile64(const float* W, int K, int N, bf16* WT, int ldo, const float* gk, LAS float* scr, int tile, int lane) {
;     ...
;     for (int hh = 0; hh < 2; ++hh) {
;         f32x4 v[8];
; #pragma unroll
;         for (int i = 0; i < 8; ++i) v[i] = *(const f32x4*)(W + (size_t)(k0 + 32 * hh + 4 * i + lk) * N + n0 + ln);
; #pragma unroll
;         for (int i = 0; i < 8; ++i) { const int kk = 32 * hh + 4 * i + lk; const float g = gk ? gk[k0 + kk] : 1.0f; LAS float* d = scr + kk * 65 + ln;
;             d[0] = v[i][0] * g; d[1] = v[i][1] * g; d[2] = v[i][2] * g; d[3] = v[i][3] * g; }
.LBB0_823:
	v_add_u32_e32 v53, v55, v63
	v_add_u32_e32 v8, 0x410, v53
	ds_write2_b32 v8, v4, v5 offset1:1
	v_add_u32_e32 v4, 0x418, v53
	ds_write2_b32 v4, v6, v7 offset1:1
	s_waitcnt vmcnt(0)
	v_pk_mul_f32 v[0:1], v[0:1], v[18:19] op_sel_hi:[1,0]
	v_add_u32_e32 v4, 0x820, v53
	ds_write2_b32 v4, v0, v1 offset1:1
	v_pk_mul_f32 v[0:1], v[2:3], v[18:19] op_sel_hi:[1,0]
	v_add_u32_e32 v2, 0x828, v53
	ds_write2_b32 v2, v0, v1 offset1:1
	v_or_b32_e32 v0, 32, v52
	v_or_b32_e32 v4, 60, v52
	v_ashrrev_i32_e32 v1, 31, v0
	v_ashrrev_i32_e32 v5, 31, v4
	v_lshlrev_b64 v[0:1], 16, v[0:1]
	v_lshlrev_b64 v[4:5], 16, v[4:5]
	v_lshl_add_u64 v[0:1], v[50:51], 0, v[0:1]
	v_lshl_add_u64 v[4:5], v[50:51], 0, v[4:5]
	global_load_dwordx4 v[26:29], v[0:1], off nt
	s_and_b64 vcc, exec, s[4:5]
	global_load_dwordx4 v[4:7], v[4:5], off nt
	v_or_b32_e32 v0, 36, v52
	v_ashrrev_i32_e32 v1, 31, v0
	v_lshlrev_b64 v[0:1], 16, v[0:1]
	v_lshl_add_u64 v[0:1], v[50:51], 0, v[0:1]
	global_load_dwordx4 v[30:33], v[0:1], off nt
	v_or_b32_e32 v0, 40, v52
	v_ashrrev_i32_e32 v1, 31, v0
	v_lshlrev_b64 v[0:1], 16, v[0:1]
	v_lshl_add_u64 v[0:1], v[50:51], 0, v[0:1]
	global_load_dwordx4 v[18:21], v[0:1], off nt
	v_or_b32_e32 v0, 44, v52
	v_ashrrev_i32_e32 v1, 31, v0
	v_lshlrev_b64 v[0:1], 16, v[0:1]
	v_lshl_add_u64 v[0:1], v[50:51], 0, v[0:1]
	global_load_dwordx4 v[22:25], v[0:1], off nt
	v_or_b32_e32 v0, 48, v52
	v_ashrrev_i32_e32 v1, 31, v0
	v_lshlrev_b64 v[0:1], 16, v[0:1]
	v_lshl_add_u64 v[0:1], v[50:51], 0, v[0:1]
	global_load_dwordx4 v[8:11], v[0:1], off nt
	v_or_b32_e32 v0, 52, v52
	v_ashrrev_i32_e32 v1, 31, v0
	v_lshlrev_b64 v[0:1], 16, v[0:1]
	v_lshl_add_u64 v[0:1], v[50:51], 0, v[0:1]
	global_load_dwordx4 v[12:15], v[0:1], off nt
	v_or_b32_e32 v0, 56, v52
	v_ashrrev_i32_e32 v1, 31, v0
	v_lshlrev_b64 v[0:1], 16, v[0:1]
	v_lshl_add_u64 v[0:1], v[50:51], 0, v[0:1]
	global_load_dwordx4 v[0:3], v[0:1], off nt
	v_mov_b32_e32 v50, 1.0
	v_mov_b32_e32 v52, 1.0
	s_cbranch_vccnz .LBB0_825
	s_ashr_i32 s19, s18, 31
	v_lshl_add_u64 v[86:87], s[18:19], 0, v[16:17]
	v_lshl_add_u64 v[86:87], v[86:87], 2, s[10:11]
	v_mov_b32_e32 v52, v180
	s_waitcnt vmcnt(0)
	v_pk_mul_f32 v[26:27], v[26:27], v[52:53] op_sel_hi:[1,0]
	v_pk_mul_f32 v[28:29], v[28:29], v[52:53] op_sel_hi:[1,0]
	v_mov_b32_e32 v52, v181

; #define LAS __attribute__((address_space(3)))
; template <bool PERMUTE, bool BLOCKED = false>
; __device__ __forceinline__ void cvt_tile64(const float* W, int K, int N, bf16* WT, int ldo, const float* gk, LAS float* scr, int tile, int lane) {
;     ...
;     for (int hh = 0; hh < 2; ++hh) {
;         f32x4 v[8];
; #pragma unroll
;         for (int i = 0; i < 8; ++i) v[i] = *(const f32x4*)(W + (size_t)(k0 + 32 * hh + 4 * i + lk) * N + n0 + ln);
; #pragma unroll
;         for (int i = 0; i < 8; ++i) { const int kk = 32 * hh + 4 * i + lk; const float g = gk ? gk[k0 + kk] : 1.0f; LAS float* d = scr + kk * 65 + ln;
;             d[0] = v[i][0] * g; d[1] = v[i][1] * g; d[2] = v[i][2] * g; d[3] = v[i][3] * g; }
;     }
; __device__ __forceinline__ void cvt_item(const CvtCtx& c, int batch, int wi, LAS float* scr, int wave, int lane) {
;     ...
;     if (wi < CVT_OUT) { cvt_tile64<false>(c.w_out + (size_t)l * DM * DM, DM, DM, c.WoutT + (size_t)l * DM * DM, DM, nullptr, scr, 8 * wi + wave, lane); return; } wi -= CVT_OUT;
.LBB0_835:
	s_andn2_b64 vcc, exec, s[0:1]
	s_cbranch_vccnz .LBB0_806
	s_add_i32 s0, s16, 0x9000
	s_ashr_i32 s1, s0, 31
	s_lshr_b32 s1, s1, 26
	s_add_i32 s0, s0, s1
	s_and_b32 s4, s0, 0xffffffc0
	s_lshl_b32 s0, s0, 6
	s_and_b32 s0, s0, 0xfffff000
	s_sub_i32 s0, s13, s0
	s_add_i32 s6, s0, 0x240000
	v_or_b32_e32 v2, s4, v16
	s_ashr_i32 s7, s6, 31
	v_ashrrev_i32_e32 v3, 31, v2
	v_lshl_add_u64 v[0:1], s[6:7], 2, v[46:47]
	v_lshlrev_b64 v[4:5], 14, v[2:3]
	v_or_b32_e32 v8, 4, v2
	v_lshl_add_u64 v[4:5], v[0:1], 0, v[4:5]
	v_ashrrev_i32_e32 v9, 31, v8
	global_load_dwordx4 v[4:7], v[4:5], off nt
	v_lshlrev_b64 v[8:9], 14, v[8:9]
	v_or_b32_e32 v12, 8, v2
	v_lshl_add_u64 v[8:9], v[0:1], 0, v[8:9]
	v_ashrrev_i32_e32 v13, 31, v12
	global_load_dwordx4 v[8:11], v[8:9], off nt
	v_lshlrev_b64 v[12:13], 14, v[12:13]
	v_or_b32_e32 v18, 12, v2
	v_lshl_add_u64 v[12:13], v[0:1], 0, v[12:13]
	v_ashrrev_i32_e32 v19, 31, v18
	global_load_dwordx4 v[12:15], v[12:13], off nt
	v_lshlrev_b64 v[18:19], 14, v[18:19]
	v_or_b32_e32 v22, 16, v2
	v_lshl_add_u64 v[18:19], v[0:1], 0, v[18:19]
	v_ashrrev_i32_e32 v23, 31, v22
	global_load_dwordx4 v[18:21], v[18:19], off nt
	v_lshlrev_b64 v[22:23], 14, v[22:23]
	v_or_b32_e32 v26, 20, v2
	v_lshl_add_u64 v[22:23], v[0:1], 0, v[22:23]
	v_ashrrev_i32_e32 v27, 31, v26
	global_load_dwordx4 v[22:25], v[22:23], off nt
	v_lshlrev_b64 v[26:27], 14, v[26:27]
	v_or_b32_e32 v30, 24, v2
	v_lshl_add_u64 v[26:27], v[0:1], 0, v[26:27]
	v_ashrrev_i32_e32 v31, 31, v30
	global_load_dwordx4 v[26:29], v[26:27], off nt
	v_lshlrev_b64 v[30:31], 14, v[30:31]
	v_or_b32_e32 v50, 28, v2
	v_lshl_add_u64 v[30:31], v[0:1], 0, v[30:31]
	v_ashrrev_i32_e32 v51, 31, v50
	global_load_dwordx4 v[30:33], v[30:31], off nt
	v_lshlrev_b64 v[50:51], 14, v[50:51]
	v_lshl_add_u64 v[50:51], v[0:1], 0, v[50:51]
	global_load_dwordx4 v[50:53], v[50:51], off nt
	v_add_u32_e32 v54, v55, v57
	v_add_u32_e32 v3, 0x410, v54
	s_ashr_i32 s5, s4, 31
	s_waitcnt vmcnt(7)
	ds_write2_b32 v54, v4, v5 offset1:1
	ds_write2_b32 v54, v6, v7 offset0:2 offset1:3
	v_or_b32_e32 v4, 32, v2
	v_ashrrev_i32_e32 v5, 31, v4
	v_lshlrev_b64 v[4:5], 14, v[4:5]
	v_lshl_add_u64 v[4:5], v[0:1], 0, v[4:5]
	s_waitcnt vmcnt(6)
	ds_write2_b32 v3, v8, v9 offset1:1
	v_add_u32_e32 v3, 0x418, v54
	v_or_b32_e32 v8, 36, v2
	ds_write2_b32 v3, v10, v11 offset1:1
	v_add_u32_e32 v3, 0x820, v54
	v_ashrrev_i32_e32 v9, 31, v8
	s_waitcnt vmcnt(5)
	ds_write2_b32 v3, v12, v13 offset1:1
	v_add_u32_e32 v3, 0x828, v54
	global_load_dwordx4 v[4:7], v[4:5], off nt
	v_lshlrev_b64 v[8:9], 14, v[8:9]
	v_or_b32_e32 v12, 40, v2
	ds_write2_b32 v3, v14, v15 offset1:1
	v_add_u32_e32 v3, 0xc30, v54
	v_lshl_add_u64 v[8:9], v[0:1], 0, v[8:9]
	v_ashrrev_i32_e32 v13, 31, v12
	s_waitcnt vmcnt(5)
	ds_write2_b32 v3, v18, v19 offset1:1
	v_add_u32_e32 v3, 0xc38, v54
	global_load_dwordx4 v[8:11], v[8:9], off nt
	v_lshlrev_b64 v[12:13], 14, v[12:13]
	v_or_b32_e32 v18, 44, v2
	ds_write2_b32 v3, v20, v21 offset1:1
	v_add_u32_e32 v3, 0x1040, v54
	v_lshl_add_u64 v[12:13], v[0:1], 0, v[12:13]
	v_ashrrev_i32_e32 v19, 31, v18
	s_waitcnt vmcnt(5)
	ds_write2_b32 v3, v22, v23 offset1:1
	v_add_u32_e32 v3, 0x1048, v54
	global_load_dwordx4 v[12:15], v[12:13], off nt
	v_lshlrev_b64 v[18:19], 14, v[18:19]
	v_or_b32_e32 v22, 48, v2
	ds_write2_b32 v3, v24, v25 offset1:1
	v_add_u32_e32 v3, 0x1450, v54
	v_lshl_add_u64 v[18:19], v[0:1], 0, v[18:19]
	v_ashrrev_i32_e32 v23, 31, v22
	s_waitcnt vmcnt(5)
	ds_write2_b32 v3, v26, v27 offset1:1
	v_add_u32_e32 v3, 0x1458, v54
	global_load_dwordx4 v[18:21], v[18:19], off nt
	v_lshlrev_b64 v[22:23], 14, v[22:23]
	v_or_b32_e32 v26, 52, v2
	ds_write2_b32 v3, v28, v29 offset1:1
	v_add_u32_e32 v3, 0x1860, v54
	v_lshl_add_u64 v[22:23], v[0:1], 0, v[22:23]
	v_ashrrev_i32_e32 v27, 31, v26
	s_waitcnt vmcnt(5)
	ds_write2_b32 v3, v30, v31 offset1:1
	v_add_u32_e32 v3, 0x1868, v54
	global_load_dwordx4 v[22:25], v[22:23], off nt
	v_lshlrev_b64 v[26:27], 14, v[26:27]
	v_or_b32_e32 v30, 56, v2
	ds_write2_b32 v3, v32, v33 offset1:1
	v_add_u32_e32 v3, 0x1c70, v54
	v_lshl_add_u64 v[26:27], v[0:1], 0, v[26:27]
	v_ashrrev_i32_e32 v31, 31, v30
	s_waitcnt vmcnt(5)
	ds_write2_b32 v3, v50, v51 offset1:1
	v_add_u32_e32 v3, 0x1c78, v54
	global_load_dwordx4 v[26:29], v[26:27], off nt
	v_lshlrev_b64 v[30:31], 14, v[30:31]
	v_or_b32_e32 v2, 60, v2
	ds_write2_b32 v3, v52, v53 offset1:1
	v_lshl_add_u64 v[30:31], v[0:1], 0, v[30:31]
	v_ashrrev_i32_e32 v3, 31, v2
	global_load_dwordx4 v[30:33], v[30:31], off nt
	v_lshlrev_b64 v[2:3], 14, v[2:3]
	v_lshl_add_u64 v[0:1], v[0:1], 0, v[2:3]
	global_load_dwordx4 v[0:3], v[0:1], off nt
	v_add_u32_e32 v50, 0x2080, v54
	s_waitcnt vmcnt(7)
	ds_write2_b32 v50, v4, v5 offset1:1
	v_add_u32_e32 v4, 0x2088, v54
	ds_write2_b32 v4, v6, v7 offset1:1
	v_add_u32_e32 v4, 0x2490, v54
	s_waitcnt vmcnt(6)
	ds_write2_b32 v4, v8, v9 offset1:1
	v_add_u32_e32 v4, 0x2498, v54
	ds_write2_b32 v4, v10, v11 offset1:1
	v_add_u32_e32 v4, 0x28a0, v54
	s_waitcnt vmcnt(5)
	ds_write2_b32 v4, v12, v13 offset1:1
	v_add_u32_e32 v4, 0x28a8, v54
	ds_write2_b32 v4, v14, v15 offset1:1
	v_add_u32_e32 v4, 0x2cb0, v54
	s_waitcnt vmcnt(4)
	ds_write2_b32 v4, v18, v19 offset1:1
	v_add_u32_e32 v4, 0x2cb8, v54
	ds_write2_b32 v4, v20, v21 offset1:1
	v_add_u32_e32 v4, 0x30c0, v54
	s_waitcnt vmcnt(3)
	ds_write2_b32 v4, v22, v23 offset1:1
	v_add_u32_e32 v4, 0x30c8, v54
	ds_write2_b32 v4, v24, v25 offset1:1
	v_add_u32_e32 v4, 0x34d0, v54
	s_waitcnt vmcnt(2)
	ds_write2_b32 v4, v26, v27 offset1:1
	v_add_u32_e32 v4, 0x34d8, v54
	ds_write2_b32 v4, v28, v29 offset1:1
	v_add_u32_e32 v4, 0x38e0, v54
	s_waitcnt vmcnt(1)
; __host__ __device__ __forceinline__ size_t blocked_off(int row, int col, int K) { return (((size_t)(row >> 8) * (K >> 6) + (col >> 6)) * 256 + (row & 255)) * 64 + (col & 63); }
; __device__ __forceinline__ unsigned cvt_pk_bf16(float lo, float hi) { const f32x2c_t v = {lo, hi}; return __builtin_bit_cast(unsigned, __builtin_convertvector(v, bf16x2c_t)); }
; #define LAS __attribute__((address_space(3)))
; #define LDS_WAIT() asm volatile("s_waitcnt lgkmcnt(0)" ::: "memory")
; __host__ __device__ __forceinline__ int win_phys_col(int n) { if (!win_rope_tile(n >> 8)) return n; const int cl = n & 255; return (n & ~255) | (cl & 63) | ((cl & 64) << 1) | ((cl & 128) >> 1); }
; template <bool PERMUTE, bool BLOCKED = false>
; __device__ __forceinline__ void cvt_tile64(const float* W, int K, int N, bf16* WT, int ldo, const float* gk, LAS float* scr, int tile, int lane) {
;     ...
;     LDS_WAIT(); asm volatile("" ::: "memory");
;     const int kc = lane & 7, nrow0 = PERMUTE ? win_phys_col(n0) : n0;
; #pragma unroll
;     for (int j = 0; j < 8; ++j) { const int n = (lane >> 3) + 8 * j; const LAS float* s = scr + (8 * kc) * 65 + n;
;         v4u o; o[0] = cvt_pk_bf16(wrnd(s[0 * 65]), wrnd(s[1 * 65])); o[1] = cvt_pk_bf16(wrnd(s[2 * 65]), wrnd(s[3 * 65])); o[2] = cvt_pk_bf16(wrnd(s[4 * 65]), wrnd(s[5 * 65])); o[3] = cvt_pk_bf16(wrnd(s[6 * 65]), wrnd(s[7 * 65]));
;         *(v4u*)(WT + (BLOCKED ? pg8::blocked_off(nrow0 + n, k0 + 8 * kc, K) : (size_t)(nrow0 + n) * ldo + k0 + 8 * kc)) = o; }
	ds_write2_b32 v4, v30, v31 offset1:1
	v_add_u32_e32 v4, 0x38e8, v54
	ds_write2_b32 v4, v32, v33 offset1:1
	v_add_u32_e32 v4, 0x3cf0, v54
	s_waitcnt vmcnt(0)
	ds_write2_b32 v4, v0, v1 offset1:1
	v_add_u32_e32 v0, 0x3cf8, v54
	ds_write2_b32 v0, v2, v3 offset1:1
	s_waitcnt lgkmcnt(0)
	ds_read2_b32 v[8:9], v75 offset1:8
	ds_read2_b32 v[10:11], v75 offset0:65 offset1:73
	ds_read2_b32 v[12:13], v75 offset0:130 offset1:138
	ds_read2_b32 v[14:15], v75 offset0:195 offset1:203
	v_lshl_add_u64 v[0:1], s[4:5], 1, v[48:49]
	s_waitcnt lgkmcnt(3)
	v_add_u32_e32 v2, 0x20000, v8
	s_waitcnt lgkmcnt(2)
	v_add_u32_e32 v3, 0x20000, v10
	v_and_b32_e32 v2, 0xfffc0000, v2
	v_and_b32_e32 v3, 0xfffc0000, v3
	v_cvt_pk_bf16_f32 v4, v2, v3
	s_waitcnt lgkmcnt(1)
	v_add_u32_e32 v2, 0x20000, v12
	s_waitcnt lgkmcnt(0)
	v_add_u32_e32 v3, 0x20000, v14
	v_and_b32_e32 v2, 0xfffc0000, v2
	v_and_b32_e32 v3, 0xfffc0000, v3
	v_cvt_pk_bf16_f32 v5, v2, v3
	v_add_u32_e32 v2, 0x400, v75
	ds_read2_b32 v[18:19], v2 offset0:4 offset1:12
	ds_read2_b32 v[20:21], v2 offset0:69 offset1:77
	ds_read2_b32 v[22:23], v2 offset0:134 offset1:142
	ds_read2_b32 v[24:25], v2 offset0:199 offset1:207
	s_waitcnt lgkmcnt(3)
	v_add_u32_e32 v3, 0x20000, v18
	s_waitcnt lgkmcnt(2)
	v_add_u32_e32 v6, 0x20000, v20
	v_and_b32_e32 v3, 0xfffc0000, v3
	v_and_b32_e32 v6, 0xfffc0000, v6
	v_cvt_pk_bf16_f32 v6, v3, v6
	s_waitcnt lgkmcnt(1)
	v_add_u32_e32 v3, 0x20000, v22
	s_waitcnt lgkmcnt(0)
	v_add_u32_e32 v7, 0x20000, v24
	v_and_b32_e32 v3, 0xfffc0000, v3
	v_and_b32_e32 v7, 0xfffc0000, v7
	v_cvt_pk_bf16_f32 v7, v3, v7
	v_add_u32_e32 v3, s0, v74
	v_add_u32_e32 v26, 0x240000, v3
	v_ashrrev_i32_e32 v27, 31, v26
	v_lshlrev_b64 v[26:27], 13, v[26:27]
	v_lshl_add_u64 v[26:27], v[0:1], 0, v[26:27]
	global_store_dwordx4 v[26:27], v[4:7], off
	v_add_u32_e32 v8, 0x20000, v25
	v_and_b32_e32 v8, 0xfffc0000, v8
	v_add_u32_e32 v4, 0x20000, v9
	v_add_u32_e32 v5, 0x20000, v11
	v_and_b32_e32 v4, 0xfffc0000, v4
	v_and_b32_e32 v5, 0xfffc0000, v5
	v_cvt_pk_bf16_f32 v4, v4, v5
	v_add_u32_e32 v5, 0x20000, v13
	v_add_u32_e32 v6, 0x20000, v15
	v_and_b32_e32 v5, 0xfffc0000, v5
	v_and_b32_e32 v6, 0xfffc0000, v6
	v_cvt_pk_bf16_f32 v5, v5, v6
	v_add_u32_e32 v6, 0x20000, v19
	v_add_u32_e32 v7, 0x20000, v21
	v_and_b32_e32 v6, 0xfffc0000, v6
	v_and_b32_e32 v7, 0xfffc0000, v7
	v_cvt_pk_bf16_f32 v6, v6, v7
	v_add_u32_e32 v7, 0x20000, v23
	v_and_b32_e32 v7, 0xfffc0000, v7
	v_cvt_pk_bf16_f32 v7, v7, v8
	v_add_u32_e32 v8, 0x240008, v3
	v_ashrrev_i32_e32 v9, 31, v8
	v_lshlrev_b64 v[8:9], 13, v[8:9]
	v_lshl_add_u64 v[8:9], v[0:1], 0, v[8:9]
	global_store_dwordx4 v[8:9], v[4:7], off
	ds_read2_b32 v[8:9], v75 offset0:16 offset1:24
	ds_read2_b32 v[10:11], v75 offset0:81 offset1:89
	ds_read2_b32 v[12:13], v75 offset0:146 offset1:154
	ds_read2_b32 v[14:15], v75 offset0:211 offset1:219
	ds_read2_b32 v[18:19], v2 offset0:20 offset1:28
	ds_read2_b32 v[20:21], v2 offset0:85 offset1:93
	s_waitcnt lgkmcnt(5)
	v_add_u32_e32 v4, 0x20000, v8
	s_waitcnt lgkmcnt(4)
	v_add_u32_e32 v5, 0x20000, v10
	v_and_b32_e32 v4, 0xfffc0000, v4
	v_and_b32_e32 v5, 0xfffc0000, v5
	ds_read2_b32 v[22:23], v2 offset0:150 offset1:158
	ds_read2_b32 v[24:25], v2 offset0:215 offset1:223
	v_cvt_pk_bf16_f32 v4, v4, v5
	s_waitcnt lgkmcnt(5)
	v_add_u32_e32 v5, 0x20000, v12
	s_waitcnt lgkmcnt(4)
	v_add_u32_e32 v6, 0x20000, v14
	v_and_b32_e32 v5, 0xfffc0000, v5
	v_and_b32_e32 v6, 0xfffc0000, v6
	v_cvt_pk_bf16_f32 v5, v5, v6
	s_waitcnt lgkmcnt(3)
	v_add_u32_e32 v6, 0x20000, v18
	s_waitcnt lgkmcnt(2)
	v_add_u32_e32 v7, 0x20000, v20
	v_and_b32_e32 v6, 0xfffc0000, v6
	v_and_b32_e32 v7, 0xfffc0000, v7
	v_add_u32_e32 v26, 0x240010, v3
	v_cvt_pk_bf16_f32 v6, v6, v7
	s_waitcnt lgkmcnt(1)
	v_add_u32_e32 v7, 0x20000, v22
	s_waitcnt lgkmcnt(0)
	v_add_u32_e32 v8, 0x20000, v24
	v_ashrrev_i32_e32 v27, 31, v26
	v_and_b32_e32 v7, 0xfffc0000, v7
	v_and_b32_e32 v8, 0xfffc0000, v8
	v_lshlrev_b64 v[26:27], 13, v[26:27]
	v_cvt_pk_bf16_f32 v7, v7, v8
	v_lshl_add_u64 v[26:27], v[0:1], 0, v[26:27]
	global_store_dwordx4 v[26:27], v[4:7], off
	v_add_u32_e32 v8, 0x20000, v25
	v_and_b32_e32 v8, 0xfffc0000, v8
	v_add_u32_e32 v4, 0x20000, v9
	v_add_u32_e32 v5, 0x20000, v11
	v_and_b32_e32 v4, 0xfffc0000, v4
	v_and_b32_e32 v5, 0xfffc0000, v5
	v_cvt_pk_bf16_f32 v4, v4, v5
	v_add_u32_e32 v5, 0x20000, v13
	v_add_u32_e32 v6, 0x20000, v15
	v_and_b32_e32 v5, 0xfffc0000, v5
	v_and_b32_e32 v6, 0xfffc0000, v6
	v_cvt_pk_bf16_f32 v5, v5, v6
	v_add_u32_e32 v6, 0x20000, v19
	v_add_u32_e32 v7, 0x20000, v21
	v_and_b32_e32 v6, 0xfffc0000, v6
	v_and_b32_e32 v7, 0xfffc0000, v7
	v_cvt_pk_bf16_f32 v6, v6, v7
	v_add_u32_e32 v7, 0x20000, v23
	v_and_b32_e32 v7, 0xfffc0000, v7
	v_cvt_pk_bf16_f32 v7, v7, v8
	v_add_u32_e32 v8, 0x240018, v3
	v_ashrrev_i32_e32 v9, 31, v8
	v_lshlrev_b64 v[8:9], 13, v[8:9]
	v_lshl_add_u64 v[8:9], v[0:1], 0, v[8:9]
	global_store_dwordx4 v[8:9], v[4:7], off
	ds_read2_b32 v[8:9], v75 offset0:32 offset1:40
	ds_read2_b32 v[10:11], v75 offset0:97 offset1:105
	ds_read2_b32 v[12:13], v75 offset0:162 offset1:170
	ds_read2_b32 v[14:15], v75 offset0:227 offset1:235
	ds_read2_b32 v[18:19], v2 offset0:36 offset1:44
	ds_read2_b32 v[20:21], v2 offset0:101 offset1:109
	s_waitcnt lgkmcnt(5)
; __host__ __device__ __forceinline__ size_t blocked_off(int row, int col, int K) { return (((size_t)(row >> 8) * (K >> 6) + (col >> 6)) * 256 + (row & 255)) * 64 + (col & 63); }
; __device__ __forceinline__ unsigned cvt_pk_bf16(float lo, float hi) { const f32x2c_t v = {lo, hi}; return __builtin_bit_cast(unsigned, __builtin_convertvector(v, bf16x2c_t)); }
; #define LAS __attribute__((address_space(3)))
; #define LDS_WAIT() asm volatile("s_waitcnt lgkmcnt(0)" ::: "memory")
; __host__ __device__ __forceinline__ int win_phys_col(int n) { if (!win_rope_tile(n >> 8)) return n; const int cl = n & 255; return (n & ~255) | (cl & 63) | ((cl & 64) << 1) | ((cl & 128) >> 1); }
; template <bool PERMUTE, bool BLOCKED = false>
; __device__ __forceinline__ void cvt_tile64(const float* W, int K, int N, bf16* WT, int ldo, const float* gk, LAS float* scr, int tile, int lane) {
;     ...
;     const int kc = lane & 7, nrow0 = PERMUTE ? win_phys_col(n0) : n0;
; #pragma unroll
;     for (int j = 0; j < 8; ++j) { const int n = (lane >> 3) + 8 * j; const LAS float* s = scr + (8 * kc) * 65 + n;
;         v4u o; o[0] = cvt_pk_bf16(wrnd(s[0 * 65]), wrnd(s[1 * 65])); o[1] = cvt_pk_bf16(wrnd(s[2 * 65]), wrnd(s[3 * 65])); o[2] = cvt_pk_bf16(wrnd(s[4 * 65]), wrnd(s[5 * 65])); o[3] = cvt_pk_bf16(wrnd(s[6 * 65]), wrnd(s[7 * 65]));
;         *(v4u*)(WT + (BLOCKED ? pg8::blocked_off(nrow0 + n, k0 + 8 * kc, K) : (size_t)(nrow0 + n) * ldo + k0 + 8 * kc)) = o; }
;     LDS_WAIT(); asm volatile("" ::: "memory");
	v_add_u32_e32 v4, 0x20000, v8
	s_waitcnt lgkmcnt(4)
	v_add_u32_e32 v5, 0x20000, v10
	v_and_b32_e32 v4, 0xfffc0000, v4
	v_and_b32_e32 v5, 0xfffc0000, v5
	ds_read2_b32 v[22:23], v2 offset0:166 offset1:174
	ds_read2_b32 v[24:25], v2 offset0:231 offset1:239
	v_cvt_pk_bf16_f32 v4, v4, v5
	s_waitcnt lgkmcnt(5)
	v_add_u32_e32 v5, 0x20000, v12
	s_waitcnt lgkmcnt(4)
	v_add_u32_e32 v6, 0x20000, v14
	v_and_b32_e32 v5, 0xfffc0000, v5
	v_and_b32_e32 v6, 0xfffc0000, v6
	v_cvt_pk_bf16_f32 v5, v5, v6
	s_waitcnt lgkmcnt(3)
	v_add_u32_e32 v6, 0x20000, v18
	s_waitcnt lgkmcnt(2)
	v_add_u32_e32 v7, 0x20000, v20
	v_and_b32_e32 v6, 0xfffc0000, v6
	v_and_b32_e32 v7, 0xfffc0000, v7
	v_add_u32_e32 v26, 0x240020, v3
	v_cvt_pk_bf16_f32 v6, v6, v7
	s_waitcnt lgkmcnt(1)
	v_add_u32_e32 v7, 0x20000, v22
	s_waitcnt lgkmcnt(0)
	v_add_u32_e32 v8, 0x20000, v24
	v_ashrrev_i32_e32 v27, 31, v26
	v_and_b32_e32 v7, 0xfffc0000, v7
	v_and_b32_e32 v8, 0xfffc0000, v8
	v_lshlrev_b64 v[26:27], 13, v[26:27]
	v_cvt_pk_bf16_f32 v7, v7, v8
	v_lshl_add_u64 v[26:27], v[0:1], 0, v[26:27]
	global_store_dwordx4 v[26:27], v[4:7], off
	v_add_u32_e32 v8, 0x20000, v25
	v_and_b32_e32 v8, 0xfffc0000, v8
	v_add_u32_e32 v4, 0x20000, v9
	v_add_u32_e32 v5, 0x20000, v11
	v_and_b32_e32 v4, 0xfffc0000, v4
	v_and_b32_e32 v5, 0xfffc0000, v5
	v_cvt_pk_bf16_f32 v4, v4, v5
	v_add_u32_e32 v5, 0x20000, v13
	v_add_u32_e32 v6, 0x20000, v15
	v_and_b32_e32 v5, 0xfffc0000, v5
	v_and_b32_e32 v6, 0xfffc0000, v6
	v_cvt_pk_bf16_f32 v5, v5, v6
	v_add_u32_e32 v6, 0x20000, v19
	v_add_u32_e32 v7, 0x20000, v21
	v_and_b32_e32 v6, 0xfffc0000, v6
	v_and_b32_e32 v7, 0xfffc0000, v7
	v_cvt_pk_bf16_f32 v6, v6, v7
	v_add_u32_e32 v7, 0x20000, v23
	v_and_b32_e32 v7, 0xfffc0000, v7
	v_cvt_pk_bf16_f32 v7, v7, v8
	v_add_u32_e32 v8, 0x240028, v3
	v_ashrrev_i32_e32 v9, 31, v8
	v_lshlrev_b64 v[8:9], 13, v[8:9]
	v_lshl_add_u64 v[8:9], v[0:1], 0, v[8:9]
	global_store_dwordx4 v[8:9], v[4:7], off
	ds_read2_b32 v[8:9], v75 offset0:48 offset1:56
	ds_read2_b32 v[10:11], v75 offset0:113 offset1:121
	ds_read2_b32 v[12:13], v75 offset0:178 offset1:186
	ds_read2_b32 v[14:15], v75 offset0:243 offset1:251
	ds_read2_b32 v[18:19], v2 offset0:52 offset1:60
	ds_read2_b32 v[20:21], v2 offset0:117 offset1:125
	s_waitcnt lgkmcnt(5)
	v_add_u32_e32 v4, 0x20000, v8
	s_waitcnt lgkmcnt(4)
	v_add_u32_e32 v5, 0x20000, v10
	v_and_b32_e32 v4, 0xfffc0000, v4
	v_and_b32_e32 v5, 0xfffc0000, v5
	ds_read2_b32 v[22:23], v2 offset0:182 offset1:190
	ds_read2_b32 v[24:25], v2 offset0:247 offset1:255
	v_cvt_pk_bf16_f32 v4, v4, v5
	s_waitcnt lgkmcnt(5)
	v_add_u32_e32 v5, 0x20000, v12
	s_waitcnt lgkmcnt(4)
	v_add_u32_e32 v6, 0x20000, v14
	v_and_b32_e32 v5, 0xfffc0000, v5
	v_and_b32_e32 v6, 0xfffc0000, v6
	v_cvt_pk_bf16_f32 v5, v5, v6
	s_waitcnt lgkmcnt(3)
	v_add_u32_e32 v6, 0x20000, v18
	s_waitcnt lgkmcnt(2)
	v_add_u32_e32 v7, 0x20000, v20
	v_and_b32_e32 v6, 0xfffc0000, v6
	v_and_b32_e32 v7, 0xfffc0000, v7
	v_add_u32_e32 v26, 0x240030, v3
	v_cvt_pk_bf16_f32 v6, v6, v7
	s_waitcnt lgkmcnt(1)
	v_add_u32_e32 v7, 0x20000, v22
	s_waitcnt lgkmcnt(0)
	v_add_u32_e32 v2, 0x20000, v24
	v_ashrrev_i32_e32 v27, 31, v26
	v_and_b32_e32 v7, 0xfffc0000, v7
	v_and_b32_e32 v2, 0xfffc0000, v2
	v_lshlrev_b64 v[26:27], 13, v[26:27]
	v_cvt_pk_bf16_f32 v7, v7, v2
	v_lshl_add_u64 v[26:27], v[0:1], 0, v[26:27]
	global_store_dwordx4 v[26:27], v[4:7], off
	v_add_u32_e32 v2, 0x20000, v9
	v_and_b32_e32 v2, 0xfffc0000, v2
	v_add_u32_e32 v4, 0x20000, v11
	v_and_b32_e32 v4, 0xfffc0000, v4
	v_cvt_pk_bf16_f32 v4, v2, v4
	v_add_u32_e32 v2, 0x20000, v13
	v_add_u32_e32 v5, 0x20000, v15
	v_and_b32_e32 v2, 0xfffc0000, v2
	v_and_b32_e32 v5, 0xfffc0000, v5
	v_cvt_pk_bf16_f32 v5, v2, v5
	v_add_u32_e32 v2, 0x20000, v19
	v_add_u32_e32 v6, 0x20000, v21
	v_and_b32_e32 v2, 0xfffc0000, v2
	v_and_b32_e32 v6, 0xfffc0000, v6
	v_cvt_pk_bf16_f32 v6, v2, v6
	v_add_u32_e32 v2, 0x20000, v23
	v_add_u32_e32 v7, 0x20000, v25
	v_and_b32_e32 v2, 0xfffc0000, v2
	v_and_b32_e32 v7, 0xfffc0000, v7
	v_cvt_pk_bf16_f32 v7, v2, v7
	v_add_u32_e32 v2, 0x240038, v3
	v_ashrrev_i32_e32 v3, 31, v2
	v_lshlrev_b64 v[2:3], 13, v[2:3]
	v_lshl_add_u64 v[0:1], v[0:1], 0, v[2:3]
	global_store_dwordx4 v[0:1], v[4:7], off
	s_waitcnt lgkmcnt(0)
	s_branch .LBB0_806

; #define LAS __attribute__((address_space(3)))
; template <bool PERMUTE, bool BLOCKED = false>
; __device__ __forceinline__ void cvt_tile64(const float* W, int K, int N, bf16* WT, int ldo, const float* gk, LAS float* scr, int tile, int lane) {
;     ...
;     for (int hh = 0; hh < 2; ++hh) {
;         f32x4 v[8];
; #pragma unroll
;         for (int i = 0; i < 8; ++i) v[i] = *(const f32x4*)(W + (size_t)(k0 + 32 * hh + 4 * i + lk) * N + n0 + ln);
; #pragma unroll
;         for (int i = 0; i < 8; ++i) { const int kk = 32 * hh + 4 * i + lk; const float g = gk ? gk[k0 + kk] : 1.0f; LAS float* d = scr + kk * 65 + ln;
;             d[0] = v[i][0] * g; d[1] = v[i][1] * g; d[2] = v[i][2] * g; d[3] = v[i][3] * g; }
;     }
; __device__ __forceinline__ void cvt_item(const CvtCtx& c, int batch, int wi, LAS float* scr, int wave, int lane) {
;     const int l = batch;
;     if (wi < CVT_OUT) { cvt_tile64<false>(c.w_out + (size_t)l * DM * DM, DM, DM, c.WoutT + (size_t)l * DM * DM, DM, nullptr, scr, 8 * wi + wave, lane); return; } wi -= CVT_OUT;
;     if (wi < CVT_UP) { cvt_tile64<false>(c.w_up + (size_t)l * DM * DFF, DM, DFF, c.WupT + (size_t)l * DFF * DM, DM, c.g_mlp + l * DM, scr, 8 * wi + wave, lane); return; } wi -= CVT_UP;
;     if (wi < CVT_DN) { cvt_tile64<false, true>(c.w_down + (size_t)l * DFF * DM, DFF, DM, c.WdnT + (size_t)l * DM * DFF, 0, nullptr, scr, 8 * wi + wave, lane); return; } wi -= CVT_DN;
;     cvt_tile64<true>(c.w_in + (size_t)1 * DM * INW, DM, INW, c.WinT + (size_t)1 * INW * DM, DM, c.g_mix + 1 * DM, scr, 8 * wi + wave, lane);
.LBB0_875:
	s_cmpk_gt_i32 s17, 0x1ff
	s_mov_b64 s[0:1], -1
	s_cbranch_scc0 .LBB0_903
	s_cmpk_gt_u32 s17, 0x9ff
	s_cbranch_scc0 .LBB0_882
	s_cmpk_gt_u32 s17, 0x11ff
	s_cbranch_scc0 .LBB0_879
	s_mul_hi_i32 s0, s16, 0x38e38e39
	s_lshr_b32 s1, s0, 31
	s_ashr_i32 s0, s0, 5
	s_add_i32 s1, s0, s1
	s_mul_i32 s0, s1, 0xffffff70
	s_lshl_b32 s4, s1, 6
	s_mulk_i32 s1, 0xdc00
	s_add_i32 s10, s15, s1
	v_or_b32_e32 v18, s4, v16
	s_ashr_i32 s11, s10, 31
	v_lshl_add_u64 v[20:21], s[10:11], 2, v[34:35]
	v_ashrrev_i32_e32 v19, 31, v18
	s_mov_b32 s1, 0x9000
	v_mad_i64_i32 v[0:1], s[18:19], v18, s1, v[20:21]
	v_lshl_add_u64 v[86:87], v[18:19], 2, s[12:13]
	global_load_dwordx4 v[22:25], v[0:1], off nt
	global_load_dword v54, v[86:87], off
	v_add_u32_e32 v19, v55, v57
	v_or_b32_e32 v0, 4, v18
	v_mad_i64_i32 v[0:1], s[18:19], v0, s1, v[20:21]
	global_load_dwordx4 v[26:29], v[0:1], off nt
	v_or_b32_e32 v0, 8, v18
	v_mad_i64_i32 v[0:1], s[18:19], v0, s1, v[20:21]
	global_load_dwordx4 v[30:33], v[0:1], off nt
	v_or_b32_e32 v0, 12, v18
	v_mad_i64_i32 v[0:1], s[18:19], v0, s1, v[20:21]
	global_load_dwordx4 v[50:53], v[0:1], off nt
	v_or_b32_e32 v0, 16, v18
	v_mad_i64_i32 v[0:1], s[18:19], v0, s1, v[20:21]
	global_load_dwordx4 v[12:15], v[0:1], off nt
	v_or_b32_e32 v0, 20, v18
	v_mad_i64_i32 v[0:1], s[18:19], v0, s1, v[20:21]
	global_load_dwordx4 v[8:11], v[0:1], off nt
	v_or_b32_e32 v0, 24, v18
	v_mad_i64_i32 v[0:1], s[18:19], v0, s1, v[20:21]
	global_load_dwordx4 v[4:7], v[0:1], off nt
	v_or_b32_e32 v0, 28, v18
	v_mad_i64_i32 v[0:1], s[18:19], v0, s1, v[20:21]
	global_load_dwordx4 v[0:3], v[0:1], off nt
	s_add_i32 s0, s16, s0
	s_ashr_i32 s5, s0, 2
	s_and_b32 s0, s0, 0x3ffffe0
	s_cmp_eq_u32 s0, 32
	s_waitcnt vmcnt(7)
	v_pk_mul_f32 v[22:23], v[22:23], v[54:55] op_sel_hi:[1,0]
	ds_write2_b32 v19, v22, v23 offset1:1
	v_pk_mul_f32 v[22:23], v[24:25], v[54:55] op_sel_hi:[1,0]
	ds_write2_b32 v19, v22, v23 offset0:2 offset1:3
	v_or_b32_e32 v22, s4, v58
	v_ashrrev_i32_e32 v23, 31, v22
	v_lshl_add_u64 v[22:23], v[22:23], 2, s[12:13]
	global_load_dword v22, v[22:23], off
	s_waitcnt vmcnt(0)
	v_pk_mul_f32 v[24:25], v[26:27], v[22:23] op_sel_hi:[1,0]
	v_add_u32_e32 v23, 0x410, v19
	ds_write2_b32 v23, v24, v25 offset1:1
	v_pk_mul_f32 v[22:23], v[28:29], v[22:23] op_sel_hi:[1,0]
	v_add_u32_e32 v24, 0x418, v19
	ds_write2_b32 v24, v22, v23 offset1:1
	v_or_b32_e32 v22, s4, v59
	v_ashrrev_i32_e32 v23, 31, v22
	v_lshl_add_u64 v[22:23], v[22:23], 2, s[12:13]
	global_load_dword v22, v[22:23], off
	s_waitcnt vmcnt(0)
	v_pk_mul_f32 v[24:25], v[30:31], v[22:23] op_sel_hi:[1,0]
	v_add_u32_e32 v23, 0x820, v19
	ds_write2_b32 v23, v24, v25 offset1:1
	v_pk_mul_f32 v[22:23], v[32:33], v[22:23] op_sel_hi:[1,0]
	v_add_u32_e32 v24, 0x828, v19
	ds_write2_b32 v24, v22, v23 offset1:1
	v_or_b32_e32 v22, s4, v60
	v_ashrrev_i32_e32 v23, 31, v22
	v_lshl_add_u64 v[22:23], v[22:23], 2, s[12:13]
	global_load_dword v22, v[22:23], off
	s_waitcnt vmcnt(0)
	v_pk_mul_f32 v[24:25], v[50:51], v[22:23] op_sel_hi:[1,0]
	v_add_u32_e32 v23, 0xc30, v19
	ds_write2_b32 v23, v24, v25 offset1:1
	v_pk_mul_f32 v[22:23], v[52:53], v[22:23] op_sel_hi:[1,0]
	v_add_u32_e32 v24, 0xc38, v19
	ds_write2_b32 v24, v22, v23 offset1:1
	v_or_b32_e32 v22, s4, v61
	v_ashrrev_i32_e32 v23, 31, v22
	v_lshl_add_u64 v[22:23], v[22:23], 2, s[12:13]
	global_load_dword v22, v[22:23], off
	s_waitcnt vmcnt(0)
	v_pk_mul_f32 v[12:13], v[12:13], v[22:23] op_sel_hi:[1,0]
	v_add_u32_e32 v23, 0x1040, v19
	ds_write2_b32 v23, v12, v13 offset1:1
	v_pk_mul_f32 v[12:13], v[14:15], v[22:23] op_sel_hi:[1,0]
	v_add_u32_e32 v14, 0x1048, v19
	ds_write2_b32 v14, v12, v13 offset1:1
	v_or_b32_e32 v12, s4, v62
	v_ashrrev_i32_e32 v13, 31, v12
	v_lshl_add_u64 v[12:13], v[12:13], 2, s[12:13]
	global_load_dword v12, v[12:13], off
	v_or_b32_e32 v14, s4, v66
	v_ashrrev_i32_e32 v15, 31, v14
	v_lshl_add_u64 v[14:15], v[14:15], 2, s[12:13]
	global_load_dword v14, v[14:15], off
	s_waitcnt vmcnt(1)
	v_pk_mul_f32 v[8:9], v[8:9], v[12:13] op_sel_hi:[1,0]
	v_add_u32_e32 v13, 0x1450, v19
	ds_write2_b32 v13, v8, v9 offset1:1
	v_pk_mul_f32 v[8:9], v[10:11], v[12:13] op_sel_hi:[1,0]
	v_add_u32_e32 v12, v55, v63
	ds_write2_b32 v12, v8, v9 offset0:2 offset1:3
	v_or_b32_e32 v8, s4, v64
	v_ashrrev_i32_e32 v9, 31, v8
	v_lshl_add_u64 v[8:9], v[8:9], 2, s[12:13]
	global_load_dword v8, v[8:9], off
	v_add_u32_e32 v13, 0xc30, v12
	s_waitcnt vmcnt(0)
	v_pk_mul_f32 v[4:5], v[4:5], v[8:9] op_sel_hi:[1,0]
	v_add_u32_e32 v9, 0x410, v12
	ds_write2_b32 v9, v4, v5 offset1:1
	v_pk_mul_f32 v[4:5], v[6:7], v[8:9] op_sel_hi:[1,0]
	v_add_u32_e32 v6, 0x418, v12
	ds_write2_b32 v6, v4, v5 offset1:1
	v_or_b32_e32 v4, s4, v65
	v_ashrrev_i32_e32 v5, 31, v4
	v_lshl_add_u64 v[4:5], v[4:5], 2, s[12:13]
	global_load_dword v4, v[4:5], off
	s_waitcnt vmcnt(0)
	v_pk_mul_f32 v[0:1], v[0:1], v[4:5] op_sel_hi:[1,0]
	v_add_u32_e32 v5, 0x820, v12
	ds_write2_b32 v5, v0, v1 offset1:1
	v_pk_mul_f32 v[0:1], v[2:3], v[4:5] op_sel_hi:[1,0]
	v_add_u32_e32 v2, 0x828, v12
	ds_write2_b32 v2, v0, v1 offset1:1
	v_or_b32_e32 v0, 32, v18
	v_mad_i64_i32 v[0:1], s[18:19], v0, s1, v[20:21]
	global_load_dwordx4 v[22:25], v[0:1], off nt
	v_or_b32_e32 v0, 36, v18
	v_mad_i64_i32 v[0:1], s[18:19], v0, s1, v[20:21]
	global_load_dwordx4 v[26:29], v[0:1], off nt
	v_or_b32_e32 v0, 40, v18
	v_mad_i64_i32 v[0:1], s[18:19], v0, s1, v[20:21]
	global_load_dwordx4 v[30:33], v[0:1], off nt
	v_or_b32_e32 v0, 44, v18
	v_mad_i64_i32 v[0:1], s[18:19], v0, s1, v[20:21]
	global_load_dwordx4 v[50:53], v[0:1], off nt
	v_or_b32_e32 v0, 48, v18
	v_mad_i64_i32 v[0:1], s[18:19], v0, s1, v[20:21]
	global_load_dwordx4 v[86:89], v[0:1], off nt
	v_or_b32_e32 v0, 52, v18
	v_mad_i64_i32 v[0:1], s[18:19], v0, s1, v[20:21]
	global_load_dwordx4 v[8:11], v[0:1], off nt
	v_or_b32_e32 v0, 56, v18
	v_mad_i64_i32 v[0:1], s[18:19], v0, s1, v[20:21]
	global_load_dwordx4 v[4:7], v[0:1], off nt
	v_or_b32_e32 v0, 60, v18
	v_mad_i64_i32 v[0:1], s[18:19], v0, s1, v[20:21]
	global_load_dwordx4 v[0:3], v[0:1], off nt
	s_cselect_b64 s[0:1], -1, 0
	s_sub_i32 s5, s5, 24
	s_cmp_lt_u32 s5, 10
	s_cselect_b64 s[18:19], -1, 0
	s_and_b32 s5, s10, 0xffffff00
	s_lshr_b32 s11, s10, 1
	s_or_b32 s5, s5, s14
	s_and_b32 s11, s11, 64
	s_or_b64 s[0:1], s[0:1], s[18:19]
	s_or_b32 s5, s5, s11
	s_and_b64 s[0:1], s[0:1], exec
	s_cselect_b32 s0, s5, s10
	s_ashr_i32 s5, s4, 31
	s_waitcnt vmcnt(7)
; __host__ __device__ __forceinline__ size_t blocked_off(int row, int col, int K) { return (((size_t)(row >> 8) * (K >> 6) + (col >> 6)) * 256 + (row & 255)) * 64 + (col & 63); }
; __device__ __forceinline__ unsigned cvt_pk_bf16(float lo, float hi) { const f32x2c_t v = {lo, hi}; return __builtin_bit_cast(unsigned, __builtin_convertvector(v, bf16x2c_t)); }
; #define LAS __attribute__((address_space(3)))
; #define LDS_WAIT() asm volatile("s_waitcnt lgkmcnt(0)" ::: "memory")
; __host__ __device__ __forceinline__ int win_phys_col(int n) { if (!win_rope_tile(n >> 8)) return n; const int cl = n & 255; return (n & ~255) | (cl & 63) | ((cl & 64) << 1) | ((cl & 128) >> 1); }
; template <bool PERMUTE, bool BLOCKED = false>
; __device__ __forceinline__ void cvt_tile64(const float* W, int K, int N, bf16* WT, int ldo, const float* gk, LAS float* scr, int tile, int lane) {
;     ...
;         for (int i = 0; i < 8; ++i) { const int kk = 32 * hh + 4 * i + lk; const float g = gk ? gk[k0 + kk] : 1.0f; LAS float* d = scr + kk * 65 + ln;
;             d[0] = v[i][0] * g; d[1] = v[i][1] * g; d[2] = v[i][2] * g; d[3] = v[i][3] * g; }
;     }
;     ...
;     LDS_WAIT(); asm volatile("" ::: "memory");
;     const int kc = lane & 7, nrow0 = PERMUTE ? win_phys_col(n0) : n0;
; #pragma unroll
;     for (int j = 0; j < 8; ++j) { const int n = (lane >> 3) + 8 * j; const LAS float* s = scr + (8 * kc) * 65 + n;
;         v4u o; o[0] = cvt_pk_bf16(wrnd(s[0 * 65]), wrnd(s[1 * 65])); o[1] = cvt_pk_bf16(wrnd(s[2 * 65]), wrnd(s[3 * 65])); o[2] = cvt_pk_bf16(wrnd(s[4 * 65]), wrnd(s[5 * 65])); o[3] = cvt_pk_bf16(wrnd(s[6 * 65]), wrnd(s[7 * 65]));
;         *(v4u*)(WT + (BLOCKED ? pg8::blocked_off(nrow0 + n, k0 + 8 * kc, K) : (size_t)(nrow0 + n) * ldo + k0 + 8 * kc)) = o; }
	v_pk_mul_f32 v[18:19], v[22:23], v[14:15] op_sel_hi:[1,0]
	ds_write2_b32 v13, v18, v19 offset1:1
	v_pk_mul_f32 v[14:15], v[24:25], v[14:15] op_sel_hi:[1,0]
	v_add_u32_e32 v13, 0xc38, v12
	ds_write2_b32 v13, v14, v15 offset1:1
	v_or_b32_e32 v14, s4, v67
	v_ashrrev_i32_e32 v15, 31, v14
	v_lshl_add_u64 v[14:15], v[14:15], 2, s[12:13]
	global_load_dword v14, v[14:15], off
	v_add_u32_e32 v13, 0x1040, v12
	v_or_b32_e32 v24, s0, v74
	v_ashrrev_i32_e32 v25, 31, v24
	v_lshlrev_b64 v[24:25], 13, v[24:25]
	s_waitcnt vmcnt(0)
	v_pk_mul_f32 v[18:19], v[26:27], v[14:15] op_sel_hi:[1,0]
	ds_write2_b32 v13, v18, v19 offset1:1
	v_pk_mul_f32 v[14:15], v[28:29], v[14:15] op_sel_hi:[1,0]
	v_add_u32_e32 v13, 0x1048, v12
	ds_write2_b32 v13, v14, v15 offset1:1
	v_or_b32_e32 v14, s4, v68
	v_ashrrev_i32_e32 v15, 31, v14
	v_lshl_add_u64 v[14:15], v[14:15], 2, s[12:13]
	global_load_dword v14, v[14:15], off
	v_add_u32_e32 v13, 0x1450, v12
	v_or_b32_e32 v26, s0, v77
	v_ashrrev_i32_e32 v27, 31, v26
	v_lshlrev_b64 v[26:27], 13, v[26:27]
	s_waitcnt vmcnt(0)
	v_pk_mul_f32 v[18:19], v[30:31], v[14:15] op_sel_hi:[1,0]
	ds_write2_b32 v13, v18, v19 offset1:1
	v_pk_mul_f32 v[14:15], v[32:33], v[14:15] op_sel_hi:[1,0]
	v_add_u32_e32 v13, 0x1458, v12
	ds_write2_b32 v13, v14, v15 offset1:1
	v_or_b32_e32 v14, s4, v69
	v_ashrrev_i32_e32 v15, 31, v14
	v_lshl_add_u64 v[14:15], v[14:15], 2, s[12:13]
	global_load_dword v14, v[14:15], off
	v_add_u32_e32 v13, 0x1860, v12
	s_waitcnt vmcnt(0)
	v_pk_mul_f32 v[18:19], v[50:51], v[14:15] op_sel_hi:[1,0]
	ds_write2_b32 v13, v18, v19 offset1:1
	v_pk_mul_f32 v[14:15], v[52:53], v[14:15] op_sel_hi:[1,0]
	v_add_u32_e32 v13, 0x1868, v12
	ds_write2_b32 v13, v14, v15 offset1:1
	v_or_b32_e32 v14, s4, v70
	v_ashrrev_i32_e32 v15, 31, v14
	v_lshl_add_u64 v[14:15], v[14:15], 2, s[12:13]
	global_load_dword v14, v[14:15], off
	v_add_u32_e32 v13, 0x1c70, v12
	s_waitcnt vmcnt(0)
	v_pk_mul_f32 v[18:19], v[86:87], v[14:15] op_sel_hi:[1,0]
	ds_write2_b32 v13, v18, v19 offset1:1
	v_pk_mul_f32 v[14:15], v[88:89], v[14:15] op_sel_hi:[1,0]
	v_add_u32_e32 v13, 0x1c78, v12
	ds_write2_b32 v13, v14, v15 offset1:1
	v_or_b32_e32 v14, s4, v71
	v_ashrrev_i32_e32 v15, 31, v14
	v_lshl_add_u64 v[14:15], v[14:15], 2, s[12:13]
	global_load_dword v14, v[14:15], off
	v_add_u32_e32 v13, 0x2080, v12
	s_waitcnt vmcnt(0)
	v_pk_mul_f32 v[8:9], v[8:9], v[14:15] op_sel_hi:[1,0]
	ds_write2_b32 v13, v8, v9 offset1:1
	v_pk_mul_f32 v[8:9], v[10:11], v[14:15] op_sel_hi:[1,0]
	v_add_u32_e32 v10, 0x2088, v12
	ds_write2_b32 v10, v8, v9 offset1:1
	v_or_b32_e32 v8, s4, v72
	v_ashrrev_i32_e32 v9, 31, v8
	v_lshl_add_u64 v[8:9], v[8:9], 2, s[12:13]
	global_load_dword v8, v[8:9], off
	s_waitcnt vmcnt(0)
	v_pk_mul_f32 v[4:5], v[4:5], v[8:9] op_sel_hi:[1,0]
	v_add_u32_e32 v9, 0x2490, v12
	ds_write2_b32 v9, v4, v5 offset1:1
	v_pk_mul_f32 v[4:5], v[6:7], v[8:9] op_sel_hi:[1,0]
	v_add_u32_e32 v6, 0x2498, v12
	ds_write2_b32 v6, v4, v5 offset1:1
	v_or_b32_e32 v4, s4, v73
	v_ashrrev_i32_e32 v5, 31, v4
	v_lshl_add_u64 v[4:5], v[4:5], 2, s[12:13]
	global_load_dword v4, v[4:5], off
	s_waitcnt vmcnt(0)
	v_pk_mul_f32 v[0:1], v[0:1], v[4:5] op_sel_hi:[1,0]
	v_add_u32_e32 v5, 0x28a0, v12
	ds_write2_b32 v5, v0, v1 offset1:1
	v_pk_mul_f32 v[0:1], v[2:3], v[4:5] op_sel_hi:[1,0]
	v_add_u32_e32 v2, 0x28a8, v12
	ds_write2_b32 v2, v0, v1 offset1:1
	s_waitcnt lgkmcnt(0)
	ds_read2_b32 v[2:3], v75 offset1:8
	ds_read2_b32 v[8:9], v75 offset0:65 offset1:73
	ds_read2_b32 v[10:11], v75 offset0:130 offset1:138
	ds_read2_b32 v[12:13], v75 offset0:195 offset1:203
	v_lshl_add_u64 v[0:1], s[4:5], 1, v[36:37]
	s_waitcnt lgkmcnt(3)
	v_add_u32_e32 v2, 0x20000, v2
	s_waitcnt lgkmcnt(2)
	v_add_u32_e32 v4, 0x20000, v8
	v_and_b32_e32 v2, 0xfffc0000, v2
	v_and_b32_e32 v4, 0xfffc0000, v4
	v_cvt_pk_bf16_f32 v4, v2, v4
	s_waitcnt lgkmcnt(1)
	v_add_u32_e32 v2, 0x20000, v10
	s_waitcnt lgkmcnt(0)
	v_add_u32_e32 v5, 0x20000, v12
	v_and_b32_e32 v2, 0xfffc0000, v2
	v_and_b32_e32 v5, 0xfffc0000, v5
	v_cvt_pk_bf16_f32 v5, v2, v5
	v_add_u32_e32 v2, 0x400, v75
	ds_read2_b32 v[14:15], v2 offset0:4 offset1:12
	ds_read2_b32 v[18:19], v2 offset0:69 offset1:77
	ds_read2_b32 v[20:21], v2 offset0:134 offset1:142
	ds_read2_b32 v[22:23], v2 offset0:199 offset1:207
	v_lshl_add_u64 v[24:25], v[0:1], 0, v[24:25]
	s_waitcnt lgkmcnt(3)
	v_add_u32_e32 v6, 0x20000, v14
	s_waitcnt lgkmcnt(2)
	v_add_u32_e32 v7, 0x20000, v18
	v_and_b32_e32 v6, 0xfffc0000, v6
	v_and_b32_e32 v7, 0xfffc0000, v7
	v_cvt_pk_bf16_f32 v6, v6, v7
	s_waitcnt lgkmcnt(1)
	v_add_u32_e32 v7, 0x20000, v20
	s_waitcnt lgkmcnt(0)
	v_add_u32_e32 v8, 0x20000, v22
	v_and_b32_e32 v7, 0xfffc0000, v7
	v_and_b32_e32 v8, 0xfffc0000, v8
	v_cvt_pk_bf16_f32 v7, v7, v8
	global_store_dwordx4 v[24:25], v[4:7], off
	v_add_u32_e32 v3, 0x20000, v3
	v_and_b32_e32 v3, 0xfffc0000, v3
	v_add_u32_e32 v4, 0x20000, v9
	v_and_b32_e32 v4, 0xfffc0000, v4
	v_cvt_pk_bf16_f32 v4, v3, v4
	v_add_u32_e32 v3, 0x20000, v11
	v_add_u32_e32 v5, 0x20000, v13
	v_and_b32_e32 v3, 0xfffc0000, v3
	v_and_b32_e32 v5, 0xfffc0000, v5
	v_cvt_pk_bf16_f32 v5, v3, v5
	v_add_u32_e32 v3, 0x20000, v15
	v_add_u32_e32 v6, 0x20000, v19
	v_and_b32_e32 v3, 0xfffc0000, v3
	v_and_b32_e32 v6, 0xfffc0000, v6
	v_or_b32_e32 v8, s0, v76
	v_cvt_pk_bf16_f32 v6, v3, v6
	v_add_u32_e32 v3, 0x20000, v21
	v_add_u32_e32 v7, 0x20000, v23
	v_ashrrev_i32_e32 v9, 31, v8
	v_and_b32_e32 v3, 0xfffc0000, v3
	v_and_b32_e32 v7, 0xfffc0000, v7
	v_lshlrev_b64 v[8:9], 13, v[8:9]
	v_cvt_pk_bf16_f32 v7, v3, v7
	v_lshl_add_u64 v[8:9], v[0:1], 0, v[8:9]
	global_store_dwordx4 v[8:9], v[4:7], off
	ds_read2_b32 v[8:9], v75 offset0:16 offset1:24
	ds_read2_b32 v[10:11], v75 offset0:81 offset1:89
	ds_read2_b32 v[12:13], v75 offset0:146 offset1:154
	ds_read2_b32 v[14:15], v75 offset0:211 offset1:219
	ds_read2_b32 v[18:19], v2 offset0:20 offset1:28
	ds_read2_b32 v[20:21], v2 offset0:85 offset1:93
	s_waitcnt lgkmcnt(5)
; __host__ __device__ __forceinline__ size_t blocked_off(int row, int col, int K) { return (((size_t)(row >> 8) * (K >> 6) + (col >> 6)) * 256 + (row & 255)) * 64 + (col & 63); }
; __device__ __forceinline__ unsigned cvt_pk_bf16(float lo, float hi) { const f32x2c_t v = {lo, hi}; return __builtin_bit_cast(unsigned, __builtin_convertvector(v, bf16x2c_t)); }
; #define LAS __attribute__((address_space(3)))
; #define LDS_WAIT() asm volatile("s_waitcnt lgkmcnt(0)" ::: "memory")
; __host__ __device__ __forceinline__ int win_phys_col(int n) { if (!win_rope_tile(n >> 8)) return n; const int cl = n & 255; return (n & ~255) | (cl & 63) | ((cl & 64) << 1) | ((cl & 128) >> 1); }
; template <bool PERMUTE, bool BLOCKED = false>
; __device__ __forceinline__ void cvt_tile64(const float* W, int K, int N, bf16* WT, int ldo, const float* gk, LAS float* scr, int tile, int lane) {
;     ...
;     const int kc = lane & 7, nrow0 = PERMUTE ? win_phys_col(n0) : n0;
; #pragma unroll
;     for (int j = 0; j < 8; ++j) { const int n = (lane >> 3) + 8 * j; const LAS float* s = scr + (8 * kc) * 65 + n;
;         v4u o; o[0] = cvt_pk_bf16(wrnd(s[0 * 65]), wrnd(s[1 * 65])); o[1] = cvt_pk_bf16(wrnd(s[2 * 65]), wrnd(s[3 * 65])); o[2] = cvt_pk_bf16(wrnd(s[4 * 65]), wrnd(s[5 * 65])); o[3] = cvt_pk_bf16(wrnd(s[6 * 65]), wrnd(s[7 * 65]));
;         *(v4u*)(WT + (BLOCKED ? pg8::blocked_off(nrow0 + n, k0 + 8 * kc, K) : (size_t)(nrow0 + n) * ldo + k0 + 8 * kc)) = o; }
;     LDS_WAIT(); asm volatile("" ::: "memory");
	v_add_u32_e32 v3, 0x20000, v8
	s_waitcnt lgkmcnt(4)
	v_add_u32_e32 v4, 0x20000, v10
	v_and_b32_e32 v3, 0xfffc0000, v3
	v_and_b32_e32 v4, 0xfffc0000, v4
	ds_read2_b32 v[22:23], v2 offset0:150 offset1:158
	ds_read2_b32 v[24:25], v2 offset0:215 offset1:223
	v_cvt_pk_bf16_f32 v4, v3, v4
	s_waitcnt lgkmcnt(5)
	v_add_u32_e32 v3, 0x20000, v12
	s_waitcnt lgkmcnt(4)
	v_add_u32_e32 v5, 0x20000, v14
	v_and_b32_e32 v3, 0xfffc0000, v3
	v_and_b32_e32 v5, 0xfffc0000, v5
	v_cvt_pk_bf16_f32 v5, v3, v5
	s_waitcnt lgkmcnt(3)
	v_add_u32_e32 v3, 0x20000, v18
	s_waitcnt lgkmcnt(2)
	v_add_u32_e32 v6, 0x20000, v20
	v_and_b32_e32 v3, 0xfffc0000, v3
	v_and_b32_e32 v6, 0xfffc0000, v6
	v_cvt_pk_bf16_f32 v6, v3, v6
	s_waitcnt lgkmcnt(1)
	v_add_u32_e32 v3, 0x20000, v22
	s_waitcnt lgkmcnt(0)
	v_add_u32_e32 v7, 0x20000, v24
	v_and_b32_e32 v3, 0xfffc0000, v3
	v_and_b32_e32 v7, 0xfffc0000, v7
	v_cvt_pk_bf16_f32 v7, v3, v7
	v_lshl_add_u64 v[26:27], v[0:1], 0, v[26:27]
	global_store_dwordx4 v[26:27], v[4:7], off
	v_add_u32_e32 v3, 0x20000, v9
	v_and_b32_e32 v3, 0xfffc0000, v3
	v_add_u32_e32 v4, 0x20000, v11
	v_and_b32_e32 v4, 0xfffc0000, v4
	v_cvt_pk_bf16_f32 v4, v3, v4
	v_add_u32_e32 v3, 0x20000, v13
	v_add_u32_e32 v5, 0x20000, v15
	v_and_b32_e32 v3, 0xfffc0000, v3
	v_and_b32_e32 v5, 0xfffc0000, v5
	v_cvt_pk_bf16_f32 v5, v3, v5
	v_add_u32_e32 v3, 0x20000, v19
	v_add_u32_e32 v6, 0x20000, v21
	v_and_b32_e32 v3, 0xfffc0000, v3
	v_and_b32_e32 v6, 0xfffc0000, v6
	v_or_b32_e32 v8, s0, v78
	v_cvt_pk_bf16_f32 v6, v3, v6
	v_add_u32_e32 v3, 0x20000, v23
	v_add_u32_e32 v7, 0x20000, v25
	v_ashrrev_i32_e32 v9, 31, v8
	v_and_b32_e32 v3, 0xfffc0000, v3
	v_and_b32_e32 v7, 0xfffc0000, v7
	v_lshlrev_b64 v[8:9], 13, v[8:9]
	v_cvt_pk_bf16_f32 v7, v3, v7
	v_lshl_add_u64 v[8:9], v[0:1], 0, v[8:9]
	global_store_dwordx4 v[8:9], v[4:7], off
	ds_read2_b32 v[8:9], v75 offset0:32 offset1:40
	ds_read2_b32 v[10:11], v75 offset0:97 offset1:105
	ds_read2_b32 v[12:13], v75 offset0:162 offset1:170
	ds_read2_b32 v[14:15], v75 offset0:227 offset1:235
	ds_read2_b32 v[18:19], v2 offset0:36 offset1:44
	ds_read2_b32 v[20:21], v2 offset0:101 offset1:109
	s_waitcnt lgkmcnt(5)
	v_add_u32_e32 v3, 0x20000, v8
	s_waitcnt lgkmcnt(4)
	v_add_u32_e32 v4, 0x20000, v10
	v_and_b32_e32 v3, 0xfffc0000, v3
	v_and_b32_e32 v4, 0xfffc0000, v4
	ds_read2_b32 v[22:23], v2 offset0:166 offset1:174
	ds_read2_b32 v[24:25], v2 offset0:231 offset1:239
	v_cvt_pk_bf16_f32 v4, v3, v4
	s_waitcnt lgkmcnt(5)
	v_add_u32_e32 v3, 0x20000, v12
	s_waitcnt lgkmcnt(4)
	v_add_u32_e32 v5, 0x20000, v14
	v_and_b32_e32 v3, 0xfffc0000, v3
	v_and_b32_e32 v5, 0xfffc0000, v5
	v_cvt_pk_bf16_f32 v5, v3, v5
	s_waitcnt lgkmcnt(3)
	v_add_u32_e32 v3, 0x20000, v18
	s_waitcnt lgkmcnt(2)
	v_add_u32_e32 v6, 0x20000, v20
	v_and_b32_e32 v3, 0xfffc0000, v3
	v_and_b32_e32 v6, 0xfffc0000, v6
	v_or_b32_e32 v26, s0, v79
	v_cvt_pk_bf16_f32 v6, v3, v6
	s_waitcnt lgkmcnt(1)
	v_add_u32_e32 v3, 0x20000, v22
	s_waitcnt lgkmcnt(0)
	v_add_u32_e32 v7, 0x20000, v24
	v_ashrrev_i32_e32 v27, 31, v26
	v_and_b32_e32 v3, 0xfffc0000, v3
	v_and_b32_e32 v7, 0xfffc0000, v7
	v_lshlrev_b64 v[26:27], 13, v[26:27]
	v_cvt_pk_bf16_f32 v7, v3, v7
	v_lshl_add_u64 v[26:27], v[0:1], 0, v[26:27]
	global_store_dwordx4 v[26:27], v[4:7], off
	v_add_u32_e32 v3, 0x20000, v9
	v_and_b32_e32 v3, 0xfffc0000, v3
	v_add_u32_e32 v4, 0x20000, v11
	v_and_b32_e32 v4, 0xfffc0000, v4
	v_cvt_pk_bf16_f32 v4, v3, v4
	v_add_u32_e32 v3, 0x20000, v13
	v_add_u32_e32 v5, 0x20000, v15
	v_and_b32_e32 v3, 0xfffc0000, v3
	v_and_b32_e32 v5, 0xfffc0000, v5
	v_cvt_pk_bf16_f32 v5, v3, v5
	v_add_u32_e32 v3, 0x20000, v19
	v_add_u32_e32 v6, 0x20000, v21
	v_and_b32_e32 v3, 0xfffc0000, v3
	v_and_b32_e32 v6, 0xfffc0000, v6
	v_or_b32_e32 v8, s0, v80
	v_cvt_pk_bf16_f32 v6, v3, v6
	v_add_u32_e32 v3, 0x20000, v23
	v_add_u32_e32 v7, 0x20000, v25
	v_ashrrev_i32_e32 v9, 31, v8
	v_and_b32_e32 v3, 0xfffc0000, v3
	v_and_b32_e32 v7, 0xfffc0000, v7
	v_lshlrev_b64 v[8:9], 13, v[8:9]
	v_cvt_pk_bf16_f32 v7, v3, v7
	v_lshl_add_u64 v[8:9], v[0:1], 0, v[8:9]
	global_store_dwordx4 v[8:9], v[4:7], off
	ds_read2_b32 v[8:9], v75 offset0:48 offset1:56
	ds_read2_b32 v[10:11], v75 offset0:113 offset1:121
	ds_read2_b32 v[12:13], v75 offset0:178 offset1:186
	ds_read2_b32 v[14:15], v75 offset0:243 offset1:251
	ds_read2_b32 v[18:19], v2 offset0:52 offset1:60
	ds_read2_b32 v[20:21], v2 offset0:117 offset1:125
	s_waitcnt lgkmcnt(5)
	v_add_u32_e32 v3, 0x20000, v8
	s_waitcnt lgkmcnt(4)
	v_add_u32_e32 v4, 0x20000, v10
	v_and_b32_e32 v3, 0xfffc0000, v3
	v_and_b32_e32 v4, 0xfffc0000, v4
	ds_read2_b32 v[22:23], v2 offset0:182 offset1:190
	ds_read2_b32 v[24:25], v2 offset0:247 offset1:255
	v_cvt_pk_bf16_f32 v4, v3, v4
	s_waitcnt lgkmcnt(5)
	v_add_u32_e32 v3, 0x20000, v12
	s_waitcnt lgkmcnt(4)
	v_add_u32_e32 v5, 0x20000, v14
	v_and_b32_e32 v3, 0xfffc0000, v3
	v_and_b32_e32 v5, 0xfffc0000, v5
	v_cvt_pk_bf16_f32 v5, v3, v5
	s_waitcnt lgkmcnt(3)
	v_add_u32_e32 v3, 0x20000, v18
	s_waitcnt lgkmcnt(2)
	v_add_u32_e32 v6, 0x20000, v20
	v_and_b32_e32 v3, 0xfffc0000, v3
	v_and_b32_e32 v6, 0xfffc0000, v6
	v_cvt_pk_bf16_f32 v6, v3, v6
	s_waitcnt lgkmcnt(1)
	v_add_u32_e32 v3, 0x20000, v22
	s_waitcnt lgkmcnt(0)
	v_add_u32_e32 v2, 0x20000, v24
	v_and_b32_e32 v3, 0xfffc0000, v3
	v_and_b32_e32 v2, 0xfffc0000, v2
	v_cvt_pk_bf16_f32 v7, v3, v2
	v_or_b32_e32 v2, s0, v81
	v_ashrrev_i32_e32 v3, 31, v2
	v_lshlrev_b64 v[2:3], 13, v[2:3]
	v_lshl_add_u64 v[2:3], v[0:1], 0, v[2:3]
	global_store_dwordx4 v[2:3], v[4:7], off
	v_add_u32_e32 v2, 0x20000, v9
	v_add_u32_e32 v3, 0x20000, v11
	v_and_b32_e32 v2, 0xfffc0000, v2
	v_and_b32_e32 v3, 0xfffc0000, v3
	v_cvt_pk_bf16_f32 v2, v2, v3
	v_add_u32_e32 v3, 0x20000, v13
	v_add_u32_e32 v4, 0x20000, v15
	v_and_b32_e32 v3, 0xfffc0000, v3
	v_and_b32_e32 v4, 0xfffc0000, v4
	v_cvt_pk_bf16_f32 v3, v3, v4
	v_add_u32_e32 v4, 0x20000, v19
	v_add_u32_e32 v5, 0x20000, v21
	v_and_b32_e32 v4, 0xfffc0000, v4
	v_and_b32_e32 v5, 0xfffc0000, v5
	v_cvt_pk_bf16_f32 v4, v4, v5
	v_add_u32_e32 v5, 0x20000, v23
	v_add_u32_e32 v6, 0x20000, v25
	v_and_b32_e32 v5, 0xfffc0000, v5
	v_and_b32_e32 v6, 0xfffc0000, v6
	v_cvt_pk_bf16_f32 v5, v5, v6
	v_or_b32_e32 v6, s0, v82
	v_ashrrev_i32_e32 v7, 31, v6
	v_lshlrev_b64 v[6:7], 13, v[6:7]
	v_lshl_add_u64 v[0:1], v[0:1], 0, v[6:7]
	global_store_dwordx4 v[0:1], v[2:5], off
	s_waitcnt lgkmcnt(0)
	s_mov_b64 s[0:1], 0
; #define LAS __attribute__((address_space(3)))
; template <bool PERMUTE, bool BLOCKED = false>
; __device__ __forceinline__ void cvt_tile64(const float* W, int K, int N, bf16* WT, int ldo, const float* gk, LAS float* scr, int tile, int lane) {
;     ...
;     for (int hh = 0; hh < 2; ++hh) {
;         f32x4 v[8];
; #pragma unroll
;         for (int i = 0; i < 8; ++i) v[i] = *(const f32x4*)(W + (size_t)(k0 + 32 * hh + 4 * i + lk) * N + n0 + ln);
; #pragma unroll
;         for (int i = 0; i < 8; ++i) { const int kk = 32 * hh + 4 * i + lk; const float g = gk ? gk[k0 + kk] : 1.0f; LAS float* d = scr + kk * 65 + ln;
;             d[0] = v[i][0] * g; d[1] = v[i][1] * g; d[2] = v[i][2] * g; d[3] = v[i][3] * g; }
;     }
; __device__ __forceinline__ void cvt_item(const CvtCtx& c, int batch, int wi, LAS float* scr, int wave, int lane) {
;     ...
;     if (wi < CVT_DN) { cvt_tile64<false, true>(c.w_down + (size_t)l * DFF * DM, DFF, DM, c.WdnT + (size_t)l * DM * DFF, 0, nullptr, scr, 8 * wi + wave, lane); return; } wi -= CVT_DN;
.LBB0_879:
	s_andn2_b64 vcc, exec, s[0:1]
	s_cbranch_vccnz .LBB0_881
	s_add_i32 s0, s16, 0x4000
	s_ashr_i32 s1, s0, 31
	s_lshr_b32 s1, s1, 26
	s_add_i32 s0, s0, s1
	s_ashr_i32 s4, s0, 6
	s_lshl_b32 s5, s4, 12
	s_andn2_b32 s0, s0, 63
	s_sub_i32 s5, s15, s5
	s_add_i32 s10, s5, 0x100000
	v_or_b32_e32 v2, s0, v16
	s_ashr_i32 s11, s10, 31
	v_ashrrev_i32_e32 v3, 31, v2
	v_lshl_add_u64 v[0:1], s[10:11], 2, v[38:39]
	v_lshlrev_b64 v[4:5], 14, v[2:3]
	v_or_b32_e32 v8, 4, v2
	v_lshl_add_u64 v[4:5], v[0:1], 0, v[4:5]
	v_ashrrev_i32_e32 v9, 31, v8
	global_load_dwordx4 v[4:7], v[4:5], off nt
	v_lshlrev_b64 v[8:9], 14, v[8:9]
	v_or_b32_e32 v12, 8, v2
	v_lshl_add_u64 v[8:9], v[0:1], 0, v[8:9]
	v_ashrrev_i32_e32 v13, 31, v12
	global_load_dwordx4 v[8:11], v[8:9], off nt
	v_lshlrev_b64 v[12:13], 14, v[12:13]
	v_or_b32_e32 v18, 12, v2
	v_lshl_add_u64 v[12:13], v[0:1], 0, v[12:13]
	v_ashrrev_i32_e32 v19, 31, v18
	global_load_dwordx4 v[12:15], v[12:13], off nt
	v_lshlrev_b64 v[18:19], 14, v[18:19]
	v_or_b32_e32 v22, 16, v2
	v_lshl_add_u64 v[18:19], v[0:1], 0, v[18:19]
	v_ashrrev_i32_e32 v23, 31, v22
	global_load_dwordx4 v[18:21], v[18:19], off nt
	v_lshlrev_b64 v[22:23], 14, v[22:23]
	v_or_b32_e32 v26, 20, v2
	v_lshl_add_u64 v[22:23], v[0:1], 0, v[22:23]
	v_ashrrev_i32_e32 v27, 31, v26
	global_load_dwordx4 v[22:25], v[22:23], off nt
	v_lshlrev_b64 v[26:27], 14, v[26:27]
	v_or_b32_e32 v30, 24, v2
	v_lshl_add_u64 v[26:27], v[0:1], 0, v[26:27]
	v_ashrrev_i32_e32 v31, 31, v30
	global_load_dwordx4 v[26:29], v[26:27], off nt
	v_lshlrev_b64 v[30:31], 14, v[30:31]
	v_or_b32_e32 v50, 28, v2
	v_lshl_add_u64 v[30:31], v[0:1], 0, v[30:31]
	v_ashrrev_i32_e32 v51, 31, v50
	global_load_dwordx4 v[30:33], v[30:31], off nt
	v_lshlrev_b64 v[50:51], 14, v[50:51]
	v_lshl_add_u64 v[50:51], v[0:1], 0, v[50:51]
	global_load_dwordx4 v[50:53], v[50:51], off nt
	v_add_u32_e32 v54, v55, v57
	v_add_u32_e32 v3, 0x410, v54
	s_ashr_i32 s10, s10, 8
	s_ashr_i32 s11, s10, 31
	s_ashr_i32 s5, s4, 31
	s_add_i32 s1, s15, 0x100000
	s_lshl_b64 s[10:11], s[10:11], 16
	s_lshl_b64 s[4:5], s[4:5], 8
	s_add_u32 s0, s10, s4
	s_addc_u32 s4, s11, s5
	s_and_b32 s1, s1, 0xc0
	s_waitcnt vmcnt(7)
	ds_write2_b32 v54, v4, v5 offset1:1
	ds_write2_b32 v54, v6, v7 offset0:2 offset1:3
	v_or_b32_e32 v4, 32, v2
	v_ashrrev_i32_e32 v5, 31, v4
	v_lshlrev_b64 v[4:5], 14, v[4:5]
	v_lshl_add_u64 v[4:5], v[0:1], 0, v[4:5]
	s_waitcnt vmcnt(6)
	ds_write2_b32 v3, v8, v9 offset1:1
	v_add_u32_e32 v3, 0x418, v54
	v_or_b32_e32 v8, 36, v2
	ds_write2_b32 v3, v10, v11 offset1:1
	v_add_u32_e32 v3, 0x820, v54
	v_ashrrev_i32_e32 v9, 31, v8
	s_waitcnt vmcnt(5)
	ds_write2_b32 v3, v12, v13 offset1:1
	v_add_u32_e32 v3, 0x828, v54
	global_load_dwordx4 v[4:7], v[4:5], off nt
	v_lshlrev_b64 v[8:9], 14, v[8:9]
	v_or_b32_e32 v12, 40, v2
	ds_write2_b32 v3, v14, v15 offset1:1
	v_add_u32_e32 v3, 0xc30, v54
	v_lshl_add_u64 v[8:9], v[0:1], 0, v[8:9]
	v_ashrrev_i32_e32 v13, 31, v12
	s_waitcnt vmcnt(5)
	ds_write2_b32 v3, v18, v19 offset1:1
	v_add_u32_e32 v3, 0xc38, v54
	global_load_dwordx4 v[8:11], v[8:9], off nt
	v_lshlrev_b64 v[12:13], 14, v[12:13]
	v_or_b32_e32 v18, 44, v2
	ds_write2_b32 v3, v20, v21 offset1:1
	v_add_u32_e32 v3, 0x1040, v54
	v_lshl_add_u64 v[12:13], v[0:1], 0, v[12:13]
	v_ashrrev_i32_e32 v19, 31, v18
	s_waitcnt vmcnt(5)
	ds_write2_b32 v3, v22, v23 offset1:1
	v_add_u32_e32 v3, 0x1048, v54
	global_load_dwordx4 v[12:15], v[12:13], off nt
	v_lshlrev_b64 v[18:19], 14, v[18:19]
	v_or_b32_e32 v22, 48, v2
	ds_write2_b32 v3, v24, v25 offset1:1
	v_add_u32_e32 v3, 0x1450, v54
	v_lshl_add_u64 v[18:19], v[0:1], 0, v[18:19]
	v_ashrrev_i32_e32 v23, 31, v22
	s_waitcnt vmcnt(5)
	ds_write2_b32 v3, v26, v27 offset1:1
	v_add_u32_e32 v3, 0x1458, v54
	global_load_dwordx4 v[18:21], v[18:19], off nt
	v_lshlrev_b64 v[22:23], 14, v[22:23]
	v_or_b32_e32 v26, 52, v2
	ds_write2_b32 v3, v28, v29 offset1:1
	v_add_u32_e32 v3, 0x1860, v54
	v_lshl_add_u64 v[22:23], v[0:1], 0, v[22:23]
	v_ashrrev_i32_e32 v27, 31, v26
	s_waitcnt vmcnt(5)
	ds_write2_b32 v3, v30, v31 offset1:1
	v_add_u32_e32 v3, 0x1868, v54
	global_load_dwordx4 v[22:25], v[22:23], off nt
	v_lshlrev_b64 v[26:27], 14, v[26:27]
	v_or_b32_e32 v30, 56, v2
	ds_write2_b32 v3, v32, v33 offset1:1
	v_add_u32_e32 v3, 0x1c70, v54
	v_lshl_add_u64 v[26:27], v[0:1], 0, v[26:27]
	v_ashrrev_i32_e32 v31, 31, v30
	s_waitcnt vmcnt(5)
	ds_write2_b32 v3, v50, v51 offset1:1
	v_add_u32_e32 v3, 0x1c78, v54
	global_load_dwordx4 v[26:29], v[26:27], off nt
	v_lshlrev_b64 v[30:31], 14, v[30:31]
	v_or_b32_e32 v2, 60, v2
	ds_write2_b32 v3, v52, v53 offset1:1
	v_lshl_add_u64 v[30:31], v[0:1], 0, v[30:31]
	v_ashrrev_i32_e32 v3, 31, v2
	global_load_dwordx4 v[30:33], v[30:31], off nt
	v_lshlrev_b64 v[2:3], 14, v[2:3]
	v_lshl_add_u64 v[0:1], v[0:1], 0, v[2:3]
	global_load_dwordx4 v[0:3], v[0:1], off nt
	v_add_u32_e32 v50, 0x2080, v54
	s_waitcnt vmcnt(7)
	ds_write2_b32 v50, v4, v5 offset1:1
	v_add_u32_e32 v4, 0x2088, v54
	ds_write2_b32 v4, v6, v7 offset1:1
	v_add_u32_e32 v4, 0x2490, v54
	s_waitcnt vmcnt(6)
	ds_write2_b32 v4, v8, v9 offset1:1
	v_add_u32_e32 v4, 0x2498, v54
	ds_write2_b32 v4, v10, v11 offset1:1
	v_add_u32_e32 v4, 0x28a0, v54
	s_waitcnt vmcnt(5)
	ds_write2_b32 v4, v12, v13 offset1:1
	v_add_u32_e32 v4, 0x28a8, v54
	ds_write2_b32 v4, v14, v15 offset1:1
	v_add_u32_e32 v4, 0x2cb0, v54
	s_waitcnt vmcnt(4)
	ds_write2_b32 v4, v18, v19 offset1:1
	v_add_u32_e32 v4, 0x2cb8, v54
	ds_write2_b32 v4, v20, v21 offset1:1
	v_add_u32_e32 v4, 0x30c0, v54
	s_waitcnt vmcnt(3)
	ds_write2_b32 v4, v22, v23 offset1:1
	v_add_u32_e32 v4, 0x30c8, v54
	ds_write2_b32 v4, v24, v25 offset1:1
	v_add_u32_e32 v4, 0x34d0, v54
	s_waitcnt vmcnt(2)
; __host__ __device__ __forceinline__ size_t blocked_off(int row, int col, int K) { return (((size_t)(row >> 8) * (K >> 6) + (col >> 6)) * 256 + (row & 255)) * 64 + (col & 63); }
; __device__ __forceinline__ unsigned cvt_pk_bf16(float lo, float hi) { const f32x2c_t v = {lo, hi}; return __builtin_bit_cast(unsigned, __builtin_convertvector(v, bf16x2c_t)); }
; #define LAS __attribute__((address_space(3)))
; #define LDS_WAIT() asm volatile("s_waitcnt lgkmcnt(0)" ::: "memory")
; __host__ __device__ __forceinline__ int win_phys_col(int n) { if (!win_rope_tile(n >> 8)) return n; const int cl = n & 255; return (n & ~255) | (cl & 63) | ((cl & 64) << 1) | ((cl & 128) >> 1); }
; template <bool PERMUTE, bool BLOCKED = false>
; __device__ __forceinline__ void cvt_tile64(const float* W, int K, int N, bf16* WT, int ldo, const float* gk, LAS float* scr, int tile, int lane) {
;     ...
;         for (int i = 0; i < 8; ++i) { const int kk = 32 * hh + 4 * i + lk; const float g = gk ? gk[k0 + kk] : 1.0f; LAS float* d = scr + kk * 65 + ln;
;             d[0] = v[i][0] * g; d[1] = v[i][1] * g; d[2] = v[i][2] * g; d[3] = v[i][3] * g; }
;     }
;     ...
;     LDS_WAIT(); asm volatile("" ::: "memory");
;     const int kc = lane & 7, nrow0 = PERMUTE ? win_phys_col(n0) : n0;
; #pragma unroll
;     for (int j = 0; j < 8; ++j) { const int n = (lane >> 3) + 8 * j; const LAS float* s = scr + (8 * kc) * 65 + n;
;         v4u o; o[0] = cvt_pk_bf16(wrnd(s[0 * 65]), wrnd(s[1 * 65])); o[1] = cvt_pk_bf16(wrnd(s[2 * 65]), wrnd(s[3 * 65])); o[2] = cvt_pk_bf16(wrnd(s[4 * 65]), wrnd(s[5 * 65])); o[3] = cvt_pk_bf16(wrnd(s[6 * 65]), wrnd(s[7 * 65]));
;         *(v4u*)(WT + (BLOCKED ? pg8::blocked_off(nrow0 + n, k0 + 8 * kc, K) : (size_t)(nrow0 + n) * ldo + k0 + 8 * kc)) = o; }
	ds_write2_b32 v4, v26, v27 offset1:1
	v_add_u32_e32 v4, 0x34d8, v54
	ds_write2_b32 v4, v28, v29 offset1:1
	v_add_u32_e32 v4, 0x38e0, v54
	s_waitcnt vmcnt(1)
	ds_write2_b32 v4, v30, v31 offset1:1
	v_add_u32_e32 v4, 0x38e8, v54
	ds_write2_b32 v4, v32, v33 offset1:1
	v_add_u32_e32 v4, 0x3cf0, v54
	s_waitcnt vmcnt(0)
	ds_write2_b32 v4, v0, v1 offset1:1
	v_add_u32_e32 v0, 0x3cf8, v54
	ds_write2_b32 v0, v2, v3 offset1:1
	s_waitcnt lgkmcnt(0)
	ds_read2_b32 v[2:3], v75 offset1:8
	ds_read2_b32 v[8:9], v75 offset0:65 offset1:73
	ds_read2_b32 v[10:11], v75 offset0:130 offset1:138
	ds_read2_b32 v[12:13], v75 offset0:195 offset1:203
	s_waitcnt lgkmcnt(3)
	v_add_u32_e32 v0, 0x20000, v2
	v_add_u32_e32 v2, 0x400, v75
	ds_read2_b32 v[14:15], v2 offset0:4 offset1:12
	ds_read2_b32 v[18:19], v2 offset0:69 offset1:77
	s_waitcnt lgkmcnt(4)
	v_add_u32_e32 v1, 0x20000, v8
	v_and_b32_e32 v0, 0xfffc0000, v0
	v_and_b32_e32 v1, 0xfffc0000, v1
	ds_read2_b32 v[20:21], v2 offset0:134 offset1:142
	ds_read2_b32 v[22:23], v2 offset0:199 offset1:207
	v_cvt_pk_bf16_f32 v4, v0, v1
	s_waitcnt lgkmcnt(5)
	v_add_u32_e32 v0, 0x20000, v10
	s_waitcnt lgkmcnt(4)
	v_add_u32_e32 v1, 0x20000, v12
	v_and_b32_e32 v0, 0xfffc0000, v0
	v_and_b32_e32 v1, 0xfffc0000, v1
	v_cvt_pk_bf16_f32 v5, v0, v1
	s_waitcnt lgkmcnt(3)
	v_add_u32_e32 v0, 0x20000, v14
	s_waitcnt lgkmcnt(2)
	v_add_u32_e32 v1, 0x20000, v18
	v_and_b32_e32 v0, 0xfffc0000, v0
	v_and_b32_e32 v1, 0xfffc0000, v1
	v_cvt_pk_bf16_f32 v6, v0, v1
	s_waitcnt lgkmcnt(1)
	v_add_u32_e32 v0, 0x20000, v20
	s_waitcnt lgkmcnt(0)
	v_add_u32_e32 v1, 0x20000, v22
	v_and_b32_e32 v0, 0xfffc0000, v0
	v_and_b32_e32 v1, 0xfffc0000, v1
	v_cvt_pk_bf16_f32 v7, v0, v1
	v_or_b32_e32 v0, s1, v74
	v_or_b32_e32 v0, s0, v0
	v_mov_b32_e32 v1, s4
	v_lshlrev_b64 v[24:25], 7, v[0:1]
	v_add_u32_e32 v0, 0x20000, v3
	v_add_u32_e32 v3, 0x20000, v9
	v_lshl_add_u64 v[24:25], v[40:41], 0, v[24:25]
	v_and_b32_e32 v0, 0xfffc0000, v0
	v_and_b32_e32 v3, 0xfffc0000, v3
	global_store_dwordx4 v[24:25], v[4:7], off
	ds_read2_b32 v[24:25], v2 offset0:215 offset1:223
	s_nop 0
	v_cvt_pk_bf16_f32 v4, v0, v3
	v_add_u32_e32 v0, 0x20000, v11
	v_add_u32_e32 v3, 0x20000, v13
	v_and_b32_e32 v0, 0xfffc0000, v0
	v_and_b32_e32 v3, 0xfffc0000, v3
	v_cvt_pk_bf16_f32 v5, v0, v3
	v_add_u32_e32 v0, 0x20000, v15
	v_add_u32_e32 v3, 0x20000, v19
	v_and_b32_e32 v0, 0xfffc0000, v0
	v_and_b32_e32 v3, 0xfffc0000, v3
	v_cvt_pk_bf16_f32 v6, v0, v3
	v_add_u32_e32 v0, 0x20000, v21
	v_add_u32_e32 v3, 0x20000, v23
	v_and_b32_e32 v0, 0xfffc0000, v0
	v_and_b32_e32 v3, 0xfffc0000, v3
	v_cvt_pk_bf16_f32 v7, v0, v3
	v_or_b32_e32 v0, s1, v76
	v_or_b32_e32 v0, s0, v0
	v_lshlrev_b64 v[8:9], 7, v[0:1]
	v_lshl_add_u64 v[8:9], v[40:41], 0, v[8:9]
	global_store_dwordx4 v[8:9], v[4:7], off
	ds_read2_b32 v[8:9], v75 offset0:16 offset1:24
	ds_read2_b32 v[10:11], v75 offset0:81 offset1:89
	ds_read2_b32 v[12:13], v75 offset0:146 offset1:154
	ds_read2_b32 v[14:15], v75 offset0:211 offset1:219
	ds_read2_b32 v[18:19], v2 offset0:20 offset1:28
	ds_read2_b32 v[20:21], v2 offset0:85 offset1:93
	s_waitcnt lgkmcnt(5)
	v_add_u32_e32 v0, 0x20000, v8
	s_waitcnt lgkmcnt(4)
	v_add_u32_e32 v3, 0x20000, v10
	v_and_b32_e32 v0, 0xfffc0000, v0
	v_and_b32_e32 v3, 0xfffc0000, v3
	ds_read2_b32 v[22:23], v2 offset0:150 offset1:158
	v_cvt_pk_bf16_f32 v4, v0, v3
	s_waitcnt lgkmcnt(4)
	v_add_u32_e32 v0, 0x20000, v12
	s_waitcnt lgkmcnt(3)
	v_add_u32_e32 v3, 0x20000, v14
	v_and_b32_e32 v0, 0xfffc0000, v0
	v_and_b32_e32 v3, 0xfffc0000, v3
	v_cvt_pk_bf16_f32 v5, v0, v3
	s_waitcnt lgkmcnt(2)
	v_add_u32_e32 v0, 0x20000, v18
	s_waitcnt lgkmcnt(1)
	v_add_u32_e32 v3, 0x20000, v20
	v_and_b32_e32 v0, 0xfffc0000, v0
	v_and_b32_e32 v3, 0xfffc0000, v3
	v_cvt_pk_bf16_f32 v6, v0, v3
	s_waitcnt lgkmcnt(0)
	v_add_u32_e32 v0, 0x20000, v22
	v_add_u32_e32 v3, 0x20000, v24
	v_and_b32_e32 v0, 0xfffc0000, v0
	v_and_b32_e32 v3, 0xfffc0000, v3
	v_cvt_pk_bf16_f32 v7, v0, v3
	v_or_b32_e32 v0, s1, v77
	v_or_b32_e32 v0, s0, v0
	v_lshlrev_b64 v[26:27], 7, v[0:1]
	v_add_u32_e32 v0, 0x20000, v9
	v_add_u32_e32 v3, 0x20000, v11
	v_lshl_add_u64 v[26:27], v[40:41], 0, v[26:27]
	v_and_b32_e32 v0, 0xfffc0000, v0
	v_and_b32_e32 v3, 0xfffc0000, v3
	global_store_dwordx4 v[26:27], v[4:7], off
	ds_read2_b32 v[10:11], v75 offset0:97 offset1:105
	s_nop 0
	v_cvt_pk_bf16_f32 v4, v0, v3
	v_add_u32_e32 v0, 0x20000, v13
	v_add_u32_e32 v3, 0x20000, v15
	v_and_b32_e32 v0, 0xfffc0000, v0
	v_and_b32_e32 v3, 0xfffc0000, v3
	v_cvt_pk_bf16_f32 v5, v0, v3
	v_add_u32_e32 v0, 0x20000, v19
	v_add_u32_e32 v3, 0x20000, v21
	v_and_b32_e32 v0, 0xfffc0000, v0
	v_and_b32_e32 v3, 0xfffc0000, v3
	v_cvt_pk_bf16_f32 v6, v0, v3
	v_add_u32_e32 v0, 0x20000, v23
	v_add_u32_e32 v3, 0x20000, v25
	v_and_b32_e32 v0, 0xfffc0000, v0
	v_and_b32_e32 v3, 0xfffc0000, v3
	v_cvt_pk_bf16_f32 v7, v0, v3
	v_or_b32_e32 v0, s1, v78
	v_or_b32_e32 v0, s0, v0
	v_lshlrev_b64 v[8:9], 7, v[0:1]
	v_lshl_add_u64 v[8:9], v[40:41], 0, v[8:9]
	global_store_dwordx4 v[8:9], v[4:7], off
	ds_read2_b32 v[8:9], v75 offset0:32 offset1:40
	ds_read2_b32 v[12:13], v75 offset0:162 offset1:170
	ds_read2_b32 v[14:15], v75 offset0:227 offset1:235
	ds_read2_b32 v[18:19], v2 offset0:36 offset1:44
	ds_read2_b32 v[20:21], v2 offset0:101 offset1:109
	s_waitcnt lgkmcnt(4)
; __host__ __device__ __forceinline__ size_t blocked_off(int row, int col, int K) { return (((size_t)(row >> 8) * (K >> 6) + (col >> 6)) * 256 + (row & 255)) * 64 + (col & 63); }
; __device__ __forceinline__ unsigned cvt_pk_bf16(float lo, float hi) { const f32x2c_t v = {lo, hi}; return __builtin_bit_cast(unsigned, __builtin_convertvector(v, bf16x2c_t)); }
; #define LAS __attribute__((address_space(3)))
; #define LDS_WAIT() asm volatile("s_waitcnt lgkmcnt(0)" ::: "memory")
; __host__ __device__ __forceinline__ int win_phys_col(int n) { if (!win_rope_tile(n >> 8)) return n; const int cl = n & 255; return (n & ~255) | (cl & 63) | ((cl & 64) << 1) | ((cl & 128) >> 1); }
; template <bool PERMUTE, bool BLOCKED = false>
; __device__ __forceinline__ void cvt_tile64(const float* W, int K, int N, bf16* WT, int ldo, const float* gk, LAS float* scr, int tile, int lane) {
;     ...
;     const int kc = lane & 7, nrow0 = PERMUTE ? win_phys_col(n0) : n0;
; #pragma unroll
;     for (int j = 0; j < 8; ++j) { const int n = (lane >> 3) + 8 * j; const LAS float* s = scr + (8 * kc) * 65 + n;
;         v4u o; o[0] = cvt_pk_bf16(wrnd(s[0 * 65]), wrnd(s[1 * 65])); o[1] = cvt_pk_bf16(wrnd(s[2 * 65]), wrnd(s[3 * 65])); o[2] = cvt_pk_bf16(wrnd(s[4 * 65]), wrnd(s[5 * 65])); o[3] = cvt_pk_bf16(wrnd(s[6 * 65]), wrnd(s[7 * 65]));
;         *(v4u*)(WT + (BLOCKED ? pg8::blocked_off(nrow0 + n, k0 + 8 * kc, K) : (size_t)(nrow0 + n) * ldo + k0 + 8 * kc)) = o; }
;     LDS_WAIT(); asm volatile("" ::: "memory");
	v_add_u32_e32 v0, 0x20000, v8
	v_add_u32_e32 v3, 0x20000, v10
	v_and_b32_e32 v0, 0xfffc0000, v0
	v_and_b32_e32 v3, 0xfffc0000, v3
	ds_read2_b32 v[22:23], v2 offset0:166 offset1:174
	ds_read2_b32 v[24:25], v2 offset0:231 offset1:239
	v_cvt_pk_bf16_f32 v4, v0, v3
	s_waitcnt lgkmcnt(5)
	v_add_u32_e32 v0, 0x20000, v12
	s_waitcnt lgkmcnt(4)
	v_add_u32_e32 v3, 0x20000, v14
	v_and_b32_e32 v0, 0xfffc0000, v0
	v_and_b32_e32 v3, 0xfffc0000, v3
	v_cvt_pk_bf16_f32 v5, v0, v3
	s_waitcnt lgkmcnt(3)
	v_add_u32_e32 v0, 0x20000, v18
	s_waitcnt lgkmcnt(2)
	v_add_u32_e32 v3, 0x20000, v20
	v_and_b32_e32 v0, 0xfffc0000, v0
	v_and_b32_e32 v3, 0xfffc0000, v3
	v_cvt_pk_bf16_f32 v6, v0, v3
	s_waitcnt lgkmcnt(1)
	v_add_u32_e32 v0, 0x20000, v22
	s_waitcnt lgkmcnt(0)
	v_add_u32_e32 v3, 0x20000, v24
	v_and_b32_e32 v0, 0xfffc0000, v0
	v_and_b32_e32 v3, 0xfffc0000, v3
	v_cvt_pk_bf16_f32 v7, v0, v3
	v_or_b32_e32 v0, s1, v79
	v_or_b32_e32 v0, s0, v0
	v_lshlrev_b64 v[26:27], 7, v[0:1]
	v_add_u32_e32 v0, 0x20000, v9
	v_add_u32_e32 v3, 0x20000, v11
	v_lshl_add_u64 v[26:27], v[40:41], 0, v[26:27]
	v_and_b32_e32 v0, 0xfffc0000, v0
	v_and_b32_e32 v3, 0xfffc0000, v3
	global_store_dwordx4 v[26:27], v[4:7], off
	ds_read2_b32 v[10:11], v75 offset0:113 offset1:121
	s_nop 0
	v_cvt_pk_bf16_f32 v4, v0, v3
	v_add_u32_e32 v0, 0x20000, v13
	v_add_u32_e32 v3, 0x20000, v15
	v_and_b32_e32 v0, 0xfffc0000, v0
	v_and_b32_e32 v3, 0xfffc0000, v3
	v_cvt_pk_bf16_f32 v5, v0, v3
	v_add_u32_e32 v0, 0x20000, v19
	v_add_u32_e32 v3, 0x20000, v21
	v_and_b32_e32 v0, 0xfffc0000, v0
	v_and_b32_e32 v3, 0xfffc0000, v3
	v_cvt_pk_bf16_f32 v6, v0, v3
	v_add_u32_e32 v0, 0x20000, v23
	v_add_u32_e32 v3, 0x20000, v25
	v_and_b32_e32 v0, 0xfffc0000, v0
	v_and_b32_e32 v3, 0xfffc0000, v3
	v_cvt_pk_bf16_f32 v7, v0, v3
	v_or_b32_e32 v0, s1, v80
	v_or_b32_e32 v0, s0, v0
	v_lshlrev_b64 v[8:9], 7, v[0:1]
	v_lshl_add_u64 v[8:9], v[40:41], 0, v[8:9]
	global_store_dwordx4 v[8:9], v[4:7], off
	ds_read2_b32 v[8:9], v75 offset0:48 offset1:56
	ds_read2_b32 v[12:13], v75 offset0:178 offset1:186
	ds_read2_b32 v[14:15], v75 offset0:243 offset1:251
	ds_read2_b32 v[18:19], v2 offset0:52 offset1:60
	ds_read2_b32 v[20:21], v2 offset0:117 offset1:125
	s_waitcnt lgkmcnt(4)
	v_add_u32_e32 v0, 0x20000, v8
	v_add_u32_e32 v3, 0x20000, v10
	v_and_b32_e32 v0, 0xfffc0000, v0
	v_and_b32_e32 v3, 0xfffc0000, v3
	ds_read2_b32 v[22:23], v2 offset0:182 offset1:190
	ds_read2_b32 v[24:25], v2 offset0:247 offset1:255
	v_cvt_pk_bf16_f32 v4, v0, v3
	s_waitcnt lgkmcnt(5)
	v_add_u32_e32 v0, 0x20000, v12
	s_waitcnt lgkmcnt(4)
	v_add_u32_e32 v3, 0x20000, v14
	v_and_b32_e32 v0, 0xfffc0000, v0
	v_and_b32_e32 v3, 0xfffc0000, v3
	v_cvt_pk_bf16_f32 v5, v0, v3
	s_waitcnt lgkmcnt(3)
	v_add_u32_e32 v0, 0x20000, v18
	s_waitcnt lgkmcnt(2)
	v_add_u32_e32 v3, 0x20000, v20
	v_and_b32_e32 v0, 0xfffc0000, v0
	v_and_b32_e32 v3, 0xfffc0000, v3
	v_cvt_pk_bf16_f32 v6, v0, v3
	s_waitcnt lgkmcnt(1)
	v_add_u32_e32 v0, 0x20000, v22
	s_waitcnt lgkmcnt(0)
	v_add_u32_e32 v2, 0x20000, v24
	v_and_b32_e32 v0, 0xfffc0000, v0
	v_and_b32_e32 v2, 0xfffc0000, v2
	v_cvt_pk_bf16_f32 v7, v0, v2
	v_or_b32_e32 v0, s1, v81
	v_or_b32_e32 v0, s0, v0
	v_lshlrev_b64 v[2:3], 7, v[0:1]
	v_lshl_add_u64 v[2:3], v[40:41], 0, v[2:3]
	global_store_dwordx4 v[2:3], v[4:7], off
	v_add_u32_e32 v0, 0x20000, v9
	v_add_u32_e32 v2, 0x20000, v11
	v_and_b32_e32 v0, 0xfffc0000, v0
	v_and_b32_e32 v2, 0xfffc0000, v2
	v_cvt_pk_bf16_f32 v2, v0, v2
	v_add_u32_e32 v0, 0x20000, v13
	v_add_u32_e32 v3, 0x20000, v15
	v_and_b32_e32 v0, 0xfffc0000, v0
	v_and_b32_e32 v3, 0xfffc0000, v3
	v_cvt_pk_bf16_f32 v3, v0, v3
	v_add_u32_e32 v0, 0x20000, v19
	v_add_u32_e32 v4, 0x20000, v21
	v_and_b32_e32 v0, 0xfffc0000, v0
	v_and_b32_e32 v4, 0xfffc0000, v4
	v_cvt_pk_bf16_f32 v4, v0, v4
	v_add_u32_e32 v0, 0x20000, v23
	v_add_u32_e32 v5, 0x20000, v25
	v_and_b32_e32 v0, 0xfffc0000, v0
	v_and_b32_e32 v5, 0xfffc0000, v5
	v_cvt_pk_bf16_f32 v5, v0, v5
	v_or_b32_e32 v0, s1, v82
	v_or_b32_e32 v0, s0, v0
	v_lshlrev_b64 v[0:1], 7, v[0:1]
	v_lshl_add_u64 v[0:1], v[40:41], 0, v[0:1]
	global_store_dwordx4 v[0:1], v[2:5], off
	s_waitcnt lgkmcnt(0)

; #define LAS __attribute__((address_space(3)))
; template <bool PERMUTE, bool BLOCKED = false>
; __device__ __forceinline__ void cvt_tile64(const float* W, int K, int N, bf16* WT, int ldo, const float* gk, LAS float* scr, int tile, int lane) {
;     ...
;     for (int hh = 0; hh < 2; ++hh) {
;         f32x4 v[8];
; #pragma unroll
;         for (int i = 0; i < 8; ++i) v[i] = *(const f32x4*)(W + (size_t)(k0 + 32 * hh + 4 * i + lk) * N + n0 + ln);
; #pragma unroll
;         for (int i = 0; i < 8; ++i) { const int kk = 32 * hh + 4 * i + lk; const float g = gk ? gk[k0 + kk] : 1.0f; LAS float* d = scr + kk * 65 + ln;
;             d[0] = v[i][0] * g; d[1] = v[i][1] * g; d[2] = v[i][2] * g; d[3] = v[i][3] * g; }
; __device__ __forceinline__ void cvt_item(const CvtCtx& c, int batch, int wi, LAS float* scr, int wave, int lane) {
;     ...
;     if (wi < CVT_UP) { cvt_tile64<false>(c.w_up + (size_t)l * DM * DFF, DM, DFF, c.WupT + (size_t)l * DFF * DM, DM, c.g_mlp + l * DM, scr, 8 * wi + wave, lane); return; } wi -= CVT_UP;
.LBB0_882:
	s_andn2_b64 vcc, exec, s[0:1]
	s_cbranch_vccnz .LBB0_902
	s_add_i32 s0, s16, 0x8000
	s_ashr_i32 s1, s0, 31
	s_lshr_b32 s1, s1, 24
	s_add_i32 s0, s0, s1
	s_ashr_i32 s0, s0, 8
	s_lshl_b32 s10, s0, 6
	s_lshl_b32 s18, s0, 14
	s_sub_i32 s0, s15, s18
	v_or_b32_e32 v52, s10, v16
	s_add_i32 s0, s0, 0x200000
	v_or_b32_e32 v2, 4, v52
	s_ashr_i32 s1, s0, 31
	v_ashrrev_i32_e32 v53, 31, v52
	v_ashrrev_i32_e32 v3, 31, v2
	v_lshl_add_u64 v[50:51], s[0:1], 2, v[42:43]
	v_lshlrev_b64 v[0:1], 16, v[52:53]
	v_lshlrev_b64 v[2:3], 16, v[2:3]
	v_lshl_add_u64 v[0:1], v[50:51], 0, v[0:1]
	v_lshl_add_u64 v[2:3], v[50:51], 0, v[2:3]
	global_load_dwordx4 v[30:33], v[0:1], off nt
	global_load_dwordx4 v[26:29], v[2:3], off nt
	v_or_b32_e32 v0, 8, v52
	v_or_b32_e32 v2, 12, v52
	v_ashrrev_i32_e32 v1, 31, v0
	v_ashrrev_i32_e32 v3, 31, v2
	v_lshlrev_b64 v[0:1], 16, v[0:1]
	v_lshlrev_b64 v[2:3], 16, v[2:3]
	v_lshl_add_u64 v[0:1], v[50:51], 0, v[0:1]
	v_lshl_add_u64 v[2:3], v[50:51], 0, v[2:3]
	global_load_dwordx4 v[22:25], v[0:1], off nt
	global_load_dwordx4 v[18:21], v[2:3], off nt
	v_or_b32_e32 v0, 16, v52
	v_or_b32_e32 v2, 20, v52
	v_ashrrev_i32_e32 v1, 31, v0
	v_ashrrev_i32_e32 v3, 31, v2
	v_lshlrev_b64 v[0:1], 16, v[0:1]
	v_lshlrev_b64 v[2:3], 16, v[2:3]
	v_lshl_add_u64 v[0:1], v[50:51], 0, v[0:1]
	v_lshl_add_u64 v[2:3], v[50:51], 0, v[2:3]
	global_load_dwordx4 v[12:15], v[0:1], off nt
	global_load_dwordx4 v[8:11], v[2:3], off nt
	v_or_b32_e32 v0, 24, v52
	v_or_b32_e32 v2, 28, v52
	v_ashrrev_i32_e32 v1, 31, v0
	v_ashrrev_i32_e32 v3, 31, v2
	v_lshlrev_b64 v[0:1], 16, v[0:1]
	v_lshlrev_b64 v[2:3], 16, v[2:3]
	v_lshl_add_u64 v[0:1], v[50:51], 0, v[0:1]
	v_lshl_add_u64 v[2:3], v[50:51], 0, v[2:3]
	global_load_dwordx4 v[4:7], v[0:1], off nt
	s_nop 0
	global_load_dwordx4 v[0:3], v[2:3], off nt
	v_cndmask_b32_e64 v56, 0, 1, s[6:7]
	v_mov_b32_e32 v54, 1.0
	v_cmp_ne_u32_e64 s[4:5], 1, v56
	s_andn2_b64 vcc, exec, s[6:7]
	v_mov_b32_e32 v56, 1.0
	s_cbranch_vccnz .LBB0_885
	v_lshl_add_u64 v[86:87], v[52:53], 2, s[8:9]
	global_load_dword v110, v[86:87], off offset:16
	global_load_dword v124, v[86:87], off offset:32
	global_load_dword v125, v[86:87], off offset:48
	global_load_dword v126, v[86:87], off offset:64
	global_load_dword v127, v[86:87], off offset:80
	global_load_dword v178, v[86:87], off offset:96
	global_load_dword v179, v[86:87], off offset:112
	global_load_dword v180, v[86:87], off offset:128
	global_load_dword v181, v[86:87], off offset:144
	global_load_dword v182, v[86:87], off offset:160
	global_load_dword v183, v[86:87], off offset:176
	global_load_dword v184, v[86:87], off offset:192
	global_load_dword v185, v[86:87], off offset:208
	global_load_dword v186, v[86:87], off offset:224
	global_load_dword v187, v[86:87], off offset:240
	global_load_dword v56, v[86:87], off
	s_waitcnt vmcnt(0)
	s_ashr_i32 s11, s10, 31
	v_lshl_add_u64 v[86:87], s[10:11], 0, v[16:17]
	v_lshl_add_u64 v[86:87], v[86:87], 2, s[8:9]
	s_waitcnt vmcnt(0)
	v_pk_mul_f32 v[30:31], v[30:31], v[56:57] op_sel_hi:[1,0]
	v_pk_mul_f32 v[32:33], v[32:33], v[56:57] op_sel_hi:[1,0]
	v_mov_b32_e32 v56, v110

; #define LAS __attribute__((address_space(3)))
; template <bool PERMUTE, bool BLOCKED = false>
; __device__ __forceinline__ void cvt_tile64(const float* W, int K, int N, bf16* WT, int ldo, const float* gk, LAS float* scr, int tile, int lane) {
;     ...
;     for (int hh = 0; hh < 2; ++hh) {
;         f32x4 v[8];
; #pragma unroll
;         for (int i = 0; i < 8; ++i) v[i] = *(const f32x4*)(W + (size_t)(k0 + 32 * hh + 4 * i + lk) * N + n0 + ln);
; #pragma unroll
;         for (int i = 0; i < 8; ++i) { const int kk = 32 * hh + 4 * i + lk; const float g = gk ? gk[k0 + kk] : 1.0f; LAS float* d = scr + kk * 65 + ln;
;             d[0] = v[i][0] * g; d[1] = v[i][1] * g; d[2] = v[i][2] * g; d[3] = v[i][3] * g; }
.LBB0_891:
	v_add_u32_e32 v53, v55, v63
	v_add_u32_e32 v8, 0x410, v53
	ds_write2_b32 v8, v4, v5 offset1:1
	v_add_u32_e32 v4, 0x418, v53
	ds_write2_b32 v4, v6, v7 offset1:1
	s_waitcnt vmcnt(0)
	v_pk_mul_f32 v[0:1], v[0:1], v[18:19] op_sel_hi:[1,0]
	v_add_u32_e32 v4, 0x820, v53
	ds_write2_b32 v4, v0, v1 offset1:1
	v_pk_mul_f32 v[0:1], v[2:3], v[18:19] op_sel_hi:[1,0]
	v_add_u32_e32 v2, 0x828, v53
	ds_write2_b32 v2, v0, v1 offset1:1
	v_or_b32_e32 v0, 32, v52
	v_or_b32_e32 v4, 60, v52
	v_ashrrev_i32_e32 v1, 31, v0
	v_ashrrev_i32_e32 v5, 31, v4
	v_lshlrev_b64 v[0:1], 16, v[0:1]
	v_lshlrev_b64 v[4:5], 16, v[4:5]
	v_lshl_add_u64 v[0:1], v[50:51], 0, v[0:1]
	v_lshl_add_u64 v[4:5], v[50:51], 0, v[4:5]
	global_load_dwordx4 v[26:29], v[0:1], off nt
	s_and_b64 vcc, exec, s[4:5]
	global_load_dwordx4 v[4:7], v[4:5], off nt
	v_or_b32_e32 v0, 36, v52
	v_ashrrev_i32_e32 v1, 31, v0
	v_lshlrev_b64 v[0:1], 16, v[0:1]
	v_lshl_add_u64 v[0:1], v[50:51], 0, v[0:1]
	global_load_dwordx4 v[30:33], v[0:1], off nt
	v_or_b32_e32 v0, 40, v52
	v_ashrrev_i32_e32 v1, 31, v0
	v_lshlrev_b64 v[0:1], 16, v[0:1]
	v_lshl_add_u64 v[0:1], v[50:51], 0, v[0:1]
	global_load_dwordx4 v[18:21], v[0:1], off nt
	v_or_b32_e32 v0, 44, v52
	v_ashrrev_i32_e32 v1, 31, v0
	v_lshlrev_b64 v[0:1], 16, v[0:1]
	v_lshl_add_u64 v[0:1], v[50:51], 0, v[0:1]
	global_load_dwordx4 v[22:25], v[0:1], off nt
	v_or_b32_e32 v0, 48, v52
	v_ashrrev_i32_e32 v1, 31, v0
	v_lshlrev_b64 v[0:1], 16, v[0:1]
	v_lshl_add_u64 v[0:1], v[50:51], 0, v[0:1]
	global_load_dwordx4 v[8:11], v[0:1], off nt
	v_or_b32_e32 v0, 52, v52
	v_ashrrev_i32_e32 v1, 31, v0
	v_lshlrev_b64 v[0:1], 16, v[0:1]
	v_lshl_add_u64 v[0:1], v[50:51], 0, v[0:1]
	global_load_dwordx4 v[12:15], v[0:1], off nt
	v_or_b32_e32 v0, 56, v52
	v_ashrrev_i32_e32 v1, 31, v0
	v_lshlrev_b64 v[0:1], 16, v[0:1]
	v_lshl_add_u64 v[0:1], v[50:51], 0, v[0:1]
	global_load_dwordx4 v[0:3], v[0:1], off nt
	v_mov_b32_e32 v50, 1.0
	v_mov_b32_e32 v52, 1.0
	s_cbranch_vccnz .LBB0_893
	s_ashr_i32 s11, s10, 31
	v_lshl_add_u64 v[86:87], s[10:11], 0, v[16:17]
	v_lshl_add_u64 v[86:87], v[86:87], 2, s[8:9]
	v_mov_b32_e32 v52, v180
	s_waitcnt vmcnt(0)
	v_pk_mul_f32 v[26:27], v[26:27], v[52:53] op_sel_hi:[1,0]
	v_pk_mul_f32 v[28:29], v[28:29], v[52:53] op_sel_hi:[1,0]
	v_mov_b32_e32 v52, v181

; #define LAS __attribute__((address_space(3)))
; template <bool PERMUTE, bool BLOCKED = false>
; __device__ __forceinline__ void cvt_tile64(const float* W, int K, int N, bf16* WT, int ldo, const float* gk, LAS float* scr, int tile, int lane) {
;     ...
;     for (int hh = 0; hh < 2; ++hh) {
;         f32x4 v[8];
; #pragma unroll
;         for (int i = 0; i < 8; ++i) v[i] = *(const f32x4*)(W + (size_t)(k0 + 32 * hh + 4 * i + lk) * N + n0 + ln);
; #pragma unroll
;         for (int i = 0; i < 8; ++i) { const int kk = 32 * hh + 4 * i + lk; const float g = gk ? gk[k0 + kk] : 1.0f; LAS float* d = scr + kk * 65 + ln;
;             d[0] = v[i][0] * g; d[1] = v[i][1] * g; d[2] = v[i][2] * g; d[3] = v[i][3] * g; }
;     }
; __device__ __forceinline__ void cvt_item(const CvtCtx& c, int batch, int wi, LAS float* scr, int wave, int lane) {
;     ...
;     if (wi < CVT_OUT) { cvt_tile64<false>(c.w_out + (size_t)l * DM * DM, DM, DM, c.WoutT + (size_t)l * DM * DM, DM, nullptr, scr, 8 * wi + wave, lane); return; } wi -= CVT_OUT;
.LBB0_903:
	s_andn2_b64 vcc, exec, s[0:1]
	s_cbranch_vccnz .LBB0_874
	s_add_i32 s0, s16, 0x9000
	s_ashr_i32 s1, s0, 31
	s_lshr_b32 s1, s1, 26
	s_add_i32 s0, s0, s1
	s_and_b32 s4, s0, 0xffffffc0
	s_lshl_b32 s0, s0, 6
	s_and_b32 s0, s0, 0xfffff000
	s_sub_i32 s0, s15, s0
	s_add_i32 s10, s0, 0x240000
	v_or_b32_e32 v2, s4, v16
	s_ashr_i32 s11, s10, 31
	v_ashrrev_i32_e32 v3, 31, v2
	v_lshl_add_u64 v[0:1], s[10:11], 2, v[46:47]
	v_lshlrev_b64 v[4:5], 14, v[2:3]
	v_or_b32_e32 v8, 4, v2
	v_lshl_add_u64 v[4:5], v[0:1], 0, v[4:5]
	v_ashrrev_i32_e32 v9, 31, v8
	global_load_dwordx4 v[4:7], v[4:5], off nt
	v_lshlrev_b64 v[8:9], 14, v[8:9]
	v_or_b32_e32 v12, 8, v2
	v_lshl_add_u64 v[8:9], v[0:1], 0, v[8:9]
	v_ashrrev_i32_e32 v13, 31, v12
	global_load_dwordx4 v[8:11], v[8:9], off nt
	v_lshlrev_b64 v[12:13], 14, v[12:13]
	v_or_b32_e32 v18, 12, v2
	v_lshl_add_u64 v[12:13], v[0:1], 0, v[12:13]
	v_ashrrev_i32_e32 v19, 31, v18
	global_load_dwordx4 v[12:15], v[12:13], off nt
	v_lshlrev_b64 v[18:19], 14, v[18:19]
	v_or_b32_e32 v22, 16, v2
	v_lshl_add_u64 v[18:19], v[0:1], 0, v[18:19]
	v_ashrrev_i32_e32 v23, 31, v22
	global_load_dwordx4 v[18:21], v[18:19], off nt
	v_lshlrev_b64 v[22:23], 14, v[22:23]
	v_or_b32_e32 v26, 20, v2
	v_lshl_add_u64 v[22:23], v[0:1], 0, v[22:23]
	v_ashrrev_i32_e32 v27, 31, v26
	global_load_dwordx4 v[22:25], v[22:23], off nt
	v_lshlrev_b64 v[26:27], 14, v[26:27]
	v_or_b32_e32 v30, 24, v2
	v_lshl_add_u64 v[26:27], v[0:1], 0, v[26:27]
	v_ashrrev_i32_e32 v31, 31, v30
	global_load_dwordx4 v[26:29], v[26:27], off nt
	v_lshlrev_b64 v[30:31], 14, v[30:31]
	v_or_b32_e32 v50, 28, v2
	v_lshl_add_u64 v[30:31], v[0:1], 0, v[30:31]
	v_ashrrev_i32_e32 v51, 31, v50
	global_load_dwordx4 v[30:33], v[30:31], off nt
	v_lshlrev_b64 v[50:51], 14, v[50:51]
	v_lshl_add_u64 v[50:51], v[0:1], 0, v[50:51]
	global_load_dwordx4 v[50:53], v[50:51], off nt
	v_add_u32_e32 v54, v55, v57
	v_add_u32_e32 v3, 0x410, v54
	s_ashr_i32 s5, s4, 31
	s_waitcnt vmcnt(7)
	ds_write2_b32 v54, v4, v5 offset1:1
	ds_write2_b32 v54, v6, v7 offset0:2 offset1:3
	v_or_b32_e32 v4, 32, v2
	v_ashrrev_i32_e32 v5, 31, v4
	v_lshlrev_b64 v[4:5], 14, v[4:5]
	v_lshl_add_u64 v[4:5], v[0:1], 0, v[4:5]
	s_waitcnt vmcnt(6)
	ds_write2_b32 v3, v8, v9 offset1:1
	v_add_u32_e32 v3, 0x418, v54
	v_or_b32_e32 v8, 36, v2
	ds_write2_b32 v3, v10, v11 offset1:1
	v_add_u32_e32 v3, 0x820, v54
	v_ashrrev_i32_e32 v9, 31, v8
	s_waitcnt vmcnt(5)
	ds_write2_b32 v3, v12, v13 offset1:1
	v_add_u32_e32 v3, 0x828, v54
	global_load_dwordx4 v[4:7], v[4:5], off nt
	v_lshlrev_b64 v[8:9], 14, v[8:9]
	v_or_b32_e32 v12, 40, v2
	ds_write2_b32 v3, v14, v15 offset1:1
	v_add_u32_e32 v3, 0xc30, v54
	v_lshl_add_u64 v[8:9], v[0:1], 0, v[8:9]
	v_ashrrev_i32_e32 v13, 31, v12
	s_waitcnt vmcnt(5)
	ds_write2_b32 v3, v18, v19 offset1:1
	v_add_u32_e32 v3, 0xc38, v54
	global_load_dwordx4 v[8:11], v[8:9], off nt
	v_lshlrev_b64 v[12:13], 14, v[12:13]
	v_or_b32_e32 v18, 44, v2
	ds_write2_b32 v3, v20, v21 offset1:1
	v_add_u32_e32 v3, 0x1040, v54
	v_lshl_add_u64 v[12:13], v[0:1], 0, v[12:13]
	v_ashrrev_i32_e32 v19, 31, v18
	s_waitcnt vmcnt(5)
	ds_write2_b32 v3, v22, v23 offset1:1
	v_add_u32_e32 v3, 0x1048, v54
	global_load_dwordx4 v[12:15], v[12:13], off nt
	v_lshlrev_b64 v[18:19], 14, v[18:19]
	v_or_b32_e32 v22, 48, v2
	ds_write2_b32 v3, v24, v25 offset1:1
	v_add_u32_e32 v3, 0x1450, v54
	v_lshl_add_u64 v[18:19], v[0:1], 0, v[18:19]
	v_ashrrev_i32_e32 v23, 31, v22
	s_waitcnt vmcnt(5)
	ds_write2_b32 v3, v26, v27 offset1:1
	v_add_u32_e32 v3, 0x1458, v54
	global_load_dwordx4 v[18:21], v[18:19], off nt
	v_lshlrev_b64 v[22:23], 14, v[22:23]
	v_or_b32_e32 v26, 52, v2
	ds_write2_b32 v3, v28, v29 offset1:1
	v_add_u32_e32 v3, 0x1860, v54
	v_lshl_add_u64 v[22:23], v[0:1], 0, v[22:23]
	v_ashrrev_i32_e32 v27, 31, v26
	s_waitcnt vmcnt(5)
	ds_write2_b32 v3, v30, v31 offset1:1
	v_add_u32_e32 v3, 0x1868, v54
	global_load_dwordx4 v[22:25], v[22:23], off nt
	v_lshlrev_b64 v[26:27], 14, v[26:27]
	v_or_b32_e32 v30, 56, v2
	ds_write2_b32 v3, v32, v33 offset1:1
	v_add_u32_e32 v3, 0x1c70, v54
	v_lshl_add_u64 v[26:27], v[0:1], 0, v[26:27]
	v_ashrrev_i32_e32 v31, 31, v30
	s_waitcnt vmcnt(5)
	ds_write2_b32 v3, v50, v51 offset1:1
	v_add_u32_e32 v3, 0x1c78, v54
	global_load_dwordx4 v[26:29], v[26:27], off nt
	v_lshlrev_b64 v[30:31], 14, v[30:31]
	v_or_b32_e32 v2, 60, v2
	ds_write2_b32 v3, v52, v53 offset1:1
	v_lshl_add_u64 v[30:31], v[0:1], 0, v[30:31]
	v_ashrrev_i32_e32 v3, 31, v2
	global_load_dwordx4 v[30:33], v[30:31], off nt
	v_lshlrev_b64 v[2:3], 14, v[2:3]
	v_lshl_add_u64 v[0:1], v[0:1], 0, v[2:3]
	global_load_dwordx4 v[0:3], v[0:1], off nt
	v_add_u32_e32 v50, 0x2080, v54
	s_waitcnt vmcnt(7)
	ds_write2_b32 v50, v4, v5 offset1:1
	v_add_u32_e32 v4, 0x2088, v54
	ds_write2_b32 v4, v6, v7 offset1:1
	v_add_u32_e32 v4, 0x2490, v54
	s_waitcnt vmcnt(6)
	ds_write2_b32 v4, v8, v9 offset1:1
	v_add_u32_e32 v4, 0x2498, v54
	ds_write2_b32 v4, v10, v11 offset1:1
	v_add_u32_e32 v4, 0x28a0, v54
	s_waitcnt vmcnt(5)
	ds_write2_b32 v4, v12, v13 offset1:1
	v_add_u32_e32 v4, 0x28a8, v54
	ds_write2_b32 v4, v14, v15 offset1:1
	v_add_u32_e32 v4, 0x2cb0, v54
	s_waitcnt vmcnt(4)
	ds_write2_b32 v4, v18, v19 offset1:1
	v_add_u32_e32 v4, 0x2cb8, v54
	ds_write2_b32 v4, v20, v21 offset1:1
	v_add_u32_e32 v4, 0x30c0, v54
	s_waitcnt vmcnt(3)
	ds_write2_b32 v4, v22, v23 offset1:1
	v_add_u32_e32 v4, 0x30c8, v54
	ds_write2_b32 v4, v24, v25 offset1:1
	v_add_u32_e32 v4, 0x34d0, v54
	s_waitcnt vmcnt(2)
	ds_write2_b32 v4, v26, v27 offset1:1
	v_add_u32_e32 v4, 0x34d8, v54
	ds_write2_b32 v4, v28, v29 offset1:1
	v_add_u32_e32 v4, 0x38e0, v54
	s_waitcnt vmcnt(1)
; __host__ __device__ __forceinline__ size_t blocked_off(int row, int col, int K) { return (((size_t)(row >> 8) * (K >> 6) + (col >> 6)) * 256 + (row & 255)) * 64 + (col & 63); }
; __device__ __forceinline__ unsigned cvt_pk_bf16(float lo, float hi) { const f32x2c_t v = {lo, hi}; return __builtin_bit_cast(unsigned, __builtin_convertvector(v, bf16x2c_t)); }
; #define LAS __attribute__((address_space(3)))
; #define LDS_WAIT() asm volatile("s_waitcnt lgkmcnt(0)" ::: "memory")
; __host__ __device__ __forceinline__ int win_phys_col(int n) { if (!win_rope_tile(n >> 8)) return n; const int cl = n & 255; return (n & ~255) | (cl & 63) | ((cl & 64) << 1) | ((cl & 128) >> 1); }
; template <bool PERMUTE, bool BLOCKED = false>
; __device__ __forceinline__ void cvt_tile64(const float* W, int K, int N, bf16* WT, int ldo, const float* gk, LAS float* scr, int tile, int lane) {
;     ...
;     LDS_WAIT(); asm volatile("" ::: "memory");
;     const int kc = lane & 7, nrow0 = PERMUTE ? win_phys_col(n0) : n0;
; #pragma unroll
;     for (int j = 0; j < 8; ++j) { const int n = (lane >> 3) + 8 * j; const LAS float* s = scr + (8 * kc) * 65 + n;
;         v4u o; o[0] = cvt_pk_bf16(wrnd(s[0 * 65]), wrnd(s[1 * 65])); o[1] = cvt_pk_bf16(wrnd(s[2 * 65]), wrnd(s[3 * 65])); o[2] = cvt_pk_bf16(wrnd(s[4 * 65]), wrnd(s[5 * 65])); o[3] = cvt_pk_bf16(wrnd(s[6 * 65]), wrnd(s[7 * 65]));
;         *(v4u*)(WT + (BLOCKED ? pg8::blocked_off(nrow0 + n, k0 + 8 * kc, K) : (size_t)(nrow0 + n) * ldo + k0 + 8 * kc)) = o; }
	ds_write2_b32 v4, v30, v31 offset1:1
	v_add_u32_e32 v4, 0x38e8, v54
	ds_write2_b32 v4, v32, v33 offset1:1
	v_add_u32_e32 v4, 0x3cf0, v54
	s_waitcnt vmcnt(0)
	ds_write2_b32 v4, v0, v1 offset1:1
	v_add_u32_e32 v0, 0x3cf8, v54
	ds_write2_b32 v0, v2, v3 offset1:1
	s_waitcnt lgkmcnt(0)
	ds_read2_b32 v[8:9], v75 offset1:8
	ds_read2_b32 v[10:11], v75 offset0:65 offset1:73
	ds_read2_b32 v[12:13], v75 offset0:130 offset1:138
	ds_read2_b32 v[14:15], v75 offset0:195 offset1:203
	v_lshl_add_u64 v[0:1], s[4:5], 1, v[48:49]
	s_waitcnt lgkmcnt(3)
	v_add_u32_e32 v2, 0x20000, v8
	s_waitcnt lgkmcnt(2)
	v_add_u32_e32 v3, 0x20000, v10
	v_and_b32_e32 v2, 0xfffc0000, v2
	v_and_b32_e32 v3, 0xfffc0000, v3
	v_cvt_pk_bf16_f32 v4, v2, v3
	s_waitcnt lgkmcnt(1)
	v_add_u32_e32 v2, 0x20000, v12
	s_waitcnt lgkmcnt(0)
	v_add_u32_e32 v3, 0x20000, v14
	v_and_b32_e32 v2, 0xfffc0000, v2
	v_and_b32_e32 v3, 0xfffc0000, v3
	v_cvt_pk_bf16_f32 v5, v2, v3
	v_add_u32_e32 v2, 0x400, v75
	ds_read2_b32 v[18:19], v2 offset0:4 offset1:12
	ds_read2_b32 v[20:21], v2 offset0:69 offset1:77
	ds_read2_b32 v[22:23], v2 offset0:134 offset1:142
	ds_read2_b32 v[24:25], v2 offset0:199 offset1:207
	s_waitcnt lgkmcnt(3)
	v_add_u32_e32 v3, 0x20000, v18
	s_waitcnt lgkmcnt(2)
	v_add_u32_e32 v6, 0x20000, v20
	v_and_b32_e32 v3, 0xfffc0000, v3
	v_and_b32_e32 v6, 0xfffc0000, v6
	v_cvt_pk_bf16_f32 v6, v3, v6
	s_waitcnt lgkmcnt(1)
	v_add_u32_e32 v3, 0x20000, v22
	s_waitcnt lgkmcnt(0)
	v_add_u32_e32 v7, 0x20000, v24
	v_and_b32_e32 v3, 0xfffc0000, v3
	v_and_b32_e32 v7, 0xfffc0000, v7
	v_cvt_pk_bf16_f32 v7, v3, v7
	v_add_u32_e32 v3, s0, v74
	v_add_u32_e32 v26, 0x240000, v3
	v_ashrrev_i32_e32 v27, 31, v26
	v_lshlrev_b64 v[26:27], 13, v[26:27]
	v_lshl_add_u64 v[26:27], v[0:1], 0, v[26:27]
	global_store_dwordx4 v[26:27], v[4:7], off
	v_add_u32_e32 v8, 0x20000, v25
	v_and_b32_e32 v8, 0xfffc0000, v8
	v_add_u32_e32 v4, 0x20000, v9
	v_add_u32_e32 v5, 0x20000, v11
	v_and_b32_e32 v4, 0xfffc0000, v4
	v_and_b32_e32 v5, 0xfffc0000, v5
	v_cvt_pk_bf16_f32 v4, v4, v5
	v_add_u32_e32 v5, 0x20000, v13
	v_add_u32_e32 v6, 0x20000, v15
	v_and_b32_e32 v5, 0xfffc0000, v5
	v_and_b32_e32 v6, 0xfffc0000, v6
	v_cvt_pk_bf16_f32 v5, v5, v6
	v_add_u32_e32 v6, 0x20000, v19
	v_add_u32_e32 v7, 0x20000, v21
	v_and_b32_e32 v6, 0xfffc0000, v6
	v_and_b32_e32 v7, 0xfffc0000, v7
	v_cvt_pk_bf16_f32 v6, v6, v7
	v_add_u32_e32 v7, 0x20000, v23
	v_and_b32_e32 v7, 0xfffc0000, v7
	v_cvt_pk_bf16_f32 v7, v7, v8
	v_add_u32_e32 v8, 0x240008, v3
	v_ashrrev_i32_e32 v9, 31, v8
	v_lshlrev_b64 v[8:9], 13, v[8:9]
	v_lshl_add_u64 v[8:9], v[0:1], 0, v[8:9]
	global_store_dwordx4 v[8:9], v[4:7], off
	ds_read2_b32 v[8:9], v75 offset0:16 offset1:24
	ds_read2_b32 v[10:11], v75 offset0:81 offset1:89
	ds_read2_b32 v[12:13], v75 offset0:146 offset1:154
	ds_read2_b32 v[14:15], v75 offset0:211 offset1:219
	ds_read2_b32 v[18:19], v2 offset0:20 offset1:28
	ds_read2_b32 v[20:21], v2 offset0:85 offset1:93
	s_waitcnt lgkmcnt(5)
	v_add_u32_e32 v4, 0x20000, v8
	s_waitcnt lgkmcnt(4)
	v_add_u32_e32 v5, 0x20000, v10
	v_and_b32_e32 v4, 0xfffc0000, v4
	v_and_b32_e32 v5, 0xfffc0000, v5
	ds_read2_b32 v[22:23], v2 offset0:150 offset1:158
	ds_read2_b32 v[24:25], v2 offset0:215 offset1:223
	v_cvt_pk_bf16_f32 v4, v4, v5
	s_waitcnt lgkmcnt(5)
	v_add_u32_e32 v5, 0x20000, v12
	s_waitcnt lgkmcnt(4)
	v_add_u32_e32 v6, 0x20000, v14
	v_and_b32_e32 v5, 0xfffc0000, v5
	v_and_b32_e32 v6, 0xfffc0000, v6
	v_cvt_pk_bf16_f32 v5, v5, v6
	s_waitcnt lgkmcnt(3)
	v_add_u32_e32 v6, 0x20000, v18
	s_waitcnt lgkmcnt(2)
	v_add_u32_e32 v7, 0x20000, v20
	v_and_b32_e32 v6, 0xfffc0000, v6
	v_and_b32_e32 v7, 0xfffc0000, v7
	v_add_u32_e32 v26, 0x240010, v3
	v_cvt_pk_bf16_f32 v6, v6, v7
	s_waitcnt lgkmcnt(1)
	v_add_u32_e32 v7, 0x20000, v22
	s_waitcnt lgkmcnt(0)
	v_add_u32_e32 v8, 0x20000, v24
	v_ashrrev_i32_e32 v27, 31, v26
	v_and_b32_e32 v7, 0xfffc0000, v7
	v_and_b32_e32 v8, 0xfffc0000, v8
	v_lshlrev_b64 v[26:27], 13, v[26:27]
	v_cvt_pk_bf16_f32 v7, v7, v8
	v_lshl_add_u64 v[26:27], v[0:1], 0, v[26:27]
	global_store_dwordx4 v[26:27], v[4:7], off
	v_add_u32_e32 v8, 0x20000, v25
	v_and_b32_e32 v8, 0xfffc0000, v8
	v_add_u32_e32 v4, 0x20000, v9
	v_add_u32_e32 v5, 0x20000, v11
	v_and_b32_e32 v4, 0xfffc0000, v4
	v_and_b32_e32 v5, 0xfffc0000, v5
	v_cvt_pk_bf16_f32 v4, v4, v5
	v_add_u32_e32 v5, 0x20000, v13
	v_add_u32_e32 v6, 0x20000, v15
	v_and_b32_e32 v5, 0xfffc0000, v5
	v_and_b32_e32 v6, 0xfffc0000, v6
	v_cvt_pk_bf16_f32 v5, v5, v6
	v_add_u32_e32 v6, 0x20000, v19
	v_add_u32_e32 v7, 0x20000, v21
	v_and_b32_e32 v6, 0xfffc0000, v6
	v_and_b32_e32 v7, 0xfffc0000, v7
	v_cvt_pk_bf16_f32 v6, v6, v7
	v_add_u32_e32 v7, 0x20000, v23
	v_and_b32_e32 v7, 0xfffc0000, v7
	v_cvt_pk_bf16_f32 v7, v7, v8
	v_add_u32_e32 v8, 0x240018, v3
	v_ashrrev_i32_e32 v9, 31, v8
	v_lshlrev_b64 v[8:9], 13, v[8:9]
	v_lshl_add_u64 v[8:9], v[0:1], 0, v[8:9]
	global_store_dwordx4 v[8:9], v[4:7], off
	ds_read2_b32 v[8:9], v75 offset0:32 offset1:40
	ds_read2_b32 v[10:11], v75 offset0:97 offset1:105
	ds_read2_b32 v[12:13], v75 offset0:162 offset1:170
	ds_read2_b32 v[14:15], v75 offset0:227 offset1:235
	ds_read2_b32 v[18:19], v2 offset0:36 offset1:44
	ds_read2_b32 v[20:21], v2 offset0:101 offset1:109
	s_waitcnt lgkmcnt(5)
; __host__ __device__ __forceinline__ size_t blocked_off(int row, int col, int K) { return (((size_t)(row >> 8) * (K >> 6) + (col >> 6)) * 256 + (row & 255)) * 64 + (col & 63); }
; __device__ __forceinline__ unsigned cvt_pk_bf16(float lo, float hi) { const f32x2c_t v = {lo, hi}; return __builtin_bit_cast(unsigned, __builtin_convertvector(v, bf16x2c_t)); }
; #define LAS __attribute__((address_space(3)))
; #define LDS_WAIT() asm volatile("s_waitcnt lgkmcnt(0)" ::: "memory")
; __host__ __device__ __forceinline__ int win_phys_col(int n) { if (!win_rope_tile(n >> 8)) return n; const int cl = n & 255; return (n & ~255) | (cl & 63) | ((cl & 64) << 1) | ((cl & 128) >> 1); }
; template <bool PERMUTE, bool BLOCKED = false>
; __device__ __forceinline__ void cvt_tile64(const float* W, int K, int N, bf16* WT, int ldo, const float* gk, LAS float* scr, int tile, int lane) {
;     ...
;     const int kc = lane & 7, nrow0 = PERMUTE ? win_phys_col(n0) : n0;
; #pragma unroll
;     for (int j = 0; j < 8; ++j) { const int n = (lane >> 3) + 8 * j; const LAS float* s = scr + (8 * kc) * 65 + n;
;         v4u o; o[0] = cvt_pk_bf16(wrnd(s[0 * 65]), wrnd(s[1 * 65])); o[1] = cvt_pk_bf16(wrnd(s[2 * 65]), wrnd(s[3 * 65])); o[2] = cvt_pk_bf16(wrnd(s[4 * 65]), wrnd(s[5 * 65])); o[3] = cvt_pk_bf16(wrnd(s[6 * 65]), wrnd(s[7 * 65]));
;         *(v4u*)(WT + (BLOCKED ? pg8::blocked_off(nrow0 + n, k0 + 8 * kc, K) : (size_t)(nrow0 + n) * ldo + k0 + 8 * kc)) = o; }
;     LDS_WAIT(); asm volatile("" ::: "memory");
	v_add_u32_e32 v4, 0x20000, v8
	s_waitcnt lgkmcnt(4)
	v_add_u32_e32 v5, 0x20000, v10
	v_and_b32_e32 v4, 0xfffc0000, v4
	v_and_b32_e32 v5, 0xfffc0000, v5
	ds_read2_b32 v[22:23], v2 offset0:166 offset1:174
	ds_read2_b32 v[24:25], v2 offset0:231 offset1:239
	v_cvt_pk_bf16_f32 v4, v4, v5
	s_waitcnt lgkmcnt(5)
	v_add_u32_e32 v5, 0x20000, v12
	s_waitcnt lgkmcnt(4)
	v_add_u32_e32 v6, 0x20000, v14
	v_and_b32_e32 v5, 0xfffc0000, v5
	v_and_b32_e32 v6, 0xfffc0000, v6
	v_cvt_pk_bf16_f32 v5, v5, v6
	s_waitcnt lgkmcnt(3)
	v_add_u32_e32 v6, 0x20000, v18
	s_waitcnt lgkmcnt(2)
	v_add_u32_e32 v7, 0x20000, v20
	v_and_b32_e32 v6, 0xfffc0000, v6
	v_and_b32_e32 v7, 0xfffc0000, v7
	v_add_u32_e32 v26, 0x240020, v3
	v_cvt_pk_bf16_f32 v6, v6, v7
	s_waitcnt lgkmcnt(1)
	v_add_u32_e32 v7, 0x20000, v22
	s_waitcnt lgkmcnt(0)
	v_add_u32_e32 v8, 0x20000, v24
	v_ashrrev_i32_e32 v27, 31, v26
	v_and_b32_e32 v7, 0xfffc0000, v7
	v_and_b32_e32 v8, 0xfffc0000, v8
	v_lshlrev_b64 v[26:27], 13, v[26:27]
	v_cvt_pk_bf16_f32 v7, v7, v8
	v_lshl_add_u64 v[26:27], v[0:1], 0, v[26:27]
	global_store_dwordx4 v[26:27], v[4:7], off
	v_add_u32_e32 v8, 0x20000, v25
	v_and_b32_e32 v8, 0xfffc0000, v8
	v_add_u32_e32 v4, 0x20000, v9
	v_add_u32_e32 v5, 0x20000, v11
	v_and_b32_e32 v4, 0xfffc0000, v4
	v_and_b32_e32 v5, 0xfffc0000, v5
	v_cvt_pk_bf16_f32 v4, v4, v5
	v_add_u32_e32 v5, 0x20000, v13
	v_add_u32_e32 v6, 0x20000, v15
	v_and_b32_e32 v5, 0xfffc0000, v5
	v_and_b32_e32 v6, 0xfffc0000, v6
	v_cvt_pk_bf16_f32 v5, v5, v6
	v_add_u32_e32 v6, 0x20000, v19
	v_add_u32_e32 v7, 0x20000, v21
	v_and_b32_e32 v6, 0xfffc0000, v6
	v_and_b32_e32 v7, 0xfffc0000, v7
	v_cvt_pk_bf16_f32 v6, v6, v7
	v_add_u32_e32 v7, 0x20000, v23
	v_and_b32_e32 v7, 0xfffc0000, v7
	v_cvt_pk_bf16_f32 v7, v7, v8
	v_add_u32_e32 v8, 0x240028, v3
	v_ashrrev_i32_e32 v9, 31, v8
	v_lshlrev_b64 v[8:9], 13, v[8:9]
	v_lshl_add_u64 v[8:9], v[0:1], 0, v[8:9]
	global_store_dwordx4 v[8:9], v[4:7], off
	ds_read2_b32 v[8:9], v75 offset0:48 offset1:56
	ds_read2_b32 v[10:11], v75 offset0:113 offset1:121
	ds_read2_b32 v[12:13], v75 offset0:178 offset1:186
	ds_read2_b32 v[14:15], v75 offset0:243 offset1:251
	ds_read2_b32 v[18:19], v2 offset0:52 offset1:60
	ds_read2_b32 v[20:21], v2 offset0:117 offset1:125
	s_waitcnt lgkmcnt(5)
	v_add_u32_e32 v4, 0x20000, v8
	s_waitcnt lgkmcnt(4)
	v_add_u32_e32 v5, 0x20000, v10
	v_and_b32_e32 v4, 0xfffc0000, v4
	v_and_b32_e32 v5, 0xfffc0000, v5
	ds_read2_b32 v[22:23], v2 offset0:182 offset1:190
	ds_read2_b32 v[24:25], v2 offset0:247 offset1:255
	v_cvt_pk_bf16_f32 v4, v4, v5
	s_waitcnt lgkmcnt(5)
	v_add_u32_e32 v5, 0x20000, v12
	s_waitcnt lgkmcnt(4)
	v_add_u32_e32 v6, 0x20000, v14
	v_and_b32_e32 v5, 0xfffc0000, v5
	v_and_b32_e32 v6, 0xfffc0000, v6
	v_cvt_pk_bf16_f32 v5, v5, v6
	s_waitcnt lgkmcnt(3)
	v_add_u32_e32 v6, 0x20000, v18
	s_waitcnt lgkmcnt(2)
	v_add_u32_e32 v7, 0x20000, v20
	v_and_b32_e32 v6, 0xfffc0000, v6
	v_and_b32_e32 v7, 0xfffc0000, v7
	v_add_u32_e32 v26, 0x240030, v3
	v_cvt_pk_bf16_f32 v6, v6, v7
	s_waitcnt lgkmcnt(1)
	v_add_u32_e32 v7, 0x20000, v22
	s_waitcnt lgkmcnt(0)
	v_add_u32_e32 v2, 0x20000, v24
	v_ashrrev_i32_e32 v27, 31, v26
	v_and_b32_e32 v7, 0xfffc0000, v7
	v_and_b32_e32 v2, 0xfffc0000, v2
	v_lshlrev_b64 v[26:27], 13, v[26:27]
	v_cvt_pk_bf16_f32 v7, v7, v2
	v_lshl_add_u64 v[26:27], v[0:1], 0, v[26:27]
	global_store_dwordx4 v[26:27], v[4:7], off
	v_add_u32_e32 v2, 0x20000, v9
	v_and_b32_e32 v2, 0xfffc0000, v2
	v_add_u32_e32 v4, 0x20000, v11
	v_and_b32_e32 v4, 0xfffc0000, v4
	v_cvt_pk_bf16_f32 v4, v2, v4
	v_add_u32_e32 v2, 0x20000, v13
	v_add_u32_e32 v5, 0x20000, v15
	v_and_b32_e32 v2, 0xfffc0000, v2
	v_and_b32_e32 v5, 0xfffc0000, v5
	v_cvt_pk_bf16_f32 v5, v2, v5
	v_add_u32_e32 v2, 0x20000, v19
	v_add_u32_e32 v6, 0x20000, v21
	v_and_b32_e32 v2, 0xfffc0000, v2
	v_and_b32_e32 v6, 0xfffc0000, v6
	v_cvt_pk_bf16_f32 v6, v2, v6
	v_add_u32_e32 v2, 0x20000, v23
	v_add_u32_e32 v7, 0x20000, v25
	v_and_b32_e32 v2, 0xfffc0000, v2
	v_and_b32_e32 v7, 0xfffc0000, v7
	v_cvt_pk_bf16_f32 v7, v2, v7
	v_add_u32_e32 v2, 0x240038, v3
	v_ashrrev_i32_e32 v3, 31, v2
	v_lshlrev_b64 v[2:3], 13, v[2:3]
	v_lshl_add_u64 v[0:1], v[0:1], 0, v[2:3]
	global_store_dwordx4 v[0:1], v[4:7], off
	s_waitcnt lgkmcnt(0)
	s_branch .LBB0_874

; __device__ __forceinline__ float bf_lo(unsigned w) { return __uint_as_float(w << 16); }
; __device__ __forceinline__ float bf_hi(unsigned w) { return __uint_as_float(w & 0xffff0000u); }
; __device__ __forceinline__ float wave_sum(float v) {
; #pragma unroll
;     for (int o = 1; o < 64; o <<= 1) v += __shfl_xor(v, o);
;     return v;
; }
; __device__ __forceinline__ void final_norm(const bf16* x, float* out, const float* g, const float* part, int gw, int ngw, int lane) {
;     for (int m = gw; m < M; m += ngw) {
;         const float rstd = 1.0f / sqrtf(wave_sum(part[(size_t)m * 64 + lane]) * (1.f / DM) + NORM_EPS);
;         const v4u* xr = (const v4u*)(x + (size_t)m * DM) + lane;
;         f32x4* o = (f32x4*)(out + (size_t)m * DM) + 2 * lane;
; #pragma unroll
;         for (int j = 0; j < 8; ++j) { const v4u v = xr[64 * j];
;             const f32x4 g0 = *((const f32x4*)g + 128 * j + 2 * lane), g1 = *((const f32x4*)g + 128 * j + 2 * lane + 1);
;             o[128 * j] = (f32x4){bf_lo(v[0]), bf_hi(v[0]), bf_lo(v[1]), bf_hi(v[1])} * rstd * g0;
;             o[128 * j + 1] = (f32x4){bf_lo(v[2]), bf_hi(v[2]), bf_lo(v[3]), bf_hi(v[3])} * rstd * g1; }
;     }
.LBB0_962:
	s_nop 0
	v_lshl_add_u64 v[0:1], s[6:7], 0, v[30:31]
	global_load_dword v0, v[0:1], off
	s_mov_b32 s1, 0x2d800000
	s_add_i32 s0, s0, s8
	v_lshl_add_u64 v[30:31], v[30:31], 0, s[14:15]
	s_cmpk_lt_i32 s0, 0x4000
	s_waitcnt vmcnt(0)
	ds_bpermute_b32 v1, v244, v0
	s_waitcnt lgkmcnt(0)
	v_add_f32_e32 v0, v0, v1
	ds_bpermute_b32 v1, v40, v0
	s_waitcnt lgkmcnt(0)
	v_add_f32_e32 v0, v0, v1
	ds_bpermute_b32 v1, v41, v0
	s_waitcnt lgkmcnt(0)
	v_add_f32_e32 v0, v0, v1
	ds_bpermute_b32 v1, v42, v0
	s_waitcnt lgkmcnt(0)
	v_add_f32_e32 v0, v0, v1
	ds_bpermute_b32 v1, v43, v0
	s_waitcnt lgkmcnt(0)
	v_add_f32_e32 v0, v0, v1
	ds_bpermute_b32 v1, v44, v0
	s_waitcnt lgkmcnt(0)
	v_add_f32_e32 v0, v0, v1
	v_fmamk_f32 v0, v0, 0x39800000, v234
	v_cmp_gt_f32_e32 vcc, s78, v0
	v_mul_f32_e32 v1, 0x4f800000, v0
	s_nop 0
	v_cndmask_b32_e32 v0, v0, v1, vcc
	v_sqrt_f32_e32 v1, v0
	s_nop 0
	v_add_u32_e32 v2, -1, v1
	v_fma_f32 v3, -v2, v1, v0
	v_cmp_ge_f32_e64 s[4:5], 0, v3
	v_add_u32_e32 v3, 1, v1
	s_nop 0
	v_cndmask_b32_e64 v2, v1, v2, s[4:5]
	v_fma_f32 v1, -v3, v1, v0
	v_cmp_lt_f32_e64 s[4:5], 0, v1
	s_nop 1
	v_cndmask_b32_e64 v1, v2, v3, s[4:5]
	v_mul_f32_e32 v2, 0x37800000, v1
	v_cndmask_b32_e32 v1, v1, v2, vcc
	v_cmp_class_f32_e32 vcc, v0, v229
	s_nop 1
	v_cndmask_b32_e32 v0, v1, v0, vcc
	v_div_scale_f32 v1, s[4:5], v0, v0, 1.0
	v_rcp_f32_e32 v2, v1
	s_nop 0
	v_fma_f32 v3, -v1, v2, 1.0
	v_fmac_f32_e32 v2, v3, v2
	v_div_scale_f32 v3, vcc, 1.0, v0, 1.0
	v_mul_f32_e32 v4, v3, v2
	v_fma_f32 v5, -v1, v4, v3
	v_fmac_f32_e32 v4, v5, v2
	v_fma_f32 v1, -v1, v4, v3
	v_div_fmas_f32 v1, v1, v2, v4
	v_div_fixup_f32 v16, v1, v0, 1.0
	v_lshl_add_u64 v[0:1], s[6:7], 0, v[28:29]
	v_add_co_u32_e32 v36, vcc, s1, v0
	s_mov_b32 s1, 0x2d801000
	s_nop 0
	v_addc_co_u32_e32 v37, vcc, 0, v1, vcc
	v_add_co_u32_e32 v34, vcc, s1, v0
	v_lshl_add_u64 v[28:29], v[28:29], 0, s[12:13]
	s_nop 0
	v_addc_co_u32_e32 v35, vcc, 0, v1, vcc
	global_load_dwordx4 v[0:3], v[34:35], off offset:-4096
	global_load_dwordx4 v[4:7], v[12:13], off offset:16
	global_load_dwordx4 v[8:11], v[12:13], off
	s_waitcnt vmcnt(2)
	v_lshlrev_b32_e32 v38, 16, v0
	v_and_b32_e32 v39, 0xffff0000, v0
	v_lshlrev_b32_e32 v0, 16, v1
	v_and_b32_e32 v1, 0xffff0000, v1
	v_pk_mul_f32 v[0:1], v[16:17], v[0:1] op_sel_hi:[0,1]
	s_waitcnt vmcnt(0)
	v_pk_mul_f32 v[10:11], v[10:11], v[0:1]
	v_lshlrev_b32_e32 v0, 16, v2
	v_and_b32_e32 v1, 0xffff0000, v2
	v_lshlrev_b32_e32 v2, 16, v3
	v_and_b32_e32 v3, 0xffff0000, v3
	v_pk_mul_f32 v[38:39], v[16:17], v[38:39] op_sel_hi:[0,1]
	v_pk_mul_f32 v[0:1], v[16:17], v[0:1] op_sel_hi:[0,1]
	v_pk_mul_f32 v[2:3], v[16:17], v[2:3] op_sel_hi:[0,1]
	v_pk_mul_f32 v[8:9], v[8:9], v[38:39]
	v_pk_mul_f32 v[2:3], v[6:7], v[2:3]
	v_pk_mul_f32 v[0:1], v[4:5], v[0:1]
	global_store_dwordx4 v[32:33], v[8:11], off nt
	global_store_dwordx4 v[32:33], v[0:3], off offset:16 nt
	global_load_dwordx4 v[0:3], v[36:37], off offset:1024
	s_nop 0
	global_load_dwordx4 v[4:7], v[12:13], off offset:2064
	global_load_dwordx4 v[8:11], v[12:13], off offset:2048
	s_waitcnt vmcnt(2)
	v_lshlrev_b32_e32 v38, 16, v0
	v_and_b32_e32 v39, 0xffff0000, v0
	v_lshlrev_b32_e32 v0, 16, v1
	v_and_b32_e32 v1, 0xffff0000, v1
	v_pk_mul_f32 v[0:1], v[16:17], v[0:1] op_sel_hi:[0,1]
	s_waitcnt vmcnt(0)
	v_pk_mul_f32 v[10:11], v[10:11], v[0:1]
	v_lshlrev_b32_e32 v0, 16, v2
	v_and_b32_e32 v1, 0xffff0000, v2
	v_lshlrev_b32_e32 v2, 16, v3
	v_and_b32_e32 v3, 0xffff0000, v3
	v_pk_mul_f32 v[38:39], v[16:17], v[38:39] op_sel_hi:[0,1]
	v_pk_mul_f32 v[0:1], v[16:17], v[0:1] op_sel_hi:[0,1]
	v_pk_mul_f32 v[2:3], v[16:17], v[2:3] op_sel_hi:[0,1]
	v_pk_mul_f32 v[8:9], v[8:9], v[38:39]
	v_pk_mul_f32 v[2:3], v[6:7], v[2:3]
	v_pk_mul_f32 v[0:1], v[4:5], v[0:1]
	global_store_dwordx4 v[32:33], v[8:11], off offset:2048 nt
	global_store_dwordx4 v[32:33], v[0:3], off offset:2064 nt
	global_load_dwordx4 v[4:7], v[36:37], off offset:2048
	s_nop 0
	global_load_dwordx4 v[0:3], v[14:15], off offset:16
	global_load_dwordx4 v[8:11], v[14:15], off
	s_waitcnt vmcnt(2)
	v_lshlrev_b32_e32 v38, 16, v4
	v_and_b32_e32 v39, 0xffff0000, v4
	v_pk_mul_f32 v[38:39], v[16:17], v[38:39] op_sel_hi:[0,1]
	v_lshlrev_b32_e32 v4, 16, v5
	v_and_b32_e32 v5, 0xffff0000, v5
	s_waitcnt vmcnt(0)
	v_pk_mul_f32 v[8:9], v[8:9], v[38:39]
	v_add_co_u32_e32 v38, vcc, s73, v32
	v_pk_mul_f32 v[4:5], v[16:17], v[4:5] op_sel_hi:[0,1]
	s_nop 0
	v_addc_co_u32_e32 v39, vcc, 0, v33, vcc
	v_pk_mul_f32 v[10:11], v[10:11], v[4:5]
	v_add_co_u32_e32 v4, vcc, s9, v32
	s_nop 1
	v_addc_co_u32_e32 v5, vcc, 0, v33, vcc
	global_store_dwordx4 v[4:5], v[8:11], off offset:-4096 nt
	s_nop 1
	v_lshlrev_b32_e32 v8, 16, v6
	v_and_b32_e32 v9, 0xffff0000, v6
	v_lshlrev_b32_e32 v6, 16, v7
	v_and_b32_e32 v7, 0xffff0000, v7
	v_pk_mul_f32 v[8:9], v[16:17], v[8:9] op_sel_hi:[0,1]
	v_pk_mul_f32 v[6:7], v[16:17], v[6:7] op_sel_hi:[0,1]
	v_pk_mul_f32 v[2:3], v[2:3], v[6:7]
	v_pk_mul_f32 v[0:1], v[0:1], v[8:9]
	global_store_dwordx4 v[38:39], v[0:3], off offset:16 nt
	global_load_dwordx4 v[0:3], v[36:37], off offset:3072
	s_nop 0
	global_load_dwordx4 v[6:9], v[18:19], off offset:16
	global_load_dwordx4 v[46:49], v[18:19], off
	s_waitcnt vmcnt(2)
; __device__ __forceinline__ float bf_lo(unsigned w) { return __uint_as_float(w << 16); }
; __device__ __forceinline__ float bf_hi(unsigned w) { return __uint_as_float(w & 0xffff0000u); }
; __device__ __forceinline__ void final_norm(const bf16* x, float* out, const float* g, const float* part, int gw, int ngw, int lane) {
;     for (int m = gw; m < M; m += ngw) {
;         const float rstd = 1.0f / sqrtf(wave_sum(part[(size_t)m * 64 + lane]) * (1.f / DM) + NORM_EPS);
;         const v4u* xr = (const v4u*)(x + (size_t)m * DM) + lane;
;         f32x4* o = (f32x4*)(out + (size_t)m * DM) + 2 * lane;
; #pragma unroll
;         for (int j = 0; j < 8; ++j) { const v4u v = xr[64 * j];
;             const f32x4 g0 = *((const f32x4*)g + 128 * j + 2 * lane), g1 = *((const f32x4*)g + 128 * j + 2 * lane + 1);
;             o[128 * j] = (f32x4){bf_lo(v[0]), bf_hi(v[0]), bf_lo(v[1]), bf_hi(v[1])} * rstd * g0;
;             o[128 * j + 1] = (f32x4){bf_lo(v[2]), bf_hi(v[2]), bf_lo(v[3]), bf_hi(v[3])} * rstd * g1; }
;     }
	v_lshlrev_b32_e32 v10, 16, v0
	v_and_b32_e32 v11, 0xffff0000, v0
	v_lshlrev_b32_e32 v0, 16, v1
	v_and_b32_e32 v1, 0xffff0000, v1
	v_pk_mul_f32 v[0:1], v[16:17], v[0:1] op_sel_hi:[0,1]
	s_waitcnt vmcnt(0)
	v_pk_mul_f32 v[48:49], v[48:49], v[0:1]
	v_lshlrev_b32_e32 v0, 16, v2
	v_and_b32_e32 v1, 0xffff0000, v2
	v_lshlrev_b32_e32 v2, 16, v3
	v_and_b32_e32 v3, 0xffff0000, v3
	v_pk_mul_f32 v[10:11], v[16:17], v[10:11] op_sel_hi:[0,1]
	v_pk_mul_f32 v[0:1], v[16:17], v[0:1] op_sel_hi:[0,1]
	v_pk_mul_f32 v[2:3], v[16:17], v[2:3] op_sel_hi:[0,1]
	v_pk_mul_f32 v[46:47], v[46:47], v[10:11]
	v_pk_mul_f32 v[2:3], v[8:9], v[2:3]
	v_pk_mul_f32 v[0:1], v[6:7], v[0:1]
	global_store_dwordx4 v[38:39], v[46:49], off offset:2048 nt
	global_store_dwordx4 v[38:39], v[0:3], off offset:2064 nt
	global_load_dwordx4 v[0:3], v[34:35], off
	s_nop 0
	global_load_dwordx4 v[6:9], v[20:21], off offset:16
	global_load_dwordx4 v[36:39], v[20:21], off
	s_waitcnt vmcnt(2)
	v_lshlrev_b32_e32 v10, 16, v0
	v_and_b32_e32 v11, 0xffff0000, v0
	v_lshlrev_b32_e32 v0, 16, v1
	v_and_b32_e32 v1, 0xffff0000, v1
	v_pk_mul_f32 v[0:1], v[16:17], v[0:1] op_sel_hi:[0,1]
	s_waitcnt vmcnt(0)
	v_pk_mul_f32 v[38:39], v[38:39], v[0:1]
	v_lshlrev_b32_e32 v0, 16, v2
	v_and_b32_e32 v1, 0xffff0000, v2
	v_lshlrev_b32_e32 v2, 16, v3
	v_and_b32_e32 v3, 0xffff0000, v3
	v_pk_mul_f32 v[10:11], v[16:17], v[10:11] op_sel_hi:[0,1]
	v_pk_mul_f32 v[0:1], v[16:17], v[0:1] op_sel_hi:[0,1]
	v_pk_mul_f32 v[2:3], v[16:17], v[2:3] op_sel_hi:[0,1]
	v_pk_mul_f32 v[36:37], v[36:37], v[10:11]
	v_pk_mul_f32 v[2:3], v[8:9], v[2:3]
	v_pk_mul_f32 v[0:1], v[6:7], v[0:1]
	global_store_dwordx4 v[4:5], v[36:39], off nt
	global_store_dwordx4 v[4:5], v[0:3], off offset:16 nt
	global_load_dwordx4 v[0:3], v[34:35], off offset:1024
	s_nop 0
	global_load_dwordx4 v[6:9], v[22:23], off offset:16
	global_load_dwordx4 v[36:39], v[22:23], off
	s_waitcnt vmcnt(2)
	v_lshlrev_b32_e32 v10, 16, v0
	v_and_b32_e32 v11, 0xffff0000, v0
	v_lshlrev_b32_e32 v0, 16, v1
	v_and_b32_e32 v1, 0xffff0000, v1
	v_pk_mul_f32 v[0:1], v[16:17], v[0:1] op_sel_hi:[0,1]
	s_waitcnt vmcnt(0)
	v_pk_mul_f32 v[38:39], v[38:39], v[0:1]
	v_lshlrev_b32_e32 v0, 16, v2
	v_and_b32_e32 v1, 0xffff0000, v2
	v_lshlrev_b32_e32 v2, 16, v3
	v_and_b32_e32 v3, 0xffff0000, v3
	v_pk_mul_f32 v[10:11], v[16:17], v[10:11] op_sel_hi:[0,1]
	v_pk_mul_f32 v[0:1], v[16:17], v[0:1] op_sel_hi:[0,1]
	v_pk_mul_f32 v[2:3], v[16:17], v[2:3] op_sel_hi:[0,1]
	v_pk_mul_f32 v[36:37], v[36:37], v[10:11]
	v_pk_mul_f32 v[2:3], v[8:9], v[2:3]
	v_pk_mul_f32 v[0:1], v[6:7], v[0:1]
	global_store_dwordx4 v[4:5], v[36:39], off offset:2048 nt
	global_store_dwordx4 v[4:5], v[0:3], off offset:2064 nt
	global_load_dwordx4 v[0:3], v[34:35], off offset:2048
	s_nop 0
	global_load_dwordx4 v[4:7], v[24:25], off offset:16
	global_load_dwordx4 v[8:11], v[24:25], off
	s_waitcnt vmcnt(2)
	v_lshlrev_b32_e32 v36, 16, v0
	v_and_b32_e32 v37, 0xffff0000, v0
	v_lshlrev_b32_e32 v0, 16, v1
	v_and_b32_e32 v1, 0xffff0000, v1
	v_pk_mul_f32 v[0:1], v[16:17], v[0:1] op_sel_hi:[0,1]
	v_pk_mul_f32 v[36:37], v[16:17], v[36:37] op_sel_hi:[0,1]
	s_waitcnt vmcnt(0)
	v_pk_mul_f32 v[10:11], v[10:11], v[0:1]
	v_lshlrev_b32_e32 v0, 16, v2
	v_and_b32_e32 v1, 0xffff0000, v2
	v_lshlrev_b32_e32 v2, 16, v3
	v_and_b32_e32 v3, 0xffff0000, v3
	v_pk_mul_f32 v[8:9], v[8:9], v[36:37]
	v_add_co_u32_e32 v36, vcc, s10, v32
	v_pk_mul_f32 v[0:1], v[16:17], v[0:1] op_sel_hi:[0,1]
	v_pk_mul_f32 v[2:3], v[16:17], v[2:3] op_sel_hi:[0,1]
	v_addc_co_u32_e32 v37, vcc, 0, v33, vcc
	v_pk_mul_f32 v[2:3], v[6:7], v[2:3]
	v_pk_mul_f32 v[0:1], v[4:5], v[0:1]
	global_store_dwordx4 v[36:37], v[8:11], off nt
	global_store_dwordx4 v[36:37], v[0:3], off offset:16 nt
	global_load_dwordx4 v[0:3], v[34:35], off offset:3072
	s_nop 0
	global_load_dwordx4 v[4:7], v[26:27], off offset:16
	global_load_dwordx4 v[8:11], v[26:27], off
	v_lshl_add_u64 v[32:33], v[32:33], 0, s[16:17]
	s_waitcnt vmcnt(2)
	v_lshlrev_b32_e32 v34, 16, v0
	v_and_b32_e32 v35, 0xffff0000, v0
	v_lshlrev_b32_e32 v0, 16, v1
	v_and_b32_e32 v1, 0xffff0000, v1
	v_pk_mul_f32 v[0:1], v[16:17], v[0:1] op_sel_hi:[0,1]
	s_waitcnt vmcnt(0)
	v_pk_mul_f32 v[10:11], v[10:11], v[0:1]
	v_lshlrev_b32_e32 v0, 16, v2
	v_and_b32_e32 v1, 0xffff0000, v2
	v_lshlrev_b32_e32 v2, 16, v3
	v_and_b32_e32 v3, 0xffff0000, v3
	v_pk_mul_f32 v[34:35], v[16:17], v[34:35] op_sel_hi:[0,1]
	v_pk_mul_f32 v[0:1], v[16:17], v[0:1] op_sel_hi:[0,1]
	v_pk_mul_f32 v[2:3], v[16:17], v[2:3] op_sel_hi:[0,1]
	v_pk_mul_f32 v[8:9], v[8:9], v[34:35]
	v_pk_mul_f32 v[2:3], v[6:7], v[2:3]
	v_pk_mul_f32 v[0:1], v[4:5], v[0:1]
	global_store_dwordx4 v[36:37], v[8:11], off offset:2048 nt
	global_store_dwordx4 v[36:37], v[0:3], off offset:2064 nt
	s_cbranch_scc1 .LBB0_962
